# GEMM bf16 epilogues (inproj, upproj, gates, merge, up): dwordx2 row-per-lane stores widened to dwordx4 via v_permlane16_swap pairs (doc 7.3), same bytes to same addresses
# speedup vs baseline: 1.0176x; 1.0118x over previous
; #define ST4(ptr, a, b, c_, d) (*(uint2*)(ptr) = make_uint2((unsigned)f2bf(a) | ((unsigned)f2bf(b) << 16), (unsigned)f2bf(c_) | ((unsigned)f2bf(d) << 16)))
; __device__ __forceinline__ void head_norm_rope_store(f32x4 (&v)[4], const float (&g)[16], const float* __restrict__ rp, float qscale, u16* __restrict__ dstp) {
;   float ss = 0.f;
; #pragma unroll
;   for (int n = 0; n < 4; ++n)
; #pragma unroll
;     for (int j = 0; j < 4; ++j) ss += v[n][j] * v[n][j];
;   { auto rr = __builtin_amdgcn_permlane16_swap(__float_as_uint(ss), __float_as_uint(ss), false, false); ss = __uint_as_float(rr[0]) + __uint_as_float(rr[1]); }
;   { auto rr = __builtin_amdgcn_permlane32_swap(__float_as_uint(ss), __float_as_uint(ss), false, false); ss = __uint_as_float(rr[0]) + __uint_as_float(rr[1]); }
;   const float rs = rsqrtf(ss * (1.f / 64.f) + EPS) * qscale;
; #pragma unroll
;   for (int h2 = 0; h2 < 2; ++h2) {
;     const float4 c01 = *(const float4*)(rp + h2 * 32), c23 = *(const float4*)(rp + h2 * 32 + 4);
; __device__ __forceinline__ void inproj_phase(const Ctx& p, int layer, int hf) {
;     ...
;     const int kind = pn < 2 ? 1 : pn < 4 ? 2 : (pn == 9 || pn == 10) ? 3 : (pn == 11 && wc < 2) ? 4 : 0;
;     if (kind == 0) {
;       ACC_LOOP( ST4(dst + (size_t)row * ldc + c0 + col, v4[0], v4[1], v4[2], v4[3]); )
;     } else {
;       const float* gp = (kind == 1 ? IN(5) : kind == 2 ? IN(6) : kind == 3 ? IN(18) : IN(19)) + layer * 64 + fq * 4;
;       float g[16];
; #pragma unroll
;       for (int n = 0; n < 4; ++n) { const float4 g4 = *(const float4*)(gp + n * 16); g[n * 4] = g4.x; g[n * 4 + 1] = g4.y; g[n * 4 + 2] = g4.z; g[n * 4 + 3] = g4.w; }
;       const float qscale = (kind == 1 || kind == 3) ? QC_64 : 1.f;
; #pragma unroll
;       for (int m = 0; m < 9; ++m) {
;         if (m < 8 || (fat && wr == 1)) {
;           const int row = m < 8 ? brow + wr * 128 + m * 16 + fr : brow + 256 + fr;
;           const int pos = hf == 0 ? row : row % L1;
;           f32x4 v[4];
; #pragma unroll
;           for (int n = 0; n < 4; ++n) v[n] = m < 8 ? acc[m < 8 ? m : 0][n] : accx[n];
;           head_norm_rope_store(v, g, rope + (size_t)pos * 64 + fq * 8, qscale, dst + (size_t)row * ldc + c0 + wc * 64 + fq * 4);
.LBB0_254:
	v_cmp_ne_u32_e32 vcc, 0, v20
	s_and_saveexec_b64 s[6:7], vcc
	s_xor_b64 s[78:79], exec, s[6:7]
	s_cbranch_execz .LBB0_258
	v_cmp_eq_u32_e64 s[6:7], 3, v20
	v_mov_b32_e32 v21, 0x27e7198
	v_mov_b32_e32 v22, 0x27e7190
	v_cmp_eq_u32_e32 vcc, 1, v20
	v_cndmask_b32_e64 v21, v21, v22, s[6:7]
	v_cmp_ne_u32_e64 s[8:9], 2, v20
	v_mov_b32_e32 v20, 0x27e7130
	s_ashr_i32 s73, s72, 31
	v_cndmask_b32_e64 v20, v20, v21, s[8:9]
	v_mov_b32_e32 v21, 0x27e7128
	v_cndmask_b32_e32 v128, v20, v21, vcc
	v_lshl_add_u64 v[20:21], s[10:11], 0, v[128:129]
	global_load_dwordx2 v[20:21], v[20:21], off
	v_readlane_b32 s8, v254, 52
	v_readlane_b32 s9, v254, 53
	s_or_b64 vcc, vcc, s[6:7]
	s_lshl_b64 s[6:7], s[72:73], 1
	v_lshlrev_b32_e32 v128, 2, v222
	v_mov_b32_e32 v229, v129
	v_add_u32_e32 v193, s68, v240
	v_pk_mul_f32 v[164:165], v[146:147], v[146:147]
	v_mov_b32_e32 v184, v158
	v_mov_b32_e32 v185, v160
	v_mov_b32_e32 v186, v154
	v_mov_b32_e32 v187, v156
	v_mov_b32_e32 v180, v146
	v_mov_b32_e32 v181, v148
	s_mov_b32 s20, 0x3c800000
	s_waitcnt vmcnt(0)
	v_lshl_add_u64 v[20:21], s[8:9], 2, v[20:21]
	s_and_b64 s[8:9], s[4:5], s[70:71]
	s_add_u32 s6, s74, s6
	v_lshl_add_u64 v[20:21], v[20:21], 0, v[128:129]
	v_mov_b32_e32 v128, 0x3e38aa3b
	s_addc_u32 s7, s75, s7
	v_cndmask_b32_e32 v192, 1.0, v128, vcc
	v_lshl_add_u64 v[162:163], s[6:7], 0, v[228:229]
	v_lshlrev_b32_e32 v128, 1, v222
	v_lshl_add_u64 v[170:171], v[162:163], 0, v[128:129]
	v_or_b32_e32 v128, v193, v238
	v_mul_hi_i32 v162, v128, s52
	v_lshrrev_b32_e32 v163, 31, v162
	v_ashrrev_i32_e32 v162, 11, v162
	v_add_u32_e32 v162, v162, v163
	v_mul_i32_i24_e32 v162, 0x1010, v162
	v_sub_u32_e32 v162, v128, v162
	v_cndmask_b32_e64 v162, v162, v128, s[62:63]
	v_ashrrev_i32_e32 v163, 31, v162
	v_lshlrev_b64 v[162:163], 8, v[162:163]
	v_lshl_add_u64 v[178:179], v[224:225], 0, v[162:163]
	v_mad_i64_i32 v[162:163], s[6:7], s76, v128, 0
	v_mul_f32_e32 v128, v159, v159
	v_fmac_f32_e32 v128, v158, v158
	v_fmac_f32_e32 v128, v160, v160
	v_fmac_f32_e32 v128, v161, v161
	v_fmac_f32_e32 v128, v150, v150
	v_fmac_f32_e32 v128, v151, v151
	v_fmac_f32_e32 v128, v152, v152
	v_fmac_f32_e32 v128, v153, v153
	v_fmac_f32_e32 v128, v154, v154
	v_fmac_f32_e32 v128, v155, v155
	v_fmac_f32_e32 v128, v156, v156
	v_fmac_f32_e32 v128, v157, v157
	v_add_f32_e32 v128, v164, v128
	v_lshl_add_u64 v[176:177], v[162:163], 1, v[170:171]
	v_pk_mul_f32 v[162:163], v[148:149], v[148:149]
	v_add_f32_e32 v128, v165, v128
	v_add_f32_e32 v128, v162, v128
	v_add_f32_e32 v128, v163, v128
	v_mov_b32_e32 v162, v128
	s_nop 1
	v_permlane16_swap_b32_e32 v128, v162
	flat_load_dwordx4 v[60:63], v[20:21]
	flat_load_dwordx4 v[52:55], v[20:21] offset:128
	flat_load_dwordx4 v[28:31], v[20:21] offset:64
	s_nop 0
	flat_load_dwordx4 v[20:23], v[20:21] offset:192
	v_add_f32_e32 v189, v128, v162
	global_load_dwordx4 v[162:165], v[178:179], off offset:16
	global_load_dwordx4 v[166:169], v[178:179], off
	v_mov_b32_e32 v160, v159
	v_mov_b32_e32 v156, v155
	v_mul_f32_e32 v128, v143, v143
	v_fmac_f32_e32 v128, v142, v142
	v_fmac_f32_e32 v128, v144, v144
	v_fmac_f32_e32 v128, v145, v145
	v_fmac_f32_e32 v128, v134, v134
	v_fmac_f32_e32 v128, v135, v135
	v_fmac_f32_e32 v128, v136, v136
	v_fmac_f32_e32 v128, v137, v137
	v_fmac_f32_e32 v128, v138, v138
	v_fmac_f32_e32 v128, v139, v139
	v_fmac_f32_e32 v128, v140, v140
	v_fmac_f32_e32 v128, v141, v141
	v_mov_b32_e32 v148, v147
	v_mov_b32_e32 v191, v189
	s_nop 1
	v_permlane32_swap_b32_e32 v189, v191
	s_waitcnt vmcnt(0) lgkmcnt(0)
	v_mov_b32_e32 v174, v60
	v_mov_b32_e32 v172, v52
	v_mov_b32_e32 v52, v28
	v_add_u32_e32 v28, v193, v242
	v_mov_b32_e32 v155, v162
	v_mov_b32_e32 v154, v166
	v_mov_b32_e32 v162, v167
	v_mov_b32_e32 v158, v168
	v_mov_b32_e32 v159, v164
	v_mov_b32_e32 v164, v169
	global_load_dwordx4 v[166:169], v[178:179], off offset:144
	global_load_dwordx4 v[194:197], v[178:179], off offset:128
	v_mov_b32_e32 v60, v20
	v_mul_hi_i32 v20, v28, s52
	v_mov_b32_e32 v175, v62
	v_mov_b32_e32 v62, v61
	v_mov_b32_e32 v61, v22
	v_mov_b32_e32 v22, v21
	v_lshrrev_b32_e32 v21, 31, v20
	v_ashrrev_i32_e32 v20, 11, v20
	v_add_u32_e32 v20, v20, v21
	v_mul_i32_i24_e32 v20, 0x1010, v20
	v_sub_u32_e32 v20, v28, v20
	v_cndmask_b32_e64 v20, v20, v28, s[62:63]
	v_ashrrev_i32_e32 v21, 31, v20
	v_mov_b32_e32 v178, v150
	v_mov_b32_e32 v179, v152
	v_mov_b32_e32 v152, v151
	v_lshlrev_b64 v[20:21], 8, v[20:21]
	v_lshl_add_u64 v[146:147], v[224:225], 0, v[20:21]
	v_mad_i64_i32 v[20:21], s[6:7], s76, v28, 0
	v_mov_b32_e32 v173, v54
	v_mov_b32_e32 v54, v53
	v_mov_b32_e32 v53, v30
	v_mov_b32_e32 v30, v29
	v_lshl_add_u64 v[28:29], v[20:21], 1, v[170:171]
	v_pk_mul_f32 v[20:21], v[132:133], v[132:133]
	s_waitcnt vmcnt(1)
	v_mov_b32_e32 v151, v166
	s_waitcnt vmcnt(0)
; #define ST4(ptr, a, b, c_, d) (*(uint2*)(ptr) = make_uint2((unsigned)f2bf(a) | ((unsigned)f2bf(b) << 16), (unsigned)f2bf(c_) | ((unsigned)f2bf(d) << 16)))
; __device__ __forceinline__ void head_norm_rope_store(f32x4 (&v)[4], const float (&g)[16], const float* __restrict__ rp, float qscale, u16* __restrict__ dstp) {
;   float ss = 0.f;
; #pragma unroll
;   for (int n = 0; n < 4; ++n)
; #pragma unroll
;     for (int j = 0; j < 4; ++j) ss += v[n][j] * v[n][j];
;   { auto rr = __builtin_amdgcn_permlane16_swap(__float_as_uint(ss), __float_as_uint(ss), false, false); ss = __uint_as_float(rr[0]) + __uint_as_float(rr[1]); }
;   { auto rr = __builtin_amdgcn_permlane32_swap(__float_as_uint(ss), __float_as_uint(ss), false, false); ss = __uint_as_float(rr[0]) + __uint_as_float(rr[1]); }
;   const float rs = rsqrtf(ss * (1.f / 64.f) + EPS) * qscale;
; #pragma unroll
;   for (int h2 = 0; h2 < 2; ++h2) {
;     const float4 c01 = *(const float4*)(rp + h2 * 32), c23 = *(const float4*)(rp + h2 * 32 + 4);
;     const float cs_[4] = {c01.x, c01.z, c23.x, c23.z}, sn_[4] = {c01.y, c01.w, c23.y, c23.w};
;     float o1[4], o2[4];
; #pragma unroll
;     for (int j = 0; j < 4; ++j) {
;       const float x1 = v[h2][j] * rs * g[h2 * 4 + j], x2 = v[h2 + 2][j] * rs * g[(h2 + 2) * 4 + j];
;       o1[j] = x1 * cs_[j] - x2 * sn_[j]; o2[j] = x1 * sn_[j] + x2 * cs_[j];
;     }
;     ST4(dstp + h2 * 16, o1[0], o1[1], o1[2], o1[3]);
;     ST4(dstp + (h2 + 2) * 16, o2[0], o2[1], o2[2], o2[3]);
;   }
; __device__ __forceinline__ void inproj_phase(const Ctx& p, int layer, int hf) {
;     ...
;       for (int m = 0; m < 9; ++m) {
;         if (m < 8 || (fat && wr == 1)) {
;           const int row = m < 8 ? brow + wr * 128 + m * 16 + fr : brow + 256 + fr;
;           const int pos = hf == 0 ? row : row % L1;
;           f32x4 v[4];
; #pragma unroll
;           for (int n = 0; n < 4; ++n) v[n] = m < 8 ? acc[m < 8 ? m : 0][n] : accx[n];
;           head_norm_rope_store(v, g, rope + (size_t)pos * 64 + fq * 8, qscale, dst + (size_t)row * ldc + c0 + wc * 64 + fq * 4);
	v_mov_b32_e32 v150, v194
	v_mov_b32_e32 v166, v195
	v_pk_mul_f32 v[194:195], v[130:131], v[130:131]
	v_mov_b32_e32 v183, v168
	v_add_f32_e32 v128, v194, v128
	v_add_f32_e32 v128, v195, v128
	v_add_f32_e32 v20, v20, v128
	v_add_f32_e32 v20, v21, v20
	v_mov_b32_e32 v21, v20
	s_nop 1
	v_permlane16_swap_b32_e32 v20, v21
	v_add_f32_e32 v188, v20, v21
	v_mov_b32_e32 v190, v188
	s_nop 1
	v_permlane32_swap_b32_e32 v188, v190
	v_pk_add_f32 v[188:189], v[188:189], v[190:191]
	v_mov_b64_e32 v[20:21], s[40:41]
	v_pk_fma_f32 v[188:189], v[188:189], s[20:21], v[20:21] op_sel_hi:[1,0,0]
	v_mov_b32_e32 v168, v197
	v_mul_f32_e32 v128, 0x4b800000, v189
	v_cmp_gt_f32_e64 s[6:7], s96, v189
	v_mov_b32_e32 v182, v196
	v_cmp_gt_f32_e32 vcc, s96, v188
	v_cndmask_b32_e64 v128, v189, v128, s[6:7]
	v_rsq_f32_e32 v128, v128
	s_nop 0
	v_mul_f32_e32 v189, 0x45800000, v128
	v_cndmask_b32_e64 v128, v128, v189, s[6:7]
	v_mul_f32_e32 v128, v192, v128
	v_pk_mul_f32 v[186:187], v[186:187], v[128:129] op_sel_hi:[1,0]
	v_pk_mul_f32 v[184:185], v[184:185], v[128:129] op_sel_hi:[1,0]
	v_pk_mul_f32 v[186:187], v[172:173], v[186:187]
	v_pk_mul_f32 v[184:185], v[174:175], v[184:185]
	v_pk_mul_f32 v[156:157], v[156:157], v[128:129] op_sel_hi:[1,0]
	v_pk_mul_f32 v[190:191], v[162:163], v[186:187]
	v_pk_mul_f32 v[160:161], v[160:161], v[128:129] op_sel_hi:[1,0]
	v_pk_mul_f32 v[156:157], v[54:55], v[156:157]
	v_pk_fma_f32 v[190:191], v[154:155], v[184:185], v[190:191] neg_lo:[0,0,1] neg_hi:[0,0,1]
	v_pk_mul_f32 v[154:155], v[154:155], v[186:187]
	v_pk_mul_f32 v[160:161], v[62:63], v[160:161]
	v_pk_mul_f32 v[194:195], v[164:165], v[156:157]
	v_pk_fma_f32 v[154:155], v[162:163], v[184:185], v[154:155]
	v_pk_mul_f32 v[156:157], v[158:159], v[156:157]
	v_pk_fma_f32 v[194:195], v[158:159], v[160:161], v[194:195] neg_lo:[0,0,1] neg_hi:[0,0,1]
	v_pk_fma_f32 v[156:157], v[164:165], v[160:161], v[156:157]
	v_and_b32_sdwa v158, v155, v232 dst_sel:DWORD dst_unused:UNUSED_PAD src0_sel:WORD_1 src1_sel:DWORD
	v_and_b32_sdwa v159, v154, v232 dst_sel:DWORD dst_unused:UNUSED_PAD src0_sel:WORD_1 src1_sel:DWORD
	v_add3_u32 v154, v154, v159, s43
	v_add3_u32 v155, v155, v158, s43
	v_and_b32_sdwa v158, v157, v232 dst_sel:DWORD dst_unused:UNUSED_PAD src0_sel:WORD_1 src1_sel:DWORD
	v_and_b32_sdwa v159, v156, v232 dst_sel:DWORD dst_unused:UNUSED_PAD src0_sel:WORD_1 src1_sel:DWORD
	v_add3_u32 v157, v157, v158, s43
	v_add3_u32 v156, v156, v159, s43
	v_and_b32_e32 v157, 0xffff0000, v157
	v_and_b32_e32 v156, 0xffff0000, v156
	v_or_b32_sdwa v155, v157, v155 dst_sel:DWORD dst_unused:UNUSED_PAD src0_sel:DWORD src1_sel:WORD_1
	v_or_b32_sdwa v154, v156, v154 dst_sel:DWORD dst_unused:UNUSED_PAD src0_sel:DWORD src1_sel:WORD_1
	v_pk_mul_f32 v[156:157], v[180:181], v[128:129] op_sel_hi:[1,0]
	s_nop 0
	v_mov_b32_e32 v212, v154
	v_mov_b32_e32 v213, v155
	v_pk_mul_f32 v[154:155], v[178:179], v[128:129] op_sel_hi:[1,0]
	v_pk_mul_f32 v[156:157], v[60:61], v[156:157]
	v_pk_mul_f32 v[148:149], v[148:149], v[128:129] op_sel_hi:[1,0]
	v_pk_mul_f32 v[154:155], v[52:53], v[154:155]
	v_pk_mul_f32 v[152:153], v[152:153], v[128:129] op_sel_hi:[1,0]
	v_pk_mul_f32 v[148:149], v[22:23], v[148:149]
	v_pk_mul_f32 v[158:159], v[156:157], v[166:167]
	v_pk_mul_f32 v[152:153], v[30:31], v[152:153]
	v_pk_fma_f32 v[158:159], v[150:151], v[154:155], v[158:159] neg_lo:[0,0,1] neg_hi:[0,0,1]
	v_pk_mul_f32 v[160:161], v[148:149], v[168:169]
	v_and_b32_sdwa v128, v159, v232 dst_sel:DWORD dst_unused:UNUSED_PAD src0_sel:WORD_1 src1_sel:DWORD
	v_pk_fma_f32 v[160:161], v[152:153], v[182:183], v[160:161] neg_lo:[0,0,1] neg_hi:[0,0,1]
	v_add3_u32 v128, v159, v128, s43
	v_and_b32_sdwa v159, v161, v232 dst_sel:DWORD dst_unused:UNUSED_PAD src0_sel:WORD_1 src1_sel:DWORD
	v_add3_u32 v159, v161, v159, s43
	v_pk_mul_f32 v[154:155], v[154:155], v[166:167]
	v_and_b32_e32 v159, 0xffff0000, v159
	v_pk_fma_f32 v[150:151], v[156:157], v[150:151], v[154:155]
	v_pk_mul_f32 v[152:153], v[152:153], v[168:169]
	v_and_b32_sdwa v189, v191, v232 dst_sel:DWORD dst_unused:UNUSED_PAD src0_sel:WORD_1 src1_sel:DWORD
	v_and_b32_sdwa v196, v190, v232 dst_sel:DWORD dst_unused:UNUSED_PAD src0_sel:WORD_1 src1_sel:DWORD
	v_and_b32_sdwa v162, v158, v232 dst_sel:DWORD dst_unused:UNUSED_PAD src0_sel:WORD_1 src1_sel:DWORD
	v_or_b32_sdwa v159, v159, v128 dst_sel:DWORD dst_unused:UNUSED_PAD src0_sel:DWORD src1_sel:WORD_1
	v_pk_fma_f32 v[148:149], v[148:149], v[182:183], v[152:153]
	v_and_b32_sdwa v128, v151, v232 dst_sel:DWORD dst_unused:UNUSED_PAD src0_sel:WORD_1 src1_sel:DWORD
	v_and_b32_sdwa v152, v150, v232 dst_sel:DWORD dst_unused:UNUSED_PAD src0_sel:WORD_1 src1_sel:DWORD
	v_add3_u32 v190, v190, v196, s43
	v_add3_u32 v189, v191, v189, s43
	v_and_b32_sdwa v191, v195, v232 dst_sel:DWORD dst_unused:UNUSED_PAD src0_sel:WORD_1 src1_sel:DWORD
	v_and_b32_sdwa v196, v194, v232 dst_sel:DWORD dst_unused:UNUSED_PAD src0_sel:WORD_1 src1_sel:DWORD
	v_add3_u32 v158, v158, v162, s43
	v_and_b32_sdwa v162, v160, v232 dst_sel:DWORD dst_unused:UNUSED_PAD src0_sel:WORD_1 src1_sel:DWORD
	v_add3_u32 v150, v150, v152, s43
	v_add3_u32 v128, v151, v128, s43
	v_and_b32_sdwa v151, v149, v232 dst_sel:DWORD dst_unused:UNUSED_PAD src0_sel:WORD_1 src1_sel:DWORD
	v_and_b32_sdwa v152, v148, v232 dst_sel:DWORD dst_unused:UNUSED_PAD src0_sel:WORD_1 src1_sel:DWORD
	v_add3_u32 v191, v195, v191, s43
	v_add3_u32 v194, v194, v196, s43
	v_add3_u32 v160, v160, v162, s43
	v_add3_u32 v149, v149, v151, s43
	v_add3_u32 v148, v148, v152, s43
	v_and_b32_e32 v191, 0xffff0000, v191
	v_and_b32_e32 v194, 0xffff0000, v194
	v_and_b32_e32 v160, 0xffff0000, v160
	v_and_b32_e32 v149, 0xffff0000, v149
	v_and_b32_e32 v148, 0xffff0000, v148
; #define ST4(ptr, a, b, c_, d) (*(uint2*)(ptr) = make_uint2((unsigned)f2bf(a) | ((unsigned)f2bf(b) << 16), (unsigned)f2bf(c_) | ((unsigned)f2bf(d) << 16)))
; __device__ __forceinline__ void head_norm_rope_store(f32x4 (&v)[4], const float (&g)[16], const float* __restrict__ rp, float qscale, u16* __restrict__ dstp) {
;   float ss = 0.f;
; #pragma unroll
;   for (int n = 0; n < 4; ++n)
; #pragma unroll
;     for (int j = 0; j < 4; ++j) ss += v[n][j] * v[n][j];
;   { auto rr = __builtin_amdgcn_permlane16_swap(__float_as_uint(ss), __float_as_uint(ss), false, false); ss = __uint_as_float(rr[0]) + __uint_as_float(rr[1]); }
;   { auto rr = __builtin_amdgcn_permlane32_swap(__float_as_uint(ss), __float_as_uint(ss), false, false); ss = __uint_as_float(rr[0]) + __uint_as_float(rr[1]); }
;   const float rs = rsqrtf(ss * (1.f / 64.f) + EPS) * qscale;
; #pragma unroll
;   for (int h2 = 0; h2 < 2; ++h2) {
;     const float4 c01 = *(const float4*)(rp + h2 * 32), c23 = *(const float4*)(rp + h2 * 32 + 4);
;     const float cs_[4] = {c01.x, c01.z, c23.x, c23.z}, sn_[4] = {c01.y, c01.w, c23.y, c23.w};
;     float o1[4], o2[4];
; #pragma unroll
;     for (int j = 0; j < 4; ++j) {
;       const float x1 = v[h2][j] * rs * g[h2 * 4 + j], x2 = v[h2 + 2][j] * rs * g[(h2 + 2) * 4 + j];
;       o1[j] = x1 * cs_[j] - x2 * sn_[j]; o2[j] = x1 * sn_[j] + x2 * cs_[j];
;     }
;     ST4(dstp + h2 * 16, o1[0], o1[1], o1[2], o1[3]);
;     ST4(dstp + (h2 + 2) * 16, o2[0], o2[1], o2[2], o2[3]);
;   }
; __device__ __forceinline__ void inproj_phase(const Ctx& p, int layer, int hf) {
;     ...
;       for (int m = 0; m < 9; ++m) {
;         if (m < 8 || (fat && wr == 1)) {
;           const int row = m < 8 ? brow + wr * 128 + m * 16 + fr : brow + 256 + fr;
;           const int pos = hf == 0 ? row : row % L1;
;           f32x4 v[4];
; #pragma unroll
;           for (int n = 0; n < 4; ++n) v[n] = m < 8 ? acc[m < 8 ? m : 0][n] : accx[n];
;           head_norm_rope_store(v, g, rope + (size_t)pos * 64 + fq * 8, qscale, dst + (size_t)row * ldc + c0 + wc * 64 + fq * 4);
	v_or_b32_sdwa v191, v191, v189 dst_sel:DWORD dst_unused:UNUSED_PAD src0_sel:DWORD src1_sel:WORD_1
	v_or_b32_sdwa v190, v194, v190 dst_sel:DWORD dst_unused:UNUSED_PAD src0_sel:DWORD src1_sel:WORD_1
	v_or_b32_sdwa v158, v160, v158 dst_sel:DWORD dst_unused:UNUSED_PAD src0_sel:DWORD src1_sel:WORD_1
	v_or_b32_sdwa v149, v149, v128 dst_sel:DWORD dst_unused:UNUSED_PAD src0_sel:DWORD src1_sel:WORD_1
	v_or_b32_sdwa v148, v148, v150 dst_sel:DWORD dst_unused:UNUSED_PAD src0_sel:DWORD src1_sel:WORD_1
	s_nop 0
	v_mov_b32_e32 v208, v190
	v_mov_b32_e32 v209, v191
	s_nop 0
	v_mov_b32_e32 v210, v158
	v_mov_b32_e32 v211, v159
	v_mbcnt_lo_u32_b32 v220, -1, 0
	v_mbcnt_hi_u32_b32 v220, -1, v220
	v_and_b32_e32 v218, 16, v220
	v_lshrrev_b32_e32 v220, 1, v218
	v_add_u32_e32 v218, v218, v220
	v_mov_b32_e32 v219, 0
	v_lshl_add_u64 v[216:217], v[176:177], 0, v[218:219]
	v_permlane16_swap_b32_e32 v208, v210
	v_permlane16_swap_b32_e32 v209, v211
	global_store_dwordx4 v[216:217], v[208:211], off
	s_nop 0
	v_mov_b32_e32 v214, v148
	v_mov_b32_e32 v215, v149
	s_nop 1
	v_permlane16_swap_b32_e32 v212, v214
	v_permlane16_swap_b32_e32 v213, v215
	global_store_dwordx4 v[216:217], v[212:215], off offset:64
	global_load_dwordx4 v[148:151], v[146:147], off
	s_nop 0
	global_load_dwordx4 v[152:155], v[146:147], off offset:16
	v_mul_f32_e32 v128, 0x4b800000, v188
	v_cndmask_b32_e32 v128, v188, v128, vcc
	v_rsq_f32_e32 v128, v128
	v_mov_b32_e32 v158, v138
	v_mov_b32_e32 v159, v140
	v_mov_b32_e32 v140, v139
	v_mul_f32_e32 v138, 0x45800000, v128
	v_cndmask_b32_e32 v128, v128, v138, vcc
	v_mul_f32_e32 v128, v192, v128
	v_mov_b32_e32 v156, v142
	v_mov_b32_e32 v157, v144
	v_mov_b32_e32 v144, v143
	v_pk_mul_f32 v[140:141], v[140:141], v[128:129] op_sel_hi:[1,0]
	v_pk_mul_f32 v[138:139], v[156:157], v[128:129] op_sel_hi:[1,0]
	v_pk_mul_f32 v[142:143], v[158:159], v[128:129] op_sel_hi:[1,0]
	v_pk_mul_f32 v[144:145], v[144:145], v[128:129] op_sel_hi:[1,0]
	v_pk_mul_f32 v[140:141], v[54:55], v[140:141]
	v_pk_mul_f32 v[142:143], v[172:173], v[142:143]
	v_pk_mul_f32 v[144:145], v[62:63], v[144:145]
	v_pk_mul_f32 v[138:139], v[174:175], v[138:139]
	s_waitcnt vmcnt(1)
	v_mov_b32_e32 v156, v148
	s_waitcnt vmcnt(0)
	v_mov_b32_e32 v157, v152
	v_mov_b32_e32 v152, v149
	v_mov_b32_e32 v149, v154
	v_mov_b32_e32 v154, v151
	v_mov_b32_e32 v148, v150
	v_pk_mul_f32 v[158:159], v[154:155], v[140:141]
	v_pk_mul_f32 v[150:151], v[152:153], v[142:143]
	v_pk_mul_f32 v[142:143], v[156:157], v[142:143]
	v_pk_mul_f32 v[140:141], v[148:149], v[140:141]
	v_pk_fma_f32 v[148:149], v[148:149], v[144:145], v[158:159] neg_lo:[0,0,1] neg_hi:[0,0,1]
	v_pk_fma_f32 v[150:151], v[156:157], v[138:139], v[150:151] neg_lo:[0,0,1] neg_hi:[0,0,1]
	v_pk_fma_f32 v[138:139], v[152:153], v[138:139], v[142:143]
	v_pk_fma_f32 v[140:141], v[154:155], v[144:145], v[140:141]
	v_and_b32_sdwa v144, v149, v232 dst_sel:DWORD dst_unused:UNUSED_PAD src0_sel:WORD_1 src1_sel:DWORD
	v_and_b32_sdwa v145, v148, v232 dst_sel:DWORD dst_unused:UNUSED_PAD src0_sel:WORD_1 src1_sel:DWORD
	v_and_b32_sdwa v142, v151, v232 dst_sel:DWORD dst_unused:UNUSED_PAD src0_sel:WORD_1 src1_sel:DWORD
	v_and_b32_sdwa v143, v150, v232 dst_sel:DWORD dst_unused:UNUSED_PAD src0_sel:WORD_1 src1_sel:DWORD
	v_and_b32_sdwa v152, v139, v232 dst_sel:DWORD dst_unused:UNUSED_PAD src0_sel:WORD_1 src1_sel:DWORD
	v_and_b32_sdwa v153, v138, v232 dst_sel:DWORD dst_unused:UNUSED_PAD src0_sel:WORD_1 src1_sel:DWORD
	v_and_b32_sdwa v154, v141, v232 dst_sel:DWORD dst_unused:UNUSED_PAD src0_sel:WORD_1 src1_sel:DWORD
	v_and_b32_sdwa v155, v140, v232 dst_sel:DWORD dst_unused:UNUSED_PAD src0_sel:WORD_1 src1_sel:DWORD
	v_add3_u32 v144, v149, v144, s43
	v_add3_u32 v145, v148, v145, s43
	v_add3_u32 v143, v150, v143, s43
	v_add3_u32 v142, v151, v142, s43
	v_add3_u32 v148, v138, v153, s43
	v_add3_u32 v149, v139, v152, s43
	v_add3_u32 v138, v141, v154, s43
	v_add3_u32 v139, v140, v155, s43
	v_and_b32_e32 v140, 0xffff0000, v144
	v_and_b32_e32 v141, 0xffff0000, v145
	v_and_b32_e32 v144, 0xffff0000, v138
	v_and_b32_e32 v145, 0xffff0000, v139
	v_or_b32_sdwa v139, v140, v142 dst_sel:DWORD dst_unused:UNUSED_PAD src0_sel:DWORD src1_sel:WORD_1
	v_or_b32_sdwa v138, v141, v143 dst_sel:DWORD dst_unused:UNUSED_PAD src0_sel:DWORD src1_sel:WORD_1
	v_or_b32_sdwa v141, v144, v149 dst_sel:DWORD dst_unused:UNUSED_PAD src0_sel:DWORD src1_sel:WORD_1
	v_or_b32_sdwa v140, v145, v148 dst_sel:DWORD dst_unused:UNUSED_PAD src0_sel:DWORD src1_sel:WORD_1
	s_nop 0
	v_mov_b32_e32 v208, v138
	v_mov_b32_e32 v209, v139
	s_nop 0
	v_mov_b32_e32 v212, v140
	v_mov_b32_e32 v213, v141
	global_load_dwordx4 v[138:141], v[146:147], off offset:128
	s_nop 0
	global_load_dwordx4 v[142:145], v[146:147], off offset:144
	v_mov_b32_e32 v148, v130
	v_mov_b32_e32 v149, v132
	v_mov_b32_e32 v132, v131
	v_mov_b32_e32 v146, v134
	v_mov_b32_e32 v147, v136
	v_mov_b32_e32 v136, v135
	v_pk_mul_f32 v[134:135], v[148:149], v[128:129] op_sel_hi:[1,0]
	v_pk_mul_f32 v[132:133], v[132:133], v[128:129] op_sel_hi:[1,0]
	v_pk_mul_f32 v[130:131], v[146:147], v[128:129] op_sel_hi:[1,0]
	v_pk_mul_f32 v[136:137], v[136:137], v[128:129] op_sel_hi:[1,0]
	v_pk_mul_f32 v[134:135], v[60:61], v[134:135]
	v_pk_mul_f32 v[132:133], v[22:23], v[132:133]
	v_pk_mul_f32 v[130:131], v[52:53], v[130:131]
	v_pk_mul_f32 v[136:137], v[30:31], v[136:137]
	s_waitcnt vmcnt(1)
	v_mov_b32_e32 v146, v138
	s_waitcnt vmcnt(0)
; #define ST4(ptr, a, b, c_, d) (*(uint2*)(ptr) = make_uint2((unsigned)f2bf(a) | ((unsigned)f2bf(b) << 16), (unsigned)f2bf(c_) | ((unsigned)f2bf(d) << 16)))
; __device__ __forceinline__ void head_norm_rope_store(f32x4 (&v)[4], const float (&g)[16], const float* __restrict__ rp, float qscale, u16* __restrict__ dstp) {
;   float ss = 0.f;
; #pragma unroll
;   for (int n = 0; n < 4; ++n)
; #pragma unroll
;     for (int j = 0; j < 4; ++j) ss += v[n][j] * v[n][j];
;   { auto rr = __builtin_amdgcn_permlane16_swap(__float_as_uint(ss), __float_as_uint(ss), false, false); ss = __uint_as_float(rr[0]) + __uint_as_float(rr[1]); }
;   { auto rr = __builtin_amdgcn_permlane32_swap(__float_as_uint(ss), __float_as_uint(ss), false, false); ss = __uint_as_float(rr[0]) + __uint_as_float(rr[1]); }
;   const float rs = rsqrtf(ss * (1.f / 64.f) + EPS) * qscale;
; #pragma unroll
;   for (int h2 = 0; h2 < 2; ++h2) {
;     const float4 c01 = *(const float4*)(rp + h2 * 32), c23 = *(const float4*)(rp + h2 * 32 + 4);
;     const float cs_[4] = {c01.x, c01.z, c23.x, c23.z}, sn_[4] = {c01.y, c01.w, c23.y, c23.w};
;     float o1[4], o2[4];
; #pragma unroll
;     for (int j = 0; j < 4; ++j) {
;       const float x1 = v[h2][j] * rs * g[h2 * 4 + j], x2 = v[h2 + 2][j] * rs * g[(h2 + 2) * 4 + j];
;       o1[j] = x1 * cs_[j] - x2 * sn_[j]; o2[j] = x1 * sn_[j] + x2 * cs_[j];
;     }
;     ST4(dstp + h2 * 16, o1[0], o1[1], o1[2], o1[3]);
;     ST4(dstp + (h2 + 2) * 16, o2[0], o2[1], o2[2], o2[3]);
;   }
; __device__ __forceinline__ void inproj_phase(const Ctx& p, int layer, int hf) {
;     ...
;       for (int m = 0; m < 9; ++m) {
;         if (m < 8 || (fat && wr == 1)) {
;           const int row = m < 8 ? brow + wr * 128 + m * 16 + fr : brow + 256 + fr;
;           const int pos = hf == 0 ? row : row % L1;
;           f32x4 v[4];
; #pragma unroll
;           for (int n = 0; n < 4; ++n) v[n] = m < 8 ? acc[m < 8 ? m : 0][n] : accx[n];
;           head_norm_rope_store(v, g, rope + (size_t)pos * 64 + fq * 8, qscale, dst + (size_t)row * ldc + c0 + wc * 64 + fq * 4);
	v_mov_b32_e32 v147, v142
	v_mov_b32_e32 v142, v139
	v_mov_b32_e32 v139, v144
	v_mov_b32_e32 v144, v141
	v_mov_b32_e32 v138, v140
	v_pk_mul_f32 v[140:141], v[134:135], v[142:143]
	v_pk_mul_f32 v[148:149], v[132:133], v[144:145]
	v_pk_mul_f32 v[142:143], v[130:131], v[142:143]
	v_pk_mul_f32 v[144:145], v[136:137], v[144:145]
	v_pk_fma_f32 v[130:131], v[146:147], v[130:131], v[140:141] neg_lo:[0,0,1] neg_hi:[0,0,1]
	v_pk_fma_f32 v[136:137], v[136:137], v[138:139], v[148:149] neg_lo:[0,0,1] neg_hi:[0,0,1]
	v_pk_fma_f32 v[132:133], v[132:133], v[138:139], v[144:145]
	v_and_b32_sdwa v128, v131, v232 dst_sel:DWORD dst_unused:UNUSED_PAD src0_sel:WORD_1 src1_sel:DWORD
	v_and_b32_sdwa v139, v137, v232 dst_sel:DWORD dst_unused:UNUSED_PAD src0_sel:WORD_1 src1_sel:DWORD
	v_and_b32_sdwa v140, v136, v232 dst_sel:DWORD dst_unused:UNUSED_PAD src0_sel:WORD_1 src1_sel:DWORD
	v_pk_fma_f32 v[134:135], v[134:135], v[146:147], v[142:143]
	v_and_b32_sdwa v138, v130, v232 dst_sel:DWORD dst_unused:UNUSED_PAD src0_sel:WORD_1 src1_sel:DWORD
	v_and_b32_sdwa v143, v133, v232 dst_sel:DWORD dst_unused:UNUSED_PAD src0_sel:WORD_1 src1_sel:DWORD
	v_and_b32_sdwa v144, v132, v232 dst_sel:DWORD dst_unused:UNUSED_PAD src0_sel:WORD_1 src1_sel:DWORD
	v_add3_u32 v128, v131, v128, s43
	v_add3_u32 v131, v137, v139, s43
	v_add3_u32 v136, v136, v140, s43
	v_and_b32_sdwa v141, v135, v232 dst_sel:DWORD dst_unused:UNUSED_PAD src0_sel:WORD_1 src1_sel:DWORD
	v_and_b32_sdwa v142, v134, v232 dst_sel:DWORD dst_unused:UNUSED_PAD src0_sel:WORD_1 src1_sel:DWORD
	v_add3_u32 v130, v130, v138, s43
	v_add3_u32 v133, v133, v143, s43
	v_add3_u32 v132, v132, v144, s43
	v_and_b32_e32 v131, 0xffff0000, v131
	v_and_b32_e32 v136, 0xffff0000, v136
	v_add3_u32 v134, v134, v142, s43
	v_add3_u32 v135, v135, v141, s43
	v_and_b32_e32 v133, 0xffff0000, v133
	v_and_b32_e32 v132, 0xffff0000, v132
	v_or_b32_sdwa v131, v131, v128 dst_sel:DWORD dst_unused:UNUSED_PAD src0_sel:DWORD src1_sel:WORD_1
	v_or_b32_sdwa v130, v136, v130 dst_sel:DWORD dst_unused:UNUSED_PAD src0_sel:DWORD src1_sel:WORD_1
	v_or_b32_sdwa v133, v133, v135 dst_sel:DWORD dst_unused:UNUSED_PAD src0_sel:DWORD src1_sel:WORD_1
	v_or_b32_sdwa v132, v132, v134 dst_sel:DWORD dst_unused:UNUSED_PAD src0_sel:DWORD src1_sel:WORD_1
	s_nop 0
	v_mov_b32_e32 v210, v130
	v_mov_b32_e32 v211, v131
	v_mbcnt_lo_u32_b32 v220, -1, 0
	v_mbcnt_hi_u32_b32 v220, -1, v220
	v_and_b32_e32 v218, 16, v220
	v_lshrrev_b32_e32 v220, 1, v218
	v_add_u32_e32 v218, v218, v220
	v_mov_b32_e32 v219, 0
	v_lshl_add_u64 v[216:217], v[28:29], 0, v[218:219]
	v_permlane16_swap_b32_e32 v208, v210
	v_permlane16_swap_b32_e32 v209, v211
	global_store_dwordx4 v[216:217], v[208:211], off
	s_nop 0
	v_mov_b32_e32 v214, v132
	v_mov_b32_e32 v215, v133
	s_nop 1
	v_permlane16_swap_b32_e32 v212, v214
	v_permlane16_swap_b32_e32 v213, v215
	global_store_dwordx4 v[216:217], v[212:215], off offset:64
	v_add_u32_e32 v128, v193, v243
	v_mul_hi_i32 v28, v128, s52
	v_lshrrev_b32_e32 v29, 31, v28
	v_ashrrev_i32_e32 v28, 11, v28
	v_add_u32_e32 v28, v28, v29
	v_mul_i32_i24_e32 v28, 0x1010, v28
	v_sub_u32_e32 v28, v128, v28
	v_cndmask_b32_e64 v28, v28, v128, s[62:63]
	v_ashrrev_i32_e32 v29, 31, v28
	v_lshlrev_b64 v[28:29], 8, v[28:29]
	v_lshl_add_u64 v[146:147], v[224:225], 0, v[28:29]
	v_mad_i64_i32 v[28:29], s[6:7], s76, v128, 0
	v_mul_f32_e32 v128, v125, v125
	v_fmac_f32_e32 v128, v124, v124
	v_fmac_f32_e32 v128, v126, v126
	v_fmac_f32_e32 v128, v127, v127
	v_fmac_f32_e32 v128, v116, v116
	v_fmac_f32_e32 v128, v117, v117
	v_fmac_f32_e32 v128, v118, v118
	v_fmac_f32_e32 v128, v119, v119
	v_fmac_f32_e32 v128, v120, v120
	v_fmac_f32_e32 v128, v121, v121
	v_fmac_f32_e32 v128, v122, v122
	v_fmac_f32_e32 v128, v123, v123
	v_pk_mul_f32 v[132:133], v[112:113], v[112:113]
	v_pk_mul_f32 v[130:131], v[114:115], v[114:115]
	v_add_f32_e32 v128, v132, v128
	v_add_f32_e32 v128, v133, v128
	v_add_f32_e32 v128, v130, v128
	v_add_f32_e32 v128, v131, v128
	v_mov_b32_e32 v130, v128
	s_nop 1
	v_permlane16_swap_b32_e32 v128, v130
	v_add_f32_e32 v139, v128, v130
	global_load_dwordx4 v[130:133], v[146:147], off offset:16
	global_load_dwordx4 v[134:137], v[146:147], off
	v_mov_b32_e32 v144, v124
	v_mov_b32_e32 v145, v126
	v_mov_b32_e32 v142, v120
	v_mov_b32_e32 v143, v122
	v_mov_b32_e32 v126, v125
	v_mov_b32_e32 v122, v121
	v_add_u32_e32 v128, v193, v244
	v_mov_b32_e32 v150, v112
	v_mul_hi_i32 v112, v128, s52
	v_mov_b32_e32 v151, v114
	v_mov_b32_e32 v114, v113
	v_lshrrev_b32_e32 v113, 31, v112
	v_ashrrev_i32_e32 v112, 11, v112
	v_add_u32_e32 v112, v112, v113
	v_mul_i32_i24_e32 v112, 0x1010, v112
	v_sub_u32_e32 v112, v128, v112
	v_cndmask_b32_e64 v112, v112, v128, s[62:63]
	v_ashrrev_i32_e32 v113, 31, v112
	v_lshlrev_b64 v[112:113], 8, v[112:113]
	v_mov_b32_e32 v152, v116
	v_mov_b32_e32 v153, v118
	v_mov_b32_e32 v118, v117
	v_lshl_add_u64 v[116:117], v[224:225], 0, v[112:113]
	v_mad_i64_i32 v[112:113], s[6:7], s76, v128, 0
	v_mul_f32_e32 v128, v109, v109
	v_fmac_f32_e32 v128, v108, v108
	v_fmac_f32_e32 v128, v110, v110
	v_fmac_f32_e32 v128, v111, v111
	v_fmac_f32_e32 v128, v100, v100
	v_fmac_f32_e32 v128, v101, v101
	v_fmac_f32_e32 v128, v102, v102
	v_fmac_f32_e32 v128, v103, v103
	v_fmac_f32_e32 v128, v104, v104
	v_fmac_f32_e32 v128, v105, v105
	v_fmac_f32_e32 v128, v106, v106
	v_fmac_f32_e32 v128, v107, v107
	v_mov_b32_e32 v141, v139
	s_nop 1
	v_permlane32_swap_b32_e32 v139, v141
	v_lshl_add_u64 v[28:29], v[28:29], 1, v[170:171]
	v_lshl_add_u64 v[112:113], v[112:113], 1, v[170:171]
	s_waitcnt vmcnt(1)
	v_mov_b32_e32 v121, v130
	s_waitcnt vmcnt(0)
; #define ST4(ptr, a, b, c_, d) (*(uint2*)(ptr) = make_uint2((unsigned)f2bf(a) | ((unsigned)f2bf(b) << 16), (unsigned)f2bf(c_) | ((unsigned)f2bf(d) << 16)))
; __device__ __forceinline__ void head_norm_rope_store(f32x4 (&v)[4], const float (&g)[16], const float* __restrict__ rp, float qscale, u16* __restrict__ dstp) {
;   float ss = 0.f;
; #pragma unroll
;   for (int n = 0; n < 4; ++n)
; #pragma unroll
;     for (int j = 0; j < 4; ++j) ss += v[n][j] * v[n][j];
;   { auto rr = __builtin_amdgcn_permlane16_swap(__float_as_uint(ss), __float_as_uint(ss), false, false); ss = __uint_as_float(rr[0]) + __uint_as_float(rr[1]); }
;   { auto rr = __builtin_amdgcn_permlane32_swap(__float_as_uint(ss), __float_as_uint(ss), false, false); ss = __uint_as_float(rr[0]) + __uint_as_float(rr[1]); }
;   const float rs = rsqrtf(ss * (1.f / 64.f) + EPS) * qscale;
; #pragma unroll
;   for (int h2 = 0; h2 < 2; ++h2) {
;     const float4 c01 = *(const float4*)(rp + h2 * 32), c23 = *(const float4*)(rp + h2 * 32 + 4);
;     const float cs_[4] = {c01.x, c01.z, c23.x, c23.z}, sn_[4] = {c01.y, c01.w, c23.y, c23.w};
;     float o1[4], o2[4];
; #pragma unroll
;     for (int j = 0; j < 4; ++j) {
;       const float x1 = v[h2][j] * rs * g[h2 * 4 + j], x2 = v[h2 + 2][j] * rs * g[(h2 + 2) * 4 + j];
;       o1[j] = x1 * cs_[j] - x2 * sn_[j]; o2[j] = x1 * sn_[j] + x2 * cs_[j];
;     }
;     ST4(dstp + h2 * 16, o1[0], o1[1], o1[2], o1[3]);
;     ST4(dstp + (h2 + 2) * 16, o2[0], o2[1], o2[2], o2[3]);
;   }
; __device__ __forceinline__ void inproj_phase(const Ctx& p, int layer, int hf) {
;     ...
;       for (int m = 0; m < 9; ++m) {
;         if (m < 8 || (fat && wr == 1)) {
;           const int row = m < 8 ? brow + wr * 128 + m * 16 + fr : brow + 256 + fr;
;           const int pos = hf == 0 ? row : row % L1;
;           f32x4 v[4];
; #pragma unroll
;           for (int n = 0; n < 4; ++n) v[n] = m < 8 ? acc[m < 8 ? m : 0][n] : accx[n];
;           head_norm_rope_store(v, g, rope + (size_t)pos * 64 + fq * 8, qscale, dst + (size_t)row * ldc + c0 + wc * 64 + fq * 4);
	v_mov_b32_e32 v120, v134
	v_mov_b32_e32 v130, v135
	v_mov_b32_e32 v124, v136
	v_mov_b32_e32 v125, v132
	v_mov_b32_e32 v132, v137
	global_load_dwordx4 v[134:137], v[146:147], off offset:144
	global_load_dwordx4 v[154:157], v[146:147], off offset:128
	s_waitcnt vmcnt(1)
	v_mov_b32_e32 v149, v136
	s_waitcnt vmcnt(0)
	v_mov_b32_e32 v148, v156
	v_mov_b32_e32 v136, v157
	v_pk_mul_f32 v[156:157], v[96:97], v[96:97]
	v_mov_b32_e32 v146, v154
	v_add_f32_e32 v128, v156, v128
	v_mov_b32_e32 v147, v134
	v_mov_b32_e32 v134, v155
	v_pk_mul_f32 v[154:155], v[98:99], v[98:99]
	v_add_f32_e32 v128, v157, v128
	v_add_f32_e32 v128, v154, v128
	v_add_f32_e32 v128, v155, v128
	v_mov_b32_e32 v138, v128
	s_nop 1
	v_permlane16_swap_b32_e32 v128, v138
	v_add_f32_e32 v138, v128, v138
	v_mov_b32_e32 v140, v138
	s_nop 1
	v_permlane32_swap_b32_e32 v138, v140
	v_pk_add_f32 v[138:139], v[138:139], v[140:141]
	s_nop 0
	v_pk_fma_f32 v[138:139], v[138:139], s[20:21], v[20:21] op_sel_hi:[1,0,0]
	s_nop 0
	v_mul_f32_e32 v128, 0x4b800000, v139
	v_cmp_gt_f32_e64 s[6:7], s96, v139
	v_cmp_gt_f32_e32 vcc, s96, v138
	s_nop 0
	v_cndmask_b32_e64 v128, v139, v128, s[6:7]
	v_rsq_f32_e32 v128, v128
	s_nop 0
	v_mul_f32_e32 v139, 0x45800000, v128
	v_cndmask_b32_e64 v128, v128, v139, s[6:7]
	v_mul_f32_e32 v128, v192, v128
	v_pk_mul_f32 v[142:143], v[142:143], v[128:129] op_sel_hi:[1,0]
	v_pk_mul_f32 v[140:141], v[144:145], v[128:129] op_sel_hi:[1,0]
	v_pk_mul_f32 v[142:143], v[172:173], v[142:143]
	v_pk_mul_f32 v[140:141], v[174:175], v[140:141]
	v_pk_mul_f32 v[122:123], v[122:123], v[128:129] op_sel_hi:[1,0]
	v_pk_mul_f32 v[144:145], v[130:131], v[142:143]
	v_pk_mul_f32 v[126:127], v[126:127], v[128:129] op_sel_hi:[1,0]
	v_pk_mul_f32 v[122:123], v[54:55], v[122:123]
	v_pk_fma_f32 v[144:145], v[120:121], v[140:141], v[144:145] neg_lo:[0,0,1] neg_hi:[0,0,1]
	v_pk_mul_f32 v[120:121], v[120:121], v[142:143]
	v_pk_mul_f32 v[126:127], v[62:63], v[126:127]
	v_pk_mul_f32 v[154:155], v[132:133], v[122:123]
	v_pk_fma_f32 v[120:121], v[130:131], v[140:141], v[120:121]
	v_pk_mul_f32 v[122:123], v[124:125], v[122:123]
	v_pk_fma_f32 v[154:155], v[124:125], v[126:127], v[154:155] neg_lo:[0,0,1] neg_hi:[0,0,1]
	v_pk_fma_f32 v[122:123], v[132:133], v[126:127], v[122:123]
	v_and_b32_sdwa v124, v121, v232 dst_sel:DWORD dst_unused:UNUSED_PAD src0_sel:WORD_1 src1_sel:DWORD
	v_and_b32_sdwa v125, v120, v232 dst_sel:DWORD dst_unused:UNUSED_PAD src0_sel:WORD_1 src1_sel:DWORD
	v_add3_u32 v120, v120, v125, s43
	v_add3_u32 v121, v121, v124, s43
	v_and_b32_sdwa v124, v123, v232 dst_sel:DWORD dst_unused:UNUSED_PAD src0_sel:WORD_1 src1_sel:DWORD
	v_and_b32_sdwa v125, v122, v232 dst_sel:DWORD dst_unused:UNUSED_PAD src0_sel:WORD_1 src1_sel:DWORD
	v_add3_u32 v123, v123, v124, s43
	v_add3_u32 v122, v122, v125, s43
	v_and_b32_e32 v123, 0xffff0000, v123
	v_and_b32_e32 v122, 0xffff0000, v122
	v_or_b32_sdwa v121, v123, v121 dst_sel:DWORD dst_unused:UNUSED_PAD src0_sel:DWORD src1_sel:WORD_1
	v_or_b32_sdwa v120, v122, v120 dst_sel:DWORD dst_unused:UNUSED_PAD src0_sel:DWORD src1_sel:WORD_1
	v_pk_mul_f32 v[122:123], v[150:151], v[128:129] op_sel_hi:[1,0]
	s_nop 0
	v_mov_b32_e32 v212, v120
	v_mov_b32_e32 v213, v121
	v_pk_mul_f32 v[120:121], v[152:153], v[128:129] op_sel_hi:[1,0]
	v_pk_mul_f32 v[122:123], v[60:61], v[122:123]
	v_pk_mul_f32 v[114:115], v[114:115], v[128:129] op_sel_hi:[1,0]
	v_pk_mul_f32 v[120:121], v[52:53], v[120:121]
	v_pk_mul_f32 v[118:119], v[118:119], v[128:129] op_sel_hi:[1,0]
	v_pk_mul_f32 v[114:115], v[22:23], v[114:115]
	v_pk_mul_f32 v[124:125], v[122:123], v[134:135]
	v_pk_mul_f32 v[118:119], v[30:31], v[118:119]
	v_pk_fma_f32 v[124:125], v[146:147], v[120:121], v[124:125] neg_lo:[0,0,1] neg_hi:[0,0,1]
	v_pk_mul_f32 v[126:127], v[114:115], v[136:137]
	v_pk_mul_f32 v[120:121], v[120:121], v[134:135]
	v_pk_fma_f32 v[126:127], v[118:119], v[148:149], v[126:127] neg_lo:[0,0,1] neg_hi:[0,0,1]
	v_pk_fma_f32 v[120:121], v[122:123], v[146:147], v[120:121]
	v_pk_mul_f32 v[118:119], v[118:119], v[136:137]
	v_and_b32_sdwa v139, v145, v232 dst_sel:DWORD dst_unused:UNUSED_PAD src0_sel:WORD_1 src1_sel:DWORD
	v_and_b32_sdwa v156, v144, v232 dst_sel:DWORD dst_unused:UNUSED_PAD src0_sel:WORD_1 src1_sel:DWORD
	v_and_b32_sdwa v128, v125, v232 dst_sel:DWORD dst_unused:UNUSED_PAD src0_sel:WORD_1 src1_sel:DWORD
	v_and_b32_sdwa v130, v124, v232 dst_sel:DWORD dst_unused:UNUSED_PAD src0_sel:WORD_1 src1_sel:DWORD
	v_pk_fma_f32 v[114:115], v[114:115], v[148:149], v[118:119]
	v_and_b32_sdwa v118, v121, v232 dst_sel:DWORD dst_unused:UNUSED_PAD src0_sel:WORD_1 src1_sel:DWORD
	v_and_b32_sdwa v119, v120, v232 dst_sel:DWORD dst_unused:UNUSED_PAD src0_sel:WORD_1 src1_sel:DWORD
	v_add3_u32 v144, v144, v156, s43
	v_add3_u32 v139, v145, v139, s43
	v_and_b32_sdwa v145, v155, v232 dst_sel:DWORD dst_unused:UNUSED_PAD src0_sel:WORD_1 src1_sel:DWORD
	v_and_b32_sdwa v156, v154, v232 dst_sel:DWORD dst_unused:UNUSED_PAD src0_sel:WORD_1 src1_sel:DWORD
	v_add3_u32 v124, v124, v130, s43
	v_add3_u32 v125, v125, v128, s43
	v_and_b32_sdwa v128, v127, v232 dst_sel:DWORD dst_unused:UNUSED_PAD src0_sel:WORD_1 src1_sel:DWORD
	v_and_b32_sdwa v130, v126, v232 dst_sel:DWORD dst_unused:UNUSED_PAD src0_sel:WORD_1 src1_sel:DWORD
	v_add3_u32 v119, v120, v119, s43
	v_add3_u32 v118, v121, v118, s43
	v_and_b32_sdwa v120, v115, v232 dst_sel:DWORD dst_unused:UNUSED_PAD src0_sel:WORD_1 src1_sel:DWORD
	v_and_b32_sdwa v121, v114, v232 dst_sel:DWORD dst_unused:UNUSED_PAD src0_sel:WORD_1 src1_sel:DWORD
	v_add3_u32 v145, v155, v145, s43
	v_add3_u32 v154, v154, v156, s43
	v_add3_u32 v127, v127, v128, s43
	v_add3_u32 v126, v126, v130, s43
	v_add3_u32 v115, v115, v120, s43
; #define ST4(ptr, a, b, c_, d) (*(uint2*)(ptr) = make_uint2((unsigned)f2bf(a) | ((unsigned)f2bf(b) << 16), (unsigned)f2bf(c_) | ((unsigned)f2bf(d) << 16)))
; __device__ __forceinline__ void head_norm_rope_store(f32x4 (&v)[4], const float (&g)[16], const float* __restrict__ rp, float qscale, u16* __restrict__ dstp) {
;   float ss = 0.f;
; #pragma unroll
;   for (int n = 0; n < 4; ++n)
; #pragma unroll
;     for (int j = 0; j < 4; ++j) ss += v[n][j] * v[n][j];
;   { auto rr = __builtin_amdgcn_permlane16_swap(__float_as_uint(ss), __float_as_uint(ss), false, false); ss = __uint_as_float(rr[0]) + __uint_as_float(rr[1]); }
;   { auto rr = __builtin_amdgcn_permlane32_swap(__float_as_uint(ss), __float_as_uint(ss), false, false); ss = __uint_as_float(rr[0]) + __uint_as_float(rr[1]); }
;   const float rs = rsqrtf(ss * (1.f / 64.f) + EPS) * qscale;
; #pragma unroll
;   for (int h2 = 0; h2 < 2; ++h2) {
;     const float4 c01 = *(const float4*)(rp + h2 * 32), c23 = *(const float4*)(rp + h2 * 32 + 4);
;     const float cs_[4] = {c01.x, c01.z, c23.x, c23.z}, sn_[4] = {c01.y, c01.w, c23.y, c23.w};
;     float o1[4], o2[4];
; #pragma unroll
;     for (int j = 0; j < 4; ++j) {
;       const float x1 = v[h2][j] * rs * g[h2 * 4 + j], x2 = v[h2 + 2][j] * rs * g[(h2 + 2) * 4 + j];
;       o1[j] = x1 * cs_[j] - x2 * sn_[j]; o2[j] = x1 * sn_[j] + x2 * cs_[j];
;     }
;     ST4(dstp + h2 * 16, o1[0], o1[1], o1[2], o1[3]);
;     ST4(dstp + (h2 + 2) * 16, o2[0], o2[1], o2[2], o2[3]);
;   }
; __device__ __forceinline__ void inproj_phase(const Ctx& p, int layer, int hf) {
;     ...
;       for (int m = 0; m < 9; ++m) {
;         if (m < 8 || (fat && wr == 1)) {
;           const int row = m < 8 ? brow + wr * 128 + m * 16 + fr : brow + 256 + fr;
;           const int pos = hf == 0 ? row : row % L1;
;           f32x4 v[4];
; #pragma unroll
;           for (int n = 0; n < 4; ++n) v[n] = m < 8 ? acc[m < 8 ? m : 0][n] : accx[n];
;           head_norm_rope_store(v, g, rope + (size_t)pos * 64 + fq * 8, qscale, dst + (size_t)row * ldc + c0 + wc * 64 + fq * 4);
	v_add3_u32 v114, v114, v121, s43
	v_and_b32_e32 v145, 0xffff0000, v145
	v_and_b32_e32 v154, 0xffff0000, v154
	v_and_b32_e32 v127, 0xffff0000, v127
	v_and_b32_e32 v126, 0xffff0000, v126
	v_and_b32_e32 v115, 0xffff0000, v115
	v_and_b32_e32 v114, 0xffff0000, v114
	v_or_b32_sdwa v145, v145, v139 dst_sel:DWORD dst_unused:UNUSED_PAD src0_sel:DWORD src1_sel:WORD_1
	v_or_b32_sdwa v144, v154, v144 dst_sel:DWORD dst_unused:UNUSED_PAD src0_sel:DWORD src1_sel:WORD_1
	v_or_b32_sdwa v125, v127, v125 dst_sel:DWORD dst_unused:UNUSED_PAD src0_sel:DWORD src1_sel:WORD_1
	v_or_b32_sdwa v124, v126, v124 dst_sel:DWORD dst_unused:UNUSED_PAD src0_sel:DWORD src1_sel:WORD_1
	v_or_b32_sdwa v115, v115, v118 dst_sel:DWORD dst_unused:UNUSED_PAD src0_sel:DWORD src1_sel:WORD_1
	v_or_b32_sdwa v114, v114, v119 dst_sel:DWORD dst_unused:UNUSED_PAD src0_sel:DWORD src1_sel:WORD_1
	s_nop 0
	v_mov_b32_e32 v208, v144
	v_mov_b32_e32 v209, v145
	s_nop 0
	v_mov_b32_e32 v210, v124
	v_mov_b32_e32 v211, v125
	v_mbcnt_lo_u32_b32 v220, -1, 0
	v_mbcnt_hi_u32_b32 v220, -1, v220
	v_and_b32_e32 v218, 16, v220
	v_lshrrev_b32_e32 v220, 1, v218
	v_add_u32_e32 v218, v218, v220
	v_mov_b32_e32 v219, 0
	v_lshl_add_u64 v[216:217], v[28:29], 0, v[218:219]
	v_permlane16_swap_b32_e32 v208, v210
	v_permlane16_swap_b32_e32 v209, v211
	global_store_dwordx4 v[216:217], v[208:211], off
	s_nop 0
	v_mov_b32_e32 v214, v114
	v_mov_b32_e32 v215, v115
	s_nop 1
	v_permlane16_swap_b32_e32 v212, v214
	v_permlane16_swap_b32_e32 v213, v215
	global_store_dwordx4 v[216:217], v[212:215], off offset:64
	global_load_dwordx4 v[118:121], v[116:117], off
	s_nop 0
	global_load_dwordx4 v[122:125], v[116:117], off offset:16
	v_mul_f32_e32 v115, 0x4b800000, v138
	v_mov_b32_e32 v114, v104
	v_cndmask_b32_e32 v104, v138, v115, vcc
	v_rsq_f32_e32 v104, v104
	v_mov_b32_e32 v115, v106
	v_mov_b32_e32 v106, v105
	v_mov_b32_e32 v29, v110
	v_mul_f32_e32 v105, 0x45800000, v104
	v_cndmask_b32_e32 v104, v104, v105, vcc
	v_mul_f32_e32 v126, v192, v104
	v_mov_b32_e32 v110, v109
	v_pk_mul_f32 v[106:107], v[106:107], v[126:127] op_sel_hi:[1,0]
	v_mov_b32_e32 v28, v108
	v_pk_mul_f32 v[104:105], v[114:115], v[126:127] op_sel_hi:[1,0]
	v_pk_mul_f32 v[108:109], v[110:111], v[126:127] op_sel_hi:[1,0]
	v_pk_mul_f32 v[106:107], v[54:55], v[106:107]
	v_pk_mul_f32 v[28:29], v[28:29], v[126:127] op_sel_hi:[1,0]
	v_pk_mul_f32 v[104:105], v[172:173], v[104:105]
	v_pk_mul_f32 v[108:109], v[62:63], v[108:109]
	v_pk_mul_f32 v[28:29], v[174:175], v[28:29]
	s_waitcnt vmcnt(1)
	v_mov_b32_e32 v110, v118
	s_waitcnt vmcnt(0)
	v_mov_b32_e32 v115, v124
	v_mov_b32_e32 v124, v121
	v_mov_b32_e32 v111, v122
	v_mov_b32_e32 v122, v119
	v_mov_b32_e32 v114, v120
	v_pk_mul_f32 v[120:121], v[124:125], v[106:107]
	v_pk_mul_f32 v[118:119], v[122:123], v[104:105]
	v_pk_mul_f32 v[104:105], v[110:111], v[104:105]
	v_pk_mul_f32 v[106:107], v[114:115], v[106:107]
	v_pk_fma_f32 v[114:115], v[114:115], v[108:109], v[120:121] neg_lo:[0,0,1] neg_hi:[0,0,1]
	v_pk_fma_f32 v[110:111], v[110:111], v[28:29], v[118:119] neg_lo:[0,0,1] neg_hi:[0,0,1]
	v_pk_fma_f32 v[28:29], v[122:123], v[28:29], v[104:105]
	v_pk_fma_f32 v[104:105], v[124:125], v[108:109], v[106:107]
	v_and_b32_sdwa v108, v115, v232 dst_sel:DWORD dst_unused:UNUSED_PAD src0_sel:WORD_1 src1_sel:DWORD
	v_and_b32_sdwa v109, v114, v232 dst_sel:DWORD dst_unused:UNUSED_PAD src0_sel:WORD_1 src1_sel:DWORD
	v_and_b32_sdwa v106, v111, v232 dst_sel:DWORD dst_unused:UNUSED_PAD src0_sel:WORD_1 src1_sel:DWORD
	v_and_b32_sdwa v107, v110, v232 dst_sel:DWORD dst_unused:UNUSED_PAD src0_sel:WORD_1 src1_sel:DWORD
	v_and_b32_sdwa v118, v29, v232 dst_sel:DWORD dst_unused:UNUSED_PAD src0_sel:WORD_1 src1_sel:DWORD
	v_and_b32_sdwa v119, v28, v232 dst_sel:DWORD dst_unused:UNUSED_PAD src0_sel:WORD_1 src1_sel:DWORD
	v_and_b32_sdwa v120, v105, v232 dst_sel:DWORD dst_unused:UNUSED_PAD src0_sel:WORD_1 src1_sel:DWORD
	v_and_b32_sdwa v121, v104, v232 dst_sel:DWORD dst_unused:UNUSED_PAD src0_sel:WORD_1 src1_sel:DWORD
	v_add3_u32 v108, v115, v108, s43
	v_add3_u32 v109, v114, v109, s43
	v_add3_u32 v107, v110, v107, s43
	v_add3_u32 v106, v111, v106, s43
	v_add3_u32 v110, v28, v119, s43
	v_add3_u32 v111, v29, v118, s43
	v_add3_u32 v28, v105, v120, s43
	v_add3_u32 v29, v104, v121, s43
	v_and_b32_e32 v104, 0xffff0000, v108
	v_and_b32_e32 v105, 0xffff0000, v109
	v_and_b32_e32 v108, 0xffff0000, v28
	v_and_b32_e32 v109, 0xffff0000, v29
	v_or_b32_sdwa v29, v104, v106 dst_sel:DWORD dst_unused:UNUSED_PAD src0_sel:DWORD src1_sel:WORD_1
	v_or_b32_sdwa v28, v105, v107 dst_sel:DWORD dst_unused:UNUSED_PAD src0_sel:DWORD src1_sel:WORD_1
	v_or_b32_sdwa v105, v108, v111 dst_sel:DWORD dst_unused:UNUSED_PAD src0_sel:DWORD src1_sel:WORD_1
	v_or_b32_sdwa v104, v109, v110 dst_sel:DWORD dst_unused:UNUSED_PAD src0_sel:DWORD src1_sel:WORD_1
	s_nop 0
	v_mov_b32_e32 v208, v28
	v_mov_b32_e32 v209, v29
	s_nop 0
	v_mov_b32_e32 v212, v104
	v_mov_b32_e32 v213, v105
	global_load_dwordx4 v[104:107], v[116:117], off offset:128
	s_nop 0
	global_load_dwordx4 v[108:111], v[116:117], off offset:144
	v_mov_b32_e32 v115, v98
	v_mov_b32_e32 v98, v97
	v_mov_b32_e32 v29, v102
	v_mov_b32_e32 v114, v96
	v_mov_b32_e32 v102, v101
	v_pk_mul_f32 v[98:99], v[98:99], v[126:127] op_sel_hi:[1,0]
	v_mov_b32_e32 v28, v100
	v_pk_mul_f32 v[96:97], v[114:115], v[126:127] op_sel_hi:[1,0]
	v_pk_mul_f32 v[100:101], v[102:103], v[126:127] op_sel_hi:[1,0]
	v_pk_mul_f32 v[98:99], v[22:23], v[98:99]
	v_pk_mul_f32 v[28:29], v[28:29], v[126:127] op_sel_hi:[1,0]
	v_pk_mul_f32 v[96:97], v[60:61], v[96:97]
	v_pk_mul_f32 v[100:101], v[30:31], v[100:101]
	v_pk_mul_f32 v[28:29], v[52:53], v[28:29]
	s_waitcnt vmcnt(1)
; #define ST4(ptr, a, b, c_, d) (*(uint2*)(ptr) = make_uint2((unsigned)f2bf(a) | ((unsigned)f2bf(b) << 16), (unsigned)f2bf(c_) | ((unsigned)f2bf(d) << 16)))
; __device__ __forceinline__ void head_norm_rope_store(f32x4 (&v)[4], const float (&g)[16], const float* __restrict__ rp, float qscale, u16* __restrict__ dstp) {
;   float ss = 0.f;
; #pragma unroll
;   for (int n = 0; n < 4; ++n)
; #pragma unroll
;     for (int j = 0; j < 4; ++j) ss += v[n][j] * v[n][j];
;   { auto rr = __builtin_amdgcn_permlane16_swap(__float_as_uint(ss), __float_as_uint(ss), false, false); ss = __uint_as_float(rr[0]) + __uint_as_float(rr[1]); }
;   { auto rr = __builtin_amdgcn_permlane32_swap(__float_as_uint(ss), __float_as_uint(ss), false, false); ss = __uint_as_float(rr[0]) + __uint_as_float(rr[1]); }
;   const float rs = rsqrtf(ss * (1.f / 64.f) + EPS) * qscale;
; #pragma unroll
;   for (int h2 = 0; h2 < 2; ++h2) {
;     const float4 c01 = *(const float4*)(rp + h2 * 32), c23 = *(const float4*)(rp + h2 * 32 + 4);
;     const float cs_[4] = {c01.x, c01.z, c23.x, c23.z}, sn_[4] = {c01.y, c01.w, c23.y, c23.w};
;     float o1[4], o2[4];
; #pragma unroll
;     for (int j = 0; j < 4; ++j) {
;       const float x1 = v[h2][j] * rs * g[h2 * 4 + j], x2 = v[h2 + 2][j] * rs * g[(h2 + 2) * 4 + j];
;       o1[j] = x1 * cs_[j] - x2 * sn_[j]; o2[j] = x1 * sn_[j] + x2 * cs_[j];
;     }
;     ST4(dstp + h2 * 16, o1[0], o1[1], o1[2], o1[3]);
;     ST4(dstp + (h2 + 2) * 16, o2[0], o2[1], o2[2], o2[3]);
;   }
; __device__ __forceinline__ void inproj_phase(const Ctx& p, int layer, int hf) {
;     ...
;       for (int m = 0; m < 9; ++m) {
;         if (m < 8 || (fat && wr == 1)) {
;           const int row = m < 8 ? brow + wr * 128 + m * 16 + fr : brow + 256 + fr;
;           const int pos = hf == 0 ? row : row % L1;
;           f32x4 v[4];
; #pragma unroll
;           for (int n = 0; n < 4; ++n) v[n] = m < 8 ? acc[m < 8 ? m : 0][n] : accx[n];
;           head_norm_rope_store(v, g, rope + (size_t)pos * 64 + fq * 8, qscale, dst + (size_t)row * ldc + c0 + wc * 64 + fq * 4);
	v_mov_b32_e32 v102, v104
	s_waitcnt vmcnt(0)
	v_mov_b32_e32 v103, v108
	v_mov_b32_e32 v108, v105
	v_mov_b32_e32 v105, v110
	v_mov_b32_e32 v110, v107
	v_mov_b32_e32 v104, v106
	v_pk_mul_f32 v[114:115], v[98:99], v[110:111]
	v_pk_mul_f32 v[106:107], v[96:97], v[108:109]
	v_pk_mul_f32 v[110:111], v[100:101], v[110:111]
	v_pk_fma_f32 v[100:101], v[100:101], v[104:105], v[114:115] neg_lo:[0,0,1] neg_hi:[0,0,1]
	v_pk_mul_f32 v[108:109], v[28:29], v[108:109]
	v_pk_fma_f32 v[28:29], v[102:103], v[28:29], v[106:107] neg_lo:[0,0,1] neg_hi:[0,0,1]
	v_pk_fma_f32 v[98:99], v[98:99], v[104:105], v[110:111]
	v_and_b32_sdwa v104, v101, v232 dst_sel:DWORD dst_unused:UNUSED_PAD src0_sel:WORD_1 src1_sel:DWORD
	v_and_b32_sdwa v105, v100, v232 dst_sel:DWORD dst_unused:UNUSED_PAD src0_sel:WORD_1 src1_sel:DWORD
	v_pk_fma_f32 v[96:97], v[96:97], v[102:103], v[108:109]
	v_and_b32_sdwa v102, v29, v232 dst_sel:DWORD dst_unused:UNUSED_PAD src0_sel:WORD_1 src1_sel:DWORD
	v_and_b32_sdwa v103, v28, v232 dst_sel:DWORD dst_unused:UNUSED_PAD src0_sel:WORD_1 src1_sel:DWORD
	v_and_b32_sdwa v108, v99, v232 dst_sel:DWORD dst_unused:UNUSED_PAD src0_sel:WORD_1 src1_sel:DWORD
	v_and_b32_sdwa v109, v98, v232 dst_sel:DWORD dst_unused:UNUSED_PAD src0_sel:WORD_1 src1_sel:DWORD
	v_add3_u32 v101, v101, v104, s43
	v_add3_u32 v100, v100, v105, s43
	v_and_b32_sdwa v106, v97, v232 dst_sel:DWORD dst_unused:UNUSED_PAD src0_sel:WORD_1 src1_sel:DWORD
	v_and_b32_sdwa v107, v96, v232 dst_sel:DWORD dst_unused:UNUSED_PAD src0_sel:WORD_1 src1_sel:DWORD
	v_add3_u32 v28, v28, v103, s43
	v_add3_u32 v29, v29, v102, s43
	v_add3_u32 v99, v99, v108, s43
	v_add3_u32 v98, v98, v109, s43
	v_and_b32_e32 v101, 0xffff0000, v101
	v_and_b32_e32 v100, 0xffff0000, v100
	v_add3_u32 v96, v96, v107, s43
	v_add3_u32 v97, v97, v106, s43
	v_and_b32_e32 v99, 0xffff0000, v99
	v_and_b32_e32 v98, 0xffff0000, v98
	v_or_b32_sdwa v29, v101, v29 dst_sel:DWORD dst_unused:UNUSED_PAD src0_sel:DWORD src1_sel:WORD_1
	v_or_b32_sdwa v28, v100, v28 dst_sel:DWORD dst_unused:UNUSED_PAD src0_sel:DWORD src1_sel:WORD_1
	v_or_b32_sdwa v97, v99, v97 dst_sel:DWORD dst_unused:UNUSED_PAD src0_sel:DWORD src1_sel:WORD_1
	v_or_b32_sdwa v96, v98, v96 dst_sel:DWORD dst_unused:UNUSED_PAD src0_sel:DWORD src1_sel:WORD_1
	s_nop 0
	v_mov_b32_e32 v210, v28
	v_mov_b32_e32 v211, v29
	v_mbcnt_lo_u32_b32 v220, -1, 0
	v_mbcnt_hi_u32_b32 v220, -1, v220
	v_and_b32_e32 v218, 16, v220
	v_lshrrev_b32_e32 v220, 1, v218
	v_add_u32_e32 v218, v218, v220
	v_mov_b32_e32 v219, 0
	v_lshl_add_u64 v[216:217], v[112:113], 0, v[218:219]
	v_permlane16_swap_b32_e32 v208, v210
	v_permlane16_swap_b32_e32 v209, v211
	global_store_dwordx4 v[216:217], v[208:211], off
	s_nop 0
	v_mov_b32_e32 v214, v96
	v_mov_b32_e32 v215, v97
	s_nop 1
	v_permlane16_swap_b32_e32 v212, v214
	v_permlane16_swap_b32_e32 v213, v215
	global_store_dwordx4 v[216:217], v[212:215], off offset:64
	v_mul_f32_e32 v100, v93, v93
	v_fmac_f32_e32 v100, v92, v92
	v_fmac_f32_e32 v100, v94, v94
	v_fmac_f32_e32 v100, v95, v95
	v_add_u32_e32 v96, v193, v245
	v_fmac_f32_e32 v100, v84, v84
	v_mul_hi_i32 v28, v96, s52
	v_fmac_f32_e32 v100, v85, v85
	v_lshrrev_b32_e32 v29, 31, v28
	v_ashrrev_i32_e32 v28, 11, v28
	v_fmac_f32_e32 v100, v86, v86
	v_add_u32_e32 v28, v28, v29
	v_fmac_f32_e32 v100, v87, v87
	v_mul_i32_i24_e32 v28, 0x1010, v28
	v_fmac_f32_e32 v100, v88, v88
	v_sub_u32_e32 v28, v96, v28
	v_fmac_f32_e32 v100, v89, v89
	v_cndmask_b32_e64 v28, v28, v96, s[62:63]
	v_fmac_f32_e32 v100, v90, v90
	v_ashrrev_i32_e32 v29, 31, v28
	v_fmac_f32_e32 v100, v91, v91
	v_pk_mul_f32 v[98:99], v[80:81], v[80:81]
	v_lshlrev_b64 v[28:29], 8, v[28:29]
	v_add_f32_e32 v98, v98, v100
	v_lshl_add_u64 v[112:113], v[224:225], 0, v[28:29]
	v_mad_i64_i32 v[28:29], s[6:7], s76, v96, 0
	v_pk_mul_f32 v[96:97], v[82:83], v[82:83]
	v_add_f32_e32 v98, v99, v98
	v_add_f32_e32 v96, v96, v98
	v_add_f32_e32 v96, v97, v96
	v_mov_b32_e32 v97, v96
	s_nop 1
	v_permlane16_swap_b32_e32 v96, v97
	v_add_f32_e32 v105, v96, v97
	global_load_dwordx4 v[96:99], v[112:113], off offset:16
	global_load_dwordx4 v[100:103], v[112:113], off
	v_mov_b32_e32 v110, v92
	v_mov_b32_e32 v111, v94
	v_mov_b32_e32 v108, v88
	v_mov_b32_e32 v109, v90
	v_mov_b32_e32 v94, v93
	v_mov_b32_e32 v90, v89
	v_add_u32_e32 v104, v193, v246
	v_mov_b32_e32 v116, v80
	v_mul_hi_i32 v80, v104, s52
	v_mov_b32_e32 v117, v82
	v_mov_b32_e32 v82, v81
	v_lshrrev_b32_e32 v81, 31, v80
	v_ashrrev_i32_e32 v80, 11, v80
	v_add_u32_e32 v80, v80, v81
	v_mul_i32_i24_e32 v80, 0x1010, v80
	v_sub_u32_e32 v80, v104, v80
	v_cndmask_b32_e64 v80, v80, v104, s[62:63]
	v_ashrrev_i32_e32 v81, 31, v80
	v_lshlrev_b64 v[80:81], 8, v[80:81]
	v_mov_b32_e32 v118, v84
	v_mov_b32_e32 v119, v86
	v_mov_b32_e32 v86, v85
	v_lshl_add_u64 v[84:85], v[224:225], 0, v[80:81]
	v_mad_i64_i32 v[80:81], s[6:7], s76, v104, 0
	v_mul_f32_e32 v104, v77, v77
	v_fmac_f32_e32 v104, v76, v76
	v_fmac_f32_e32 v104, v78, v78
	v_fmac_f32_e32 v104, v79, v79
	v_fmac_f32_e32 v104, v68, v68
	v_fmac_f32_e32 v104, v69, v69
	v_fmac_f32_e32 v104, v70, v70
	v_fmac_f32_e32 v104, v71, v71
	v_fmac_f32_e32 v104, v72, v72
	v_fmac_f32_e32 v104, v73, v73
	v_fmac_f32_e32 v104, v74, v74
	v_fmac_f32_e32 v104, v75, v75
	v_mov_b32_e32 v107, v105
	s_nop 1
	v_permlane32_swap_b32_e32 v105, v107
	v_lshl_add_u64 v[28:29], v[28:29], 1, v[170:171]
	v_lshl_add_u64 v[80:81], v[80:81], 1, v[170:171]
	s_waitcnt vmcnt(1)
	v_mov_b32_e32 v89, v96
	s_waitcnt vmcnt(0)
	v_mov_b32_e32 v88, v100
	v_mov_b32_e32 v96, v101
	v_mov_b32_e32 v92, v102
	v_mov_b32_e32 v93, v98
	v_mov_b32_e32 v98, v103
	global_load_dwordx4 v[100:103], v[112:113], off offset:144
	global_load_dwordx4 v[120:123], v[112:113], off offset:128
	s_waitcnt vmcnt(1)
; #define ST4(ptr, a, b, c_, d) (*(uint2*)(ptr) = make_uint2((unsigned)f2bf(a) | ((unsigned)f2bf(b) << 16), (unsigned)f2bf(c_) | ((unsigned)f2bf(d) << 16)))
; __device__ __forceinline__ void head_norm_rope_store(f32x4 (&v)[4], const float (&g)[16], const float* __restrict__ rp, float qscale, u16* __restrict__ dstp) {
;   float ss = 0.f;
; #pragma unroll
;   for (int n = 0; n < 4; ++n)
; #pragma unroll
;     for (int j = 0; j < 4; ++j) ss += v[n][j] * v[n][j];
;   { auto rr = __builtin_amdgcn_permlane16_swap(__float_as_uint(ss), __float_as_uint(ss), false, false); ss = __uint_as_float(rr[0]) + __uint_as_float(rr[1]); }
;   { auto rr = __builtin_amdgcn_permlane32_swap(__float_as_uint(ss), __float_as_uint(ss), false, false); ss = __uint_as_float(rr[0]) + __uint_as_float(rr[1]); }
;   const float rs = rsqrtf(ss * (1.f / 64.f) + EPS) * qscale;
; #pragma unroll
;   for (int h2 = 0; h2 < 2; ++h2) {
;     const float4 c01 = *(const float4*)(rp + h2 * 32), c23 = *(const float4*)(rp + h2 * 32 + 4);
;     const float cs_[4] = {c01.x, c01.z, c23.x, c23.z}, sn_[4] = {c01.y, c01.w, c23.y, c23.w};
;     float o1[4], o2[4];
; #pragma unroll
;     for (int j = 0; j < 4; ++j) {
;       const float x1 = v[h2][j] * rs * g[h2 * 4 + j], x2 = v[h2 + 2][j] * rs * g[(h2 + 2) * 4 + j];
;       o1[j] = x1 * cs_[j] - x2 * sn_[j]; o2[j] = x1 * sn_[j] + x2 * cs_[j];
;     }
;     ST4(dstp + h2 * 16, o1[0], o1[1], o1[2], o1[3]);
;     ST4(dstp + (h2 + 2) * 16, o2[0], o2[1], o2[2], o2[3]);
;   }
; __device__ __forceinline__ void inproj_phase(const Ctx& p, int layer, int hf) {
;     ...
;       for (int m = 0; m < 9; ++m) {
;         if (m < 8 || (fat && wr == 1)) {
;           const int row = m < 8 ? brow + wr * 128 + m * 16 + fr : brow + 256 + fr;
;           const int pos = hf == 0 ? row : row % L1;
;           f32x4 v[4];
; #pragma unroll
;           for (int n = 0; n < 4; ++n) v[n] = m < 8 ? acc[m < 8 ? m : 0][n] : accx[n];
;           head_norm_rope_store(v, g, rope + (size_t)pos * 64 + fq * 8, qscale, dst + (size_t)row * ldc + c0 + wc * 64 + fq * 4);
	v_mov_b32_e32 v115, v102
	s_waitcnt vmcnt(0)
	v_mov_b32_e32 v114, v122
	v_mov_b32_e32 v102, v123
	v_pk_mul_f32 v[122:123], v[64:65], v[64:65]
	v_mov_b32_e32 v112, v120
	v_add_f32_e32 v104, v122, v104
	v_mov_b32_e32 v113, v100
	v_mov_b32_e32 v100, v121
	v_pk_mul_f32 v[120:121], v[66:67], v[66:67]
	v_add_f32_e32 v104, v123, v104
	v_add_f32_e32 v104, v120, v104
	v_add_f32_e32 v104, v121, v104
	v_mov_b32_e32 v106, v104
	s_nop 1
	v_permlane16_swap_b32_e32 v104, v106
	v_add_f32_e32 v104, v104, v106
	v_mov_b32_e32 v106, v104
	s_nop 1
	v_permlane32_swap_b32_e32 v104, v106
	v_pk_add_f32 v[104:105], v[104:105], v[106:107]
	s_nop 0
	v_pk_fma_f32 v[104:105], v[104:105], s[20:21], v[20:21] op_sel_hi:[1,0,0]
	s_nop 0
	v_mul_f32_e32 v106, 0x4b800000, v105
	v_cmp_gt_f32_e64 s[6:7], s96, v105
	v_cmp_gt_f32_e32 vcc, s96, v104
	s_nop 0
	v_cndmask_b32_e64 v105, v105, v106, s[6:7]
	v_rsq_f32_e32 v105, v105
	s_nop 0
	v_mul_f32_e32 v106, 0x45800000, v105
	v_cndmask_b32_e64 v105, v105, v106, s[6:7]
	v_mul_f32_e32 v106, v192, v105
	v_pk_mul_f32 v[108:109], v[108:109], v[106:107] op_sel_hi:[1,0]
	v_pk_mul_f32 v[110:111], v[110:111], v[106:107] op_sel_hi:[1,0]
	v_pk_mul_f32 v[108:109], v[172:173], v[108:109]
	v_pk_mul_f32 v[110:111], v[174:175], v[110:111]
	v_pk_mul_f32 v[90:91], v[90:91], v[106:107] op_sel_hi:[1,0]
	v_pk_mul_f32 v[120:121], v[96:97], v[108:109]
	v_pk_mul_f32 v[94:95], v[94:95], v[106:107] op_sel_hi:[1,0]
	v_pk_mul_f32 v[90:91], v[54:55], v[90:91]
	v_pk_fma_f32 v[120:121], v[88:89], v[110:111], v[120:121] neg_lo:[0,0,1] neg_hi:[0,0,1]
	v_pk_mul_f32 v[88:89], v[88:89], v[108:109]
	v_pk_mul_f32 v[94:95], v[62:63], v[94:95]
	v_pk_mul_f32 v[122:123], v[98:99], v[90:91]
	v_pk_fma_f32 v[88:89], v[96:97], v[110:111], v[88:89]
	v_pk_mul_f32 v[90:91], v[92:93], v[90:91]
	v_pk_fma_f32 v[122:123], v[92:93], v[94:95], v[122:123] neg_lo:[0,0,1] neg_hi:[0,0,1]
	v_pk_fma_f32 v[90:91], v[98:99], v[94:95], v[90:91]
	v_and_b32_sdwa v92, v89, v232 dst_sel:DWORD dst_unused:UNUSED_PAD src0_sel:WORD_1 src1_sel:DWORD
	v_and_b32_sdwa v93, v88, v232 dst_sel:DWORD dst_unused:UNUSED_PAD src0_sel:WORD_1 src1_sel:DWORD
	v_add3_u32 v88, v88, v93, s43
	v_add3_u32 v89, v89, v92, s43
	v_and_b32_sdwa v92, v91, v232 dst_sel:DWORD dst_unused:UNUSED_PAD src0_sel:WORD_1 src1_sel:DWORD
	v_and_b32_sdwa v93, v90, v232 dst_sel:DWORD dst_unused:UNUSED_PAD src0_sel:WORD_1 src1_sel:DWORD
	v_and_b32_sdwa v107, v120, v232 dst_sel:DWORD dst_unused:UNUSED_PAD src0_sel:WORD_1 src1_sel:DWORD
	v_add3_u32 v91, v91, v92, s43
	v_add3_u32 v90, v90, v93, s43
	v_add3_u32 v107, v120, v107, s43
	v_and_b32_e32 v91, 0xffff0000, v91
	v_and_b32_e32 v90, 0xffff0000, v90
	v_or_b32_sdwa v89, v91, v89 dst_sel:DWORD dst_unused:UNUSED_PAD src0_sel:DWORD src1_sel:WORD_1
	v_or_b32_sdwa v88, v90, v88 dst_sel:DWORD dst_unused:UNUSED_PAD src0_sel:DWORD src1_sel:WORD_1
	v_pk_mul_f32 v[90:91], v[116:117], v[106:107] op_sel_hi:[1,0]
	s_nop 0
	v_mov_b32_e32 v212, v88
	v_mov_b32_e32 v213, v89
	v_pk_mul_f32 v[88:89], v[118:119], v[106:107] op_sel_hi:[1,0]
	v_pk_mul_f32 v[90:91], v[60:61], v[90:91]
	v_pk_mul_f32 v[82:83], v[82:83], v[106:107] op_sel_hi:[1,0]
	v_pk_mul_f32 v[88:89], v[52:53], v[88:89]
	v_pk_mul_f32 v[86:87], v[86:87], v[106:107] op_sel_hi:[1,0]
	v_pk_mul_f32 v[82:83], v[22:23], v[82:83]
	v_pk_mul_f32 v[92:93], v[90:91], v[100:101]
	v_pk_mul_f32 v[86:87], v[30:31], v[86:87]
	v_pk_fma_f32 v[92:93], v[112:113], v[88:89], v[92:93] neg_lo:[0,0,1] neg_hi:[0,0,1]
	v_pk_mul_f32 v[94:95], v[82:83], v[102:103]
	v_pk_mul_f32 v[88:89], v[88:89], v[100:101]
	v_pk_fma_f32 v[94:95], v[86:87], v[114:115], v[94:95] neg_lo:[0,0,1] neg_hi:[0,0,1]
	v_pk_fma_f32 v[88:89], v[90:91], v[112:113], v[88:89]
	v_pk_mul_f32 v[86:87], v[86:87], v[102:103]
	v_and_b32_sdwa v105, v121, v232 dst_sel:DWORD dst_unused:UNUSED_PAD src0_sel:WORD_1 src1_sel:DWORD
	v_and_b32_sdwa v96, v93, v232 dst_sel:DWORD dst_unused:UNUSED_PAD src0_sel:WORD_1 src1_sel:DWORD
	v_and_b32_sdwa v97, v92, v232 dst_sel:DWORD dst_unused:UNUSED_PAD src0_sel:WORD_1 src1_sel:DWORD
	v_pk_fma_f32 v[82:83], v[82:83], v[114:115], v[86:87]
	v_and_b32_sdwa v86, v89, v232 dst_sel:DWORD dst_unused:UNUSED_PAD src0_sel:WORD_1 src1_sel:DWORD
	v_and_b32_sdwa v87, v88, v232 dst_sel:DWORD dst_unused:UNUSED_PAD src0_sel:WORD_1 src1_sel:DWORD
	v_add3_u32 v105, v121, v105, s43
	v_and_b32_sdwa v120, v123, v232 dst_sel:DWORD dst_unused:UNUSED_PAD src0_sel:WORD_1 src1_sel:DWORD
	v_and_b32_sdwa v121, v122, v232 dst_sel:DWORD dst_unused:UNUSED_PAD src0_sel:WORD_1 src1_sel:DWORD
	v_add3_u32 v92, v92, v97, s43
	v_add3_u32 v93, v93, v96, s43
	v_and_b32_sdwa v96, v95, v232 dst_sel:DWORD dst_unused:UNUSED_PAD src0_sel:WORD_1 src1_sel:DWORD
	v_and_b32_sdwa v97, v94, v232 dst_sel:DWORD dst_unused:UNUSED_PAD src0_sel:WORD_1 src1_sel:DWORD
	v_add3_u32 v87, v88, v87, s43
	v_add3_u32 v86, v89, v86, s43
	v_and_b32_sdwa v88, v83, v232 dst_sel:DWORD dst_unused:UNUSED_PAD src0_sel:WORD_1 src1_sel:DWORD
	v_and_b32_sdwa v89, v82, v232 dst_sel:DWORD dst_unused:UNUSED_PAD src0_sel:WORD_1 src1_sel:DWORD
	v_add3_u32 v120, v123, v120, s43
	v_add3_u32 v121, v122, v121, s43
	v_add3_u32 v95, v95, v96, s43
	v_add3_u32 v94, v94, v97, s43
	v_add3_u32 v83, v83, v88, s43
	v_add3_u32 v82, v82, v89, s43
	v_and_b32_e32 v120, 0xffff0000, v120
	v_and_b32_e32 v122, 0xffff0000, v121
	v_and_b32_e32 v95, 0xffff0000, v95
	v_and_b32_e32 v94, 0xffff0000, v94
	v_and_b32_e32 v83, 0xffff0000, v83
	v_and_b32_e32 v82, 0xffff0000, v82
	v_or_b32_sdwa v121, v120, v105 dst_sel:DWORD dst_unused:UNUSED_PAD src0_sel:DWORD src1_sel:WORD_1
	v_or_b32_sdwa v120, v122, v107 dst_sel:DWORD dst_unused:UNUSED_PAD src0_sel:DWORD src1_sel:WORD_1
; #define ST4(ptr, a, b, c_, d) (*(uint2*)(ptr) = make_uint2((unsigned)f2bf(a) | ((unsigned)f2bf(b) << 16), (unsigned)f2bf(c_) | ((unsigned)f2bf(d) << 16)))
; __device__ __forceinline__ void head_norm_rope_store(f32x4 (&v)[4], const float (&g)[16], const float* __restrict__ rp, float qscale, u16* __restrict__ dstp) {
;   float ss = 0.f;
; #pragma unroll
;   for (int n = 0; n < 4; ++n)
; #pragma unroll
;     for (int j = 0; j < 4; ++j) ss += v[n][j] * v[n][j];
;   { auto rr = __builtin_amdgcn_permlane16_swap(__float_as_uint(ss), __float_as_uint(ss), false, false); ss = __uint_as_float(rr[0]) + __uint_as_float(rr[1]); }
;   { auto rr = __builtin_amdgcn_permlane32_swap(__float_as_uint(ss), __float_as_uint(ss), false, false); ss = __uint_as_float(rr[0]) + __uint_as_float(rr[1]); }
;   const float rs = rsqrtf(ss * (1.f / 64.f) + EPS) * qscale;
; #pragma unroll
;   for (int h2 = 0; h2 < 2; ++h2) {
;     const float4 c01 = *(const float4*)(rp + h2 * 32), c23 = *(const float4*)(rp + h2 * 32 + 4);
;     const float cs_[4] = {c01.x, c01.z, c23.x, c23.z}, sn_[4] = {c01.y, c01.w, c23.y, c23.w};
;     float o1[4], o2[4];
; #pragma unroll
;     for (int j = 0; j < 4; ++j) {
;       const float x1 = v[h2][j] * rs * g[h2 * 4 + j], x2 = v[h2 + 2][j] * rs * g[(h2 + 2) * 4 + j];
;       o1[j] = x1 * cs_[j] - x2 * sn_[j]; o2[j] = x1 * sn_[j] + x2 * cs_[j];
;     }
;     ST4(dstp + h2 * 16, o1[0], o1[1], o1[2], o1[3]);
;     ST4(dstp + (h2 + 2) * 16, o2[0], o2[1], o2[2], o2[3]);
;   }
; __device__ __forceinline__ void inproj_phase(const Ctx& p, int layer, int hf) {
;     ...
;       for (int m = 0; m < 9; ++m) {
;         if (m < 8 || (fat && wr == 1)) {
;           const int row = m < 8 ? brow + wr * 128 + m * 16 + fr : brow + 256 + fr;
;           const int pos = hf == 0 ? row : row % L1;
;           f32x4 v[4];
; #pragma unroll
;           for (int n = 0; n < 4; ++n) v[n] = m < 8 ? acc[m < 8 ? m : 0][n] : accx[n];
;           head_norm_rope_store(v, g, rope + (size_t)pos * 64 + fq * 8, qscale, dst + (size_t)row * ldc + c0 + wc * 64 + fq * 4);
	v_or_b32_sdwa v93, v95, v93 dst_sel:DWORD dst_unused:UNUSED_PAD src0_sel:DWORD src1_sel:WORD_1
	v_or_b32_sdwa v92, v94, v92 dst_sel:DWORD dst_unused:UNUSED_PAD src0_sel:DWORD src1_sel:WORD_1
	v_or_b32_sdwa v83, v83, v86 dst_sel:DWORD dst_unused:UNUSED_PAD src0_sel:DWORD src1_sel:WORD_1
	v_or_b32_sdwa v82, v82, v87 dst_sel:DWORD dst_unused:UNUSED_PAD src0_sel:DWORD src1_sel:WORD_1
	s_nop 0
	v_mov_b32_e32 v208, v120
	v_mov_b32_e32 v209, v121
	s_nop 0
	v_mov_b32_e32 v210, v92
	v_mov_b32_e32 v211, v93
	v_mbcnt_lo_u32_b32 v220, -1, 0
	v_mbcnt_hi_u32_b32 v220, -1, v220
	v_and_b32_e32 v218, 16, v220
	v_lshrrev_b32_e32 v220, 1, v218
	v_add_u32_e32 v218, v218, v220
	v_mov_b32_e32 v219, 0
	v_lshl_add_u64 v[216:217], v[28:29], 0, v[218:219]
	v_permlane16_swap_b32_e32 v208, v210
	v_permlane16_swap_b32_e32 v209, v211
	global_store_dwordx4 v[216:217], v[208:211], off
	s_nop 0
	v_mov_b32_e32 v214, v82
	v_mov_b32_e32 v215, v83
	s_nop 1
	v_permlane16_swap_b32_e32 v212, v214
	v_permlane16_swap_b32_e32 v213, v215
	global_store_dwordx4 v[216:217], v[212:215], off offset:64
	global_load_dwordx4 v[86:89], v[84:85], off
	s_nop 0
	global_load_dwordx4 v[90:93], v[84:85], off offset:16
	v_mul_f32_e32 v83, 0x4b800000, v104
	v_mov_b32_e32 v82, v72
	v_cndmask_b32_e32 v72, v104, v83, vcc
	v_rsq_f32_e32 v72, v72
	v_mov_b32_e32 v83, v74
	v_mov_b32_e32 v74, v73
	v_mov_b32_e32 v29, v78
	v_mul_f32_e32 v73, 0x45800000, v72
	v_cndmask_b32_e32 v72, v72, v73, vcc
	v_mul_f32_e32 v94, v192, v72
	v_mov_b32_e32 v78, v77
	v_pk_mul_f32 v[74:75], v[74:75], v[94:95] op_sel_hi:[1,0]
	v_mov_b32_e32 v28, v76
	v_pk_mul_f32 v[72:73], v[82:83], v[94:95] op_sel_hi:[1,0]
	v_pk_mul_f32 v[76:77], v[78:79], v[94:95] op_sel_hi:[1,0]
	v_pk_mul_f32 v[74:75], v[54:55], v[74:75]
	v_pk_mul_f32 v[28:29], v[28:29], v[94:95] op_sel_hi:[1,0]
	v_pk_mul_f32 v[72:73], v[172:173], v[72:73]
	v_pk_mul_f32 v[76:77], v[62:63], v[76:77]
	v_pk_mul_f32 v[28:29], v[174:175], v[28:29]
	s_waitcnt vmcnt(1)
	v_mov_b32_e32 v78, v86
	s_waitcnt vmcnt(0)
	v_mov_b32_e32 v83, v92
	v_mov_b32_e32 v92, v89
	v_mov_b32_e32 v79, v90
	v_mov_b32_e32 v90, v87
	v_mov_b32_e32 v82, v88
	v_pk_mul_f32 v[88:89], v[92:93], v[74:75]
	v_pk_mul_f32 v[86:87], v[90:91], v[72:73]
	v_pk_mul_f32 v[72:73], v[78:79], v[72:73]
	v_pk_mul_f32 v[74:75], v[82:83], v[74:75]
	v_pk_fma_f32 v[82:83], v[82:83], v[76:77], v[88:89] neg_lo:[0,0,1] neg_hi:[0,0,1]
	v_pk_fma_f32 v[78:79], v[78:79], v[28:29], v[86:87] neg_lo:[0,0,1] neg_hi:[0,0,1]
	v_pk_fma_f32 v[28:29], v[90:91], v[28:29], v[72:73]
	v_pk_fma_f32 v[72:73], v[92:93], v[76:77], v[74:75]
	v_and_b32_sdwa v76, v83, v232 dst_sel:DWORD dst_unused:UNUSED_PAD src0_sel:WORD_1 src1_sel:DWORD
	v_and_b32_sdwa v77, v82, v232 dst_sel:DWORD dst_unused:UNUSED_PAD src0_sel:WORD_1 src1_sel:DWORD
	v_and_b32_sdwa v74, v79, v232 dst_sel:DWORD dst_unused:UNUSED_PAD src0_sel:WORD_1 src1_sel:DWORD
	v_and_b32_sdwa v75, v78, v232 dst_sel:DWORD dst_unused:UNUSED_PAD src0_sel:WORD_1 src1_sel:DWORD
	v_and_b32_sdwa v86, v29, v232 dst_sel:DWORD dst_unused:UNUSED_PAD src0_sel:WORD_1 src1_sel:DWORD
	v_and_b32_sdwa v87, v28, v232 dst_sel:DWORD dst_unused:UNUSED_PAD src0_sel:WORD_1 src1_sel:DWORD
	v_and_b32_sdwa v88, v73, v232 dst_sel:DWORD dst_unused:UNUSED_PAD src0_sel:WORD_1 src1_sel:DWORD
	v_and_b32_sdwa v89, v72, v232 dst_sel:DWORD dst_unused:UNUSED_PAD src0_sel:WORD_1 src1_sel:DWORD
	v_add3_u32 v76, v83, v76, s43
	v_add3_u32 v77, v82, v77, s43
	v_add3_u32 v75, v78, v75, s43
	v_add3_u32 v74, v79, v74, s43
	v_add3_u32 v78, v28, v87, s43
	v_add3_u32 v79, v29, v86, s43
	v_add3_u32 v28, v73, v88, s43
	v_add3_u32 v29, v72, v89, s43
	v_and_b32_e32 v72, 0xffff0000, v76
	v_and_b32_e32 v73, 0xffff0000, v77
	v_and_b32_e32 v76, 0xffff0000, v28
	v_and_b32_e32 v77, 0xffff0000, v29
	v_or_b32_sdwa v29, v72, v74 dst_sel:DWORD dst_unused:UNUSED_PAD src0_sel:DWORD src1_sel:WORD_1
	v_or_b32_sdwa v28, v73, v75 dst_sel:DWORD dst_unused:UNUSED_PAD src0_sel:DWORD src1_sel:WORD_1
	v_or_b32_sdwa v73, v76, v79 dst_sel:DWORD dst_unused:UNUSED_PAD src0_sel:DWORD src1_sel:WORD_1
	v_or_b32_sdwa v72, v77, v78 dst_sel:DWORD dst_unused:UNUSED_PAD src0_sel:DWORD src1_sel:WORD_1
	s_nop 0
	v_mov_b32_e32 v208, v28
	v_mov_b32_e32 v209, v29
	s_nop 0
	v_mov_b32_e32 v212, v72
	v_mov_b32_e32 v213, v73
	global_load_dwordx4 v[72:75], v[84:85], off offset:128
	s_nop 0
	global_load_dwordx4 v[76:79], v[84:85], off offset:144
	v_mov_b32_e32 v83, v66
	v_mov_b32_e32 v66, v65
	v_mov_b32_e32 v29, v70
	v_mov_b32_e32 v82, v64
	v_mov_b32_e32 v70, v69
	v_pk_mul_f32 v[66:67], v[66:67], v[94:95] op_sel_hi:[1,0]
	v_mov_b32_e32 v28, v68
	v_pk_mul_f32 v[64:65], v[82:83], v[94:95] op_sel_hi:[1,0]
	v_pk_mul_f32 v[68:69], v[70:71], v[94:95] op_sel_hi:[1,0]
	v_pk_mul_f32 v[66:67], v[22:23], v[66:67]
	v_pk_mul_f32 v[28:29], v[28:29], v[94:95] op_sel_hi:[1,0]
	v_pk_mul_f32 v[64:65], v[60:61], v[64:65]
	v_pk_mul_f32 v[68:69], v[30:31], v[68:69]
	v_pk_mul_f32 v[28:29], v[52:53], v[28:29]
	s_waitcnt vmcnt(1)
	v_mov_b32_e32 v70, v72
	s_waitcnt vmcnt(0)
; #define ST4(ptr, a, b, c_, d) (*(uint2*)(ptr) = make_uint2((unsigned)f2bf(a) | ((unsigned)f2bf(b) << 16), (unsigned)f2bf(c_) | ((unsigned)f2bf(d) << 16)))
; __device__ __forceinline__ void head_norm_rope_store(f32x4 (&v)[4], const float (&g)[16], const float* __restrict__ rp, float qscale, u16* __restrict__ dstp) {
;   float ss = 0.f;
; #pragma unroll
;   for (int n = 0; n < 4; ++n)
; #pragma unroll
;     for (int j = 0; j < 4; ++j) ss += v[n][j] * v[n][j];
;   { auto rr = __builtin_amdgcn_permlane16_swap(__float_as_uint(ss), __float_as_uint(ss), false, false); ss = __uint_as_float(rr[0]) + __uint_as_float(rr[1]); }
;   { auto rr = __builtin_amdgcn_permlane32_swap(__float_as_uint(ss), __float_as_uint(ss), false, false); ss = __uint_as_float(rr[0]) + __uint_as_float(rr[1]); }
;   const float rs = rsqrtf(ss * (1.f / 64.f) + EPS) * qscale;
; #pragma unroll
;   for (int h2 = 0; h2 < 2; ++h2) {
;     const float4 c01 = *(const float4*)(rp + h2 * 32), c23 = *(const float4*)(rp + h2 * 32 + 4);
;     const float cs_[4] = {c01.x, c01.z, c23.x, c23.z}, sn_[4] = {c01.y, c01.w, c23.y, c23.w};
;     float o1[4], o2[4];
; #pragma unroll
;     for (int j = 0; j < 4; ++j) {
;       const float x1 = v[h2][j] * rs * g[h2 * 4 + j], x2 = v[h2 + 2][j] * rs * g[(h2 + 2) * 4 + j];
;       o1[j] = x1 * cs_[j] - x2 * sn_[j]; o2[j] = x1 * sn_[j] + x2 * cs_[j];
;     }
;     ST4(dstp + h2 * 16, o1[0], o1[1], o1[2], o1[3]);
;     ST4(dstp + (h2 + 2) * 16, o2[0], o2[1], o2[2], o2[3]);
;   }
; __device__ __forceinline__ void inproj_phase(const Ctx& p, int layer, int hf) {
;     ...
;       for (int m = 0; m < 9; ++m) {
;         if (m < 8 || (fat && wr == 1)) {
;           const int row = m < 8 ? brow + wr * 128 + m * 16 + fr : brow + 256 + fr;
;           const int pos = hf == 0 ? row : row % L1;
;           f32x4 v[4];
; #pragma unroll
;           for (int n = 0; n < 4; ++n) v[n] = m < 8 ? acc[m < 8 ? m : 0][n] : accx[n];
;           head_norm_rope_store(v, g, rope + (size_t)pos * 64 + fq * 8, qscale, dst + (size_t)row * ldc + c0 + wc * 64 + fq * 4);
	v_mov_b32_e32 v71, v76
	v_mov_b32_e32 v76, v73
	v_mov_b32_e32 v73, v78
	v_mov_b32_e32 v78, v75
	v_mov_b32_e32 v72, v74
	v_pk_mul_f32 v[82:83], v[66:67], v[78:79]
	v_pk_mul_f32 v[74:75], v[64:65], v[76:77]
	v_pk_mul_f32 v[78:79], v[68:69], v[78:79]
	v_pk_fma_f32 v[68:69], v[68:69], v[72:73], v[82:83] neg_lo:[0,0,1] neg_hi:[0,0,1]
	v_pk_mul_f32 v[76:77], v[28:29], v[76:77]
	v_pk_fma_f32 v[28:29], v[70:71], v[28:29], v[74:75] neg_lo:[0,0,1] neg_hi:[0,0,1]
	v_pk_fma_f32 v[66:67], v[66:67], v[72:73], v[78:79]
	v_and_b32_sdwa v72, v69, v232 dst_sel:DWORD dst_unused:UNUSED_PAD src0_sel:WORD_1 src1_sel:DWORD
	v_and_b32_sdwa v73, v68, v232 dst_sel:DWORD dst_unused:UNUSED_PAD src0_sel:WORD_1 src1_sel:DWORD
	v_pk_fma_f32 v[64:65], v[64:65], v[70:71], v[76:77]
	v_and_b32_sdwa v70, v29, v232 dst_sel:DWORD dst_unused:UNUSED_PAD src0_sel:WORD_1 src1_sel:DWORD
	v_and_b32_sdwa v71, v28, v232 dst_sel:DWORD dst_unused:UNUSED_PAD src0_sel:WORD_1 src1_sel:DWORD
	v_and_b32_sdwa v76, v67, v232 dst_sel:DWORD dst_unused:UNUSED_PAD src0_sel:WORD_1 src1_sel:DWORD
	v_and_b32_sdwa v77, v66, v232 dst_sel:DWORD dst_unused:UNUSED_PAD src0_sel:WORD_1 src1_sel:DWORD
	v_add3_u32 v69, v69, v72, s43
	v_add3_u32 v68, v68, v73, s43
	v_and_b32_sdwa v74, v65, v232 dst_sel:DWORD dst_unused:UNUSED_PAD src0_sel:WORD_1 src1_sel:DWORD
	v_and_b32_sdwa v75, v64, v232 dst_sel:DWORD dst_unused:UNUSED_PAD src0_sel:WORD_1 src1_sel:DWORD
	v_add3_u32 v28, v28, v71, s43
	v_add3_u32 v29, v29, v70, s43
	v_add3_u32 v67, v67, v76, s43
	v_add3_u32 v66, v66, v77, s43
	v_and_b32_e32 v69, 0xffff0000, v69
	v_and_b32_e32 v68, 0xffff0000, v68
	v_add3_u32 v64, v64, v75, s43
	v_add3_u32 v65, v65, v74, s43
	v_and_b32_e32 v67, 0xffff0000, v67
	v_and_b32_e32 v66, 0xffff0000, v66
	v_or_b32_sdwa v29, v69, v29 dst_sel:DWORD dst_unused:UNUSED_PAD src0_sel:DWORD src1_sel:WORD_1
	v_or_b32_sdwa v28, v68, v28 dst_sel:DWORD dst_unused:UNUSED_PAD src0_sel:DWORD src1_sel:WORD_1
	v_or_b32_sdwa v65, v67, v65 dst_sel:DWORD dst_unused:UNUSED_PAD src0_sel:DWORD src1_sel:WORD_1
	v_or_b32_sdwa v64, v66, v64 dst_sel:DWORD dst_unused:UNUSED_PAD src0_sel:DWORD src1_sel:WORD_1
	s_nop 0
	v_mov_b32_e32 v210, v28
	v_mov_b32_e32 v211, v29
	v_mbcnt_lo_u32_b32 v220, -1, 0
	v_mbcnt_hi_u32_b32 v220, -1, v220
	v_and_b32_e32 v218, 16, v220
	v_lshrrev_b32_e32 v220, 1, v218
	v_add_u32_e32 v218, v218, v220
	v_mov_b32_e32 v219, 0
	v_lshl_add_u64 v[216:217], v[80:81], 0, v[218:219]
	v_permlane16_swap_b32_e32 v208, v210
	v_permlane16_swap_b32_e32 v209, v211
	global_store_dwordx4 v[216:217], v[208:211], off
	s_nop 0
	v_mov_b32_e32 v214, v64
	v_mov_b32_e32 v215, v65
	s_nop 1
	v_permlane16_swap_b32_e32 v212, v214
	v_permlane16_swap_b32_e32 v213, v215
	global_store_dwordx4 v[216:217], v[212:215], off offset:64
	v_mul_f32_e32 v68, v57, v57
	v_fmac_f32_e32 v68, v56, v56
	v_fmac_f32_e32 v68, v58, v58
	v_fmac_f32_e32 v68, v59, v59
	v_add_u32_e32 v64, v193, v247
	v_fmac_f32_e32 v68, v44, v44
	v_mul_hi_i32 v28, v64, s52
	v_fmac_f32_e32 v68, v45, v45
	v_lshrrev_b32_e32 v29, 31, v28
	v_ashrrev_i32_e32 v28, 11, v28
	v_fmac_f32_e32 v68, v46, v46
	v_add_u32_e32 v28, v28, v29
	v_fmac_f32_e32 v68, v47, v47
	v_mul_i32_i24_e32 v28, 0x1010, v28
	v_fmac_f32_e32 v68, v48, v48
	v_sub_u32_e32 v28, v64, v28
	v_fmac_f32_e32 v68, v49, v49
	v_cndmask_b32_e64 v28, v28, v64, s[62:63]
	v_fmac_f32_e32 v68, v50, v50
	v_ashrrev_i32_e32 v29, 31, v28
	v_fmac_f32_e32 v68, v51, v51
	v_pk_mul_f32 v[66:67], v[40:41], v[40:41]
	v_lshlrev_b64 v[28:29], 8, v[28:29]
	v_add_f32_e32 v66, v66, v68
	v_lshl_add_u64 v[80:81], v[224:225], 0, v[28:29]
	v_mad_i64_i32 v[28:29], s[6:7], s76, v64, 0
	v_pk_mul_f32 v[64:65], v[42:43], v[42:43]
	v_add_f32_e32 v66, v67, v66
	v_add_f32_e32 v64, v64, v66
	v_add_f32_e32 v64, v65, v64
	v_mov_b32_e32 v65, v64
	s_nop 1
	v_permlane16_swap_b32_e32 v64, v65
	v_add_f32_e32 v73, v64, v65
	global_load_dwordx4 v[64:67], v[80:81], off offset:16
	global_load_dwordx4 v[68:71], v[80:81], off
	v_mov_b32_e32 v78, v56
	v_mov_b32_e32 v79, v58
	v_mov_b32_e32 v76, v48
	v_mov_b32_e32 v77, v50
	v_mov_b32_e32 v58, v57
	v_mov_b32_e32 v50, v49
	v_add_u32_e32 v72, v193, v248
	v_mov_b32_e32 v84, v40
	v_mul_hi_i32 v40, v72, s52
	v_mov_b32_e32 v85, v42
	v_mov_b32_e32 v42, v41
	v_lshrrev_b32_e32 v41, 31, v40
	v_ashrrev_i32_e32 v40, 11, v40
	v_add_u32_e32 v40, v40, v41
	v_mul_i32_i24_e32 v40, 0x1010, v40
	v_sub_u32_e32 v40, v72, v40
	v_cndmask_b32_e64 v40, v40, v72, s[62:63]
	v_ashrrev_i32_e32 v41, 31, v40
	v_lshlrev_b64 v[40:41], 8, v[40:41]
	v_mov_b32_e32 v86, v44
	v_mov_b32_e32 v87, v46
	v_mov_b32_e32 v46, v45
	v_lshl_add_u64 v[44:45], v[224:225], 0, v[40:41]
	v_mad_i64_i32 v[40:41], s[6:7], s76, v72, 0
	v_mul_f32_e32 v72, v37, v37
	v_fmac_f32_e32 v72, v36, v36
	v_fmac_f32_e32 v72, v38, v38
	v_fmac_f32_e32 v72, v39, v39
	v_fmac_f32_e32 v72, v24, v24
	v_fmac_f32_e32 v72, v25, v25
	v_fmac_f32_e32 v72, v26, v26
	v_fmac_f32_e32 v72, v27, v27
	v_fmac_f32_e32 v72, v32, v32
	v_fmac_f32_e32 v72, v33, v33
	v_fmac_f32_e32 v72, v34, v34
	v_fmac_f32_e32 v72, v35, v35
	v_mov_b32_e32 v75, v73
	s_nop 1
	v_permlane32_swap_b32_e32 v73, v75
	v_lshl_add_u64 v[28:29], v[28:29], 1, v[170:171]
	v_lshl_add_u64 v[40:41], v[40:41], 1, v[170:171]
	s_waitcnt vmcnt(1)
	v_mov_b32_e32 v49, v64
	s_waitcnt vmcnt(0)
	v_mov_b32_e32 v48, v68
	v_mov_b32_e32 v64, v69
	v_mov_b32_e32 v56, v70
	v_mov_b32_e32 v57, v66
	v_mov_b32_e32 v66, v71
	global_load_dwordx4 v[68:71], v[80:81], off offset:144
	global_load_dwordx4 v[88:91], v[80:81], off offset:128
	s_waitcnt vmcnt(1)
	v_mov_b32_e32 v83, v70
	s_waitcnt vmcnt(0)
; #define ST4(ptr, a, b, c_, d) (*(uint2*)(ptr) = make_uint2((unsigned)f2bf(a) | ((unsigned)f2bf(b) << 16), (unsigned)f2bf(c_) | ((unsigned)f2bf(d) << 16)))
; __device__ __forceinline__ void head_norm_rope_store(f32x4 (&v)[4], const float (&g)[16], const float* __restrict__ rp, float qscale, u16* __restrict__ dstp) {
;   float ss = 0.f;
; #pragma unroll
;   for (int n = 0; n < 4; ++n)
; #pragma unroll
;     for (int j = 0; j < 4; ++j) ss += v[n][j] * v[n][j];
;   { auto rr = __builtin_amdgcn_permlane16_swap(__float_as_uint(ss), __float_as_uint(ss), false, false); ss = __uint_as_float(rr[0]) + __uint_as_float(rr[1]); }
;   { auto rr = __builtin_amdgcn_permlane32_swap(__float_as_uint(ss), __float_as_uint(ss), false, false); ss = __uint_as_float(rr[0]) + __uint_as_float(rr[1]); }
;   const float rs = rsqrtf(ss * (1.f / 64.f) + EPS) * qscale;
; #pragma unroll
;   for (int h2 = 0; h2 < 2; ++h2) {
;     const float4 c01 = *(const float4*)(rp + h2 * 32), c23 = *(const float4*)(rp + h2 * 32 + 4);
;     const float cs_[4] = {c01.x, c01.z, c23.x, c23.z}, sn_[4] = {c01.y, c01.w, c23.y, c23.w};
;     float o1[4], o2[4];
; #pragma unroll
;     for (int j = 0; j < 4; ++j) {
;       const float x1 = v[h2][j] * rs * g[h2 * 4 + j], x2 = v[h2 + 2][j] * rs * g[(h2 + 2) * 4 + j];
;       o1[j] = x1 * cs_[j] - x2 * sn_[j]; o2[j] = x1 * sn_[j] + x2 * cs_[j];
;     }
;     ST4(dstp + h2 * 16, o1[0], o1[1], o1[2], o1[3]);
;     ST4(dstp + (h2 + 2) * 16, o2[0], o2[1], o2[2], o2[3]);
;   }
; __device__ __forceinline__ void inproj_phase(const Ctx& p, int layer, int hf) {
;     ...
;       for (int m = 0; m < 9; ++m) {
;         if (m < 8 || (fat && wr == 1)) {
;           const int row = m < 8 ? brow + wr * 128 + m * 16 + fr : brow + 256 + fr;
;           const int pos = hf == 0 ? row : row % L1;
;           f32x4 v[4];
; #pragma unroll
;           for (int n = 0; n < 4; ++n) v[n] = m < 8 ? acc[m < 8 ? m : 0][n] : accx[n];
;           head_norm_rope_store(v, g, rope + (size_t)pos * 64 + fq * 8, qscale, dst + (size_t)row * ldc + c0 + wc * 64 + fq * 4);
	v_mov_b32_e32 v82, v90
	v_mov_b32_e32 v70, v91
	v_pk_mul_f32 v[90:91], v[16:17], v[16:17]
	v_mov_b32_e32 v80, v88
	v_add_f32_e32 v72, v90, v72
	v_mov_b32_e32 v81, v68
	v_mov_b32_e32 v68, v89
	v_pk_mul_f32 v[88:89], v[18:19], v[18:19]
	v_add_f32_e32 v72, v91, v72
	v_add_f32_e32 v72, v88, v72
	v_add_f32_e32 v72, v89, v72
	v_mov_b32_e32 v74, v72
	s_nop 1
	v_permlane16_swap_b32_e32 v72, v74
	v_add_f32_e32 v72, v72, v74
	v_mov_b32_e32 v74, v72
	s_nop 1
	v_permlane32_swap_b32_e32 v72, v74
	v_pk_add_f32 v[72:73], v[72:73], v[74:75]
	s_nop 0
	v_pk_fma_f32 v[20:21], v[72:73], s[20:21], v[20:21] op_sel_hi:[1,0,0]
	s_nop 0
	v_mul_f32_e32 v72, 0x4b800000, v21
	v_cmp_gt_f32_e64 s[6:7], s96, v21
	v_cmp_gt_f32_e32 vcc, s96, v20
	s_nop 0
	v_cndmask_b32_e64 v21, v21, v72, s[6:7]
	v_rsq_f32_e32 v21, v21
	s_nop 0
	v_mul_f32_e32 v72, 0x45800000, v21
	v_cndmask_b32_e64 v21, v21, v72, s[6:7]
	v_mul_f32_e32 v72, v192, v21
	v_pk_mul_f32 v[76:77], v[76:77], v[72:73] op_sel_hi:[1,0]
	v_pk_mul_f32 v[74:75], v[78:79], v[72:73] op_sel_hi:[1,0]
	v_pk_mul_f32 v[76:77], v[172:173], v[76:77]
	v_pk_mul_f32 v[50:51], v[50:51], v[72:73] op_sel_hi:[1,0]
	v_pk_mul_f32 v[74:75], v[174:175], v[74:75]
	v_pk_mul_f32 v[58:59], v[58:59], v[72:73] op_sel_hi:[1,0]
	v_pk_mul_f32 v[50:51], v[54:55], v[50:51]
	v_pk_mul_f32 v[78:79], v[64:65], v[76:77]
	v_pk_mul_f32 v[58:59], v[62:63], v[58:59]
	v_pk_fma_f32 v[78:79], v[48:49], v[74:75], v[78:79] neg_lo:[0,0,1] neg_hi:[0,0,1]
	v_pk_mul_f32 v[88:89], v[66:67], v[50:51]
	v_and_b32_sdwa v73, v78, v232 dst_sel:DWORD dst_unused:UNUSED_PAD src0_sel:WORD_1 src1_sel:DWORD
	v_pk_fma_f32 v[88:89], v[56:57], v[58:59], v[88:89] neg_lo:[0,0,1] neg_hi:[0,0,1]
	v_and_b32_sdwa v21, v79, v232 dst_sel:DWORD dst_unused:UNUSED_PAD src0_sel:WORD_1 src1_sel:DWORD
	v_add3_u32 v73, v78, v73, s43
	v_and_b32_sdwa v78, v89, v232 dst_sel:DWORD dst_unused:UNUSED_PAD src0_sel:WORD_1 src1_sel:DWORD
	v_add3_u32 v21, v79, v21, s43
	v_and_b32_sdwa v79, v88, v232 dst_sel:DWORD dst_unused:UNUSED_PAD src0_sel:WORD_1 src1_sel:DWORD
	v_add3_u32 v78, v89, v78, s43
	v_pk_mul_f32 v[48:49], v[48:49], v[76:77]
	v_add3_u32 v79, v88, v79, s43
	v_and_b32_e32 v78, 0xffff0000, v78
	v_pk_fma_f32 v[48:49], v[64:65], v[74:75], v[48:49]
	v_pk_mul_f32 v[50:51], v[56:57], v[50:51]
	v_and_b32_e32 v88, 0xffff0000, v79
	v_or_b32_sdwa v79, v78, v21 dst_sel:DWORD dst_unused:UNUSED_PAD src0_sel:DWORD src1_sel:WORD_1
	v_pk_fma_f32 v[50:51], v[66:67], v[58:59], v[50:51]
	v_and_b32_sdwa v21, v49, v232 dst_sel:DWORD dst_unused:UNUSED_PAD src0_sel:WORD_1 src1_sel:DWORD
	v_and_b32_sdwa v56, v48, v232 dst_sel:DWORD dst_unused:UNUSED_PAD src0_sel:WORD_1 src1_sel:DWORD
	v_add3_u32 v48, v48, v56, s43
	v_add3_u32 v21, v49, v21, s43
	v_and_b32_sdwa v49, v51, v232 dst_sel:DWORD dst_unused:UNUSED_PAD src0_sel:WORD_1 src1_sel:DWORD
	v_and_b32_sdwa v56, v50, v232 dst_sel:DWORD dst_unused:UNUSED_PAD src0_sel:WORD_1 src1_sel:DWORD
	v_add3_u32 v49, v51, v49, s43
	v_add3_u32 v50, v50, v56, s43
	v_and_b32_e32 v49, 0xffff0000, v49
	v_and_b32_e32 v50, 0xffff0000, v50
	v_or_b32_sdwa v49, v49, v21 dst_sel:DWORD dst_unused:UNUSED_PAD src0_sel:DWORD src1_sel:WORD_1
	v_or_b32_sdwa v48, v50, v48 dst_sel:DWORD dst_unused:UNUSED_PAD src0_sel:DWORD src1_sel:WORD_1
	v_pk_mul_f32 v[50:51], v[84:85], v[72:73] op_sel_hi:[1,0]
	s_nop 0
	v_mov_b32_e32 v212, v48
	v_mov_b32_e32 v213, v49
	v_pk_mul_f32 v[48:49], v[86:87], v[72:73] op_sel_hi:[1,0]
	v_pk_mul_f32 v[50:51], v[60:61], v[50:51]
	v_pk_mul_f32 v[42:43], v[42:43], v[72:73] op_sel_hi:[1,0]
	v_pk_mul_f32 v[48:49], v[52:53], v[48:49]
	v_pk_mul_f32 v[46:47], v[46:47], v[72:73] op_sel_hi:[1,0]
	v_pk_mul_f32 v[42:43], v[22:23], v[42:43]
	v_pk_mul_f32 v[56:57], v[50:51], v[68:69]
	v_pk_mul_f32 v[46:47], v[30:31], v[46:47]
	v_pk_fma_f32 v[56:57], v[80:81], v[48:49], v[56:57] neg_lo:[0,0,1] neg_hi:[0,0,1]
	v_pk_mul_f32 v[58:59], v[42:43], v[70:71]
	v_and_b32_sdwa v21, v57, v232 dst_sel:DWORD dst_unused:UNUSED_PAD src0_sel:WORD_1 src1_sel:DWORD
	v_pk_fma_f32 v[58:59], v[46:47], v[82:83], v[58:59] neg_lo:[0,0,1] neg_hi:[0,0,1]
	v_pk_mul_f32 v[48:49], v[48:49], v[68:69]
	v_add3_u32 v21, v57, v21, s43
	v_and_b32_sdwa v57, v59, v232 dst_sel:DWORD dst_unused:UNUSED_PAD src0_sel:WORD_1 src1_sel:DWORD
	v_pk_fma_f32 v[48:49], v[50:51], v[80:81], v[48:49]
	v_pk_mul_f32 v[46:47], v[46:47], v[70:71]
	v_and_b32_sdwa v64, v56, v232 dst_sel:DWORD dst_unused:UNUSED_PAD src0_sel:WORD_1 src1_sel:DWORD
	v_add3_u32 v57, v59, v57, s43
	v_pk_fma_f32 v[42:43], v[42:43], v[82:83], v[46:47]
	v_and_b32_sdwa v46, v48, v232 dst_sel:DWORD dst_unused:UNUSED_PAD src0_sel:WORD_1 src1_sel:DWORD
	v_add3_u32 v56, v56, v64, s43
	v_and_b32_sdwa v64, v58, v232 dst_sel:DWORD dst_unused:UNUSED_PAD src0_sel:WORD_1 src1_sel:DWORD
	v_and_b32_e32 v57, 0xffff0000, v57
	v_add3_u32 v46, v48, v46, s43
	v_and_b32_sdwa v47, v43, v232 dst_sel:DWORD dst_unused:UNUSED_PAD src0_sel:WORD_1 src1_sel:DWORD
	v_and_b32_sdwa v48, v42, v232 dst_sel:DWORD dst_unused:UNUSED_PAD src0_sel:WORD_1 src1_sel:DWORD
	v_add3_u32 v58, v58, v64, s43
	v_or_b32_sdwa v57, v57, v21 dst_sel:DWORD dst_unused:UNUSED_PAD src0_sel:DWORD src1_sel:WORD_1
	v_and_b32_sdwa v21, v49, v232 dst_sel:DWORD dst_unused:UNUSED_PAD src0_sel:WORD_1 src1_sel:DWORD
	v_add3_u32 v43, v43, v47, s43
	v_add3_u32 v42, v42, v48, s43
	v_and_b32_e32 v58, 0xffff0000, v58
	v_add3_u32 v21, v49, v21, s43
	v_and_b32_e32 v43, 0xffff0000, v43
	v_and_b32_e32 v42, 0xffff0000, v42
	v_or_b32_sdwa v78, v88, v73 dst_sel:DWORD dst_unused:UNUSED_PAD src0_sel:DWORD src1_sel:WORD_1
	v_or_b32_sdwa v56, v58, v56 dst_sel:DWORD dst_unused:UNUSED_PAD src0_sel:DWORD src1_sel:WORD_1
; #define ST4(ptr, a, b, c_, d) (*(uint2*)(ptr) = make_uint2((unsigned)f2bf(a) | ((unsigned)f2bf(b) << 16), (unsigned)f2bf(c_) | ((unsigned)f2bf(d) << 16)))
; __device__ __forceinline__ void head_norm_rope_store(f32x4 (&v)[4], const float (&g)[16], const float* __restrict__ rp, float qscale, u16* __restrict__ dstp) {
;   float ss = 0.f;
; #pragma unroll
;   for (int n = 0; n < 4; ++n)
; #pragma unroll
;     for (int j = 0; j < 4; ++j) ss += v[n][j] * v[n][j];
;   { auto rr = __builtin_amdgcn_permlane16_swap(__float_as_uint(ss), __float_as_uint(ss), false, false); ss = __uint_as_float(rr[0]) + __uint_as_float(rr[1]); }
;   { auto rr = __builtin_amdgcn_permlane32_swap(__float_as_uint(ss), __float_as_uint(ss), false, false); ss = __uint_as_float(rr[0]) + __uint_as_float(rr[1]); }
;   const float rs = rsqrtf(ss * (1.f / 64.f) + EPS) * qscale;
; #pragma unroll
;   for (int h2 = 0; h2 < 2; ++h2) {
;     const float4 c01 = *(const float4*)(rp + h2 * 32), c23 = *(const float4*)(rp + h2 * 32 + 4);
;     const float cs_[4] = {c01.x, c01.z, c23.x, c23.z}, sn_[4] = {c01.y, c01.w, c23.y, c23.w};
;     float o1[4], o2[4];
; #pragma unroll
;     for (int j = 0; j < 4; ++j) {
;       const float x1 = v[h2][j] * rs * g[h2 * 4 + j], x2 = v[h2 + 2][j] * rs * g[(h2 + 2) * 4 + j];
;       o1[j] = x1 * cs_[j] - x2 * sn_[j]; o2[j] = x1 * sn_[j] + x2 * cs_[j];
;     }
;     ST4(dstp + h2 * 16, o1[0], o1[1], o1[2], o1[3]);
;     ST4(dstp + (h2 + 2) * 16, o2[0], o2[1], o2[2], o2[3]);
;   }
; __device__ __forceinline__ void inproj_phase(const Ctx& p, int layer, int hf) {
;     ...
;       for (int m = 0; m < 9; ++m) {
;         if (m < 8 || (fat && wr == 1)) {
;           const int row = m < 8 ? brow + wr * 128 + m * 16 + fr : brow + 256 + fr;
;           const int pos = hf == 0 ? row : row % L1;
;           f32x4 v[4];
; #pragma unroll
;           for (int n = 0; n < 4; ++n) v[n] = m < 8 ? acc[m < 8 ? m : 0][n] : accx[n];
;           head_norm_rope_store(v, g, rope + (size_t)pos * 64 + fq * 8, qscale, dst + (size_t)row * ldc + c0 + wc * 64 + fq * 4);
	v_or_b32_sdwa v43, v43, v21 dst_sel:DWORD dst_unused:UNUSED_PAD src0_sel:DWORD src1_sel:WORD_1
	v_or_b32_sdwa v42, v42, v46 dst_sel:DWORD dst_unused:UNUSED_PAD src0_sel:DWORD src1_sel:WORD_1
	s_nop 0
	v_mov_b32_e32 v208, v78
	v_mov_b32_e32 v209, v79
	s_nop 0
	v_mov_b32_e32 v210, v56
	v_mov_b32_e32 v211, v57
	v_mbcnt_lo_u32_b32 v220, -1, 0
	v_mbcnt_hi_u32_b32 v220, -1, v220
	v_and_b32_e32 v218, 16, v220
	v_lshrrev_b32_e32 v220, 1, v218
	v_add_u32_e32 v218, v218, v220
	v_mov_b32_e32 v219, 0
	v_lshl_add_u64 v[216:217], v[28:29], 0, v[218:219]
	v_permlane16_swap_b32_e32 v208, v210
	v_permlane16_swap_b32_e32 v209, v211
	global_store_dwordx4 v[216:217], v[208:211], off
	s_nop 0
	v_mov_b32_e32 v214, v42
	v_mov_b32_e32 v215, v43
	s_nop 1
	v_permlane16_swap_b32_e32 v212, v214
	v_permlane16_swap_b32_e32 v213, v215
	global_store_dwordx4 v[216:217], v[212:215], off offset:64
	global_load_dwordx4 v[46:49], v[44:45], off
	s_nop 0
	global_load_dwordx4 v[56:59], v[44:45], off offset:16
	v_mul_f32_e32 v21, 0x4b800000, v20
	v_cndmask_b32_e32 v20, v20, v21, vcc
	v_rsq_f32_e32 v20, v20
	v_mov_b32_e32 v43, v34
	v_mov_b32_e32 v34, v33
	v_mov_b32_e32 v29, v38
	v_mul_f32_e32 v21, 0x45800000, v20
	v_cndmask_b32_e32 v20, v20, v21, vcc
	v_mul_f32_e32 v20, v192, v20
	v_mov_b32_e32 v42, v32
	v_mov_b32_e32 v38, v37
	v_pk_mul_f32 v[34:35], v[34:35], v[20:21] op_sel_hi:[1,0]
	v_mov_b32_e32 v28, v36
	v_pk_mul_f32 v[32:33], v[42:43], v[20:21] op_sel_hi:[1,0]
	v_pk_mul_f32 v[36:37], v[38:39], v[20:21] op_sel_hi:[1,0]
	v_pk_mul_f32 v[34:35], v[54:55], v[34:35]
	v_pk_mul_f32 v[28:29], v[28:29], v[20:21] op_sel_hi:[1,0]
	v_pk_mul_f32 v[32:33], v[172:173], v[32:33]
	v_pk_mul_f32 v[36:37], v[62:63], v[36:37]
	v_pk_mul_f32 v[28:29], v[174:175], v[28:29]
	s_waitcnt vmcnt(1)
	v_mov_b32_e32 v38, v46
	s_waitcnt vmcnt(0)
	v_mov_b32_e32 v43, v58
	v_mov_b32_e32 v58, v49
	v_mov_b32_e32 v39, v56
	v_mov_b32_e32 v56, v47
	v_mov_b32_e32 v42, v48
	v_pk_mul_f32 v[48:49], v[58:59], v[34:35]
	v_pk_mul_f32 v[46:47], v[56:57], v[32:33]
	v_pk_mul_f32 v[32:33], v[38:39], v[32:33]
	v_pk_mul_f32 v[34:35], v[42:43], v[34:35]
	v_pk_fma_f32 v[42:43], v[42:43], v[36:37], v[48:49] neg_lo:[0,0,1] neg_hi:[0,0,1]
	v_pk_fma_f32 v[38:39], v[38:39], v[28:29], v[46:47] neg_lo:[0,0,1] neg_hi:[0,0,1]
	v_pk_fma_f32 v[28:29], v[56:57], v[28:29], v[32:33]
	v_pk_fma_f32 v[32:33], v[58:59], v[36:37], v[34:35]
	v_and_b32_sdwa v35, v43, v232 dst_sel:DWORD dst_unused:UNUSED_PAD src0_sel:WORD_1 src1_sel:DWORD
	v_and_b32_sdwa v36, v42, v232 dst_sel:DWORD dst_unused:UNUSED_PAD src0_sel:WORD_1 src1_sel:DWORD
	v_and_b32_sdwa v21, v39, v232 dst_sel:DWORD dst_unused:UNUSED_PAD src0_sel:WORD_1 src1_sel:DWORD
	v_and_b32_sdwa v34, v38, v232 dst_sel:DWORD dst_unused:UNUSED_PAD src0_sel:WORD_1 src1_sel:DWORD
	v_and_b32_sdwa v37, v29, v232 dst_sel:DWORD dst_unused:UNUSED_PAD src0_sel:WORD_1 src1_sel:DWORD
	v_and_b32_sdwa v46, v28, v232 dst_sel:DWORD dst_unused:UNUSED_PAD src0_sel:WORD_1 src1_sel:DWORD
	v_and_b32_sdwa v47, v33, v232 dst_sel:DWORD dst_unused:UNUSED_PAD src0_sel:WORD_1 src1_sel:DWORD
	v_and_b32_sdwa v48, v32, v232 dst_sel:DWORD dst_unused:UNUSED_PAD src0_sel:WORD_1 src1_sel:DWORD
	v_add3_u32 v35, v43, v35, s43
	v_add3_u32 v36, v42, v36, s43
	v_add3_u32 v34, v38, v34, s43
	v_add3_u32 v21, v39, v21, s43
	v_add3_u32 v38, v28, v46, s43
	v_add3_u32 v37, v29, v37, s43
	v_add3_u32 v28, v33, v47, s43
	v_add3_u32 v29, v32, v48, s43
	v_and_b32_e32 v32, 0xffff0000, v35
	v_and_b32_e32 v33, 0xffff0000, v36
	v_and_b32_e32 v35, 0xffff0000, v28
	v_and_b32_e32 v36, 0xffff0000, v29
	v_or_b32_sdwa v29, v32, v21 dst_sel:DWORD dst_unused:UNUSED_PAD src0_sel:DWORD src1_sel:WORD_1
	v_or_b32_sdwa v28, v33, v34 dst_sel:DWORD dst_unused:UNUSED_PAD src0_sel:DWORD src1_sel:WORD_1
	v_or_b32_sdwa v33, v35, v37 dst_sel:DWORD dst_unused:UNUSED_PAD src0_sel:DWORD src1_sel:WORD_1
	v_or_b32_sdwa v32, v36, v38 dst_sel:DWORD dst_unused:UNUSED_PAD src0_sel:DWORD src1_sel:WORD_1
	s_nop 0
	v_mov_b32_e32 v208, v28
	v_mov_b32_e32 v209, v29
	s_nop 0
	v_mov_b32_e32 v212, v32
	v_mov_b32_e32 v213, v33
	global_load_dwordx4 v[32:35], v[44:45], off offset:128
	s_nop 0
	global_load_dwordx4 v[36:39], v[44:45], off offset:144
	v_mov_b32_e32 v43, v18
	v_mov_b32_e32 v18, v17
	v_mov_b32_e32 v28, v24
	v_mov_b32_e32 v29, v26
	v_mov_b32_e32 v42, v16
	v_mov_b32_e32 v26, v25
	v_pk_mul_f32 v[18:19], v[18:19], v[20:21] op_sel_hi:[1,0]
	v_pk_mul_f32 v[16:17], v[28:29], v[20:21] op_sel_hi:[1,0]
	v_pk_mul_f32 v[24:25], v[42:43], v[20:21] op_sel_hi:[1,0]
	v_pk_mul_f32 v[26:27], v[26:27], v[20:21] op_sel_hi:[1,0]
	v_pk_mul_f32 v[18:19], v[22:23], v[18:19]
	v_pk_mul_f32 v[20:21], v[60:61], v[24:25]
	v_pk_mul_f32 v[24:25], v[30:31], v[26:27]
	v_pk_mul_f32 v[16:17], v[52:53], v[16:17]
	s_waitcnt vmcnt(1)
	v_mov_b32_e32 v28, v34
	s_waitcnt vmcnt(0)
; #define ST4(ptr, a, b, c_, d) (*(uint2*)(ptr) = make_uint2((unsigned)f2bf(a) | ((unsigned)f2bf(b) << 16), (unsigned)f2bf(c_) | ((unsigned)f2bf(d) << 16)))
; __device__ __forceinline__ void head_norm_rope_store(f32x4 (&v)[4], const float (&g)[16], const float* __restrict__ rp, float qscale, u16* __restrict__ dstp) {
;   float ss = 0.f;
; #pragma unroll
;   for (int n = 0; n < 4; ++n)
; #pragma unroll
;     for (int j = 0; j < 4; ++j) ss += v[n][j] * v[n][j];
;   { auto rr = __builtin_amdgcn_permlane16_swap(__float_as_uint(ss), __float_as_uint(ss), false, false); ss = __uint_as_float(rr[0]) + __uint_as_float(rr[1]); }
;   { auto rr = __builtin_amdgcn_permlane32_swap(__float_as_uint(ss), __float_as_uint(ss), false, false); ss = __uint_as_float(rr[0]) + __uint_as_float(rr[1]); }
;   const float rs = rsqrtf(ss * (1.f / 64.f) + EPS) * qscale;
; #pragma unroll
;   for (int h2 = 0; h2 < 2; ++h2) {
;     const float4 c01 = *(const float4*)(rp + h2 * 32), c23 = *(const float4*)(rp + h2 * 32 + 4);
;     const float cs_[4] = {c01.x, c01.z, c23.x, c23.z}, sn_[4] = {c01.y, c01.w, c23.y, c23.w};
;     float o1[4], o2[4];
; #pragma unroll
;     for (int j = 0; j < 4; ++j) {
;       const float x1 = v[h2][j] * rs * g[h2 * 4 + j], x2 = v[h2 + 2][j] * rs * g[(h2 + 2) * 4 + j];
;       o1[j] = x1 * cs_[j] - x2 * sn_[j]; o2[j] = x1 * sn_[j] + x2 * cs_[j];
;     }
;     ST4(dstp + h2 * 16, o1[0], o1[1], o1[2], o1[3]);
;     ST4(dstp + (h2 + 2) * 16, o2[0], o2[1], o2[2], o2[3]);
;   }
; __device__ __forceinline__ void inproj_phase(const Ctx& p, int layer, int hf) {
;     ...
;       for (int m = 0; m < 9; ++m) {
;         if (m < 8 || (fat && wr == 1)) {
;           const int row = m < 8 ? brow + wr * 128 + m * 16 + fr : brow + 256 + fr;
;           const int pos = hf == 0 ? row : row % L1;
;           f32x4 v[4];
; #pragma unroll
;           for (int n = 0; n < 4; ++n) v[n] = m < 8 ? acc[m < 8 ? m : 0][n] : accx[n];
;           head_norm_rope_store(v, g, rope + (size_t)pos * 64 + fq * 8, qscale, dst + (size_t)row * ldc + c0 + wc * 64 + fq * 4);
	v_mov_b32_e32 v29, v38
	v_mov_b32_e32 v38, v35
	v_mov_b32_e32 v27, v36
	v_mov_b32_e32 v36, v33
	v_pk_mul_f32 v[34:35], v[18:19], v[38:39]
	v_mov_b32_e32 v26, v32
	v_pk_mul_f32 v[32:33], v[20:21], v[36:37]
	v_pk_mul_f32 v[38:39], v[24:25], v[38:39]
	v_pk_fma_f32 v[24:25], v[24:25], v[28:29], v[34:35] neg_lo:[0,0,1] neg_hi:[0,0,1]
	v_pk_mul_f32 v[36:37], v[16:17], v[36:37]
	v_pk_fma_f32 v[16:17], v[26:27], v[16:17], v[32:33] neg_lo:[0,0,1] neg_hi:[0,0,1]
	v_pk_fma_f32 v[18:19], v[18:19], v[28:29], v[38:39]
	v_and_b32_sdwa v28, v25, v232 dst_sel:DWORD dst_unused:UNUSED_PAD src0_sel:WORD_1 src1_sel:DWORD
	v_and_b32_sdwa v29, v24, v232 dst_sel:DWORD dst_unused:UNUSED_PAD src0_sel:WORD_1 src1_sel:DWORD
	v_pk_fma_f32 v[20:21], v[20:21], v[26:27], v[36:37]
	v_and_b32_sdwa v26, v17, v232 dst_sel:DWORD dst_unused:UNUSED_PAD src0_sel:WORD_1 src1_sel:DWORD
	v_and_b32_sdwa v27, v16, v232 dst_sel:DWORD dst_unused:UNUSED_PAD src0_sel:WORD_1 src1_sel:DWORD
	v_and_b32_sdwa v34, v19, v232 dst_sel:DWORD dst_unused:UNUSED_PAD src0_sel:WORD_1 src1_sel:DWORD
	v_and_b32_sdwa v35, v18, v232 dst_sel:DWORD dst_unused:UNUSED_PAD src0_sel:WORD_1 src1_sel:DWORD
	v_add3_u32 v25, v25, v28, s43
	v_add3_u32 v24, v24, v29, s43
	v_and_b32_sdwa v32, v21, v232 dst_sel:DWORD dst_unused:UNUSED_PAD src0_sel:WORD_1 src1_sel:DWORD
	v_and_b32_sdwa v33, v20, v232 dst_sel:DWORD dst_unused:UNUSED_PAD src0_sel:WORD_1 src1_sel:DWORD
	v_add3_u32 v16, v16, v27, s43
	v_add3_u32 v17, v17, v26, s43
	v_add3_u32 v19, v19, v34, s43
	v_add3_u32 v18, v18, v35, s43
	v_and_b32_e32 v25, 0xffff0000, v25
	v_and_b32_e32 v24, 0xffff0000, v24
	v_add3_u32 v20, v20, v33, s43
	v_add3_u32 v21, v21, v32, s43
	v_and_b32_e32 v19, 0xffff0000, v19
	v_and_b32_e32 v18, 0xffff0000, v18
	v_or_b32_sdwa v17, v25, v17 dst_sel:DWORD dst_unused:UNUSED_PAD src0_sel:DWORD src1_sel:WORD_1
	v_or_b32_sdwa v16, v24, v16 dst_sel:DWORD dst_unused:UNUSED_PAD src0_sel:DWORD src1_sel:WORD_1
	v_or_b32_sdwa v19, v19, v21 dst_sel:DWORD dst_unused:UNUSED_PAD src0_sel:DWORD src1_sel:WORD_1
	v_or_b32_sdwa v18, v18, v20 dst_sel:DWORD dst_unused:UNUSED_PAD src0_sel:DWORD src1_sel:WORD_1
	s_nop 0
	v_mov_b32_e32 v210, v16
	v_mov_b32_e32 v211, v17
	v_mbcnt_lo_u32_b32 v220, -1, 0
	v_mbcnt_hi_u32_b32 v220, -1, v220
	v_and_b32_e32 v218, 16, v220
	v_lshrrev_b32_e32 v220, 1, v218
	v_add_u32_e32 v218, v218, v220
	v_mov_b32_e32 v219, 0
	v_lshl_add_u64 v[216:217], v[40:41], 0, v[218:219]
	v_permlane16_swap_b32_e32 v208, v210
	v_permlane16_swap_b32_e32 v209, v211
	global_store_dwordx4 v[216:217], v[208:211], off
	s_nop 0
	v_mov_b32_e32 v214, v18
	v_mov_b32_e32 v215, v19
	s_nop 1
	v_permlane16_swap_b32_e32 v212, v214
	v_permlane16_swap_b32_e32 v213, v215
	global_store_dwordx4 v[216:217], v[212:215], off offset:64
	s_and_saveexec_b64 s[6:7], s[8:9]
	s_cbranch_execz .LBB0_257
	v_add_u32_e32 v18, s68, v239
	v_mul_hi_i32 v16, v18, s52
	v_lshrrev_b32_e32 v17, 31, v16
	v_ashrrev_i32_e32 v16, 11, v16
	v_add_u32_e32 v16, v16, v17
	v_mul_i32_i24_e32 v16, 0x1010, v16
	v_sub_u32_e32 v16, v18, v16
	v_cndmask_b32_e64 v16, v16, v18, s[62:63]
	v_ashrrev_i32_e32 v17, 31, v16
	v_lshlrev_b64 v[16:17], 8, v[16:17]
	v_lshl_add_u64 v[26:27], v[224:225], 0, v[16:17]
	v_mad_i64_i32 v[16:17], s[8:9], s76, v18, 0
	v_lshl_add_u64 v[20:21], v[16:17], 1, v[170:171]
	v_mul_f32_e32 v16, v13, v13
	v_fmac_f32_e32 v16, v12, v12
	v_fmac_f32_e32 v16, v14, v14
	v_fmac_f32_e32 v16, v15, v15
	v_fmac_f32_e32 v16, v4, v4
	v_fmac_f32_e32 v16, v5, v5
	v_fmac_f32_e32 v16, v6, v6
	v_fmac_f32_e32 v16, v7, v7
	v_fmac_f32_e32 v16, v8, v8
	v_fmac_f32_e32 v16, v9, v9
	v_fmac_f32_e32 v16, v10, v10
	v_fmac_f32_e32 v16, v11, v11
	v_fmac_f32_e32 v16, v0, v0
	v_fmac_f32_e32 v16, v1, v1
	v_fmac_f32_e32 v16, v2, v2
	v_fmac_f32_e32 v16, v3, v3
	v_mov_b32_e32 v17, v16
	s_nop 1
	v_permlane16_swap_b32_e32 v16, v17
	v_add_f32_e32 v16, v16, v17
	v_mov_b32_e32 v17, v16
	s_nop 1
	v_permlane32_swap_b32_e32 v16, v17
	v_add_f32_e32 v16, v16, v17
	v_fmamk_f32 v16, v16, 0x3c800000, v235
	v_cmp_gt_f32_e32 vcc, s96, v16
	v_mul_f32_e32 v17, 0x4b800000, v16
	v_mov_b32_e32 v32, v8
	v_cndmask_b32_e32 v16, v16, v17, vcc
	v_rsq_f32_e32 v16, v16
	v_mov_b32_e32 v33, v10
	v_mov_b32_e32 v28, v12
	v_mov_b32_e32 v29, v14
	v_mul_f32_e32 v17, 0x45800000, v16
	v_cndmask_b32_e32 v16, v16, v17, vcc
	v_mul_f32_e32 v24, v192, v16
	global_load_dwordx4 v[16:19], v[26:27], off offset:16
	global_load_dwordx4 v[34:37], v[26:27], off
	v_pk_mul_f32 v[32:33], v[32:33], v[24:25] op_sel_hi:[1,0]
	v_mov_b32_e32 v10, v9
	v_pk_mul_f32 v[28:29], v[28:29], v[24:25] op_sel_hi:[1,0]
	v_pk_mul_f32 v[32:33], v[172:173], v[32:33]
	v_mov_b32_e32 v14, v13
	v_pk_mul_f32 v[8:9], v[10:11], v[24:25] op_sel_hi:[1,0]
	v_pk_mul_f32 v[28:29], v[174:175], v[28:29]
	v_pk_mul_f32 v[12:13], v[14:15], v[24:25] op_sel_hi:[1,0]
	v_pk_mul_f32 v[8:9], v[54:55], v[8:9]
	v_pk_mul_f32 v[12:13], v[62:63], v[12:13]
	s_waitcnt vmcnt(1)
	v_mov_b32_e32 v11, v16
	s_waitcnt vmcnt(0)
; #define ST4(ptr, a, b, c_, d) (*(uint2*)(ptr) = make_uint2((unsigned)f2bf(a) | ((unsigned)f2bf(b) << 16), (unsigned)f2bf(c_) | ((unsigned)f2bf(d) << 16)))
; __device__ __forceinline__ void head_norm_rope_store(f32x4 (&v)[4], const float (&g)[16], const float* __restrict__ rp, float qscale, u16* __restrict__ dstp) {
;   float ss = 0.f;
; #pragma unroll
;   for (int n = 0; n < 4; ++n)
; #pragma unroll
;     for (int j = 0; j < 4; ++j) ss += v[n][j] * v[n][j];
;   { auto rr = __builtin_amdgcn_permlane16_swap(__float_as_uint(ss), __float_as_uint(ss), false, false); ss = __uint_as_float(rr[0]) + __uint_as_float(rr[1]); }
;   { auto rr = __builtin_amdgcn_permlane32_swap(__float_as_uint(ss), __float_as_uint(ss), false, false); ss = __uint_as_float(rr[0]) + __uint_as_float(rr[1]); }
;   const float rs = rsqrtf(ss * (1.f / 64.f) + EPS) * qscale;
; #pragma unroll
;   for (int h2 = 0; h2 < 2; ++h2) {
;     const float4 c01 = *(const float4*)(rp + h2 * 32), c23 = *(const float4*)(rp + h2 * 32 + 4);
;     const float cs_[4] = {c01.x, c01.z, c23.x, c23.z}, sn_[4] = {c01.y, c01.w, c23.y, c23.w};
;     float o1[4], o2[4];
; #pragma unroll
;     for (int j = 0; j < 4; ++j) {
;       const float x1 = v[h2][j] * rs * g[h2 * 4 + j], x2 = v[h2 + 2][j] * rs * g[(h2 + 2) * 4 + j];
;       o1[j] = x1 * cs_[j] - x2 * sn_[j]; o2[j] = x1 * sn_[j] + x2 * cs_[j];
;     }
;     ST4(dstp + h2 * 16, o1[0], o1[1], o1[2], o1[3]);
;     ST4(dstp + (h2 + 2) * 16, o2[0], o2[1], o2[2], o2[3]);
;   }
; __device__ __forceinline__ void inproj_phase(const Ctx& p, int layer, int hf) {
;     ...
;       for (int m = 0; m < 9; ++m) {
;         if (m < 8 || (fat && wr == 1)) {
;           const int row = m < 8 ? brow + wr * 128 + m * 16 + fr : brow + 256 + fr;
;           const int pos = hf == 0 ? row : row % L1;
;           f32x4 v[4];
; #pragma unroll
;           for (int n = 0; n < 4; ++n) v[n] = m < 8 ? acc[m < 8 ? m : 0][n] : accx[n];
;           head_norm_rope_store(v, g, rope + (size_t)pos * 64 + fq * 8, qscale, dst + (size_t)row * ldc + c0 + wc * 64 + fq * 4);
	v_mov_b32_e32 v16, v35
	v_mov_b32_e32 v10, v34
	v_pk_mul_f32 v[14:15], v[16:17], v[32:33]
	v_mov_b32_e32 v34, v36
	v_pk_fma_f32 v[14:15], v[10:11], v[28:29], v[14:15] neg_lo:[0,0,1] neg_hi:[0,0,1]
	v_mov_b32_e32 v35, v18
	v_mov_b32_e32 v18, v37
	v_pk_mul_f32 v[10:11], v[10:11], v[32:33]
	v_pk_mul_f32 v[36:37], v[18:19], v[8:9]
	v_pk_fma_f32 v[10:11], v[16:17], v[28:29], v[10:11]
	v_pk_mul_f32 v[8:9], v[34:35], v[8:9]
	v_pk_fma_f32 v[36:37], v[34:35], v[12:13], v[36:37] neg_lo:[0,0,1] neg_hi:[0,0,1]
	v_and_b32_sdwa v25, v15, v232 dst_sel:DWORD dst_unused:UNUSED_PAD src0_sel:WORD_1 src1_sel:DWORD
	v_and_b32_sdwa v38, v14, v232 dst_sel:DWORD dst_unused:UNUSED_PAD src0_sel:WORD_1 src1_sel:DWORD
	v_pk_fma_f32 v[8:9], v[18:19], v[12:13], v[8:9]
	v_and_b32_sdwa v12, v11, v232 dst_sel:DWORD dst_unused:UNUSED_PAD src0_sel:WORD_1 src1_sel:DWORD
	v_and_b32_sdwa v13, v10, v232 dst_sel:DWORD dst_unused:UNUSED_PAD src0_sel:WORD_1 src1_sel:DWORD
	v_add3_u32 v14, v14, v38, s43
	v_add3_u32 v15, v15, v25, s43
	v_and_b32_sdwa v25, v37, v232 dst_sel:DWORD dst_unused:UNUSED_PAD src0_sel:WORD_1 src1_sel:DWORD
	v_and_b32_sdwa v38, v36, v232 dst_sel:DWORD dst_unused:UNUSED_PAD src0_sel:WORD_1 src1_sel:DWORD
	v_add3_u32 v10, v10, v13, s43
	v_add3_u32 v11, v11, v12, s43
	v_and_b32_sdwa v12, v9, v232 dst_sel:DWORD dst_unused:UNUSED_PAD src0_sel:WORD_1 src1_sel:DWORD
	v_and_b32_sdwa v13, v8, v232 dst_sel:DWORD dst_unused:UNUSED_PAD src0_sel:WORD_1 src1_sel:DWORD
	v_add3_u32 v25, v37, v25, s43
	v_add3_u32 v36, v36, v38, s43
	v_add3_u32 v9, v9, v12, s43
	v_add3_u32 v8, v8, v13, s43
	v_and_b32_e32 v25, 0xffff0000, v25
	v_and_b32_e32 v36, 0xffff0000, v36
	v_and_b32_e32 v9, 0xffff0000, v9
	v_and_b32_e32 v8, 0xffff0000, v8
	v_or_b32_sdwa v15, v25, v15 dst_sel:DWORD dst_unused:UNUSED_PAD src0_sel:DWORD src1_sel:WORD_1
	v_or_b32_sdwa v14, v36, v14 dst_sel:DWORD dst_unused:UNUSED_PAD src0_sel:DWORD src1_sel:WORD_1
	v_or_b32_sdwa v9, v9, v11 dst_sel:DWORD dst_unused:UNUSED_PAD src0_sel:DWORD src1_sel:WORD_1
	v_or_b32_sdwa v8, v8, v10 dst_sel:DWORD dst_unused:UNUSED_PAD src0_sel:DWORD src1_sel:WORD_1
	s_nop 0
	v_mov_b32_e32 v208, v14
	v_mov_b32_e32 v209, v15
	s_nop 0
	v_mov_b32_e32 v212, v8
	v_mov_b32_e32 v213, v9
	global_load_dwordx4 v[8:11], v[26:27], off offset:144
	s_nop 0
	global_load_dwordx4 v[12:15], v[26:27], off offset:128
	v_mov_b32_e32 v18, v0
	v_mov_b32_e32 v19, v2
	v_mov_b32_e32 v16, v4
	v_mov_b32_e32 v17, v6
	v_pk_mul_f32 v[18:19], v[18:19], v[24:25] op_sel_hi:[1,0]
	v_mov_b32_e32 v2, v1
	v_pk_mul_f32 v[16:17], v[16:17], v[24:25] op_sel_hi:[1,0]
	v_pk_mul_f32 v[18:19], v[60:61], v[18:19]
	v_mov_b32_e32 v6, v5
	v_pk_mul_f32 v[0:1], v[2:3], v[24:25] op_sel_hi:[1,0]
	v_pk_mul_f32 v[16:17], v[52:53], v[16:17]
	v_pk_mul_f32 v[4:5], v[6:7], v[24:25] op_sel_hi:[1,0]
	v_pk_mul_f32 v[0:1], v[22:23], v[0:1]
	v_pk_mul_f32 v[4:5], v[30:31], v[4:5]
	s_waitcnt vmcnt(1)
	v_mov_b32_e32 v3, v8
	s_waitcnt vmcnt(0)
	v_mov_b32_e32 v8, v13
	v_mov_b32_e32 v2, v12
	v_pk_mul_f32 v[6:7], v[18:19], v[8:9]
	v_mov_b32_e32 v13, v10
	v_mov_b32_e32 v10, v15
	v_pk_fma_f32 v[6:7], v[2:3], v[16:17], v[6:7] neg_lo:[0,0,1] neg_hi:[0,0,1]
	v_mov_b32_e32 v12, v14
	v_pk_mul_f32 v[14:15], v[0:1], v[10:11]
	v_and_b32_sdwa v22, v7, v232 dst_sel:DWORD dst_unused:UNUSED_PAD src0_sel:WORD_1 src1_sel:DWORD
	v_pk_fma_f32 v[14:15], v[4:5], v[12:13], v[14:15] neg_lo:[0,0,1] neg_hi:[0,0,1]
	v_and_b32_sdwa v23, v6, v232 dst_sel:DWORD dst_unused:UNUSED_PAD src0_sel:WORD_1 src1_sel:DWORD
	v_add3_u32 v6, v6, v23, s43
	v_add3_u32 v7, v7, v22, s43
	v_and_b32_sdwa v22, v15, v232 dst_sel:DWORD dst_unused:UNUSED_PAD src0_sel:WORD_1 src1_sel:DWORD
	v_and_b32_sdwa v23, v14, v232 dst_sel:DWORD dst_unused:UNUSED_PAD src0_sel:WORD_1 src1_sel:DWORD
	v_add3_u32 v15, v15, v22, s43
	v_add3_u32 v14, v14, v23, s43
	v_and_b32_e32 v15, 0xffff0000, v15
	v_and_b32_e32 v14, 0xffff0000, v14
	v_or_b32_sdwa v7, v15, v7 dst_sel:DWORD dst_unused:UNUSED_PAD src0_sel:DWORD src1_sel:WORD_1
	v_or_b32_sdwa v6, v14, v6 dst_sel:DWORD dst_unused:UNUSED_PAD src0_sel:DWORD src1_sel:WORD_1
	s_nop 0
	v_mov_b32_e32 v210, v6
	v_mov_b32_e32 v211, v7
	v_mbcnt_lo_u32_b32 v220, -1, 0
	v_mbcnt_hi_u32_b32 v220, -1, v220
	v_and_b32_e32 v218, 16, v220
	v_lshrrev_b32_e32 v220, 1, v218
	v_add_u32_e32 v218, v218, v220
	v_mov_b32_e32 v219, 0
	v_lshl_add_u64 v[216:217], v[20:21], 0, v[218:219]
	v_permlane16_swap_b32_e32 v208, v210
	v_permlane16_swap_b32_e32 v209, v211
	global_store_dwordx4 v[216:217], v[208:211], off
	v_pk_mul_f32 v[6:7], v[16:17], v[8:9]
	v_pk_mul_f32 v[4:5], v[4:5], v[10:11]
	v_pk_fma_f32 v[2:3], v[18:19], v[2:3], v[6:7]
	v_pk_fma_f32 v[0:1], v[0:1], v[12:13], v[4:5]
	v_and_b32_sdwa v4, v3, v232 dst_sel:DWORD dst_unused:UNUSED_PAD src0_sel:WORD_1 src1_sel:DWORD
	v_and_b32_sdwa v5, v2, v232 dst_sel:DWORD dst_unused:UNUSED_PAD src0_sel:WORD_1 src1_sel:DWORD
	v_add3_u32 v2, v2, v5, s43
	v_add3_u32 v3, v3, v4, s43
	v_and_b32_sdwa v4, v1, v232 dst_sel:DWORD dst_unused:UNUSED_PAD src0_sel:WORD_1 src1_sel:DWORD
	v_and_b32_sdwa v5, v0, v232 dst_sel:DWORD dst_unused:UNUSED_PAD src0_sel:WORD_1 src1_sel:DWORD
	v_add3_u32 v1, v1, v4, s43
	v_add3_u32 v0, v0, v5, s43
	v_and_b32_e32 v1, 0xffff0000, v1
	v_and_b32_e32 v0, 0xffff0000, v0
	v_or_b32_sdwa v1, v1, v3 dst_sel:DWORD dst_unused:UNUSED_PAD src0_sel:DWORD src1_sel:WORD_1
	v_or_b32_sdwa v0, v0, v2 dst_sel:DWORD dst_unused:UNUSED_PAD src0_sel:DWORD src1_sel:WORD_1
	s_nop 0
	v_mov_b32_e32 v214, v0
	v_mov_b32_e32 v215, v1
	s_nop 1
	v_permlane16_swap_b32_e32 v212, v214
	v_permlane16_swap_b32_e32 v213, v215
	global_store_dwordx4 v[216:217], v[212:215], off offset:64

; #define ST4(ptr, a, b, c_, d) (*(uint2*)(ptr) = make_uint2((unsigned)f2bf(a) | ((unsigned)f2bf(b) << 16), (unsigned)f2bf(c_) | ((unsigned)f2bf(d) << 16)))
; __device__ __forceinline__ void inproj_phase(const Ctx& p, int layer, int hf) {
;     ...
;     if (pn < 6) { dst = (u16*)(p.ws + A_DA); ldc = 1536; c0 = bcol; }
;     else if (pn < 9) { dst = (u16*)(p.ws + A_MLAC); ldc = 768; c0 = bcol - 1536; }
;     else { dst = (u16*)(p.ws + A_GQA); ldc = 768; c0 = bcol - 2304; }
;     const int kind = pn < 2 ? 1 : pn < 4 ? 2 : (pn == 9 || pn == 10) ? 3 : (pn == 11 && wc < 2) ? 4 : 0;
;     if (kind == 0) {
;       ACC_LOOP( ST4(dst + (size_t)row * ldc + c0 + col, v4[0], v4[1], v4[2], v4[3]); )
.LBB0_259:
	s_ashr_i32 s73, s72, 31
	s_lshl_b64 s[8:9], s[72:73], 1
	v_and_b32_sdwa v23, v158, v232 dst_sel:DWORD dst_unused:UNUSED_PAD src0_sel:WORD_1 src1_sel:DWORD
	v_add_u32_e32 v28, s68, v241
	s_add_u32 s8, s74, s8
	v_add3_u32 v29, v158, v23, s43
	v_and_b32_sdwa v23, v161, v232 dst_sel:DWORD dst_unused:UNUSED_PAD src0_sel:WORD_1 src1_sel:DWORD
	v_and_b32_sdwa v30, v159, v232 dst_sel:DWORD dst_unused:UNUSED_PAD src0_sel:WORD_1 src1_sel:DWORD
	s_addc_u32 s9, s75, s9
	v_mad_i64_i32 v[20:21], s[20:21], s76, v28, 0
	v_and_b32_sdwa v22, v160, v232 dst_sel:DWORD dst_unused:UNUSED_PAD src0_sel:WORD_1 src1_sel:DWORD
	v_add3_u32 v23, v161, v23, s43
	v_add3_u32 v30, v159, v30, s43
	v_lshl_add_u64 v[20:21], v[20:21], 1, s[8:9]
	v_lshlrev_b32_e32 v128, 1, v226
	v_add3_u32 v22, v160, v22, s43
	v_and_b32_e32 v23, 0xffff0000, v23
	v_and_b32_e32 v30, 0xffff0000, v30
	v_lshl_add_u64 v[20:21], v[20:21], 0, v[128:129]
	v_or_b32_sdwa v23, v23, v22 dst_sel:DWORD dst_unused:UNUSED_PAD src0_sel:DWORD src1_sel:WORD_1
	v_or_b32_sdwa v22, v30, v29 dst_sel:DWORD dst_unused:UNUSED_PAD src0_sel:DWORD src1_sel:WORD_1
	s_nop 0
	v_mov_b32_e32 v208, v22
	v_mov_b32_e32 v209, v23
	v_and_b32_sdwa v23, v150, v232 dst_sel:DWORD dst_unused:UNUSED_PAD src0_sel:WORD_1 src1_sel:DWORD
	v_add3_u32 v29, v150, v23, s43
	v_and_b32_sdwa v23, v153, v232 dst_sel:DWORD dst_unused:UNUSED_PAD src0_sel:WORD_1 src1_sel:DWORD
	v_and_b32_sdwa v30, v151, v232 dst_sel:DWORD dst_unused:UNUSED_PAD src0_sel:WORD_1 src1_sel:DWORD
	v_and_b32_sdwa v22, v152, v232 dst_sel:DWORD dst_unused:UNUSED_PAD src0_sel:WORD_1 src1_sel:DWORD
	v_add3_u32 v23, v153, v23, s43
	v_add3_u32 v30, v151, v30, s43
	v_add3_u32 v22, v152, v22, s43
	v_and_b32_e32 v23, 0xffff0000, v23
	v_and_b32_e32 v30, 0xffff0000, v30
	v_or_b32_sdwa v23, v23, v22 dst_sel:DWORD dst_unused:UNUSED_PAD src0_sel:DWORD src1_sel:WORD_1
	v_or_b32_sdwa v22, v30, v29 dst_sel:DWORD dst_unused:UNUSED_PAD src0_sel:DWORD src1_sel:WORD_1
	s_nop 0
	v_mov_b32_e32 v210, v22
	v_mov_b32_e32 v211, v23
	v_mbcnt_lo_u32_b32 v220, -1, 0
	v_mbcnt_hi_u32_b32 v220, -1, v220
	v_and_b32_e32 v218, 16, v220
	v_lshrrev_b32_e32 v220, 1, v218
	v_add_u32_e32 v218, v218, v220
	v_mov_b32_e32 v219, 0
	v_lshl_add_u64 v[216:217], v[20:21], 0, v[218:219]
	v_permlane16_swap_b32_e32 v208, v210
	v_permlane16_swap_b32_e32 v209, v211
	global_store_dwordx4 v[216:217], v[208:211], off
	v_and_b32_sdwa v23, v154, v232 dst_sel:DWORD dst_unused:UNUSED_PAD src0_sel:WORD_1 src1_sel:DWORD
	v_add3_u32 v29, v154, v23, s43
	v_and_b32_sdwa v23, v157, v232 dst_sel:DWORD dst_unused:UNUSED_PAD src0_sel:WORD_1 src1_sel:DWORD
	v_and_b32_sdwa v30, v155, v232 dst_sel:DWORD dst_unused:UNUSED_PAD src0_sel:WORD_1 src1_sel:DWORD
	v_and_b32_sdwa v22, v156, v232 dst_sel:DWORD dst_unused:UNUSED_PAD src0_sel:WORD_1 src1_sel:DWORD
	v_add3_u32 v23, v157, v23, s43
	v_add3_u32 v30, v155, v30, s43
	v_add3_u32 v22, v156, v22, s43
	v_and_b32_e32 v23, 0xffff0000, v23
	v_and_b32_e32 v30, 0xffff0000, v30
	v_or_b32_sdwa v23, v23, v22 dst_sel:DWORD dst_unused:UNUSED_PAD src0_sel:DWORD src1_sel:WORD_1
	v_or_b32_sdwa v22, v30, v29 dst_sel:DWORD dst_unused:UNUSED_PAD src0_sel:DWORD src1_sel:WORD_1
	s_nop 0
	v_mov_b32_e32 v212, v22
	v_mov_b32_e32 v213, v23
	v_and_b32_sdwa v23, v146, v232 dst_sel:DWORD dst_unused:UNUSED_PAD src0_sel:WORD_1 src1_sel:DWORD
	v_add3_u32 v29, v146, v23, s43
	v_and_b32_sdwa v23, v149, v232 dst_sel:DWORD dst_unused:UNUSED_PAD src0_sel:WORD_1 src1_sel:DWORD
	v_and_b32_sdwa v30, v147, v232 dst_sel:DWORD dst_unused:UNUSED_PAD src0_sel:WORD_1 src1_sel:DWORD
	v_and_b32_sdwa v22, v148, v232 dst_sel:DWORD dst_unused:UNUSED_PAD src0_sel:WORD_1 src1_sel:DWORD
	v_add3_u32 v23, v149, v23, s43
	v_add3_u32 v30, v147, v30, s43
	v_add3_u32 v22, v148, v22, s43
	v_and_b32_e32 v23, 0xffff0000, v23
	v_and_b32_e32 v30, 0xffff0000, v30
	v_or_b32_sdwa v23, v23, v22 dst_sel:DWORD dst_unused:UNUSED_PAD src0_sel:DWORD src1_sel:WORD_1
	v_or_b32_sdwa v22, v30, v29 dst_sel:DWORD dst_unused:UNUSED_PAD src0_sel:DWORD src1_sel:WORD_1
	s_nop 0
	v_mov_b32_e32 v214, v22
	v_mov_b32_e32 v215, v23
	s_nop 1
	v_permlane16_swap_b32_e32 v212, v214
	v_permlane16_swap_b32_e32 v213, v215
	global_store_dwordx4 v[216:217], v[212:215], off offset:64
	v_and_b32_sdwa v23, v142, v232 dst_sel:DWORD dst_unused:UNUSED_PAD src0_sel:WORD_1 src1_sel:DWORD
	v_add_u32_e32 v20, 16, v28
	v_add3_u32 v29, v142, v23, s43
	v_and_b32_sdwa v23, v145, v232 dst_sel:DWORD dst_unused:UNUSED_PAD src0_sel:WORD_1 src1_sel:DWORD
	v_and_b32_sdwa v30, v143, v232 dst_sel:DWORD dst_unused:UNUSED_PAD src0_sel:WORD_1 src1_sel:DWORD
	v_mad_i64_i32 v[20:21], s[20:21], s76, v20, 0
	v_and_b32_sdwa v22, v144, v232 dst_sel:DWORD dst_unused:UNUSED_PAD src0_sel:WORD_1 src1_sel:DWORD
	v_add3_u32 v23, v145, v23, s43
	v_add3_u32 v30, v143, v30, s43
	v_lshl_add_u64 v[20:21], v[20:21], 1, s[8:9]
	v_add3_u32 v22, v144, v22, s43
	v_and_b32_e32 v23, 0xffff0000, v23
	v_and_b32_e32 v30, 0xffff0000, v30
	v_lshl_add_u64 v[20:21], v[20:21], 0, v[128:129]
	v_or_b32_sdwa v23, v23, v22 dst_sel:DWORD dst_unused:UNUSED_PAD src0_sel:DWORD src1_sel:WORD_1
	v_or_b32_sdwa v22, v30, v29 dst_sel:DWORD dst_unused:UNUSED_PAD src0_sel:DWORD src1_sel:WORD_1
	s_nop 0
	v_mov_b32_e32 v208, v22
	v_mov_b32_e32 v209, v23
	v_and_b32_sdwa v23, v134, v232 dst_sel:DWORD dst_unused:UNUSED_PAD src0_sel:WORD_1 src1_sel:DWORD
	v_add3_u32 v29, v134, v23, s43
	v_and_b32_sdwa v23, v137, v232 dst_sel:DWORD dst_unused:UNUSED_PAD src0_sel:WORD_1 src1_sel:DWORD
	v_and_b32_sdwa v30, v135, v232 dst_sel:DWORD dst_unused:UNUSED_PAD src0_sel:WORD_1 src1_sel:DWORD
	v_and_b32_sdwa v22, v136, v232 dst_sel:DWORD dst_unused:UNUSED_PAD src0_sel:WORD_1 src1_sel:DWORD
; #define ST4(ptr, a, b, c_, d) (*(uint2*)(ptr) = make_uint2((unsigned)f2bf(a) | ((unsigned)f2bf(b) << 16), (unsigned)f2bf(c_) | ((unsigned)f2bf(d) << 16)))
; __device__ __forceinline__ void inproj_phase(const Ctx& p, int layer, int hf) {
;     ...
;     if (pn < 6) { dst = (u16*)(p.ws + A_DA); ldc = 1536; c0 = bcol; }
;     else if (pn < 9) { dst = (u16*)(p.ws + A_MLAC); ldc = 768; c0 = bcol - 1536; }
;     else { dst = (u16*)(p.ws + A_GQA); ldc = 768; c0 = bcol - 2304; }
;     const int kind = pn < 2 ? 1 : pn < 4 ? 2 : (pn == 9 || pn == 10) ? 3 : (pn == 11 && wc < 2) ? 4 : 0;
;     if (kind == 0) {
;       ACC_LOOP( ST4(dst + (size_t)row * ldc + c0 + col, v4[0], v4[1], v4[2], v4[3]); )
	v_add3_u32 v23, v137, v23, s43
	v_add3_u32 v30, v135, v30, s43
	v_add3_u32 v22, v136, v22, s43
	v_and_b32_e32 v23, 0xffff0000, v23
	v_and_b32_e32 v30, 0xffff0000, v30
	v_or_b32_sdwa v23, v23, v22 dst_sel:DWORD dst_unused:UNUSED_PAD src0_sel:DWORD src1_sel:WORD_1
	v_or_b32_sdwa v22, v30, v29 dst_sel:DWORD dst_unused:UNUSED_PAD src0_sel:DWORD src1_sel:WORD_1
	s_nop 0
	v_mov_b32_e32 v210, v22
	v_mov_b32_e32 v211, v23
	v_mbcnt_lo_u32_b32 v220, -1, 0
	v_mbcnt_hi_u32_b32 v220, -1, v220
	v_and_b32_e32 v218, 16, v220
	v_lshrrev_b32_e32 v220, 1, v218
	v_add_u32_e32 v218, v218, v220
	v_mov_b32_e32 v219, 0
	v_lshl_add_u64 v[216:217], v[20:21], 0, v[218:219]
	v_permlane16_swap_b32_e32 v208, v210
	v_permlane16_swap_b32_e32 v209, v211
	global_store_dwordx4 v[216:217], v[208:211], off
	v_and_b32_sdwa v23, v138, v232 dst_sel:DWORD dst_unused:UNUSED_PAD src0_sel:WORD_1 src1_sel:DWORD
	v_add3_u32 v29, v138, v23, s43
	v_and_b32_sdwa v23, v141, v232 dst_sel:DWORD dst_unused:UNUSED_PAD src0_sel:WORD_1 src1_sel:DWORD
	v_and_b32_sdwa v30, v139, v232 dst_sel:DWORD dst_unused:UNUSED_PAD src0_sel:WORD_1 src1_sel:DWORD
	v_and_b32_sdwa v22, v140, v232 dst_sel:DWORD dst_unused:UNUSED_PAD src0_sel:WORD_1 src1_sel:DWORD
	v_add3_u32 v23, v141, v23, s43
	v_add3_u32 v30, v139, v30, s43
	v_add3_u32 v22, v140, v22, s43
	v_and_b32_e32 v23, 0xffff0000, v23
	v_and_b32_e32 v30, 0xffff0000, v30
	v_or_b32_sdwa v23, v23, v22 dst_sel:DWORD dst_unused:UNUSED_PAD src0_sel:DWORD src1_sel:WORD_1
	v_or_b32_sdwa v22, v30, v29 dst_sel:DWORD dst_unused:UNUSED_PAD src0_sel:DWORD src1_sel:WORD_1
	s_nop 0
	v_mov_b32_e32 v212, v22
	v_mov_b32_e32 v213, v23
	v_and_b32_sdwa v23, v130, v232 dst_sel:DWORD dst_unused:UNUSED_PAD src0_sel:WORD_1 src1_sel:DWORD
	v_add3_u32 v29, v130, v23, s43
	v_and_b32_sdwa v23, v133, v232 dst_sel:DWORD dst_unused:UNUSED_PAD src0_sel:WORD_1 src1_sel:DWORD
	v_and_b32_sdwa v30, v131, v232 dst_sel:DWORD dst_unused:UNUSED_PAD src0_sel:WORD_1 src1_sel:DWORD
	v_and_b32_sdwa v22, v132, v232 dst_sel:DWORD dst_unused:UNUSED_PAD src0_sel:WORD_1 src1_sel:DWORD
	v_add3_u32 v23, v133, v23, s43
	v_add3_u32 v30, v131, v30, s43
	v_add3_u32 v22, v132, v22, s43
	v_and_b32_e32 v23, 0xffff0000, v23
	v_and_b32_e32 v30, 0xffff0000, v30
	v_or_b32_sdwa v23, v23, v22 dst_sel:DWORD dst_unused:UNUSED_PAD src0_sel:DWORD src1_sel:WORD_1
	v_or_b32_sdwa v22, v30, v29 dst_sel:DWORD dst_unused:UNUSED_PAD src0_sel:DWORD src1_sel:WORD_1
	s_nop 0
	v_mov_b32_e32 v214, v22
	v_mov_b32_e32 v215, v23
	s_nop 1
	v_permlane16_swap_b32_e32 v212, v214
	v_permlane16_swap_b32_e32 v213, v215
	global_store_dwordx4 v[216:217], v[212:215], off offset:64
	v_and_b32_sdwa v23, v124, v232 dst_sel:DWORD dst_unused:UNUSED_PAD src0_sel:WORD_1 src1_sel:DWORD
	v_add_u32_e32 v20, 32, v28
	v_add3_u32 v29, v124, v23, s43
	v_and_b32_sdwa v23, v127, v232 dst_sel:DWORD dst_unused:UNUSED_PAD src0_sel:WORD_1 src1_sel:DWORD
	v_and_b32_sdwa v30, v125, v232 dst_sel:DWORD dst_unused:UNUSED_PAD src0_sel:WORD_1 src1_sel:DWORD
	v_mad_i64_i32 v[20:21], s[20:21], s76, v20, 0
	v_and_b32_sdwa v22, v126, v232 dst_sel:DWORD dst_unused:UNUSED_PAD src0_sel:WORD_1 src1_sel:DWORD
	v_add3_u32 v23, v127, v23, s43
	v_add3_u32 v30, v125, v30, s43
	v_lshl_add_u64 v[20:21], v[20:21], 1, s[8:9]
	v_add3_u32 v22, v126, v22, s43
	v_and_b32_e32 v23, 0xffff0000, v23
	v_and_b32_e32 v30, 0xffff0000, v30
	v_lshl_add_u64 v[20:21], v[20:21], 0, v[128:129]
	v_or_b32_sdwa v23, v23, v22 dst_sel:DWORD dst_unused:UNUSED_PAD src0_sel:DWORD src1_sel:WORD_1
	v_or_b32_sdwa v22, v30, v29 dst_sel:DWORD dst_unused:UNUSED_PAD src0_sel:DWORD src1_sel:WORD_1
	s_nop 0
	v_mov_b32_e32 v208, v22
	v_mov_b32_e32 v209, v23
	v_and_b32_sdwa v23, v116, v232 dst_sel:DWORD dst_unused:UNUSED_PAD src0_sel:WORD_1 src1_sel:DWORD
	v_add3_u32 v29, v116, v23, s43
	v_and_b32_sdwa v23, v119, v232 dst_sel:DWORD dst_unused:UNUSED_PAD src0_sel:WORD_1 src1_sel:DWORD
	v_and_b32_sdwa v30, v117, v232 dst_sel:DWORD dst_unused:UNUSED_PAD src0_sel:WORD_1 src1_sel:DWORD
	v_and_b32_sdwa v22, v118, v232 dst_sel:DWORD dst_unused:UNUSED_PAD src0_sel:WORD_1 src1_sel:DWORD
	v_add3_u32 v23, v119, v23, s43
	v_add3_u32 v30, v117, v30, s43
	v_add3_u32 v22, v118, v22, s43
	v_and_b32_e32 v23, 0xffff0000, v23
	v_and_b32_e32 v30, 0xffff0000, v30
	v_or_b32_sdwa v23, v23, v22 dst_sel:DWORD dst_unused:UNUSED_PAD src0_sel:DWORD src1_sel:WORD_1
	v_or_b32_sdwa v22, v30, v29 dst_sel:DWORD dst_unused:UNUSED_PAD src0_sel:DWORD src1_sel:WORD_1
	s_nop 0
	v_mov_b32_e32 v210, v22
	v_mov_b32_e32 v211, v23
	v_mbcnt_lo_u32_b32 v220, -1, 0
	v_mbcnt_hi_u32_b32 v220, -1, v220
	v_and_b32_e32 v218, 16, v220
	v_lshrrev_b32_e32 v220, 1, v218
	v_add_u32_e32 v218, v218, v220
	v_mov_b32_e32 v219, 0
	v_lshl_add_u64 v[216:217], v[20:21], 0, v[218:219]
	v_permlane16_swap_b32_e32 v208, v210
	v_permlane16_swap_b32_e32 v209, v211
	global_store_dwordx4 v[216:217], v[208:211], off
	v_and_b32_sdwa v23, v120, v232 dst_sel:DWORD dst_unused:UNUSED_PAD src0_sel:WORD_1 src1_sel:DWORD
	v_add3_u32 v29, v120, v23, s43
	v_and_b32_sdwa v23, v123, v232 dst_sel:DWORD dst_unused:UNUSED_PAD src0_sel:WORD_1 src1_sel:DWORD
	v_and_b32_sdwa v30, v121, v232 dst_sel:DWORD dst_unused:UNUSED_PAD src0_sel:WORD_1 src1_sel:DWORD
	v_and_b32_sdwa v22, v122, v232 dst_sel:DWORD dst_unused:UNUSED_PAD src0_sel:WORD_1 src1_sel:DWORD
	v_add3_u32 v23, v123, v23, s43
	v_add3_u32 v30, v121, v30, s43
	v_add3_u32 v22, v122, v22, s43
	v_and_b32_e32 v23, 0xffff0000, v23
	v_and_b32_e32 v30, 0xffff0000, v30
	v_or_b32_sdwa v23, v23, v22 dst_sel:DWORD dst_unused:UNUSED_PAD src0_sel:DWORD src1_sel:WORD_1
	v_or_b32_sdwa v22, v30, v29 dst_sel:DWORD dst_unused:UNUSED_PAD src0_sel:DWORD src1_sel:WORD_1
; #define ST4(ptr, a, b, c_, d) (*(uint2*)(ptr) = make_uint2((unsigned)f2bf(a) | ((unsigned)f2bf(b) << 16), (unsigned)f2bf(c_) | ((unsigned)f2bf(d) << 16)))
; __device__ __forceinline__ void inproj_phase(const Ctx& p, int layer, int hf) {
;     ...
;     if (pn < 6) { dst = (u16*)(p.ws + A_DA); ldc = 1536; c0 = bcol; }
;     else if (pn < 9) { dst = (u16*)(p.ws + A_MLAC); ldc = 768; c0 = bcol - 1536; }
;     else { dst = (u16*)(p.ws + A_GQA); ldc = 768; c0 = bcol - 2304; }
;     const int kind = pn < 2 ? 1 : pn < 4 ? 2 : (pn == 9 || pn == 10) ? 3 : (pn == 11 && wc < 2) ? 4 : 0;
;     if (kind == 0) {
;       ACC_LOOP( ST4(dst + (size_t)row * ldc + c0 + col, v4[0], v4[1], v4[2], v4[3]); )
	s_nop 0
	v_mov_b32_e32 v212, v22
	v_mov_b32_e32 v213, v23
	v_and_b32_sdwa v23, v112, v232 dst_sel:DWORD dst_unused:UNUSED_PAD src0_sel:WORD_1 src1_sel:DWORD
	v_add3_u32 v29, v112, v23, s43
	v_and_b32_sdwa v23, v115, v232 dst_sel:DWORD dst_unused:UNUSED_PAD src0_sel:WORD_1 src1_sel:DWORD
	v_and_b32_sdwa v30, v113, v232 dst_sel:DWORD dst_unused:UNUSED_PAD src0_sel:WORD_1 src1_sel:DWORD
	v_and_b32_sdwa v22, v114, v232 dst_sel:DWORD dst_unused:UNUSED_PAD src0_sel:WORD_1 src1_sel:DWORD
	v_add3_u32 v23, v115, v23, s43
	v_add3_u32 v30, v113, v30, s43
	v_add3_u32 v22, v114, v22, s43
	v_and_b32_e32 v23, 0xffff0000, v23
	v_and_b32_e32 v30, 0xffff0000, v30
	v_or_b32_sdwa v23, v23, v22 dst_sel:DWORD dst_unused:UNUSED_PAD src0_sel:DWORD src1_sel:WORD_1
	v_or_b32_sdwa v22, v30, v29 dst_sel:DWORD dst_unused:UNUSED_PAD src0_sel:DWORD src1_sel:WORD_1
	s_nop 0
	v_mov_b32_e32 v214, v22
	v_mov_b32_e32 v215, v23
	s_nop 1
	v_permlane16_swap_b32_e32 v212, v214
	v_permlane16_swap_b32_e32 v213, v215
	global_store_dwordx4 v[216:217], v[212:215], off offset:64
	v_and_b32_sdwa v23, v108, v232 dst_sel:DWORD dst_unused:UNUSED_PAD src0_sel:WORD_1 src1_sel:DWORD
	v_add_u32_e32 v20, 48, v28
	v_add3_u32 v29, v108, v23, s43
	v_and_b32_sdwa v23, v111, v232 dst_sel:DWORD dst_unused:UNUSED_PAD src0_sel:WORD_1 src1_sel:DWORD
	v_and_b32_sdwa v30, v109, v232 dst_sel:DWORD dst_unused:UNUSED_PAD src0_sel:WORD_1 src1_sel:DWORD
	v_mad_i64_i32 v[20:21], s[20:21], s76, v20, 0
	v_and_b32_sdwa v22, v110, v232 dst_sel:DWORD dst_unused:UNUSED_PAD src0_sel:WORD_1 src1_sel:DWORD
	v_add3_u32 v23, v111, v23, s43
	v_add3_u32 v30, v109, v30, s43
	v_lshl_add_u64 v[20:21], v[20:21], 1, s[8:9]
	v_add3_u32 v22, v110, v22, s43
	v_and_b32_e32 v23, 0xffff0000, v23
	v_and_b32_e32 v30, 0xffff0000, v30
	v_lshl_add_u64 v[20:21], v[20:21], 0, v[128:129]
	v_or_b32_sdwa v23, v23, v22 dst_sel:DWORD dst_unused:UNUSED_PAD src0_sel:DWORD src1_sel:WORD_1
	v_or_b32_sdwa v22, v30, v29 dst_sel:DWORD dst_unused:UNUSED_PAD src0_sel:DWORD src1_sel:WORD_1
	s_nop 0
	v_mov_b32_e32 v208, v22
	v_mov_b32_e32 v209, v23
	v_and_b32_sdwa v23, v100, v232 dst_sel:DWORD dst_unused:UNUSED_PAD src0_sel:WORD_1 src1_sel:DWORD
	v_add3_u32 v29, v100, v23, s43
	v_and_b32_sdwa v23, v103, v232 dst_sel:DWORD dst_unused:UNUSED_PAD src0_sel:WORD_1 src1_sel:DWORD
	v_and_b32_sdwa v30, v101, v232 dst_sel:DWORD dst_unused:UNUSED_PAD src0_sel:WORD_1 src1_sel:DWORD
	v_and_b32_sdwa v22, v102, v232 dst_sel:DWORD dst_unused:UNUSED_PAD src0_sel:WORD_1 src1_sel:DWORD
	v_add3_u32 v23, v103, v23, s43
	v_add3_u32 v30, v101, v30, s43
	v_add3_u32 v22, v102, v22, s43
	v_and_b32_e32 v23, 0xffff0000, v23
	v_and_b32_e32 v30, 0xffff0000, v30
	v_or_b32_sdwa v23, v23, v22 dst_sel:DWORD dst_unused:UNUSED_PAD src0_sel:DWORD src1_sel:WORD_1
	v_or_b32_sdwa v22, v30, v29 dst_sel:DWORD dst_unused:UNUSED_PAD src0_sel:DWORD src1_sel:WORD_1
	s_nop 0
	v_mov_b32_e32 v210, v22
	v_mov_b32_e32 v211, v23
	v_mbcnt_lo_u32_b32 v220, -1, 0
	v_mbcnt_hi_u32_b32 v220, -1, v220
	v_and_b32_e32 v218, 16, v220
	v_lshrrev_b32_e32 v220, 1, v218
	v_add_u32_e32 v218, v218, v220
	v_mov_b32_e32 v219, 0
	v_lshl_add_u64 v[216:217], v[20:21], 0, v[218:219]
	v_permlane16_swap_b32_e32 v208, v210
	v_permlane16_swap_b32_e32 v209, v211
	global_store_dwordx4 v[216:217], v[208:211], off
	v_and_b32_sdwa v23, v104, v232 dst_sel:DWORD dst_unused:UNUSED_PAD src0_sel:WORD_1 src1_sel:DWORD
	v_add3_u32 v29, v104, v23, s43
	v_and_b32_sdwa v23, v107, v232 dst_sel:DWORD dst_unused:UNUSED_PAD src0_sel:WORD_1 src1_sel:DWORD
	v_and_b32_sdwa v30, v105, v232 dst_sel:DWORD dst_unused:UNUSED_PAD src0_sel:WORD_1 src1_sel:DWORD
	v_and_b32_sdwa v22, v106, v232 dst_sel:DWORD dst_unused:UNUSED_PAD src0_sel:WORD_1 src1_sel:DWORD
	v_add3_u32 v23, v107, v23, s43
	v_add3_u32 v30, v105, v30, s43
	v_add3_u32 v22, v106, v22, s43
	v_and_b32_e32 v23, 0xffff0000, v23
	v_and_b32_e32 v30, 0xffff0000, v30
	v_or_b32_sdwa v23, v23, v22 dst_sel:DWORD dst_unused:UNUSED_PAD src0_sel:DWORD src1_sel:WORD_1
	v_or_b32_sdwa v22, v30, v29 dst_sel:DWORD dst_unused:UNUSED_PAD src0_sel:DWORD src1_sel:WORD_1
	s_nop 0
	v_mov_b32_e32 v212, v22
	v_mov_b32_e32 v213, v23
	v_and_b32_sdwa v23, v96, v232 dst_sel:DWORD dst_unused:UNUSED_PAD src0_sel:WORD_1 src1_sel:DWORD
	v_add3_u32 v29, v96, v23, s43
	v_and_b32_sdwa v23, v99, v232 dst_sel:DWORD dst_unused:UNUSED_PAD src0_sel:WORD_1 src1_sel:DWORD
	v_and_b32_sdwa v30, v97, v232 dst_sel:DWORD dst_unused:UNUSED_PAD src0_sel:WORD_1 src1_sel:DWORD
	v_and_b32_sdwa v22, v98, v232 dst_sel:DWORD dst_unused:UNUSED_PAD src0_sel:WORD_1 src1_sel:DWORD
	v_add3_u32 v23, v99, v23, s43
	v_add3_u32 v30, v97, v30, s43
	v_add3_u32 v22, v98, v22, s43
	v_and_b32_e32 v23, 0xffff0000, v23
	v_and_b32_e32 v30, 0xffff0000, v30
	v_or_b32_sdwa v23, v23, v22 dst_sel:DWORD dst_unused:UNUSED_PAD src0_sel:DWORD src1_sel:WORD_1
	v_or_b32_sdwa v22, v30, v29 dst_sel:DWORD dst_unused:UNUSED_PAD src0_sel:DWORD src1_sel:WORD_1
	s_nop 0
	v_mov_b32_e32 v214, v22
	v_mov_b32_e32 v215, v23
	s_nop 1
	v_permlane16_swap_b32_e32 v212, v214
	v_permlane16_swap_b32_e32 v213, v215
	global_store_dwordx4 v[216:217], v[212:215], off offset:64
	v_and_b32_sdwa v23, v92, v232 dst_sel:DWORD dst_unused:UNUSED_PAD src0_sel:WORD_1 src1_sel:DWORD
	v_add_u32_e32 v20, 64, v28
	v_add3_u32 v29, v92, v23, s43
	v_and_b32_sdwa v23, v95, v232 dst_sel:DWORD dst_unused:UNUSED_PAD src0_sel:WORD_1 src1_sel:DWORD
	v_and_b32_sdwa v30, v93, v232 dst_sel:DWORD dst_unused:UNUSED_PAD src0_sel:WORD_1 src1_sel:DWORD
	v_mad_i64_i32 v[20:21], s[20:21], s76, v20, 0
	v_and_b32_sdwa v22, v94, v232 dst_sel:DWORD dst_unused:UNUSED_PAD src0_sel:WORD_1 src1_sel:DWORD
	v_add3_u32 v23, v95, v23, s43
; #define ST4(ptr, a, b, c_, d) (*(uint2*)(ptr) = make_uint2((unsigned)f2bf(a) | ((unsigned)f2bf(b) << 16), (unsigned)f2bf(c_) | ((unsigned)f2bf(d) << 16)))
; __device__ __forceinline__ void inproj_phase(const Ctx& p, int layer, int hf) {
;     ...
;     if (pn < 6) { dst = (u16*)(p.ws + A_DA); ldc = 1536; c0 = bcol; }
;     else if (pn < 9) { dst = (u16*)(p.ws + A_MLAC); ldc = 768; c0 = bcol - 1536; }
;     else { dst = (u16*)(p.ws + A_GQA); ldc = 768; c0 = bcol - 2304; }
;     const int kind = pn < 2 ? 1 : pn < 4 ? 2 : (pn == 9 || pn == 10) ? 3 : (pn == 11 && wc < 2) ? 4 : 0;
;     if (kind == 0) {
;       ACC_LOOP( ST4(dst + (size_t)row * ldc + c0 + col, v4[0], v4[1], v4[2], v4[3]); )
	v_add3_u32 v30, v93, v30, s43
	v_lshl_add_u64 v[20:21], v[20:21], 1, s[8:9]
	v_add3_u32 v22, v94, v22, s43
	v_and_b32_e32 v23, 0xffff0000, v23
	v_and_b32_e32 v30, 0xffff0000, v30
	v_lshl_add_u64 v[20:21], v[20:21], 0, v[128:129]
	v_or_b32_sdwa v23, v23, v22 dst_sel:DWORD dst_unused:UNUSED_PAD src0_sel:DWORD src1_sel:WORD_1
	v_or_b32_sdwa v22, v30, v29 dst_sel:DWORD dst_unused:UNUSED_PAD src0_sel:DWORD src1_sel:WORD_1
	s_nop 0
	v_mov_b32_e32 v208, v22
	v_mov_b32_e32 v209, v23
	v_and_b32_sdwa v23, v84, v232 dst_sel:DWORD dst_unused:UNUSED_PAD src0_sel:WORD_1 src1_sel:DWORD
	v_add3_u32 v29, v84, v23, s43
	v_and_b32_sdwa v23, v87, v232 dst_sel:DWORD dst_unused:UNUSED_PAD src0_sel:WORD_1 src1_sel:DWORD
	v_and_b32_sdwa v30, v85, v232 dst_sel:DWORD dst_unused:UNUSED_PAD src0_sel:WORD_1 src1_sel:DWORD
	v_and_b32_sdwa v22, v86, v232 dst_sel:DWORD dst_unused:UNUSED_PAD src0_sel:WORD_1 src1_sel:DWORD
	v_add3_u32 v23, v87, v23, s43
	v_add3_u32 v30, v85, v30, s43
	v_add3_u32 v22, v86, v22, s43
	v_and_b32_e32 v23, 0xffff0000, v23
	v_and_b32_e32 v30, 0xffff0000, v30
	v_or_b32_sdwa v23, v23, v22 dst_sel:DWORD dst_unused:UNUSED_PAD src0_sel:DWORD src1_sel:WORD_1
	v_or_b32_sdwa v22, v30, v29 dst_sel:DWORD dst_unused:UNUSED_PAD src0_sel:DWORD src1_sel:WORD_1
	s_nop 0
	v_mov_b32_e32 v210, v22
	v_mov_b32_e32 v211, v23
	v_mbcnt_lo_u32_b32 v220, -1, 0
	v_mbcnt_hi_u32_b32 v220, -1, v220
	v_and_b32_e32 v218, 16, v220
	v_lshrrev_b32_e32 v220, 1, v218
	v_add_u32_e32 v218, v218, v220
	v_mov_b32_e32 v219, 0
	v_lshl_add_u64 v[216:217], v[20:21], 0, v[218:219]
	v_permlane16_swap_b32_e32 v208, v210
	v_permlane16_swap_b32_e32 v209, v211
	global_store_dwordx4 v[216:217], v[208:211], off
	v_and_b32_sdwa v23, v88, v232 dst_sel:DWORD dst_unused:UNUSED_PAD src0_sel:WORD_1 src1_sel:DWORD
	v_add3_u32 v29, v88, v23, s43
	v_and_b32_sdwa v23, v91, v232 dst_sel:DWORD dst_unused:UNUSED_PAD src0_sel:WORD_1 src1_sel:DWORD
	v_and_b32_sdwa v30, v89, v232 dst_sel:DWORD dst_unused:UNUSED_PAD src0_sel:WORD_1 src1_sel:DWORD
	v_and_b32_sdwa v22, v90, v232 dst_sel:DWORD dst_unused:UNUSED_PAD src0_sel:WORD_1 src1_sel:DWORD
	v_add3_u32 v23, v91, v23, s43
	v_add3_u32 v30, v89, v30, s43
	v_add3_u32 v22, v90, v22, s43
	v_and_b32_e32 v23, 0xffff0000, v23
	v_and_b32_e32 v30, 0xffff0000, v30
	v_or_b32_sdwa v23, v23, v22 dst_sel:DWORD dst_unused:UNUSED_PAD src0_sel:DWORD src1_sel:WORD_1
	v_or_b32_sdwa v22, v30, v29 dst_sel:DWORD dst_unused:UNUSED_PAD src0_sel:DWORD src1_sel:WORD_1
	s_nop 0
	v_mov_b32_e32 v212, v22
	v_mov_b32_e32 v213, v23
	v_and_b32_sdwa v23, v80, v232 dst_sel:DWORD dst_unused:UNUSED_PAD src0_sel:WORD_1 src1_sel:DWORD
	v_add3_u32 v29, v80, v23, s43
	v_and_b32_sdwa v23, v83, v232 dst_sel:DWORD dst_unused:UNUSED_PAD src0_sel:WORD_1 src1_sel:DWORD
	v_and_b32_sdwa v30, v81, v232 dst_sel:DWORD dst_unused:UNUSED_PAD src0_sel:WORD_1 src1_sel:DWORD
	v_and_b32_sdwa v22, v82, v232 dst_sel:DWORD dst_unused:UNUSED_PAD src0_sel:WORD_1 src1_sel:DWORD
	v_add3_u32 v23, v83, v23, s43
	v_add3_u32 v30, v81, v30, s43
	v_add3_u32 v22, v82, v22, s43
	v_and_b32_e32 v23, 0xffff0000, v23
	v_and_b32_e32 v30, 0xffff0000, v30
	v_or_b32_sdwa v23, v23, v22 dst_sel:DWORD dst_unused:UNUSED_PAD src0_sel:DWORD src1_sel:WORD_1
	v_or_b32_sdwa v22, v30, v29 dst_sel:DWORD dst_unused:UNUSED_PAD src0_sel:DWORD src1_sel:WORD_1
	s_nop 0
	v_mov_b32_e32 v214, v22
	v_mov_b32_e32 v215, v23
	s_nop 1
	v_permlane16_swap_b32_e32 v212, v214
	v_permlane16_swap_b32_e32 v213, v215
	global_store_dwordx4 v[216:217], v[212:215], off offset:64
	v_and_b32_sdwa v23, v76, v232 dst_sel:DWORD dst_unused:UNUSED_PAD src0_sel:WORD_1 src1_sel:DWORD
	v_add_u32_e32 v20, 0x50, v28
	v_add3_u32 v29, v76, v23, s43
	v_and_b32_sdwa v23, v79, v232 dst_sel:DWORD dst_unused:UNUSED_PAD src0_sel:WORD_1 src1_sel:DWORD
	v_and_b32_sdwa v30, v77, v232 dst_sel:DWORD dst_unused:UNUSED_PAD src0_sel:WORD_1 src1_sel:DWORD
	v_mad_i64_i32 v[20:21], s[20:21], s76, v20, 0
	v_and_b32_sdwa v22, v78, v232 dst_sel:DWORD dst_unused:UNUSED_PAD src0_sel:WORD_1 src1_sel:DWORD
	v_add3_u32 v23, v79, v23, s43
	v_add3_u32 v30, v77, v30, s43
	v_lshl_add_u64 v[20:21], v[20:21], 1, s[8:9]
	v_add3_u32 v22, v78, v22, s43
	v_and_b32_e32 v23, 0xffff0000, v23
	v_and_b32_e32 v30, 0xffff0000, v30
	v_lshl_add_u64 v[20:21], v[20:21], 0, v[128:129]
	v_or_b32_sdwa v23, v23, v22 dst_sel:DWORD dst_unused:UNUSED_PAD src0_sel:DWORD src1_sel:WORD_1
	v_or_b32_sdwa v22, v30, v29 dst_sel:DWORD dst_unused:UNUSED_PAD src0_sel:DWORD src1_sel:WORD_1
	s_nop 0
	v_mov_b32_e32 v208, v22
	v_mov_b32_e32 v209, v23
	v_and_b32_sdwa v23, v68, v232 dst_sel:DWORD dst_unused:UNUSED_PAD src0_sel:WORD_1 src1_sel:DWORD
	v_add3_u32 v29, v68, v23, s43
	v_and_b32_sdwa v23, v71, v232 dst_sel:DWORD dst_unused:UNUSED_PAD src0_sel:WORD_1 src1_sel:DWORD
	v_and_b32_sdwa v30, v69, v232 dst_sel:DWORD dst_unused:UNUSED_PAD src0_sel:WORD_1 src1_sel:DWORD
	v_and_b32_sdwa v22, v70, v232 dst_sel:DWORD dst_unused:UNUSED_PAD src0_sel:WORD_1 src1_sel:DWORD
	v_add3_u32 v23, v71, v23, s43
	v_add3_u32 v30, v69, v30, s43
	v_add3_u32 v22, v70, v22, s43
	v_and_b32_e32 v23, 0xffff0000, v23
	v_and_b32_e32 v30, 0xffff0000, v30
	v_or_b32_sdwa v23, v23, v22 dst_sel:DWORD dst_unused:UNUSED_PAD src0_sel:DWORD src1_sel:WORD_1
	v_or_b32_sdwa v22, v30, v29 dst_sel:DWORD dst_unused:UNUSED_PAD src0_sel:DWORD src1_sel:WORD_1
	s_nop 0
	v_mov_b32_e32 v210, v22
	v_mov_b32_e32 v211, v23
	v_mbcnt_lo_u32_b32 v220, -1, 0
	v_mbcnt_hi_u32_b32 v220, -1, v220
	v_and_b32_e32 v218, 16, v220
	v_lshrrev_b32_e32 v220, 1, v218
	v_add_u32_e32 v218, v218, v220
	v_mov_b32_e32 v219, 0
	v_lshl_add_u64 v[216:217], v[20:21], 0, v[218:219]
	v_permlane16_swap_b32_e32 v208, v210
; #define ST4(ptr, a, b, c_, d) (*(uint2*)(ptr) = make_uint2((unsigned)f2bf(a) | ((unsigned)f2bf(b) << 16), (unsigned)f2bf(c_) | ((unsigned)f2bf(d) << 16)))
; __device__ __forceinline__ void inproj_phase(const Ctx& p, int layer, int hf) {
;     ...
;     if (pn < 6) { dst = (u16*)(p.ws + A_DA); ldc = 1536; c0 = bcol; }
;     else if (pn < 9) { dst = (u16*)(p.ws + A_MLAC); ldc = 768; c0 = bcol - 1536; }
;     else { dst = (u16*)(p.ws + A_GQA); ldc = 768; c0 = bcol - 2304; }
;     const int kind = pn < 2 ? 1 : pn < 4 ? 2 : (pn == 9 || pn == 10) ? 3 : (pn == 11 && wc < 2) ? 4 : 0;
;     if (kind == 0) {
;       ACC_LOOP( ST4(dst + (size_t)row * ldc + c0 + col, v4[0], v4[1], v4[2], v4[3]); )
	v_permlane16_swap_b32_e32 v209, v211
	global_store_dwordx4 v[216:217], v[208:211], off
	v_and_b32_sdwa v23, v72, v232 dst_sel:DWORD dst_unused:UNUSED_PAD src0_sel:WORD_1 src1_sel:DWORD
	v_add3_u32 v29, v72, v23, s43
	v_and_b32_sdwa v23, v75, v232 dst_sel:DWORD dst_unused:UNUSED_PAD src0_sel:WORD_1 src1_sel:DWORD
	v_and_b32_sdwa v30, v73, v232 dst_sel:DWORD dst_unused:UNUSED_PAD src0_sel:WORD_1 src1_sel:DWORD
	v_and_b32_sdwa v22, v74, v232 dst_sel:DWORD dst_unused:UNUSED_PAD src0_sel:WORD_1 src1_sel:DWORD
	v_add3_u32 v23, v75, v23, s43
	v_add3_u32 v30, v73, v30, s43
	v_add3_u32 v22, v74, v22, s43
	v_and_b32_e32 v23, 0xffff0000, v23
	v_and_b32_e32 v30, 0xffff0000, v30
	v_or_b32_sdwa v23, v23, v22 dst_sel:DWORD dst_unused:UNUSED_PAD src0_sel:DWORD src1_sel:WORD_1
	v_or_b32_sdwa v22, v30, v29 dst_sel:DWORD dst_unused:UNUSED_PAD src0_sel:DWORD src1_sel:WORD_1
	s_nop 0
	v_mov_b32_e32 v212, v22
	v_mov_b32_e32 v213, v23
	v_and_b32_sdwa v23, v64, v232 dst_sel:DWORD dst_unused:UNUSED_PAD src0_sel:WORD_1 src1_sel:DWORD
	v_add3_u32 v29, v64, v23, s43
	v_and_b32_sdwa v23, v67, v232 dst_sel:DWORD dst_unused:UNUSED_PAD src0_sel:WORD_1 src1_sel:DWORD
	v_and_b32_sdwa v30, v65, v232 dst_sel:DWORD dst_unused:UNUSED_PAD src0_sel:WORD_1 src1_sel:DWORD
	v_and_b32_sdwa v22, v66, v232 dst_sel:DWORD dst_unused:UNUSED_PAD src0_sel:WORD_1 src1_sel:DWORD
	v_add3_u32 v23, v67, v23, s43
	v_add3_u32 v30, v65, v30, s43
	v_add3_u32 v22, v66, v22, s43
	v_and_b32_e32 v23, 0xffff0000, v23
	v_and_b32_e32 v30, 0xffff0000, v30
	v_or_b32_sdwa v23, v23, v22 dst_sel:DWORD dst_unused:UNUSED_PAD src0_sel:DWORD src1_sel:WORD_1
	v_or_b32_sdwa v22, v30, v29 dst_sel:DWORD dst_unused:UNUSED_PAD src0_sel:DWORD src1_sel:WORD_1
	s_nop 0
	v_mov_b32_e32 v214, v22
	v_mov_b32_e32 v215, v23
	s_nop 1
	v_permlane16_swap_b32_e32 v212, v214
	v_permlane16_swap_b32_e32 v213, v215
	global_store_dwordx4 v[216:217], v[212:215], off offset:64
	v_and_b32_sdwa v23, v56, v232 dst_sel:DWORD dst_unused:UNUSED_PAD src0_sel:WORD_1 src1_sel:DWORD
	v_add_u32_e32 v20, 0x60, v28
	v_add3_u32 v29, v56, v23, s43
	v_and_b32_sdwa v23, v59, v232 dst_sel:DWORD dst_unused:UNUSED_PAD src0_sel:WORD_1 src1_sel:DWORD
	v_and_b32_sdwa v30, v57, v232 dst_sel:DWORD dst_unused:UNUSED_PAD src0_sel:WORD_1 src1_sel:DWORD
	v_mad_i64_i32 v[20:21], s[20:21], s76, v20, 0
	v_and_b32_sdwa v22, v58, v232 dst_sel:DWORD dst_unused:UNUSED_PAD src0_sel:WORD_1 src1_sel:DWORD
	v_add3_u32 v23, v59, v23, s43
	v_add3_u32 v30, v57, v30, s43
	v_lshl_add_u64 v[20:21], v[20:21], 1, s[8:9]
	v_add3_u32 v22, v58, v22, s43
	v_and_b32_e32 v23, 0xffff0000, v23
	v_and_b32_e32 v30, 0xffff0000, v30
	v_lshl_add_u64 v[20:21], v[20:21], 0, v[128:129]
	v_or_b32_sdwa v23, v23, v22 dst_sel:DWORD dst_unused:UNUSED_PAD src0_sel:DWORD src1_sel:WORD_1
	v_or_b32_sdwa v22, v30, v29 dst_sel:DWORD dst_unused:UNUSED_PAD src0_sel:DWORD src1_sel:WORD_1
	s_nop 0
	v_mov_b32_e32 v208, v22
	v_mov_b32_e32 v209, v23
	v_and_b32_sdwa v23, v44, v232 dst_sel:DWORD dst_unused:UNUSED_PAD src0_sel:WORD_1 src1_sel:DWORD
	v_add3_u32 v29, v44, v23, s43
	v_and_b32_sdwa v23, v47, v232 dst_sel:DWORD dst_unused:UNUSED_PAD src0_sel:WORD_1 src1_sel:DWORD
	v_and_b32_sdwa v30, v45, v232 dst_sel:DWORD dst_unused:UNUSED_PAD src0_sel:WORD_1 src1_sel:DWORD
	v_and_b32_sdwa v22, v46, v232 dst_sel:DWORD dst_unused:UNUSED_PAD src0_sel:WORD_1 src1_sel:DWORD
	v_add3_u32 v23, v47, v23, s43
	v_add3_u32 v30, v45, v30, s43
	v_add3_u32 v22, v46, v22, s43
	v_and_b32_e32 v23, 0xffff0000, v23
	v_and_b32_e32 v30, 0xffff0000, v30
	v_or_b32_sdwa v23, v23, v22 dst_sel:DWORD dst_unused:UNUSED_PAD src0_sel:DWORD src1_sel:WORD_1
	v_or_b32_sdwa v22, v30, v29 dst_sel:DWORD dst_unused:UNUSED_PAD src0_sel:DWORD src1_sel:WORD_1
	s_nop 0
	v_mov_b32_e32 v210, v22
	v_mov_b32_e32 v211, v23
	v_mbcnt_lo_u32_b32 v220, -1, 0
	v_mbcnt_hi_u32_b32 v220, -1, v220
	v_and_b32_e32 v218, 16, v220
	v_lshrrev_b32_e32 v220, 1, v218
	v_add_u32_e32 v218, v218, v220
	v_mov_b32_e32 v219, 0
	v_lshl_add_u64 v[216:217], v[20:21], 0, v[218:219]
	v_permlane16_swap_b32_e32 v208, v210
	v_permlane16_swap_b32_e32 v209, v211
	global_store_dwordx4 v[216:217], v[208:211], off
	v_and_b32_sdwa v23, v48, v232 dst_sel:DWORD dst_unused:UNUSED_PAD src0_sel:WORD_1 src1_sel:DWORD
	v_add3_u32 v29, v48, v23, s43
	v_and_b32_sdwa v23, v51, v232 dst_sel:DWORD dst_unused:UNUSED_PAD src0_sel:WORD_1 src1_sel:DWORD
	v_and_b32_sdwa v30, v49, v232 dst_sel:DWORD dst_unused:UNUSED_PAD src0_sel:WORD_1 src1_sel:DWORD
	v_and_b32_sdwa v22, v50, v232 dst_sel:DWORD dst_unused:UNUSED_PAD src0_sel:WORD_1 src1_sel:DWORD
	v_add3_u32 v23, v51, v23, s43
	v_add3_u32 v30, v49, v30, s43
	v_add3_u32 v22, v50, v22, s43
	v_and_b32_e32 v23, 0xffff0000, v23
	v_and_b32_e32 v30, 0xffff0000, v30
	v_or_b32_sdwa v23, v23, v22 dst_sel:DWORD dst_unused:UNUSED_PAD src0_sel:DWORD src1_sel:WORD_1
	v_or_b32_sdwa v22, v30, v29 dst_sel:DWORD dst_unused:UNUSED_PAD src0_sel:DWORD src1_sel:WORD_1
	s_nop 0
	v_mov_b32_e32 v212, v22
	v_mov_b32_e32 v213, v23
	v_and_b32_sdwa v23, v40, v232 dst_sel:DWORD dst_unused:UNUSED_PAD src0_sel:WORD_1 src1_sel:DWORD
	v_add3_u32 v29, v40, v23, s43
	v_and_b32_sdwa v23, v43, v232 dst_sel:DWORD dst_unused:UNUSED_PAD src0_sel:WORD_1 src1_sel:DWORD
	v_and_b32_sdwa v30, v41, v232 dst_sel:DWORD dst_unused:UNUSED_PAD src0_sel:WORD_1 src1_sel:DWORD
	v_and_b32_sdwa v22, v42, v232 dst_sel:DWORD dst_unused:UNUSED_PAD src0_sel:WORD_1 src1_sel:DWORD
	v_add3_u32 v23, v43, v23, s43
	v_add3_u32 v30, v41, v30, s43
	v_add3_u32 v22, v42, v22, s43
	v_and_b32_e32 v23, 0xffff0000, v23
	v_and_b32_e32 v30, 0xffff0000, v30
	v_or_b32_sdwa v23, v23, v22 dst_sel:DWORD dst_unused:UNUSED_PAD src0_sel:DWORD src1_sel:WORD_1
; #define ST4(ptr, a, b, c_, d) (*(uint2*)(ptr) = make_uint2((unsigned)f2bf(a) | ((unsigned)f2bf(b) << 16), (unsigned)f2bf(c_) | ((unsigned)f2bf(d) << 16)))
; __device__ __forceinline__ void inproj_phase(const Ctx& p, int layer, int hf) {
;     ...
;     if (pn < 6) { dst = (u16*)(p.ws + A_DA); ldc = 1536; c0 = bcol; }
;     else if (pn < 9) { dst = (u16*)(p.ws + A_MLAC); ldc = 768; c0 = bcol - 1536; }
;     else { dst = (u16*)(p.ws + A_GQA); ldc = 768; c0 = bcol - 2304; }
;     const int kind = pn < 2 ? 1 : pn < 4 ? 2 : (pn == 9 || pn == 10) ? 3 : (pn == 11 && wc < 2) ? 4 : 0;
;     if (kind == 0) {
;       ACC_LOOP( ST4(dst + (size_t)row * ldc + c0 + col, v4[0], v4[1], v4[2], v4[3]); )
	v_or_b32_sdwa v22, v30, v29 dst_sel:DWORD dst_unused:UNUSED_PAD src0_sel:DWORD src1_sel:WORD_1
	s_nop 0
	v_mov_b32_e32 v214, v22
	v_mov_b32_e32 v215, v23
	s_nop 1
	v_permlane16_swap_b32_e32 v212, v214
	v_permlane16_swap_b32_e32 v213, v215
	global_store_dwordx4 v[216:217], v[212:215], off offset:64
	v_and_b32_sdwa v23, v36, v232 dst_sel:DWORD dst_unused:UNUSED_PAD src0_sel:WORD_1 src1_sel:DWORD
	v_add_u32_e32 v20, 0x70, v28
	v_add3_u32 v28, v36, v23, s43
	v_and_b32_sdwa v23, v39, v232 dst_sel:DWORD dst_unused:UNUSED_PAD src0_sel:WORD_1 src1_sel:DWORD
	v_and_b32_sdwa v29, v37, v232 dst_sel:DWORD dst_unused:UNUSED_PAD src0_sel:WORD_1 src1_sel:DWORD
	v_mad_i64_i32 v[20:21], s[20:21], s76, v20, 0
	v_and_b32_sdwa v22, v38, v232 dst_sel:DWORD dst_unused:UNUSED_PAD src0_sel:WORD_1 src1_sel:DWORD
	v_add3_u32 v23, v39, v23, s43
	v_add3_u32 v29, v37, v29, s43
	v_lshl_add_u64 v[20:21], v[20:21], 1, s[8:9]
	v_add3_u32 v22, v38, v22, s43
	v_and_b32_e32 v23, 0xffff0000, v23
	v_and_b32_e32 v29, 0xffff0000, v29
	v_lshl_add_u64 v[20:21], v[20:21], 0, v[128:129]
	v_or_b32_sdwa v23, v23, v22 dst_sel:DWORD dst_unused:UNUSED_PAD src0_sel:DWORD src1_sel:WORD_1
	v_or_b32_sdwa v22, v29, v28 dst_sel:DWORD dst_unused:UNUSED_PAD src0_sel:DWORD src1_sel:WORD_1
	s_nop 0
	v_mov_b32_e32 v208, v22
	v_mov_b32_e32 v209, v23
	v_and_b32_sdwa v22, v26, v232 dst_sel:DWORD dst_unused:UNUSED_PAD src0_sel:WORD_1 src1_sel:DWORD
	v_and_b32_sdwa v23, v24, v232 dst_sel:DWORD dst_unused:UNUSED_PAD src0_sel:WORD_1 src1_sel:DWORD
	v_add3_u32 v24, v24, v23, s43
	v_add3_u32 v22, v26, v22, s43
	v_and_b32_sdwa v23, v27, v232 dst_sel:DWORD dst_unused:UNUSED_PAD src0_sel:WORD_1 src1_sel:DWORD
	v_and_b32_sdwa v26, v25, v232 dst_sel:DWORD dst_unused:UNUSED_PAD src0_sel:WORD_1 src1_sel:DWORD
	v_add3_u32 v23, v27, v23, s43
	v_add3_u32 v25, v25, v26, s43
	v_and_b32_e32 v23, 0xffff0000, v23
	v_and_b32_e32 v25, 0xffff0000, v25
	v_or_b32_sdwa v23, v23, v22 dst_sel:DWORD dst_unused:UNUSED_PAD src0_sel:DWORD src1_sel:WORD_1
	v_or_b32_sdwa v22, v25, v24 dst_sel:DWORD dst_unused:UNUSED_PAD src0_sel:DWORD src1_sel:WORD_1
	s_nop 0
	v_mov_b32_e32 v210, v22
	v_mov_b32_e32 v211, v23
	v_mbcnt_lo_u32_b32 v220, -1, 0
	v_mbcnt_hi_u32_b32 v220, -1, v220
	v_and_b32_e32 v218, 16, v220
	v_lshrrev_b32_e32 v220, 1, v218
	v_add_u32_e32 v218, v218, v220
	v_mov_b32_e32 v219, 0
	v_lshl_add_u64 v[216:217], v[20:21], 0, v[218:219]
	v_permlane16_swap_b32_e32 v208, v210
	v_permlane16_swap_b32_e32 v209, v211
	global_store_dwordx4 v[216:217], v[208:211], off
	v_and_b32_sdwa v23, v32, v232 dst_sel:DWORD dst_unused:UNUSED_PAD src0_sel:WORD_1 src1_sel:DWORD
	v_add3_u32 v24, v32, v23, s43
	v_and_b32_sdwa v23, v35, v232 dst_sel:DWORD dst_unused:UNUSED_PAD src0_sel:WORD_1 src1_sel:DWORD
	v_and_b32_sdwa v25, v33, v232 dst_sel:DWORD dst_unused:UNUSED_PAD src0_sel:WORD_1 src1_sel:DWORD
	v_and_b32_sdwa v22, v34, v232 dst_sel:DWORD dst_unused:UNUSED_PAD src0_sel:WORD_1 src1_sel:DWORD
	v_add3_u32 v23, v35, v23, s43
	v_add3_u32 v25, v33, v25, s43
	v_add3_u32 v22, v34, v22, s43
	v_and_b32_e32 v23, 0xffff0000, v23
	v_and_b32_e32 v25, 0xffff0000, v25
	v_or_b32_sdwa v23, v23, v22 dst_sel:DWORD dst_unused:UNUSED_PAD src0_sel:DWORD src1_sel:WORD_1
	v_or_b32_sdwa v22, v25, v24 dst_sel:DWORD dst_unused:UNUSED_PAD src0_sel:DWORD src1_sel:WORD_1
	s_nop 0
	v_mov_b32_e32 v212, v22
	v_mov_b32_e32 v213, v23
	v_and_b32_sdwa v22, v18, v232 dst_sel:DWORD dst_unused:UNUSED_PAD src0_sel:WORD_1 src1_sel:DWORD
	v_and_b32_sdwa v23, v16, v232 dst_sel:DWORD dst_unused:UNUSED_PAD src0_sel:WORD_1 src1_sel:DWORD
	v_add3_u32 v16, v16, v23, s43
	v_add3_u32 v18, v18, v22, s43
	v_and_b32_sdwa v22, v19, v232 dst_sel:DWORD dst_unused:UNUSED_PAD src0_sel:WORD_1 src1_sel:DWORD
	v_and_b32_sdwa v23, v17, v232 dst_sel:DWORD dst_unused:UNUSED_PAD src0_sel:WORD_1 src1_sel:DWORD
	v_add3_u32 v19, v19, v22, s43
	v_add3_u32 v17, v17, v23, s43
	v_and_b32_e32 v19, 0xffff0000, v19
	v_and_b32_e32 v22, 0xffff0000, v17
	v_or_b32_sdwa v17, v19, v18 dst_sel:DWORD dst_unused:UNUSED_PAD src0_sel:DWORD src1_sel:WORD_1
	v_or_b32_sdwa v16, v22, v16 dst_sel:DWORD dst_unused:UNUSED_PAD src0_sel:DWORD src1_sel:WORD_1
	s_nop 0
	v_mov_b32_e32 v214, v16
	v_mov_b32_e32 v215, v17
	s_nop 1
	v_permlane16_swap_b32_e32 v212, v214
	v_permlane16_swap_b32_e32 v213, v215
	global_store_dwordx4 v[216:217], v[212:215], off offset:64
	s_and_b64 s[20:21], s[4:5], s[70:71]
	s_and_saveexec_b64 s[8:9], s[20:21]
	s_cbranch_execz .LBB0_230
; #define ST4(ptr, a, b, c_, d) (*(uint2*)(ptr) = make_uint2((unsigned)f2bf(a) | ((unsigned)f2bf(b) << 16), (unsigned)f2bf(c_) | ((unsigned)f2bf(d) << 16)))
; __device__ __forceinline__ void inproj_phase(const Ctx& p, int layer, int hf) {
;     ...
;     if (pn < 6) { dst = (u16*)(p.ws + A_DA); ldc = 1536; c0 = bcol; }
;     else if (pn < 9) { dst = (u16*)(p.ws + A_MLAC); ldc = 768; c0 = bcol - 1536; }
;     else { dst = (u16*)(p.ws + A_GQA); ldc = 768; c0 = bcol - 2304; }
;     const int kind = pn < 2 ? 1 : pn < 4 ? 2 : (pn == 9 || pn == 10) ? 3 : (pn == 11 && wc < 2) ? 4 : 0;
;     if (kind == 0) {
;       ACC_LOOP( ST4(dst + (size_t)row * ldc + c0 + col, v4[0], v4[1], v4[2], v4[3]); )
	v_add_u32_e32 v16, s68, v239
	v_and_b32_sdwa v18, v14, v232 dst_sel:DWORD dst_unused:UNUSED_PAD src0_sel:WORD_1 src1_sel:DWORD
	v_and_b32_sdwa v19, v12, v232 dst_sel:DWORD dst_unused:UNUSED_PAD src0_sel:WORD_1 src1_sel:DWORD
	v_mad_i64_i32 v[16:17], s[20:21], s76, v16, 0
	v_add3_u32 v12, v12, v19, s43
	v_add3_u32 v14, v14, v18, s43
	v_and_b32_sdwa v18, v15, v232 dst_sel:DWORD dst_unused:UNUSED_PAD src0_sel:WORD_1 src1_sel:DWORD
	v_and_b32_sdwa v19, v13, v232 dst_sel:DWORD dst_unused:UNUSED_PAD src0_sel:WORD_1 src1_sel:DWORD
	v_lshl_add_u64 v[16:17], v[16:17], 1, s[74:75]
	v_add3_u32 v15, v15, v18, s43
	v_add3_u32 v13, v13, v19, s43
	v_lshl_add_u64 v[16:17], s[72:73], 1, v[16:17]
	v_and_b32_e32 v15, 0xffff0000, v15
	v_and_b32_e32 v18, 0xffff0000, v13
	v_lshl_add_u64 v[16:17], v[16:17], 0, v[128:129]
	v_or_b32_sdwa v13, v15, v14 dst_sel:DWORD dst_unused:UNUSED_PAD src0_sel:DWORD src1_sel:WORD_1
	v_or_b32_sdwa v12, v18, v12 dst_sel:DWORD dst_unused:UNUSED_PAD src0_sel:DWORD src1_sel:WORD_1
	s_nop 0
	v_mov_b32_e32 v208, v12
	v_mov_b32_e32 v209, v13
	v_and_b32_sdwa v12, v6, v232 dst_sel:DWORD dst_unused:UNUSED_PAD src0_sel:WORD_1 src1_sel:DWORD
	v_and_b32_sdwa v13, v4, v232 dst_sel:DWORD dst_unused:UNUSED_PAD src0_sel:WORD_1 src1_sel:DWORD
	v_add3_u32 v4, v4, v13, s43
	v_add3_u32 v6, v6, v12, s43
	v_and_b32_sdwa v12, v7, v232 dst_sel:DWORD dst_unused:UNUSED_PAD src0_sel:WORD_1 src1_sel:DWORD
	v_and_b32_sdwa v13, v5, v232 dst_sel:DWORD dst_unused:UNUSED_PAD src0_sel:WORD_1 src1_sel:DWORD
	v_add3_u32 v7, v7, v12, s43
	v_add3_u32 v5, v5, v13, s43
	v_and_b32_e32 v7, 0xffff0000, v7
	v_and_b32_e32 v12, 0xffff0000, v5
	v_or_b32_sdwa v5, v7, v6 dst_sel:DWORD dst_unused:UNUSED_PAD src0_sel:DWORD src1_sel:WORD_1
	v_or_b32_sdwa v4, v12, v4 dst_sel:DWORD dst_unused:UNUSED_PAD src0_sel:DWORD src1_sel:WORD_1
	s_nop 0
	v_mov_b32_e32 v210, v4
	v_mov_b32_e32 v211, v5
	v_mbcnt_lo_u32_b32 v220, -1, 0
	v_mbcnt_hi_u32_b32 v220, -1, v220
	v_and_b32_e32 v218, 16, v220
	v_lshrrev_b32_e32 v220, 1, v218
	v_add_u32_e32 v218, v218, v220
	v_mov_b32_e32 v219, 0
	v_lshl_add_u64 v[216:217], v[16:17], 0, v[218:219]
	v_permlane16_swap_b32_e32 v208, v210
	v_permlane16_swap_b32_e32 v209, v211
	global_store_dwordx4 v[216:217], v[208:211], off
	v_and_b32_sdwa v5, v8, v232 dst_sel:DWORD dst_unused:UNUSED_PAD src0_sel:WORD_1 src1_sel:DWORD
	v_add3_u32 v6, v8, v5, s43
	v_and_b32_sdwa v5, v11, v232 dst_sel:DWORD dst_unused:UNUSED_PAD src0_sel:WORD_1 src1_sel:DWORD
	v_and_b32_sdwa v7, v9, v232 dst_sel:DWORD dst_unused:UNUSED_PAD src0_sel:WORD_1 src1_sel:DWORD
	v_and_b32_sdwa v4, v10, v232 dst_sel:DWORD dst_unused:UNUSED_PAD src0_sel:WORD_1 src1_sel:DWORD
	v_add3_u32 v5, v11, v5, s43
	v_add3_u32 v7, v9, v7, s43
	v_add3_u32 v4, v10, v4, s43
	v_and_b32_e32 v5, 0xffff0000, v5
	v_and_b32_e32 v7, 0xffff0000, v7
	v_or_b32_sdwa v5, v5, v4 dst_sel:DWORD dst_unused:UNUSED_PAD src0_sel:DWORD src1_sel:WORD_1
	v_or_b32_sdwa v4, v7, v6 dst_sel:DWORD dst_unused:UNUSED_PAD src0_sel:DWORD src1_sel:WORD_1
	s_nop 0
	v_mov_b32_e32 v212, v4
	v_mov_b32_e32 v213, v5
	v_and_b32_sdwa v4, v2, v232 dst_sel:DWORD dst_unused:UNUSED_PAD src0_sel:WORD_1 src1_sel:DWORD
	v_and_b32_sdwa v5, v0, v232 dst_sel:DWORD dst_unused:UNUSED_PAD src0_sel:WORD_1 src1_sel:DWORD
	v_add3_u32 v0, v0, v5, s43
	v_add3_u32 v2, v2, v4, s43
	v_and_b32_sdwa v4, v3, v232 dst_sel:DWORD dst_unused:UNUSED_PAD src0_sel:WORD_1 src1_sel:DWORD
	v_and_b32_sdwa v5, v1, v232 dst_sel:DWORD dst_unused:UNUSED_PAD src0_sel:WORD_1 src1_sel:DWORD
	v_add3_u32 v3, v3, v4, s43
	v_add3_u32 v1, v1, v5, s43
	v_and_b32_e32 v3, 0xffff0000, v3
	v_and_b32_e32 v4, 0xffff0000, v1
	v_or_b32_sdwa v1, v3, v2 dst_sel:DWORD dst_unused:UNUSED_PAD src0_sel:DWORD src1_sel:WORD_1
	v_or_b32_sdwa v0, v4, v0 dst_sel:DWORD dst_unused:UNUSED_PAD src0_sel:DWORD src1_sel:WORD_1
	s_nop 0
	v_mov_b32_e32 v214, v0
	v_mov_b32_e32 v215, v1
	s_nop 1
	v_permlane16_swap_b32_e32 v212, v214
	v_permlane16_swap_b32_e32 v213, v215
	global_store_dwordx4 v[216:217], v[212:215], off offset:64
	s_branch .LBB0_230

; #define ST4(ptr, a, b, c_, d) (*(uint2*)(ptr) = make_uint2((unsigned)f2bf(a) | ((unsigned)f2bf(b) << 16), (unsigned)f2bf(c_) | ((unsigned)f2bf(d) << 16)))
; __device__ __forceinline__ void upproj_phase(const Ctx& p, int hf) {
;     ...
;     u16* dst; int ldc, c0;
;     if (pn < 3) { dst = (u16*)(p.ws + A_QM); ldc = 768; c0 = pn * 256; }
;     else if (wc < 2) { dst = (u16*)(p.ws + A_KM); ldc = 768; c0 = h * 192; }
;     else { dst = (u16*)(p.ws + A_VM); ldc = 512; c0 = h * 128 - 128; }
;     ACC_LOOP( ST4(dst + (size_t)row * ldc + c0 + col, v4[0], v4[1], v4[2], v4[3]); )
.LBB0_297:
	v_add_u32_e32 v156, s73, v182
	v_ashrrev_i32_e32 v128, 31, v156
	v_mul_lo_u32 v128, v148, v128
	v_mul_lo_u32 v157, v149, v156
	v_mad_u64_u32 v[154:155], s[16:17], v148, v156, 0
	v_add3_u32 v155, v155, v128, v157
	v_and_b32_sdwa v157, v144, v232 dst_sel:DWORD dst_unused:UNUSED_PAD src0_sel:WORD_1 src1_sel:DWORD
	v_and_b32_sdwa v158, v142, v232 dst_sel:DWORD dst_unused:UNUSED_PAD src0_sel:WORD_1 src1_sel:DWORD
	v_ashrrev_i32_e32 v151, 31, v150
	v_add3_u32 v142, v142, v158, s43
	v_add3_u32 v144, v144, v157, s43
	v_and_b32_sdwa v157, v145, v232 dst_sel:DWORD dst_unused:UNUSED_PAD src0_sel:WORD_1 src1_sel:DWORD
	v_and_b32_sdwa v158, v143, v232 dst_sel:DWORD dst_unused:UNUSED_PAD src0_sel:WORD_1 src1_sel:DWORD
	v_lshl_add_u64 v[152:153], v[150:151], 1, v[146:147]
	v_add3_u32 v145, v145, v157, s43
	v_add3_u32 v143, v143, v158, s43
	v_lshl_add_u64 v[154:155], v[154:155], 1, v[152:153]
	v_lshlrev_b32_e32 v128, 1, v166
	v_and_b32_e32 v145, 0xffff0000, v145
	v_and_b32_e32 v157, 0xffff0000, v143
	v_lshl_add_u64 v[154:155], v[154:155], 0, v[128:129]
	v_or_b32_sdwa v143, v145, v144 dst_sel:DWORD dst_unused:UNUSED_PAD src0_sel:DWORD src1_sel:WORD_1
	v_or_b32_sdwa v142, v157, v142 dst_sel:DWORD dst_unused:UNUSED_PAD src0_sel:DWORD src1_sel:WORD_1
	s_nop 0
	v_mov_b32_e32 v212, v142
	v_mov_b32_e32 v213, v143
	v_and_b32_sdwa v142, v140, v232 dst_sel:DWORD dst_unused:UNUSED_PAD src0_sel:WORD_1 src1_sel:DWORD
	v_and_b32_sdwa v143, v138, v232 dst_sel:DWORD dst_unused:UNUSED_PAD src0_sel:WORD_1 src1_sel:DWORD
	v_add3_u32 v138, v138, v143, s43
	v_add3_u32 v140, v140, v142, s43
	v_and_b32_sdwa v142, v141, v232 dst_sel:DWORD dst_unused:UNUSED_PAD src0_sel:WORD_1 src1_sel:DWORD
	v_and_b32_sdwa v143, v139, v232 dst_sel:DWORD dst_unused:UNUSED_PAD src0_sel:WORD_1 src1_sel:DWORD
	v_add3_u32 v141, v141, v142, s43
	v_add3_u32 v139, v139, v143, s43
	v_and_b32_e32 v141, 0xffff0000, v141
	v_and_b32_e32 v142, 0xffff0000, v139
	v_or_b32_sdwa v139, v141, v140 dst_sel:DWORD dst_unused:UNUSED_PAD src0_sel:DWORD src1_sel:WORD_1
	v_or_b32_sdwa v138, v142, v138 dst_sel:DWORD dst_unused:UNUSED_PAD src0_sel:DWORD src1_sel:WORD_1
	s_nop 0
	v_mov_b32_e32 v214, v138
	v_mov_b32_e32 v215, v139
	v_mbcnt_lo_u32_b32 v224, -1, 0
	v_mbcnt_hi_u32_b32 v224, -1, v224
	v_and_b32_e32 v222, 16, v224
	v_lshrrev_b32_e32 v224, 1, v222
	v_add_u32_e32 v222, v222, v224
	v_mov_b32_e32 v223, 0
	v_lshl_add_u64 v[220:221], v[154:155], 0, v[222:223]
	v_permlane16_swap_b32_e32 v212, v214
	v_permlane16_swap_b32_e32 v213, v215
	global_store_dwordx4 v[220:221], v[212:215], off
	v_and_b32_sdwa v138, v136, v232 dst_sel:DWORD dst_unused:UNUSED_PAD src0_sel:WORD_1 src1_sel:DWORD
	v_and_b32_sdwa v139, v134, v232 dst_sel:DWORD dst_unused:UNUSED_PAD src0_sel:WORD_1 src1_sel:DWORD
	v_add3_u32 v134, v134, v139, s43
	v_add3_u32 v136, v136, v138, s43
	v_and_b32_sdwa v138, v137, v232 dst_sel:DWORD dst_unused:UNUSED_PAD src0_sel:WORD_1 src1_sel:DWORD
	v_and_b32_sdwa v139, v135, v232 dst_sel:DWORD dst_unused:UNUSED_PAD src0_sel:WORD_1 src1_sel:DWORD
	v_add3_u32 v137, v137, v138, s43
	v_add3_u32 v135, v135, v139, s43
	v_and_b32_e32 v137, 0xffff0000, v137
	v_and_b32_e32 v138, 0xffff0000, v135
	v_or_b32_sdwa v135, v137, v136 dst_sel:DWORD dst_unused:UNUSED_PAD src0_sel:DWORD src1_sel:WORD_1
	v_or_b32_sdwa v134, v138, v134 dst_sel:DWORD dst_unused:UNUSED_PAD src0_sel:DWORD src1_sel:WORD_1
	s_nop 0
	v_mov_b32_e32 v216, v134
	v_mov_b32_e32 v217, v135
	v_and_b32_sdwa v134, v126, v232 dst_sel:DWORD dst_unused:UNUSED_PAD src0_sel:WORD_1 src1_sel:DWORD
	v_and_b32_sdwa v135, v124, v232 dst_sel:DWORD dst_unused:UNUSED_PAD src0_sel:WORD_1 src1_sel:DWORD
	v_add3_u32 v124, v124, v135, s43
	v_add3_u32 v126, v126, v134, s43
	v_and_b32_sdwa v134, v127, v232 dst_sel:DWORD dst_unused:UNUSED_PAD src0_sel:WORD_1 src1_sel:DWORD
	v_and_b32_sdwa v135, v125, v232 dst_sel:DWORD dst_unused:UNUSED_PAD src0_sel:WORD_1 src1_sel:DWORD
	v_add3_u32 v127, v127, v134, s43
	v_add3_u32 v125, v125, v135, s43
	v_and_b32_e32 v127, 0xffff0000, v127
	v_and_b32_e32 v134, 0xffff0000, v125
	v_or_b32_sdwa v125, v127, v126 dst_sel:DWORD dst_unused:UNUSED_PAD src0_sel:DWORD src1_sel:WORD_1
	v_or_b32_sdwa v124, v134, v124 dst_sel:DWORD dst_unused:UNUSED_PAD src0_sel:DWORD src1_sel:WORD_1
	s_nop 0
	v_mov_b32_e32 v218, v124
	v_mov_b32_e32 v219, v125
	s_nop 1
	v_permlane16_swap_b32_e32 v216, v218
	v_permlane16_swap_b32_e32 v217, v219
	global_store_dwordx4 v[220:221], v[216:219], off offset:64
	v_add_u32_e32 v124, 16, v156
	v_ashrrev_i32_e32 v125, 31, v124
	v_mul_lo_u32 v126, v148, v125
	v_mul_lo_u32 v127, v149, v124
	v_mad_u64_u32 v[124:125], s[16:17], v148, v124, 0
	v_add3_u32 v125, v125, v126, v127
	v_and_b32_sdwa v126, v132, v232 dst_sel:DWORD dst_unused:UNUSED_PAD src0_sel:WORD_1 src1_sel:DWORD
	v_and_b32_sdwa v127, v130, v232 dst_sel:DWORD dst_unused:UNUSED_PAD src0_sel:WORD_1 src1_sel:DWORD
	v_add3_u32 v130, v130, v127, s43
	v_add3_u32 v126, v132, v126, s43
	v_and_b32_sdwa v127, v133, v232 dst_sel:DWORD dst_unused:UNUSED_PAD src0_sel:WORD_1 src1_sel:DWORD
	v_and_b32_sdwa v132, v131, v232 dst_sel:DWORD dst_unused:UNUSED_PAD src0_sel:WORD_1 src1_sel:DWORD
	v_add3_u32 v127, v133, v127, s43
	v_add3_u32 v131, v131, v132, s43
	v_lshl_add_u64 v[124:125], v[124:125], 1, v[152:153]
	v_and_b32_e32 v127, 0xffff0000, v127
	v_and_b32_e32 v131, 0xffff0000, v131
	v_lshl_add_u64 v[124:125], v[124:125], 0, v[128:129]
	v_or_b32_sdwa v127, v127, v126 dst_sel:DWORD dst_unused:UNUSED_PAD src0_sel:DWORD src1_sel:WORD_1
	v_or_b32_sdwa v126, v131, v130 dst_sel:DWORD dst_unused:UNUSED_PAD src0_sel:DWORD src1_sel:WORD_1
	s_nop 0
	v_mov_b32_e32 v212, v126
	v_mov_b32_e32 v213, v127
; #define ST4(ptr, a, b, c_, d) (*(uint2*)(ptr) = make_uint2((unsigned)f2bf(a) | ((unsigned)f2bf(b) << 16), (unsigned)f2bf(c_) | ((unsigned)f2bf(d) << 16)))
; __device__ __forceinline__ void upproj_phase(const Ctx& p, int hf) {
;     ...
;     u16* dst; int ldc, c0;
;     if (pn < 3) { dst = (u16*)(p.ws + A_QM); ldc = 768; c0 = pn * 256; }
;     else if (wc < 2) { dst = (u16*)(p.ws + A_KM); ldc = 768; c0 = h * 192; }
;     else { dst = (u16*)(p.ws + A_VM); ldc = 512; c0 = h * 128 - 128; }
;     ACC_LOOP( ST4(dst + (size_t)row * ldc + c0 + col, v4[0], v4[1], v4[2], v4[3]); )
	v_and_b32_sdwa v126, v122, v232 dst_sel:DWORD dst_unused:UNUSED_PAD src0_sel:WORD_1 src1_sel:DWORD
	v_and_b32_sdwa v127, v120, v232 dst_sel:DWORD dst_unused:UNUSED_PAD src0_sel:WORD_1 src1_sel:DWORD
	v_add3_u32 v120, v120, v127, s43
	v_add3_u32 v122, v122, v126, s43
	v_and_b32_sdwa v126, v123, v232 dst_sel:DWORD dst_unused:UNUSED_PAD src0_sel:WORD_1 src1_sel:DWORD
	v_and_b32_sdwa v127, v121, v232 dst_sel:DWORD dst_unused:UNUSED_PAD src0_sel:WORD_1 src1_sel:DWORD
	v_add3_u32 v123, v123, v126, s43
	v_add3_u32 v121, v121, v127, s43
	v_and_b32_e32 v123, 0xffff0000, v123
	v_and_b32_e32 v126, 0xffff0000, v121
	v_or_b32_sdwa v121, v123, v122 dst_sel:DWORD dst_unused:UNUSED_PAD src0_sel:DWORD src1_sel:WORD_1
	v_or_b32_sdwa v120, v126, v120 dst_sel:DWORD dst_unused:UNUSED_PAD src0_sel:DWORD src1_sel:WORD_1
	s_nop 0
	v_mov_b32_e32 v214, v120
	v_mov_b32_e32 v215, v121
	v_mbcnt_lo_u32_b32 v224, -1, 0
	v_mbcnt_hi_u32_b32 v224, -1, v224
	v_and_b32_e32 v222, 16, v224
	v_lshrrev_b32_e32 v224, 1, v222
	v_add_u32_e32 v222, v222, v224
	v_mov_b32_e32 v223, 0
	v_lshl_add_u64 v[220:221], v[124:125], 0, v[222:223]
	v_permlane16_swap_b32_e32 v212, v214
	v_permlane16_swap_b32_e32 v213, v215
	global_store_dwordx4 v[220:221], v[212:215], off
	v_and_b32_sdwa v120, v118, v232 dst_sel:DWORD dst_unused:UNUSED_PAD src0_sel:WORD_1 src1_sel:DWORD
	v_and_b32_sdwa v121, v116, v232 dst_sel:DWORD dst_unused:UNUSED_PAD src0_sel:WORD_1 src1_sel:DWORD
	v_add3_u32 v116, v116, v121, s43
	v_add3_u32 v118, v118, v120, s43
	v_and_b32_sdwa v120, v119, v232 dst_sel:DWORD dst_unused:UNUSED_PAD src0_sel:WORD_1 src1_sel:DWORD
	v_and_b32_sdwa v121, v117, v232 dst_sel:DWORD dst_unused:UNUSED_PAD src0_sel:WORD_1 src1_sel:DWORD
	v_add3_u32 v119, v119, v120, s43
	v_add3_u32 v117, v117, v121, s43
	v_and_b32_e32 v119, 0xffff0000, v119
	v_and_b32_e32 v120, 0xffff0000, v117
	v_or_b32_sdwa v117, v119, v118 dst_sel:DWORD dst_unused:UNUSED_PAD src0_sel:DWORD src1_sel:WORD_1
	v_or_b32_sdwa v116, v120, v116 dst_sel:DWORD dst_unused:UNUSED_PAD src0_sel:DWORD src1_sel:WORD_1
	s_nop 0
	v_mov_b32_e32 v216, v116
	v_mov_b32_e32 v217, v117
	v_and_b32_sdwa v116, v114, v232 dst_sel:DWORD dst_unused:UNUSED_PAD src0_sel:WORD_1 src1_sel:DWORD
	v_and_b32_sdwa v117, v112, v232 dst_sel:DWORD dst_unused:UNUSED_PAD src0_sel:WORD_1 src1_sel:DWORD
	v_add3_u32 v112, v112, v117, s43
	v_add3_u32 v114, v114, v116, s43
	v_and_b32_sdwa v116, v115, v232 dst_sel:DWORD dst_unused:UNUSED_PAD src0_sel:WORD_1 src1_sel:DWORD
	v_and_b32_sdwa v117, v113, v232 dst_sel:DWORD dst_unused:UNUSED_PAD src0_sel:WORD_1 src1_sel:DWORD
	v_add3_u32 v115, v115, v116, s43
	v_add3_u32 v113, v113, v117, s43
	v_and_b32_e32 v115, 0xffff0000, v115
	v_and_b32_e32 v116, 0xffff0000, v113
	v_or_b32_sdwa v113, v115, v114 dst_sel:DWORD dst_unused:UNUSED_PAD src0_sel:DWORD src1_sel:WORD_1
	v_or_b32_sdwa v112, v116, v112 dst_sel:DWORD dst_unused:UNUSED_PAD src0_sel:DWORD src1_sel:WORD_1
	s_nop 0
	v_mov_b32_e32 v218, v112
	v_mov_b32_e32 v219, v113
	s_nop 1
	v_permlane16_swap_b32_e32 v216, v218
	v_permlane16_swap_b32_e32 v217, v219
	global_store_dwordx4 v[220:221], v[216:219], off offset:64
	v_add_u32_e32 v112, 32, v156
	v_ashrrev_i32_e32 v113, 31, v112
	v_mul_lo_u32 v114, v148, v113
	v_mul_lo_u32 v115, v149, v112
	v_mad_u64_u32 v[112:113], s[16:17], v148, v112, 0
	v_add3_u32 v113, v113, v114, v115
	v_and_b32_sdwa v114, v110, v232 dst_sel:DWORD dst_unused:UNUSED_PAD src0_sel:WORD_1 src1_sel:DWORD
	v_and_b32_sdwa v115, v108, v232 dst_sel:DWORD dst_unused:UNUSED_PAD src0_sel:WORD_1 src1_sel:DWORD
	v_add3_u32 v108, v108, v115, s43
	v_add3_u32 v110, v110, v114, s43
	v_and_b32_sdwa v114, v111, v232 dst_sel:DWORD dst_unused:UNUSED_PAD src0_sel:WORD_1 src1_sel:DWORD
	v_and_b32_sdwa v115, v109, v232 dst_sel:DWORD dst_unused:UNUSED_PAD src0_sel:WORD_1 src1_sel:DWORD
	v_add3_u32 v111, v111, v114, s43
	v_add3_u32 v109, v109, v115, s43
	v_lshl_add_u64 v[112:113], v[112:113], 1, v[152:153]
	v_and_b32_e32 v111, 0xffff0000, v111
	v_and_b32_e32 v114, 0xffff0000, v109
	v_lshl_add_u64 v[112:113], v[112:113], 0, v[128:129]
	v_or_b32_sdwa v109, v111, v110 dst_sel:DWORD dst_unused:UNUSED_PAD src0_sel:DWORD src1_sel:WORD_1
	v_or_b32_sdwa v108, v114, v108 dst_sel:DWORD dst_unused:UNUSED_PAD src0_sel:DWORD src1_sel:WORD_1
	s_nop 0
	v_mov_b32_e32 v212, v108
	v_mov_b32_e32 v213, v109
	v_and_b32_sdwa v108, v106, v232 dst_sel:DWORD dst_unused:UNUSED_PAD src0_sel:WORD_1 src1_sel:DWORD
	v_and_b32_sdwa v109, v104, v232 dst_sel:DWORD dst_unused:UNUSED_PAD src0_sel:WORD_1 src1_sel:DWORD
	v_add3_u32 v104, v104, v109, s43
	v_add3_u32 v106, v106, v108, s43
	v_and_b32_sdwa v108, v107, v232 dst_sel:DWORD dst_unused:UNUSED_PAD src0_sel:WORD_1 src1_sel:DWORD
	v_and_b32_sdwa v109, v105, v232 dst_sel:DWORD dst_unused:UNUSED_PAD src0_sel:WORD_1 src1_sel:DWORD
	v_add3_u32 v107, v107, v108, s43
	v_add3_u32 v105, v105, v109, s43
	v_and_b32_e32 v107, 0xffff0000, v107
	v_and_b32_e32 v108, 0xffff0000, v105
	v_or_b32_sdwa v105, v107, v106 dst_sel:DWORD dst_unused:UNUSED_PAD src0_sel:DWORD src1_sel:WORD_1
	v_or_b32_sdwa v104, v108, v104 dst_sel:DWORD dst_unused:UNUSED_PAD src0_sel:DWORD src1_sel:WORD_1
	s_nop 0
	v_mov_b32_e32 v214, v104
	v_mov_b32_e32 v215, v105
	v_mbcnt_lo_u32_b32 v224, -1, 0
	v_mbcnt_hi_u32_b32 v224, -1, v224
	v_and_b32_e32 v222, 16, v224
	v_lshrrev_b32_e32 v224, 1, v222
	v_add_u32_e32 v222, v222, v224
	v_mov_b32_e32 v223, 0
	v_lshl_add_u64 v[220:221], v[112:113], 0, v[222:223]
	v_permlane16_swap_b32_e32 v212, v214
	v_permlane16_swap_b32_e32 v213, v215
	global_store_dwordx4 v[220:221], v[212:215], off
	v_and_b32_sdwa v104, v102, v232 dst_sel:DWORD dst_unused:UNUSED_PAD src0_sel:WORD_1 src1_sel:DWORD
; #define ST4(ptr, a, b, c_, d) (*(uint2*)(ptr) = make_uint2((unsigned)f2bf(a) | ((unsigned)f2bf(b) << 16), (unsigned)f2bf(c_) | ((unsigned)f2bf(d) << 16)))
; __device__ __forceinline__ void upproj_phase(const Ctx& p, int hf) {
;     ...
;     u16* dst; int ldc, c0;
;     if (pn < 3) { dst = (u16*)(p.ws + A_QM); ldc = 768; c0 = pn * 256; }
;     else if (wc < 2) { dst = (u16*)(p.ws + A_KM); ldc = 768; c0 = h * 192; }
;     else { dst = (u16*)(p.ws + A_VM); ldc = 512; c0 = h * 128 - 128; }
;     ACC_LOOP( ST4(dst + (size_t)row * ldc + c0 + col, v4[0], v4[1], v4[2], v4[3]); )
	v_and_b32_sdwa v105, v100, v232 dst_sel:DWORD dst_unused:UNUSED_PAD src0_sel:WORD_1 src1_sel:DWORD
	v_add3_u32 v100, v100, v105, s43
	v_add3_u32 v102, v102, v104, s43
	v_and_b32_sdwa v104, v103, v232 dst_sel:DWORD dst_unused:UNUSED_PAD src0_sel:WORD_1 src1_sel:DWORD
	v_and_b32_sdwa v105, v101, v232 dst_sel:DWORD dst_unused:UNUSED_PAD src0_sel:WORD_1 src1_sel:DWORD
	v_add3_u32 v103, v103, v104, s43
	v_add3_u32 v101, v101, v105, s43
	v_and_b32_e32 v103, 0xffff0000, v103
	v_and_b32_e32 v104, 0xffff0000, v101
	v_or_b32_sdwa v101, v103, v102 dst_sel:DWORD dst_unused:UNUSED_PAD src0_sel:DWORD src1_sel:WORD_1
	v_or_b32_sdwa v100, v104, v100 dst_sel:DWORD dst_unused:UNUSED_PAD src0_sel:DWORD src1_sel:WORD_1
	s_nop 0
	v_mov_b32_e32 v216, v100
	v_mov_b32_e32 v217, v101
	v_and_b32_sdwa v100, v98, v232 dst_sel:DWORD dst_unused:UNUSED_PAD src0_sel:WORD_1 src1_sel:DWORD
	v_and_b32_sdwa v101, v96, v232 dst_sel:DWORD dst_unused:UNUSED_PAD src0_sel:WORD_1 src1_sel:DWORD
	v_add3_u32 v96, v96, v101, s43
	v_add3_u32 v98, v98, v100, s43
	v_and_b32_sdwa v100, v99, v232 dst_sel:DWORD dst_unused:UNUSED_PAD src0_sel:WORD_1 src1_sel:DWORD
	v_and_b32_sdwa v101, v97, v232 dst_sel:DWORD dst_unused:UNUSED_PAD src0_sel:WORD_1 src1_sel:DWORD
	v_add3_u32 v99, v99, v100, s43
	v_add3_u32 v97, v97, v101, s43
	v_and_b32_e32 v99, 0xffff0000, v99
	v_and_b32_e32 v100, 0xffff0000, v97
	v_or_b32_sdwa v97, v99, v98 dst_sel:DWORD dst_unused:UNUSED_PAD src0_sel:DWORD src1_sel:WORD_1
	v_or_b32_sdwa v96, v100, v96 dst_sel:DWORD dst_unused:UNUSED_PAD src0_sel:DWORD src1_sel:WORD_1
	s_nop 0
	v_mov_b32_e32 v218, v96
	v_mov_b32_e32 v219, v97
	s_nop 1
	v_permlane16_swap_b32_e32 v216, v218
	v_permlane16_swap_b32_e32 v217, v219
	global_store_dwordx4 v[220:221], v[216:219], off offset:64
	v_add_u32_e32 v96, 48, v156
	v_ashrrev_i32_e32 v97, 31, v96
	v_mul_lo_u32 v98, v148, v97
	v_mul_lo_u32 v99, v149, v96
	v_mad_u64_u32 v[96:97], s[16:17], v148, v96, 0
	v_add3_u32 v97, v97, v98, v99
	v_and_b32_sdwa v98, v94, v232 dst_sel:DWORD dst_unused:UNUSED_PAD src0_sel:WORD_1 src1_sel:DWORD
	v_and_b32_sdwa v99, v92, v232 dst_sel:DWORD dst_unused:UNUSED_PAD src0_sel:WORD_1 src1_sel:DWORD
	v_add3_u32 v92, v92, v99, s43
	v_add3_u32 v94, v94, v98, s43
	v_and_b32_sdwa v98, v95, v232 dst_sel:DWORD dst_unused:UNUSED_PAD src0_sel:WORD_1 src1_sel:DWORD
	v_and_b32_sdwa v99, v93, v232 dst_sel:DWORD dst_unused:UNUSED_PAD src0_sel:WORD_1 src1_sel:DWORD
	v_add3_u32 v95, v95, v98, s43
	v_add3_u32 v93, v93, v99, s43
	v_lshl_add_u64 v[96:97], v[96:97], 1, v[152:153]
	v_and_b32_e32 v95, 0xffff0000, v95
	v_and_b32_e32 v98, 0xffff0000, v93
	v_lshl_add_u64 v[96:97], v[96:97], 0, v[128:129]
	v_or_b32_sdwa v93, v95, v94 dst_sel:DWORD dst_unused:UNUSED_PAD src0_sel:DWORD src1_sel:WORD_1
	v_or_b32_sdwa v92, v98, v92 dst_sel:DWORD dst_unused:UNUSED_PAD src0_sel:DWORD src1_sel:WORD_1
	s_nop 0
	v_mov_b32_e32 v212, v92
	v_mov_b32_e32 v213, v93
	v_and_b32_sdwa v92, v90, v232 dst_sel:DWORD dst_unused:UNUSED_PAD src0_sel:WORD_1 src1_sel:DWORD
	v_and_b32_sdwa v93, v88, v232 dst_sel:DWORD dst_unused:UNUSED_PAD src0_sel:WORD_1 src1_sel:DWORD
	v_add3_u32 v88, v88, v93, s43
	v_add3_u32 v90, v90, v92, s43
	v_and_b32_sdwa v92, v91, v232 dst_sel:DWORD dst_unused:UNUSED_PAD src0_sel:WORD_1 src1_sel:DWORD
	v_and_b32_sdwa v93, v89, v232 dst_sel:DWORD dst_unused:UNUSED_PAD src0_sel:WORD_1 src1_sel:DWORD
	v_add3_u32 v91, v91, v92, s43
	v_add3_u32 v89, v89, v93, s43
	v_and_b32_e32 v91, 0xffff0000, v91
	v_and_b32_e32 v92, 0xffff0000, v89
	v_or_b32_sdwa v89, v91, v90 dst_sel:DWORD dst_unused:UNUSED_PAD src0_sel:DWORD src1_sel:WORD_1
	v_or_b32_sdwa v88, v92, v88 dst_sel:DWORD dst_unused:UNUSED_PAD src0_sel:DWORD src1_sel:WORD_1
	s_nop 0
	v_mov_b32_e32 v214, v88
	v_mov_b32_e32 v215, v89
	v_mbcnt_lo_u32_b32 v224, -1, 0
	v_mbcnt_hi_u32_b32 v224, -1, v224
	v_and_b32_e32 v222, 16, v224
	v_lshrrev_b32_e32 v224, 1, v222
	v_add_u32_e32 v222, v222, v224
	v_mov_b32_e32 v223, 0
	v_lshl_add_u64 v[220:221], v[96:97], 0, v[222:223]
	v_permlane16_swap_b32_e32 v212, v214
	v_permlane16_swap_b32_e32 v213, v215
	global_store_dwordx4 v[220:221], v[212:215], off
	v_and_b32_sdwa v88, v86, v232 dst_sel:DWORD dst_unused:UNUSED_PAD src0_sel:WORD_1 src1_sel:DWORD
	v_and_b32_sdwa v89, v84, v232 dst_sel:DWORD dst_unused:UNUSED_PAD src0_sel:WORD_1 src1_sel:DWORD
	v_add3_u32 v84, v84, v89, s43
	v_add3_u32 v86, v86, v88, s43
	v_and_b32_sdwa v88, v87, v232 dst_sel:DWORD dst_unused:UNUSED_PAD src0_sel:WORD_1 src1_sel:DWORD
	v_and_b32_sdwa v89, v85, v232 dst_sel:DWORD dst_unused:UNUSED_PAD src0_sel:WORD_1 src1_sel:DWORD
	v_add3_u32 v87, v87, v88, s43
	v_add3_u32 v85, v85, v89, s43
	v_and_b32_e32 v87, 0xffff0000, v87
	v_and_b32_e32 v88, 0xffff0000, v85
	v_or_b32_sdwa v85, v87, v86 dst_sel:DWORD dst_unused:UNUSED_PAD src0_sel:DWORD src1_sel:WORD_1
	v_or_b32_sdwa v84, v88, v84 dst_sel:DWORD dst_unused:UNUSED_PAD src0_sel:DWORD src1_sel:WORD_1
	s_nop 0
	v_mov_b32_e32 v216, v84
	v_mov_b32_e32 v217, v85
	v_and_b32_sdwa v84, v82, v232 dst_sel:DWORD dst_unused:UNUSED_PAD src0_sel:WORD_1 src1_sel:DWORD
	v_and_b32_sdwa v85, v80, v232 dst_sel:DWORD dst_unused:UNUSED_PAD src0_sel:WORD_1 src1_sel:DWORD
	v_add3_u32 v80, v80, v85, s43
	v_add3_u32 v82, v82, v84, s43
	v_and_b32_sdwa v84, v83, v232 dst_sel:DWORD dst_unused:UNUSED_PAD src0_sel:WORD_1 src1_sel:DWORD
	v_and_b32_sdwa v85, v81, v232 dst_sel:DWORD dst_unused:UNUSED_PAD src0_sel:WORD_1 src1_sel:DWORD
	v_add3_u32 v83, v83, v84, s43
	v_add3_u32 v81, v81, v85, s43
	v_and_b32_e32 v83, 0xffff0000, v83
	v_and_b32_e32 v84, 0xffff0000, v81
	v_or_b32_sdwa v81, v83, v82 dst_sel:DWORD dst_unused:UNUSED_PAD src0_sel:DWORD src1_sel:WORD_1
; #define ST4(ptr, a, b, c_, d) (*(uint2*)(ptr) = make_uint2((unsigned)f2bf(a) | ((unsigned)f2bf(b) << 16), (unsigned)f2bf(c_) | ((unsigned)f2bf(d) << 16)))
; __device__ __forceinline__ void upproj_phase(const Ctx& p, int hf) {
;     ...
;     u16* dst; int ldc, c0;
;     if (pn < 3) { dst = (u16*)(p.ws + A_QM); ldc = 768; c0 = pn * 256; }
;     else if (wc < 2) { dst = (u16*)(p.ws + A_KM); ldc = 768; c0 = h * 192; }
;     else { dst = (u16*)(p.ws + A_VM); ldc = 512; c0 = h * 128 - 128; }
;     ACC_LOOP( ST4(dst + (size_t)row * ldc + c0 + col, v4[0], v4[1], v4[2], v4[3]); )
	v_or_b32_sdwa v80, v84, v80 dst_sel:DWORD dst_unused:UNUSED_PAD src0_sel:DWORD src1_sel:WORD_1
	s_nop 0
	v_mov_b32_e32 v218, v80
	v_mov_b32_e32 v219, v81
	s_nop 1
	v_permlane16_swap_b32_e32 v216, v218
	v_permlane16_swap_b32_e32 v217, v219
	global_store_dwordx4 v[220:221], v[216:219], off offset:64
	v_add_u32_e32 v80, 64, v156
	v_ashrrev_i32_e32 v81, 31, v80
	v_mul_lo_u32 v82, v148, v81
	v_mul_lo_u32 v83, v149, v80
	v_mad_u64_u32 v[80:81], s[16:17], v148, v80, 0
	v_add3_u32 v81, v81, v82, v83
	v_and_b32_sdwa v82, v78, v232 dst_sel:DWORD dst_unused:UNUSED_PAD src0_sel:WORD_1 src1_sel:DWORD
	v_and_b32_sdwa v83, v76, v232 dst_sel:DWORD dst_unused:UNUSED_PAD src0_sel:WORD_1 src1_sel:DWORD
	v_add3_u32 v76, v76, v83, s43
	v_add3_u32 v78, v78, v82, s43
	v_and_b32_sdwa v82, v79, v232 dst_sel:DWORD dst_unused:UNUSED_PAD src0_sel:WORD_1 src1_sel:DWORD
	v_and_b32_sdwa v83, v77, v232 dst_sel:DWORD dst_unused:UNUSED_PAD src0_sel:WORD_1 src1_sel:DWORD
	v_add3_u32 v79, v79, v82, s43
	v_add3_u32 v77, v77, v83, s43
	v_lshl_add_u64 v[80:81], v[80:81], 1, v[152:153]
	v_and_b32_e32 v79, 0xffff0000, v79
	v_and_b32_e32 v82, 0xffff0000, v77
	v_lshl_add_u64 v[80:81], v[80:81], 0, v[128:129]
	v_or_b32_sdwa v77, v79, v78 dst_sel:DWORD dst_unused:UNUSED_PAD src0_sel:DWORD src1_sel:WORD_1
	v_or_b32_sdwa v76, v82, v76 dst_sel:DWORD dst_unused:UNUSED_PAD src0_sel:DWORD src1_sel:WORD_1
	s_nop 0
	v_mov_b32_e32 v212, v76
	v_mov_b32_e32 v213, v77
	v_and_b32_sdwa v76, v74, v232 dst_sel:DWORD dst_unused:UNUSED_PAD src0_sel:WORD_1 src1_sel:DWORD
	v_and_b32_sdwa v77, v72, v232 dst_sel:DWORD dst_unused:UNUSED_PAD src0_sel:WORD_1 src1_sel:DWORD
	v_add3_u32 v72, v72, v77, s43
	v_add3_u32 v74, v74, v76, s43
	v_and_b32_sdwa v76, v75, v232 dst_sel:DWORD dst_unused:UNUSED_PAD src0_sel:WORD_1 src1_sel:DWORD
	v_and_b32_sdwa v77, v73, v232 dst_sel:DWORD dst_unused:UNUSED_PAD src0_sel:WORD_1 src1_sel:DWORD
	v_add3_u32 v75, v75, v76, s43
	v_add3_u32 v73, v73, v77, s43
	v_and_b32_e32 v75, 0xffff0000, v75
	v_and_b32_e32 v76, 0xffff0000, v73
	v_or_b32_sdwa v73, v75, v74 dst_sel:DWORD dst_unused:UNUSED_PAD src0_sel:DWORD src1_sel:WORD_1
	v_or_b32_sdwa v72, v76, v72 dst_sel:DWORD dst_unused:UNUSED_PAD src0_sel:DWORD src1_sel:WORD_1
	s_nop 0
	v_mov_b32_e32 v214, v72
	v_mov_b32_e32 v215, v73
	v_mbcnt_lo_u32_b32 v224, -1, 0
	v_mbcnt_hi_u32_b32 v224, -1, v224
	v_and_b32_e32 v222, 16, v224
	v_lshrrev_b32_e32 v224, 1, v222
	v_add_u32_e32 v222, v222, v224
	v_mov_b32_e32 v223, 0
	v_lshl_add_u64 v[220:221], v[80:81], 0, v[222:223]
	v_permlane16_swap_b32_e32 v212, v214
	v_permlane16_swap_b32_e32 v213, v215
	global_store_dwordx4 v[220:221], v[212:215], off
	v_and_b32_sdwa v72, v70, v232 dst_sel:DWORD dst_unused:UNUSED_PAD src0_sel:WORD_1 src1_sel:DWORD
	v_and_b32_sdwa v73, v68, v232 dst_sel:DWORD dst_unused:UNUSED_PAD src0_sel:WORD_1 src1_sel:DWORD
	v_add3_u32 v68, v68, v73, s43
	v_add3_u32 v70, v70, v72, s43
	v_and_b32_sdwa v72, v71, v232 dst_sel:DWORD dst_unused:UNUSED_PAD src0_sel:WORD_1 src1_sel:DWORD
	v_and_b32_sdwa v73, v69, v232 dst_sel:DWORD dst_unused:UNUSED_PAD src0_sel:WORD_1 src1_sel:DWORD
	v_add3_u32 v71, v71, v72, s43
	v_add3_u32 v69, v69, v73, s43
	v_and_b32_e32 v71, 0xffff0000, v71
	v_and_b32_e32 v72, 0xffff0000, v69
	v_or_b32_sdwa v69, v71, v70 dst_sel:DWORD dst_unused:UNUSED_PAD src0_sel:DWORD src1_sel:WORD_1
	v_or_b32_sdwa v68, v72, v68 dst_sel:DWORD dst_unused:UNUSED_PAD src0_sel:DWORD src1_sel:WORD_1
	s_nop 0
	v_mov_b32_e32 v216, v68
	v_mov_b32_e32 v217, v69
	v_and_b32_sdwa v68, v66, v232 dst_sel:DWORD dst_unused:UNUSED_PAD src0_sel:WORD_1 src1_sel:DWORD
	v_and_b32_sdwa v69, v64, v232 dst_sel:DWORD dst_unused:UNUSED_PAD src0_sel:WORD_1 src1_sel:DWORD
	v_add3_u32 v64, v64, v69, s43
	v_add3_u32 v66, v66, v68, s43
	v_and_b32_sdwa v68, v67, v232 dst_sel:DWORD dst_unused:UNUSED_PAD src0_sel:WORD_1 src1_sel:DWORD
	v_and_b32_sdwa v69, v65, v232 dst_sel:DWORD dst_unused:UNUSED_PAD src0_sel:WORD_1 src1_sel:DWORD
	v_add3_u32 v67, v67, v68, s43
	v_add3_u32 v65, v65, v69, s43
	v_and_b32_e32 v67, 0xffff0000, v67
	v_and_b32_e32 v68, 0xffff0000, v65
	v_or_b32_sdwa v65, v67, v66 dst_sel:DWORD dst_unused:UNUSED_PAD src0_sel:DWORD src1_sel:WORD_1
	v_or_b32_sdwa v64, v68, v64 dst_sel:DWORD dst_unused:UNUSED_PAD src0_sel:DWORD src1_sel:WORD_1
	s_nop 0
	v_mov_b32_e32 v218, v64
	v_mov_b32_e32 v219, v65
	s_nop 1
	v_permlane16_swap_b32_e32 v216, v218
	v_permlane16_swap_b32_e32 v217, v219
	global_store_dwordx4 v[220:221], v[216:219], off offset:64
	v_add_u32_e32 v64, 0x50, v156
	v_ashrrev_i32_e32 v65, 31, v64
	v_mul_lo_u32 v66, v148, v65
	v_mul_lo_u32 v67, v149, v64
	v_mad_u64_u32 v[64:65], s[16:17], v148, v64, 0
	v_add3_u32 v65, v65, v66, v67
	v_and_b32_sdwa v66, v62, v232 dst_sel:DWORD dst_unused:UNUSED_PAD src0_sel:WORD_1 src1_sel:DWORD
	v_and_b32_sdwa v67, v60, v232 dst_sel:DWORD dst_unused:UNUSED_PAD src0_sel:WORD_1 src1_sel:DWORD
	v_add3_u32 v60, v60, v67, s43
	v_add3_u32 v62, v62, v66, s43
	v_and_b32_sdwa v66, v63, v232 dst_sel:DWORD dst_unused:UNUSED_PAD src0_sel:WORD_1 src1_sel:DWORD
	v_and_b32_sdwa v67, v61, v232 dst_sel:DWORD dst_unused:UNUSED_PAD src0_sel:WORD_1 src1_sel:DWORD
	v_add3_u32 v63, v63, v66, s43
	v_add3_u32 v61, v61, v67, s43
	v_lshl_add_u64 v[64:65], v[64:65], 1, v[152:153]
	v_and_b32_e32 v63, 0xffff0000, v63
	v_and_b32_e32 v66, 0xffff0000, v61
	v_lshl_add_u64 v[64:65], v[64:65], 0, v[128:129]
	v_or_b32_sdwa v61, v63, v62 dst_sel:DWORD dst_unused:UNUSED_PAD src0_sel:DWORD src1_sel:WORD_1
	v_or_b32_sdwa v60, v66, v60 dst_sel:DWORD dst_unused:UNUSED_PAD src0_sel:DWORD src1_sel:WORD_1
	s_nop 0
	v_mov_b32_e32 v212, v60
	v_mov_b32_e32 v213, v61
; #define ST4(ptr, a, b, c_, d) (*(uint2*)(ptr) = make_uint2((unsigned)f2bf(a) | ((unsigned)f2bf(b) << 16), (unsigned)f2bf(c_) | ((unsigned)f2bf(d) << 16)))
; __device__ __forceinline__ void upproj_phase(const Ctx& p, int hf) {
;     ...
;     u16* dst; int ldc, c0;
;     if (pn < 3) { dst = (u16*)(p.ws + A_QM); ldc = 768; c0 = pn * 256; }
;     else if (wc < 2) { dst = (u16*)(p.ws + A_KM); ldc = 768; c0 = h * 192; }
;     else { dst = (u16*)(p.ws + A_VM); ldc = 512; c0 = h * 128 - 128; }
;     ACC_LOOP( ST4(dst + (size_t)row * ldc + c0 + col, v4[0], v4[1], v4[2], v4[3]); )
	v_and_b32_sdwa v60, v58, v232 dst_sel:DWORD dst_unused:UNUSED_PAD src0_sel:WORD_1 src1_sel:DWORD
	v_and_b32_sdwa v61, v56, v232 dst_sel:DWORD dst_unused:UNUSED_PAD src0_sel:WORD_1 src1_sel:DWORD
	v_add3_u32 v56, v56, v61, s43
	v_add3_u32 v58, v58, v60, s43
	v_and_b32_sdwa v60, v59, v232 dst_sel:DWORD dst_unused:UNUSED_PAD src0_sel:WORD_1 src1_sel:DWORD
	v_and_b32_sdwa v61, v57, v232 dst_sel:DWORD dst_unused:UNUSED_PAD src0_sel:WORD_1 src1_sel:DWORD
	v_add3_u32 v59, v59, v60, s43
	v_add3_u32 v57, v57, v61, s43
	v_and_b32_e32 v59, 0xffff0000, v59
	v_and_b32_e32 v60, 0xffff0000, v57
	v_or_b32_sdwa v57, v59, v58 dst_sel:DWORD dst_unused:UNUSED_PAD src0_sel:DWORD src1_sel:WORD_1
	v_or_b32_sdwa v56, v60, v56 dst_sel:DWORD dst_unused:UNUSED_PAD src0_sel:DWORD src1_sel:WORD_1
	s_nop 0
	v_mov_b32_e32 v214, v56
	v_mov_b32_e32 v215, v57
	v_mbcnt_lo_u32_b32 v224, -1, 0
	v_mbcnt_hi_u32_b32 v224, -1, v224
	v_and_b32_e32 v222, 16, v224
	v_lshrrev_b32_e32 v224, 1, v222
	v_add_u32_e32 v222, v222, v224
	v_mov_b32_e32 v223, 0
	v_lshl_add_u64 v[220:221], v[64:65], 0, v[222:223]
	v_permlane16_swap_b32_e32 v212, v214
	v_permlane16_swap_b32_e32 v213, v215
	global_store_dwordx4 v[220:221], v[212:215], off
	v_and_b32_sdwa v56, v54, v232 dst_sel:DWORD dst_unused:UNUSED_PAD src0_sel:WORD_1 src1_sel:DWORD
	v_and_b32_sdwa v57, v52, v232 dst_sel:DWORD dst_unused:UNUSED_PAD src0_sel:WORD_1 src1_sel:DWORD
	v_add3_u32 v52, v52, v57, s43
	v_add3_u32 v54, v54, v56, s43
	v_and_b32_sdwa v56, v55, v232 dst_sel:DWORD dst_unused:UNUSED_PAD src0_sel:WORD_1 src1_sel:DWORD
	v_and_b32_sdwa v57, v53, v232 dst_sel:DWORD dst_unused:UNUSED_PAD src0_sel:WORD_1 src1_sel:DWORD
	v_add3_u32 v55, v55, v56, s43
	v_add3_u32 v53, v53, v57, s43
	v_and_b32_e32 v55, 0xffff0000, v55
	v_and_b32_e32 v56, 0xffff0000, v53
	v_or_b32_sdwa v53, v55, v54 dst_sel:DWORD dst_unused:UNUSED_PAD src0_sel:DWORD src1_sel:WORD_1
	v_or_b32_sdwa v52, v56, v52 dst_sel:DWORD dst_unused:UNUSED_PAD src0_sel:DWORD src1_sel:WORD_1
	s_nop 0
	v_mov_b32_e32 v216, v52
	v_mov_b32_e32 v217, v53
	v_and_b32_sdwa v52, v50, v232 dst_sel:DWORD dst_unused:UNUSED_PAD src0_sel:WORD_1 src1_sel:DWORD
	v_and_b32_sdwa v53, v48, v232 dst_sel:DWORD dst_unused:UNUSED_PAD src0_sel:WORD_1 src1_sel:DWORD
	v_add3_u32 v48, v48, v53, s43
	v_add3_u32 v50, v50, v52, s43
	v_and_b32_sdwa v52, v51, v232 dst_sel:DWORD dst_unused:UNUSED_PAD src0_sel:WORD_1 src1_sel:DWORD
	v_and_b32_sdwa v53, v49, v232 dst_sel:DWORD dst_unused:UNUSED_PAD src0_sel:WORD_1 src1_sel:DWORD
	v_add3_u32 v51, v51, v52, s43
	v_add3_u32 v49, v49, v53, s43
	v_and_b32_e32 v51, 0xffff0000, v51
	v_and_b32_e32 v52, 0xffff0000, v49
	v_or_b32_sdwa v49, v51, v50 dst_sel:DWORD dst_unused:UNUSED_PAD src0_sel:DWORD src1_sel:WORD_1
	v_or_b32_sdwa v48, v52, v48 dst_sel:DWORD dst_unused:UNUSED_PAD src0_sel:DWORD src1_sel:WORD_1
	s_nop 0
	v_mov_b32_e32 v218, v48
	v_mov_b32_e32 v219, v49
	s_nop 1
	v_permlane16_swap_b32_e32 v216, v218
	v_permlane16_swap_b32_e32 v217, v219
	global_store_dwordx4 v[220:221], v[216:219], off offset:64
	v_add_u32_e32 v48, 0x60, v156
	v_ashrrev_i32_e32 v49, 31, v48
	v_mul_lo_u32 v50, v148, v49
	v_mul_lo_u32 v51, v149, v48
	v_mad_u64_u32 v[48:49], s[16:17], v148, v48, 0
	v_add3_u32 v49, v49, v50, v51
	v_and_b32_sdwa v50, v46, v232 dst_sel:DWORD dst_unused:UNUSED_PAD src0_sel:WORD_1 src1_sel:DWORD
	v_and_b32_sdwa v51, v44, v232 dst_sel:DWORD dst_unused:UNUSED_PAD src0_sel:WORD_1 src1_sel:DWORD
	v_add3_u32 v44, v44, v51, s43
	v_add3_u32 v46, v46, v50, s43
	v_and_b32_sdwa v50, v47, v232 dst_sel:DWORD dst_unused:UNUSED_PAD src0_sel:WORD_1 src1_sel:DWORD
	v_and_b32_sdwa v51, v45, v232 dst_sel:DWORD dst_unused:UNUSED_PAD src0_sel:WORD_1 src1_sel:DWORD
	v_add3_u32 v47, v47, v50, s43
	v_add3_u32 v45, v45, v51, s43
	v_lshl_add_u64 v[48:49], v[48:49], 1, v[152:153]
	v_and_b32_e32 v47, 0xffff0000, v47
	v_and_b32_e32 v50, 0xffff0000, v45
	v_lshl_add_u64 v[48:49], v[48:49], 0, v[128:129]
	v_or_b32_sdwa v45, v47, v46 dst_sel:DWORD dst_unused:UNUSED_PAD src0_sel:DWORD src1_sel:WORD_1
	v_or_b32_sdwa v44, v50, v44 dst_sel:DWORD dst_unused:UNUSED_PAD src0_sel:DWORD src1_sel:WORD_1
	s_nop 0
	v_mov_b32_e32 v212, v44
	v_mov_b32_e32 v213, v45
	v_and_b32_sdwa v44, v42, v232 dst_sel:DWORD dst_unused:UNUSED_PAD src0_sel:WORD_1 src1_sel:DWORD
	v_and_b32_sdwa v45, v40, v232 dst_sel:DWORD dst_unused:UNUSED_PAD src0_sel:WORD_1 src1_sel:DWORD
	v_add3_u32 v40, v40, v45, s43
	v_add3_u32 v42, v42, v44, s43
	v_and_b32_sdwa v44, v43, v232 dst_sel:DWORD dst_unused:UNUSED_PAD src0_sel:WORD_1 src1_sel:DWORD
	v_and_b32_sdwa v45, v41, v232 dst_sel:DWORD dst_unused:UNUSED_PAD src0_sel:WORD_1 src1_sel:DWORD
	v_add3_u32 v43, v43, v44, s43
	v_add3_u32 v41, v41, v45, s43
	v_and_b32_e32 v43, 0xffff0000, v43
	v_and_b32_e32 v44, 0xffff0000, v41
	v_or_b32_sdwa v41, v43, v42 dst_sel:DWORD dst_unused:UNUSED_PAD src0_sel:DWORD src1_sel:WORD_1
	v_or_b32_sdwa v40, v44, v40 dst_sel:DWORD dst_unused:UNUSED_PAD src0_sel:DWORD src1_sel:WORD_1
	s_nop 0
	v_mov_b32_e32 v214, v40
	v_mov_b32_e32 v215, v41
	v_mbcnt_lo_u32_b32 v224, -1, 0
	v_mbcnt_hi_u32_b32 v224, -1, v224
	v_and_b32_e32 v222, 16, v224
	v_lshrrev_b32_e32 v224, 1, v222
	v_add_u32_e32 v222, v222, v224
	v_mov_b32_e32 v223, 0
	v_lshl_add_u64 v[220:221], v[48:49], 0, v[222:223]
	v_permlane16_swap_b32_e32 v212, v214
	v_permlane16_swap_b32_e32 v213, v215
	global_store_dwordx4 v[220:221], v[212:215], off
	v_and_b32_sdwa v40, v38, v232 dst_sel:DWORD dst_unused:UNUSED_PAD src0_sel:WORD_1 src1_sel:DWORD
	v_and_b32_sdwa v41, v36, v232 dst_sel:DWORD dst_unused:UNUSED_PAD src0_sel:WORD_1 src1_sel:DWORD
	v_add3_u32 v36, v36, v41, s43
	v_add3_u32 v38, v38, v40, s43
; #define ST4(ptr, a, b, c_, d) (*(uint2*)(ptr) = make_uint2((unsigned)f2bf(a) | ((unsigned)f2bf(b) << 16), (unsigned)f2bf(c_) | ((unsigned)f2bf(d) << 16)))
; __device__ __forceinline__ void upproj_phase(const Ctx& p, int hf) {
;     ...
;     u16* dst; int ldc, c0;
;     if (pn < 3) { dst = (u16*)(p.ws + A_QM); ldc = 768; c0 = pn * 256; }
;     else if (wc < 2) { dst = (u16*)(p.ws + A_KM); ldc = 768; c0 = h * 192; }
;     else { dst = (u16*)(p.ws + A_VM); ldc = 512; c0 = h * 128 - 128; }
;     ACC_LOOP( ST4(dst + (size_t)row * ldc + c0 + col, v4[0], v4[1], v4[2], v4[3]); )
	v_and_b32_sdwa v40, v39, v232 dst_sel:DWORD dst_unused:UNUSED_PAD src0_sel:WORD_1 src1_sel:DWORD
	v_and_b32_sdwa v41, v37, v232 dst_sel:DWORD dst_unused:UNUSED_PAD src0_sel:WORD_1 src1_sel:DWORD
	v_add3_u32 v39, v39, v40, s43
	v_add3_u32 v37, v37, v41, s43
	v_and_b32_e32 v39, 0xffff0000, v39
	v_and_b32_e32 v40, 0xffff0000, v37
	v_or_b32_sdwa v37, v39, v38 dst_sel:DWORD dst_unused:UNUSED_PAD src0_sel:DWORD src1_sel:WORD_1
	v_or_b32_sdwa v36, v40, v36 dst_sel:DWORD dst_unused:UNUSED_PAD src0_sel:DWORD src1_sel:WORD_1
	s_nop 0
	v_mov_b32_e32 v216, v36
	v_mov_b32_e32 v217, v37
	v_and_b32_sdwa v36, v34, v232 dst_sel:DWORD dst_unused:UNUSED_PAD src0_sel:WORD_1 src1_sel:DWORD
	v_and_b32_sdwa v37, v32, v232 dst_sel:DWORD dst_unused:UNUSED_PAD src0_sel:WORD_1 src1_sel:DWORD
	v_add3_u32 v32, v32, v37, s43
	v_add3_u32 v34, v34, v36, s43
	v_and_b32_sdwa v36, v35, v232 dst_sel:DWORD dst_unused:UNUSED_PAD src0_sel:WORD_1 src1_sel:DWORD
	v_and_b32_sdwa v37, v33, v232 dst_sel:DWORD dst_unused:UNUSED_PAD src0_sel:WORD_1 src1_sel:DWORD
	v_add3_u32 v35, v35, v36, s43
	v_add3_u32 v33, v33, v37, s43
	v_and_b32_e32 v35, 0xffff0000, v35
	v_and_b32_e32 v36, 0xffff0000, v33
	v_or_b32_sdwa v33, v35, v34 dst_sel:DWORD dst_unused:UNUSED_PAD src0_sel:DWORD src1_sel:WORD_1
	v_or_b32_sdwa v32, v36, v32 dst_sel:DWORD dst_unused:UNUSED_PAD src0_sel:DWORD src1_sel:WORD_1
	s_nop 0
	v_mov_b32_e32 v218, v32
	v_mov_b32_e32 v219, v33
	s_nop 1
	v_permlane16_swap_b32_e32 v216, v218
	v_permlane16_swap_b32_e32 v217, v219
	global_store_dwordx4 v[220:221], v[216:219], off offset:64
	v_add_u32_e32 v32, 0x70, v156
	v_ashrrev_i32_e32 v33, 31, v32
	v_mul_lo_u32 v34, v148, v33
	v_mul_lo_u32 v35, v149, v32
	v_mad_u64_u32 v[32:33], s[16:17], v148, v32, 0
	v_add3_u32 v33, v33, v34, v35
	v_and_b32_sdwa v34, v30, v232 dst_sel:DWORD dst_unused:UNUSED_PAD src0_sel:WORD_1 src1_sel:DWORD
	v_and_b32_sdwa v35, v28, v232 dst_sel:DWORD dst_unused:UNUSED_PAD src0_sel:WORD_1 src1_sel:DWORD
	v_add3_u32 v28, v28, v35, s43
	v_add3_u32 v30, v30, v34, s43
	v_and_b32_sdwa v34, v31, v232 dst_sel:DWORD dst_unused:UNUSED_PAD src0_sel:WORD_1 src1_sel:DWORD
	v_and_b32_sdwa v35, v29, v232 dst_sel:DWORD dst_unused:UNUSED_PAD src0_sel:WORD_1 src1_sel:DWORD
	v_add3_u32 v31, v31, v34, s43
	v_add3_u32 v29, v29, v35, s43
	v_lshl_add_u64 v[32:33], v[32:33], 1, v[152:153]
	v_and_b32_e32 v31, 0xffff0000, v31
	v_and_b32_e32 v34, 0xffff0000, v29
	v_lshl_add_u64 v[32:33], v[32:33], 0, v[128:129]
	v_or_b32_sdwa v29, v31, v30 dst_sel:DWORD dst_unused:UNUSED_PAD src0_sel:DWORD src1_sel:WORD_1
	v_or_b32_sdwa v28, v34, v28 dst_sel:DWORD dst_unused:UNUSED_PAD src0_sel:DWORD src1_sel:WORD_1
	s_nop 0
	v_mov_b32_e32 v212, v28
	v_mov_b32_e32 v213, v29
	v_and_b32_sdwa v28, v26, v232 dst_sel:DWORD dst_unused:UNUSED_PAD src0_sel:WORD_1 src1_sel:DWORD
	v_and_b32_sdwa v29, v24, v232 dst_sel:DWORD dst_unused:UNUSED_PAD src0_sel:WORD_1 src1_sel:DWORD
	v_add3_u32 v24, v24, v29, s43
	v_add3_u32 v26, v26, v28, s43
	v_and_b32_sdwa v28, v27, v232 dst_sel:DWORD dst_unused:UNUSED_PAD src0_sel:WORD_1 src1_sel:DWORD
	v_and_b32_sdwa v29, v25, v232 dst_sel:DWORD dst_unused:UNUSED_PAD src0_sel:WORD_1 src1_sel:DWORD
	v_add3_u32 v27, v27, v28, s43
	v_add3_u32 v25, v25, v29, s43
	v_and_b32_e32 v27, 0xffff0000, v27
	v_and_b32_e32 v28, 0xffff0000, v25
	v_or_b32_sdwa v25, v27, v26 dst_sel:DWORD dst_unused:UNUSED_PAD src0_sel:DWORD src1_sel:WORD_1
	v_or_b32_sdwa v24, v28, v24 dst_sel:DWORD dst_unused:UNUSED_PAD src0_sel:DWORD src1_sel:WORD_1
	s_nop 0
	v_mov_b32_e32 v214, v24
	v_mov_b32_e32 v215, v25
	v_mbcnt_lo_u32_b32 v224, -1, 0
	v_mbcnt_hi_u32_b32 v224, -1, v224
	v_and_b32_e32 v222, 16, v224
	v_lshrrev_b32_e32 v224, 1, v222
	v_add_u32_e32 v222, v222, v224
	v_mov_b32_e32 v223, 0
	v_lshl_add_u64 v[220:221], v[32:33], 0, v[222:223]
	v_permlane16_swap_b32_e32 v212, v214
	v_permlane16_swap_b32_e32 v213, v215
	global_store_dwordx4 v[220:221], v[212:215], off
	v_and_b32_sdwa v24, v22, v232 dst_sel:DWORD dst_unused:UNUSED_PAD src0_sel:WORD_1 src1_sel:DWORD
	v_and_b32_sdwa v25, v20, v232 dst_sel:DWORD dst_unused:UNUSED_PAD src0_sel:WORD_1 src1_sel:DWORD
	v_add3_u32 v20, v20, v25, s43
	v_add3_u32 v22, v22, v24, s43
	v_and_b32_sdwa v24, v23, v232 dst_sel:DWORD dst_unused:UNUSED_PAD src0_sel:WORD_1 src1_sel:DWORD
	v_and_b32_sdwa v25, v21, v232 dst_sel:DWORD dst_unused:UNUSED_PAD src0_sel:WORD_1 src1_sel:DWORD
	v_add3_u32 v23, v23, v24, s43
	v_add3_u32 v21, v21, v25, s43
	v_and_b32_e32 v23, 0xffff0000, v23
	v_and_b32_e32 v24, 0xffff0000, v21
	v_or_b32_sdwa v21, v23, v22 dst_sel:DWORD dst_unused:UNUSED_PAD src0_sel:DWORD src1_sel:WORD_1
	v_or_b32_sdwa v20, v24, v20 dst_sel:DWORD dst_unused:UNUSED_PAD src0_sel:DWORD src1_sel:WORD_1
	s_nop 0
	v_mov_b32_e32 v216, v20
	v_mov_b32_e32 v217, v21
	v_and_b32_sdwa v20, v18, v232 dst_sel:DWORD dst_unused:UNUSED_PAD src0_sel:WORD_1 src1_sel:DWORD
	v_and_b32_sdwa v21, v16, v232 dst_sel:DWORD dst_unused:UNUSED_PAD src0_sel:WORD_1 src1_sel:DWORD
	v_add3_u32 v16, v16, v21, s43
	v_add3_u32 v18, v18, v20, s43
	v_and_b32_sdwa v20, v19, v232 dst_sel:DWORD dst_unused:UNUSED_PAD src0_sel:WORD_1 src1_sel:DWORD
	v_and_b32_sdwa v21, v17, v232 dst_sel:DWORD dst_unused:UNUSED_PAD src0_sel:WORD_1 src1_sel:DWORD
	v_add3_u32 v19, v19, v20, s43
	v_add3_u32 v17, v17, v21, s43
	v_and_b32_e32 v19, 0xffff0000, v19
	v_and_b32_e32 v20, 0xffff0000, v17
	v_or_b32_sdwa v17, v19, v18 dst_sel:DWORD dst_unused:UNUSED_PAD src0_sel:DWORD src1_sel:WORD_1
	v_or_b32_sdwa v16, v20, v16 dst_sel:DWORD dst_unused:UNUSED_PAD src0_sel:DWORD src1_sel:WORD_1
	s_nop 0
	v_mov_b32_e32 v218, v16
	v_mov_b32_e32 v219, v17
	s_nop 1
	v_permlane16_swap_b32_e32 v216, v218
	v_permlane16_swap_b32_e32 v217, v219
	global_store_dwordx4 v[220:221], v[216:219], off offset:64
	s_and_b64 s[16:17], s[4:5], s[14:15]
	s_and_saveexec_b64 s[14:15], s[16:17]
	s_cbranch_execz .LBB0_270
; #define ST4(ptr, a, b, c_, d) (*(uint2*)(ptr) = make_uint2((unsigned)f2bf(a) | ((unsigned)f2bf(b) << 16), (unsigned)f2bf(c_) | ((unsigned)f2bf(d) << 16)))
; __device__ __forceinline__ void upproj_phase(const Ctx& p, int hf) {
;     ...
;     u16* dst; int ldc, c0;
;     if (pn < 3) { dst = (u16*)(p.ws + A_QM); ldc = 768; c0 = pn * 256; }
;     else if (wc < 2) { dst = (u16*)(p.ws + A_KM); ldc = 768; c0 = h * 192; }
;     else { dst = (u16*)(p.ws + A_VM); ldc = 512; c0 = h * 128 - 128; }
;     ACC_LOOP( ST4(dst + (size_t)row * ldc + c0 + col, v4[0], v4[1], v4[2], v4[3]); )
	v_add_u32_e32 v16, s73, v167
	v_ashrrev_i32_e32 v17, 31, v16
	v_mul_lo_u32 v18, v148, v17
	v_mul_lo_u32 v19, v149, v16
	v_mad_u64_u32 v[16:17], s[16:17], v148, v16, 0
	v_add3_u32 v17, v17, v18, v19
	v_and_b32_sdwa v18, v14, v232 dst_sel:DWORD dst_unused:UNUSED_PAD src0_sel:WORD_1 src1_sel:DWORD
	v_and_b32_sdwa v19, v12, v232 dst_sel:DWORD dst_unused:UNUSED_PAD src0_sel:WORD_1 src1_sel:DWORD
	v_add3_u32 v12, v12, v19, s43
	v_add3_u32 v14, v14, v18, s43
	v_and_b32_sdwa v18, v15, v232 dst_sel:DWORD dst_unused:UNUSED_PAD src0_sel:WORD_1 src1_sel:DWORD
	v_and_b32_sdwa v19, v13, v232 dst_sel:DWORD dst_unused:UNUSED_PAD src0_sel:WORD_1 src1_sel:DWORD
	v_lshl_add_u64 v[16:17], v[16:17], 1, v[146:147]
	v_add3_u32 v15, v15, v18, s43
	v_add3_u32 v13, v13, v19, s43
	v_lshl_add_u64 v[16:17], v[150:151], 1, v[16:17]
	v_and_b32_e32 v15, 0xffff0000, v15
	v_and_b32_e32 v18, 0xffff0000, v13
	v_lshl_add_u64 v[16:17], v[16:17], 0, v[128:129]
	v_or_b32_sdwa v13, v15, v14 dst_sel:DWORD dst_unused:UNUSED_PAD src0_sel:DWORD src1_sel:WORD_1
	v_or_b32_sdwa v12, v18, v12 dst_sel:DWORD dst_unused:UNUSED_PAD src0_sel:DWORD src1_sel:WORD_1
	s_nop 0
	v_mov_b32_e32 v212, v12
	v_mov_b32_e32 v213, v13
	v_and_b32_sdwa v12, v10, v232 dst_sel:DWORD dst_unused:UNUSED_PAD src0_sel:WORD_1 src1_sel:DWORD
	v_and_b32_sdwa v13, v8, v232 dst_sel:DWORD dst_unused:UNUSED_PAD src0_sel:WORD_1 src1_sel:DWORD
	v_add3_u32 v8, v8, v13, s43
	v_add3_u32 v10, v10, v12, s43
	v_and_b32_sdwa v12, v11, v232 dst_sel:DWORD dst_unused:UNUSED_PAD src0_sel:WORD_1 src1_sel:DWORD
	v_and_b32_sdwa v13, v9, v232 dst_sel:DWORD dst_unused:UNUSED_PAD src0_sel:WORD_1 src1_sel:DWORD
	v_add3_u32 v11, v11, v12, s43
	v_add3_u32 v9, v9, v13, s43
	v_and_b32_e32 v11, 0xffff0000, v11
	v_and_b32_e32 v12, 0xffff0000, v9
	v_or_b32_sdwa v9, v11, v10 dst_sel:DWORD dst_unused:UNUSED_PAD src0_sel:DWORD src1_sel:WORD_1
	v_or_b32_sdwa v8, v12, v8 dst_sel:DWORD dst_unused:UNUSED_PAD src0_sel:DWORD src1_sel:WORD_1
	s_nop 0
	v_mov_b32_e32 v214, v8
	v_mov_b32_e32 v215, v9
	v_mbcnt_lo_u32_b32 v224, -1, 0
	v_mbcnt_hi_u32_b32 v224, -1, v224
	v_and_b32_e32 v222, 16, v224
	v_lshrrev_b32_e32 v224, 1, v222
	v_add_u32_e32 v222, v222, v224
	v_mov_b32_e32 v223, 0
	v_lshl_add_u64 v[220:221], v[16:17], 0, v[222:223]
	v_permlane16_swap_b32_e32 v212, v214
	v_permlane16_swap_b32_e32 v213, v215
	global_store_dwordx4 v[220:221], v[212:215], off
	v_and_b32_sdwa v8, v6, v232 dst_sel:DWORD dst_unused:UNUSED_PAD src0_sel:WORD_1 src1_sel:DWORD
	v_and_b32_sdwa v9, v4, v232 dst_sel:DWORD dst_unused:UNUSED_PAD src0_sel:WORD_1 src1_sel:DWORD
	v_add3_u32 v4, v4, v9, s43
	v_add3_u32 v6, v6, v8, s43
	v_and_b32_sdwa v8, v7, v232 dst_sel:DWORD dst_unused:UNUSED_PAD src0_sel:WORD_1 src1_sel:DWORD
	v_and_b32_sdwa v9, v5, v232 dst_sel:DWORD dst_unused:UNUSED_PAD src0_sel:WORD_1 src1_sel:DWORD
	v_add3_u32 v7, v7, v8, s43
	v_add3_u32 v5, v5, v9, s43
	v_and_b32_e32 v7, 0xffff0000, v7
	v_and_b32_e32 v8, 0xffff0000, v5
	v_or_b32_sdwa v5, v7, v6 dst_sel:DWORD dst_unused:UNUSED_PAD src0_sel:DWORD src1_sel:WORD_1
	v_or_b32_sdwa v4, v8, v4 dst_sel:DWORD dst_unused:UNUSED_PAD src0_sel:DWORD src1_sel:WORD_1
	s_nop 0
	v_mov_b32_e32 v216, v4
	v_mov_b32_e32 v217, v5
	v_and_b32_sdwa v4, v2, v232 dst_sel:DWORD dst_unused:UNUSED_PAD src0_sel:WORD_1 src1_sel:DWORD
	v_and_b32_sdwa v5, v0, v232 dst_sel:DWORD dst_unused:UNUSED_PAD src0_sel:WORD_1 src1_sel:DWORD
	v_add3_u32 v0, v0, v5, s43
	v_add3_u32 v2, v2, v4, s43
	v_and_b32_sdwa v4, v3, v232 dst_sel:DWORD dst_unused:UNUSED_PAD src0_sel:WORD_1 src1_sel:DWORD
	v_and_b32_sdwa v5, v1, v232 dst_sel:DWORD dst_unused:UNUSED_PAD src0_sel:WORD_1 src1_sel:DWORD
	v_add3_u32 v3, v3, v4, s43
	v_add3_u32 v1, v1, v5, s43
	v_and_b32_e32 v3, 0xffff0000, v3
	v_and_b32_e32 v4, 0xffff0000, v1
	v_or_b32_sdwa v1, v3, v2 dst_sel:DWORD dst_unused:UNUSED_PAD src0_sel:DWORD src1_sel:WORD_1
	v_or_b32_sdwa v0, v4, v0 dst_sel:DWORD dst_unused:UNUSED_PAD src0_sel:DWORD src1_sel:WORD_1
	s_nop 0
	v_mov_b32_e32 v218, v0
	v_mov_b32_e32 v219, v1
	s_nop 1
	v_permlane16_swap_b32_e32 v216, v218
	v_permlane16_swap_b32_e32 v217, v219
	global_store_dwordx4 v[220:221], v[216:219], off offset:64
	s_branch .LBB0_270

; #define ST4(ptr, a, b, c_, d) (*(uint2*)(ptr) = make_uint2((unsigned)f2bf(a) | ((unsigned)f2bf(b) << 16), (unsigned)f2bf(c_) | ((unsigned)f2bf(d) << 16)))
; template <int EPI>
; __device__ __forceinline__ void gemm_phase(const Ctx& p, int hf, const u16* __restrict__ A, int lda, const u16* __restrict__ Bt, int K, int nN, u16* __restrict__ dst, int ldc, bool fromx = false) {
;     ...
;     else if constexpr (EPI == EPI_SIGMOID) { ACC_LOOP( _Pragma("unroll") for (int e = 0; e < 4; ++e) v4[e] = __builtin_amdgcn_rcpf(1.f + __expf(-v4[e]));
;                                                         ST4(dst + (size_t)row * ldc + bcol + col, v4[0], v4[1], v4[2], v4[3]); ) }
.LBB0_1305:
	s_or_b64 exec, exec, s[18:19]
	v_mul_f32_e32 v142, 0xbfb8aa3b, v142
	v_mul_f32_e32 v144, 0xbfb8aa3b, v144
	v_exp_f32_e32 v149, v142
	v_mul_f32_e32 v142, 0xbfb8aa3b, v143
	v_exp_f32_e32 v144, v144
	v_mul_f32_e32 v145, 0xbfb8aa3b, v145
	v_exp_f32_e32 v150, v142
	v_exp_f32_e32 v145, v145
	v_add_f32_e32 v149, 1.0, v149
	v_add_f32_e32 v144, 1.0, v144
	v_mul_f32_e32 v138, 0xbfb8aa3b, v138
	v_mul_f32_e32 v140, 0xbfb8aa3b, v140
	v_rcp_f32_e32 v149, v149
	v_add_f32_e32 v150, 1.0, v150
	v_rcp_f32_e32 v144, v144
	v_add_f32_e32 v145, 1.0, v145
	v_exp_f32_e32 v138, v138
	v_mul_f32_e32 v139, 0xbfb8aa3b, v139
	v_exp_f32_e32 v140, v140
	v_mul_f32_e32 v141, 0xbfb8aa3b, v141
	v_rcp_f32_e32 v150, v150
	v_rcp_f32_e32 v145, v145
	v_exp_f32_e32 v139, v139
	v_exp_f32_e32 v141, v141
	s_lshl_b64 s[0:1], s[12:13], 1
	s_add_u32 s0, s4, s0
	v_and_b32_sdwa v151, v144, v232 dst_sel:DWORD dst_unused:UNUSED_PAD src0_sel:WORD_1 src1_sel:DWORD
	v_and_b32_sdwa v152, v149, v232 dst_sel:DWORD dst_unused:UNUSED_PAD src0_sel:WORD_1 src1_sel:DWORD
	v_add_f32_e32 v138, 1.0, v138
	v_add_f32_e32 v140, 1.0, v140
	v_mul_f32_e32 v134, 0xbfb8aa3b, v134
	v_mul_f32_e32 v136, 0xbfb8aa3b, v136
	s_addc_u32 s1, s5, s1
	v_add3_u32 v149, v149, v152, s43
	v_add3_u32 v144, v144, v151, s43
	v_and_b32_sdwa v151, v145, v232 dst_sel:DWORD dst_unused:UNUSED_PAD src0_sel:WORD_1 src1_sel:DWORD
	v_and_b32_sdwa v152, v150, v232 dst_sel:DWORD dst_unused:UNUSED_PAD src0_sel:WORD_1 src1_sel:DWORD
	v_rcp_f32_e32 v138, v138
	v_add_f32_e32 v139, 1.0, v139
	v_rcp_f32_e32 v140, v140
	v_add_f32_e32 v141, 1.0, v141
	v_exp_f32_e32 v134, v134
	v_mul_f32_e32 v135, 0xbfb8aa3b, v135
	v_exp_f32_e32 v136, v136
	v_mul_f32_e32 v137, 0xbfb8aa3b, v137
	v_add_u32_e32 v148, s14, v181
	v_mov_b64_e32 v[146:147], s[0:1]
	v_add3_u32 v145, v145, v151, s43
	v_add3_u32 v150, v150, v152, s43
	v_rcp_f32_e32 v139, v139
	v_rcp_f32_e32 v141, v141
	v_exp_f32_e32 v135, v135
	v_exp_f32_e32 v137, v137
	v_mad_i64_i32 v[142:143], s[0:1], v148, s84, v[146:147]
	v_and_b32_e32 v145, 0xffff0000, v145
	v_and_b32_e32 v150, 0xffff0000, v150
	v_lshl_add_u64 v[142:143], v[142:143], 0, v[128:129]
	v_or_b32_sdwa v145, v145, v144 dst_sel:DWORD dst_unused:UNUSED_PAD src0_sel:DWORD src1_sel:WORD_1
	v_or_b32_sdwa v144, v150, v149 dst_sel:DWORD dst_unused:UNUSED_PAD src0_sel:DWORD src1_sel:WORD_1
	s_waitcnt vmcnt(0)
	s_barrier
	s_nop 0
	v_mov_b32_e32 v212, v144
	v_mov_b32_e32 v213, v145
	v_and_b32_sdwa v144, v140, v232 dst_sel:DWORD dst_unused:UNUSED_PAD src0_sel:WORD_1 src1_sel:DWORD
	v_and_b32_sdwa v145, v138, v232 dst_sel:DWORD dst_unused:UNUSED_PAD src0_sel:WORD_1 src1_sel:DWORD
	v_add_f32_e32 v134, 1.0, v134
	v_add_f32_e32 v136, 1.0, v136
	v_mul_f32_e32 v130, 0xbfb8aa3b, v130
	v_mul_f32_e32 v132, 0xbfb8aa3b, v132
	v_add3_u32 v138, v138, v145, s43
	v_add3_u32 v140, v140, v144, s43
	v_and_b32_sdwa v144, v141, v232 dst_sel:DWORD dst_unused:UNUSED_PAD src0_sel:WORD_1 src1_sel:DWORD
	v_and_b32_sdwa v145, v139, v232 dst_sel:DWORD dst_unused:UNUSED_PAD src0_sel:WORD_1 src1_sel:DWORD
	v_rcp_f32_e32 v134, v134
	v_add_f32_e32 v135, 1.0, v135
	v_rcp_f32_e32 v136, v136
	v_add_f32_e32 v137, 1.0, v137
	v_exp_f32_e32 v130, v130
	v_mul_f32_e32 v131, 0xbfb8aa3b, v131
	v_exp_f32_e32 v132, v132
	v_mul_f32_e32 v133, 0xbfb8aa3b, v133
	v_add3_u32 v141, v141, v144, s43
	v_add3_u32 v139, v139, v145, s43
	v_rcp_f32_e32 v135, v135
	v_rcp_f32_e32 v137, v137
	v_exp_f32_e32 v131, v131
	v_exp_f32_e32 v133, v133
	v_and_b32_e32 v141, 0xffff0000, v141
	v_and_b32_e32 v144, 0xffff0000, v139
	v_or_b32_sdwa v139, v141, v140 dst_sel:DWORD dst_unused:UNUSED_PAD src0_sel:DWORD src1_sel:WORD_1
	v_or_b32_sdwa v138, v144, v138 dst_sel:DWORD dst_unused:UNUSED_PAD src0_sel:DWORD src1_sel:WORD_1
	s_nop 0
	v_mov_b32_e32 v214, v138
	v_mov_b32_e32 v215, v139
	v_mbcnt_lo_u32_b32 v224, -1, 0
	v_mbcnt_hi_u32_b32 v224, -1, v224
	v_and_b32_e32 v222, 16, v224
	v_lshrrev_b32_e32 v224, 1, v222
	v_add_u32_e32 v222, v222, v224
	v_mov_b32_e32 v223, 0
	v_lshl_add_u64 v[220:221], v[142:143], 0, v[222:223]
	v_permlane16_swap_b32_e32 v212, v214
	v_permlane16_swap_b32_e32 v213, v215
	global_store_dwordx4 v[220:221], v[212:215], off
	v_and_b32_sdwa v138, v136, v232 dst_sel:DWORD dst_unused:UNUSED_PAD src0_sel:WORD_1 src1_sel:DWORD
	v_and_b32_sdwa v139, v134, v232 dst_sel:DWORD dst_unused:UNUSED_PAD src0_sel:WORD_1 src1_sel:DWORD
	v_add_f32_e32 v130, 1.0, v130
	v_add_f32_e32 v132, 1.0, v132
	v_add3_u32 v134, v134, v139, s43
	v_add3_u32 v136, v136, v138, s43
	v_and_b32_sdwa v138, v137, v232 dst_sel:DWORD dst_unused:UNUSED_PAD src0_sel:WORD_1 src1_sel:DWORD
	v_and_b32_sdwa v139, v135, v232 dst_sel:DWORD dst_unused:UNUSED_PAD src0_sel:WORD_1 src1_sel:DWORD
	v_rcp_f32_e32 v130, v130
	v_add_f32_e32 v131, 1.0, v131
	v_rcp_f32_e32 v132, v132
	v_add_f32_e32 v133, 1.0, v133
	v_add3_u32 v137, v137, v138, s43
	v_add3_u32 v135, v135, v139, s43
	v_rcp_f32_e32 v131, v131
	v_rcp_f32_e32 v133, v133
	v_and_b32_e32 v137, 0xffff0000, v137
	v_and_b32_e32 v138, 0xffff0000, v135
	v_or_b32_sdwa v135, v137, v136 dst_sel:DWORD dst_unused:UNUSED_PAD src0_sel:DWORD src1_sel:WORD_1
	v_or_b32_sdwa v134, v138, v134 dst_sel:DWORD dst_unused:UNUSED_PAD src0_sel:DWORD src1_sel:WORD_1
	s_nop 0
	v_mov_b32_e32 v216, v134
	v_mov_b32_e32 v217, v135
	v_and_b32_sdwa v134, v132, v232 dst_sel:DWORD dst_unused:UNUSED_PAD src0_sel:WORD_1 src1_sel:DWORD
	v_and_b32_sdwa v135, v130, v232 dst_sel:DWORD dst_unused:UNUSED_PAD src0_sel:WORD_1 src1_sel:DWORD
	v_add3_u32 v130, v130, v135, s43
	v_add3_u32 v132, v132, v134, s43
	v_and_b32_sdwa v134, v133, v232 dst_sel:DWORD dst_unused:UNUSED_PAD src0_sel:WORD_1 src1_sel:DWORD
; #define ST4(ptr, a, b, c_, d) (*(uint2*)(ptr) = make_uint2((unsigned)f2bf(a) | ((unsigned)f2bf(b) << 16), (unsigned)f2bf(c_) | ((unsigned)f2bf(d) << 16)))
; template <int EPI>
; __device__ __forceinline__ void gemm_phase(const Ctx& p, int hf, const u16* __restrict__ A, int lda, const u16* __restrict__ Bt, int K, int nN, u16* __restrict__ dst, int ldc, bool fromx = false) {
;     ...
;     else if constexpr (EPI == EPI_SIGMOID) { ACC_LOOP( _Pragma("unroll") for (int e = 0; e < 4; ++e) v4[e] = __builtin_amdgcn_rcpf(1.f + __expf(-v4[e]));
;                                                         ST4(dst + (size_t)row * ldc + bcol + col, v4[0], v4[1], v4[2], v4[3]); ) }
	v_and_b32_sdwa v135, v131, v232 dst_sel:DWORD dst_unused:UNUSED_PAD src0_sel:WORD_1 src1_sel:DWORD
	v_add3_u32 v133, v133, v134, s43
	v_add3_u32 v131, v131, v135, s43
	v_and_b32_e32 v133, 0xffff0000, v133
	v_and_b32_e32 v134, 0xffff0000, v131
	v_or_b32_sdwa v131, v133, v132 dst_sel:DWORD dst_unused:UNUSED_PAD src0_sel:DWORD src1_sel:WORD_1
	v_or_b32_sdwa v130, v134, v130 dst_sel:DWORD dst_unused:UNUSED_PAD src0_sel:DWORD src1_sel:WORD_1
	s_nop 0
	v_mov_b32_e32 v218, v130
	v_mov_b32_e32 v219, v131
	s_nop 1
	v_permlane16_swap_b32_e32 v216, v218
	v_permlane16_swap_b32_e32 v217, v219
	global_store_dwordx4 v[220:221], v[216:219], off offset:64
	v_mul_f32_e32 v124, 0xbfb8aa3b, v124
	v_mul_f32_e32 v126, 0xbfb8aa3b, v126
	v_exp_f32_e32 v131, v124
	v_mul_f32_e32 v124, 0xbfb8aa3b, v125
	v_exp_f32_e32 v126, v126
	v_mul_f32_e32 v127, 0xbfb8aa3b, v127
	v_exp_f32_e32 v132, v124
	v_exp_f32_e32 v127, v127
	v_add_u32_e32 v130, 16, v148
	v_mad_i64_i32 v[124:125], s[0:1], v130, s84, v[146:147]
	v_add_f32_e32 v130, 1.0, v131
	v_add_f32_e32 v126, 1.0, v126
	v_mul_f32_e32 v120, 0xbfb8aa3b, v120
	v_mul_f32_e32 v122, 0xbfb8aa3b, v122
	v_rcp_f32_e32 v130, v130
	v_add_f32_e32 v131, 1.0, v132
	v_rcp_f32_e32 v126, v126
	v_add_f32_e32 v127, 1.0, v127
	v_exp_f32_e32 v120, v120
	v_mul_f32_e32 v121, 0xbfb8aa3b, v121
	v_exp_f32_e32 v122, v122
	v_mul_f32_e32 v123, 0xbfb8aa3b, v123
	v_rcp_f32_e32 v131, v131
	v_rcp_f32_e32 v127, v127
	v_exp_f32_e32 v121, v121
	v_exp_f32_e32 v123, v123
	v_and_b32_sdwa v132, v126, v232 dst_sel:DWORD dst_unused:UNUSED_PAD src0_sel:WORD_1 src1_sel:DWORD
	v_and_b32_sdwa v133, v130, v232 dst_sel:DWORD dst_unused:UNUSED_PAD src0_sel:WORD_1 src1_sel:DWORD
	v_add_f32_e32 v120, 1.0, v120
	v_add_f32_e32 v122, 1.0, v122
	v_mul_f32_e32 v116, 0xbfb8aa3b, v116
	v_mul_f32_e32 v118, 0xbfb8aa3b, v118
	v_add3_u32 v130, v130, v133, s43
	v_add3_u32 v126, v126, v132, s43
	v_and_b32_sdwa v132, v127, v232 dst_sel:DWORD dst_unused:UNUSED_PAD src0_sel:WORD_1 src1_sel:DWORD
	v_and_b32_sdwa v133, v131, v232 dst_sel:DWORD dst_unused:UNUSED_PAD src0_sel:WORD_1 src1_sel:DWORD
	v_rcp_f32_e32 v120, v120
	v_add_f32_e32 v121, 1.0, v121
	v_rcp_f32_e32 v122, v122
	v_add_f32_e32 v123, 1.0, v123
	v_exp_f32_e32 v116, v116
	v_mul_f32_e32 v117, 0xbfb8aa3b, v117
	v_exp_f32_e32 v118, v118
	v_mul_f32_e32 v119, 0xbfb8aa3b, v119
	v_add3_u32 v127, v127, v132, s43
	v_add3_u32 v131, v131, v133, s43
	v_rcp_f32_e32 v121, v121
	v_rcp_f32_e32 v123, v123
	v_exp_f32_e32 v117, v117
	v_exp_f32_e32 v119, v119
	v_and_b32_e32 v127, 0xffff0000, v127
	v_and_b32_e32 v131, 0xffff0000, v131
	v_lshl_add_u64 v[124:125], v[124:125], 0, v[128:129]
	v_or_b32_sdwa v127, v127, v126 dst_sel:DWORD dst_unused:UNUSED_PAD src0_sel:DWORD src1_sel:WORD_1
	v_or_b32_sdwa v126, v131, v130 dst_sel:DWORD dst_unused:UNUSED_PAD src0_sel:DWORD src1_sel:WORD_1
	s_nop 0
	v_mov_b32_e32 v212, v126
	v_mov_b32_e32 v213, v127
	v_and_b32_sdwa v126, v122, v232 dst_sel:DWORD dst_unused:UNUSED_PAD src0_sel:WORD_1 src1_sel:DWORD
	v_and_b32_sdwa v127, v120, v232 dst_sel:DWORD dst_unused:UNUSED_PAD src0_sel:WORD_1 src1_sel:DWORD
	v_add_f32_e32 v116, 1.0, v116
	v_add_f32_e32 v118, 1.0, v118
	v_mul_f32_e32 v112, 0xbfb8aa3b, v112
	v_mul_f32_e32 v114, 0xbfb8aa3b, v114
	v_add3_u32 v120, v120, v127, s43
	v_add3_u32 v122, v122, v126, s43
	v_and_b32_sdwa v126, v123, v232 dst_sel:DWORD dst_unused:UNUSED_PAD src0_sel:WORD_1 src1_sel:DWORD
	v_and_b32_sdwa v127, v121, v232 dst_sel:DWORD dst_unused:UNUSED_PAD src0_sel:WORD_1 src1_sel:DWORD
	v_rcp_f32_e32 v116, v116
	v_add_f32_e32 v117, 1.0, v117
	v_rcp_f32_e32 v118, v118
	v_add_f32_e32 v119, 1.0, v119
	v_exp_f32_e32 v112, v112
	v_mul_f32_e32 v113, 0xbfb8aa3b, v113
	v_exp_f32_e32 v114, v114
	v_mul_f32_e32 v115, 0xbfb8aa3b, v115
	v_add3_u32 v123, v123, v126, s43
	v_add3_u32 v121, v121, v127, s43
	v_rcp_f32_e32 v117, v117
	v_rcp_f32_e32 v119, v119
	v_exp_f32_e32 v113, v113
	v_exp_f32_e32 v115, v115
	v_and_b32_e32 v123, 0xffff0000, v123
	v_and_b32_e32 v126, 0xffff0000, v121
	v_or_b32_sdwa v121, v123, v122 dst_sel:DWORD dst_unused:UNUSED_PAD src0_sel:DWORD src1_sel:WORD_1
	v_or_b32_sdwa v120, v126, v120 dst_sel:DWORD dst_unused:UNUSED_PAD src0_sel:DWORD src1_sel:WORD_1
	s_nop 0
	v_mov_b32_e32 v214, v120
	v_mov_b32_e32 v215, v121
	v_mbcnt_lo_u32_b32 v224, -1, 0
	v_mbcnt_hi_u32_b32 v224, -1, v224
	v_and_b32_e32 v222, 16, v224
	v_lshrrev_b32_e32 v224, 1, v222
	v_add_u32_e32 v222, v222, v224
	v_mov_b32_e32 v223, 0
	v_lshl_add_u64 v[220:221], v[124:125], 0, v[222:223]
	v_permlane16_swap_b32_e32 v212, v214
	v_permlane16_swap_b32_e32 v213, v215
	global_store_dwordx4 v[220:221], v[212:215], off
	v_and_b32_sdwa v120, v118, v232 dst_sel:DWORD dst_unused:UNUSED_PAD src0_sel:WORD_1 src1_sel:DWORD
	v_and_b32_sdwa v121, v116, v232 dst_sel:DWORD dst_unused:UNUSED_PAD src0_sel:WORD_1 src1_sel:DWORD
	v_add_f32_e32 v112, 1.0, v112
	v_add_f32_e32 v114, 1.0, v114
	v_add3_u32 v116, v116, v121, s43
	v_add3_u32 v118, v118, v120, s43
	v_and_b32_sdwa v120, v119, v232 dst_sel:DWORD dst_unused:UNUSED_PAD src0_sel:WORD_1 src1_sel:DWORD
	v_and_b32_sdwa v121, v117, v232 dst_sel:DWORD dst_unused:UNUSED_PAD src0_sel:WORD_1 src1_sel:DWORD
	v_rcp_f32_e32 v112, v112
	v_add_f32_e32 v113, 1.0, v113
	v_rcp_f32_e32 v114, v114
	v_add_f32_e32 v115, 1.0, v115
	v_add3_u32 v119, v119, v120, s43
	v_add3_u32 v117, v117, v121, s43
	v_rcp_f32_e32 v113, v113
	v_rcp_f32_e32 v115, v115
	v_and_b32_e32 v119, 0xffff0000, v119
	v_and_b32_e32 v120, 0xffff0000, v117
	v_or_b32_sdwa v117, v119, v118 dst_sel:DWORD dst_unused:UNUSED_PAD src0_sel:DWORD src1_sel:WORD_1
	v_or_b32_sdwa v116, v120, v116 dst_sel:DWORD dst_unused:UNUSED_PAD src0_sel:DWORD src1_sel:WORD_1
; #define ST4(ptr, a, b, c_, d) (*(uint2*)(ptr) = make_uint2((unsigned)f2bf(a) | ((unsigned)f2bf(b) << 16), (unsigned)f2bf(c_) | ((unsigned)f2bf(d) << 16)))
; template <int EPI>
; __device__ __forceinline__ void gemm_phase(const Ctx& p, int hf, const u16* __restrict__ A, int lda, const u16* __restrict__ Bt, int K, int nN, u16* __restrict__ dst, int ldc, bool fromx = false) {
;     ...
;     else if constexpr (EPI == EPI_SIGMOID) { ACC_LOOP( _Pragma("unroll") for (int e = 0; e < 4; ++e) v4[e] = __builtin_amdgcn_rcpf(1.f + __expf(-v4[e]));
;                                                         ST4(dst + (size_t)row * ldc + bcol + col, v4[0], v4[1], v4[2], v4[3]); ) }
	s_nop 0
	v_mov_b32_e32 v216, v116
	v_mov_b32_e32 v217, v117
	v_and_b32_sdwa v116, v114, v232 dst_sel:DWORD dst_unused:UNUSED_PAD src0_sel:WORD_1 src1_sel:DWORD
	v_and_b32_sdwa v117, v112, v232 dst_sel:DWORD dst_unused:UNUSED_PAD src0_sel:WORD_1 src1_sel:DWORD
	v_add3_u32 v112, v112, v117, s43
	v_add3_u32 v114, v114, v116, s43
	v_and_b32_sdwa v116, v115, v232 dst_sel:DWORD dst_unused:UNUSED_PAD src0_sel:WORD_1 src1_sel:DWORD
	v_and_b32_sdwa v117, v113, v232 dst_sel:DWORD dst_unused:UNUSED_PAD src0_sel:WORD_1 src1_sel:DWORD
	v_add3_u32 v115, v115, v116, s43
	v_add3_u32 v113, v113, v117, s43
	v_and_b32_e32 v115, 0xffff0000, v115
	v_and_b32_e32 v116, 0xffff0000, v113
	v_or_b32_sdwa v113, v115, v114 dst_sel:DWORD dst_unused:UNUSED_PAD src0_sel:DWORD src1_sel:WORD_1
	v_or_b32_sdwa v112, v116, v112 dst_sel:DWORD dst_unused:UNUSED_PAD src0_sel:DWORD src1_sel:WORD_1
	s_nop 0
	v_mov_b32_e32 v218, v112
	v_mov_b32_e32 v219, v113
	s_nop 1
	v_permlane16_swap_b32_e32 v216, v218
	v_permlane16_swap_b32_e32 v217, v219
	global_store_dwordx4 v[220:221], v[216:219], off offset:64
	v_mul_f32_e32 v108, 0xbfb8aa3b, v108
	v_mul_f32_e32 v110, 0xbfb8aa3b, v110
	v_exp_f32_e32 v113, v108
	v_mul_f32_e32 v108, 0xbfb8aa3b, v109
	v_exp_f32_e32 v110, v110
	v_mul_f32_e32 v111, 0xbfb8aa3b, v111
	v_exp_f32_e32 v114, v108
	v_exp_f32_e32 v111, v111
	v_add_u32_e32 v112, 32, v148
	v_mad_i64_i32 v[108:109], s[0:1], v112, s84, v[146:147]
	v_add_f32_e32 v112, 1.0, v113
	v_add_f32_e32 v110, 1.0, v110
	v_mul_f32_e32 v104, 0xbfb8aa3b, v104
	v_mul_f32_e32 v106, 0xbfb8aa3b, v106
	v_rcp_f32_e32 v112, v112
	v_add_f32_e32 v113, 1.0, v114
	v_rcp_f32_e32 v110, v110
	v_add_f32_e32 v111, 1.0, v111
	v_exp_f32_e32 v104, v104
	v_mul_f32_e32 v105, 0xbfb8aa3b, v105
	v_exp_f32_e32 v106, v106
	v_mul_f32_e32 v107, 0xbfb8aa3b, v107
	v_rcp_f32_e32 v113, v113
	v_rcp_f32_e32 v111, v111
	v_exp_f32_e32 v105, v105
	v_exp_f32_e32 v107, v107
	v_and_b32_sdwa v114, v110, v232 dst_sel:DWORD dst_unused:UNUSED_PAD src0_sel:WORD_1 src1_sel:DWORD
	v_and_b32_sdwa v115, v112, v232 dst_sel:DWORD dst_unused:UNUSED_PAD src0_sel:WORD_1 src1_sel:DWORD
	v_add_f32_e32 v104, 1.0, v104
	v_add_f32_e32 v106, 1.0, v106
	v_mul_f32_e32 v100, 0xbfb8aa3b, v100
	v_mul_f32_e32 v102, 0xbfb8aa3b, v102
	v_add3_u32 v112, v112, v115, s43
	v_add3_u32 v110, v110, v114, s43
	v_and_b32_sdwa v114, v111, v232 dst_sel:DWORD dst_unused:UNUSED_PAD src0_sel:WORD_1 src1_sel:DWORD
	v_and_b32_sdwa v115, v113, v232 dst_sel:DWORD dst_unused:UNUSED_PAD src0_sel:WORD_1 src1_sel:DWORD
	v_rcp_f32_e32 v104, v104
	v_add_f32_e32 v105, 1.0, v105
	v_rcp_f32_e32 v106, v106
	v_add_f32_e32 v107, 1.0, v107
	v_exp_f32_e32 v100, v100
	v_mul_f32_e32 v101, 0xbfb8aa3b, v101
	v_exp_f32_e32 v102, v102
	v_mul_f32_e32 v103, 0xbfb8aa3b, v103
	v_add3_u32 v111, v111, v114, s43
	v_add3_u32 v113, v113, v115, s43
	v_rcp_f32_e32 v105, v105
	v_rcp_f32_e32 v107, v107
	v_exp_f32_e32 v101, v101
	v_exp_f32_e32 v103, v103
	v_and_b32_e32 v111, 0xffff0000, v111
	v_and_b32_e32 v113, 0xffff0000, v113
	v_lshl_add_u64 v[108:109], v[108:109], 0, v[128:129]
	v_or_b32_sdwa v111, v111, v110 dst_sel:DWORD dst_unused:UNUSED_PAD src0_sel:DWORD src1_sel:WORD_1
	v_or_b32_sdwa v110, v113, v112 dst_sel:DWORD dst_unused:UNUSED_PAD src0_sel:DWORD src1_sel:WORD_1
	s_nop 0
	v_mov_b32_e32 v212, v110
	v_mov_b32_e32 v213, v111
	v_and_b32_sdwa v110, v106, v232 dst_sel:DWORD dst_unused:UNUSED_PAD src0_sel:WORD_1 src1_sel:DWORD
	v_and_b32_sdwa v111, v104, v232 dst_sel:DWORD dst_unused:UNUSED_PAD src0_sel:WORD_1 src1_sel:DWORD
	v_add_f32_e32 v100, 1.0, v100
	v_add_f32_e32 v102, 1.0, v102
	v_mul_f32_e32 v96, 0xbfb8aa3b, v96
	v_mul_f32_e32 v98, 0xbfb8aa3b, v98
	v_add3_u32 v104, v104, v111, s43
	v_add3_u32 v106, v106, v110, s43
	v_and_b32_sdwa v110, v107, v232 dst_sel:DWORD dst_unused:UNUSED_PAD src0_sel:WORD_1 src1_sel:DWORD
	v_and_b32_sdwa v111, v105, v232 dst_sel:DWORD dst_unused:UNUSED_PAD src0_sel:WORD_1 src1_sel:DWORD
	v_rcp_f32_e32 v100, v100
	v_add_f32_e32 v101, 1.0, v101
	v_rcp_f32_e32 v102, v102
	v_add_f32_e32 v103, 1.0, v103
	v_exp_f32_e32 v96, v96
	v_mul_f32_e32 v97, 0xbfb8aa3b, v97
	v_exp_f32_e32 v98, v98
	v_mul_f32_e32 v99, 0xbfb8aa3b, v99
	v_add3_u32 v107, v107, v110, s43
	v_add3_u32 v105, v105, v111, s43
	v_rcp_f32_e32 v101, v101
	v_rcp_f32_e32 v103, v103
	v_exp_f32_e32 v97, v97
	v_exp_f32_e32 v99, v99
	v_and_b32_e32 v107, 0xffff0000, v107
	v_and_b32_e32 v110, 0xffff0000, v105
	v_or_b32_sdwa v105, v107, v106 dst_sel:DWORD dst_unused:UNUSED_PAD src0_sel:DWORD src1_sel:WORD_1
	v_or_b32_sdwa v104, v110, v104 dst_sel:DWORD dst_unused:UNUSED_PAD src0_sel:DWORD src1_sel:WORD_1
	s_nop 0
	v_mov_b32_e32 v214, v104
	v_mov_b32_e32 v215, v105
	v_mbcnt_lo_u32_b32 v224, -1, 0
	v_mbcnt_hi_u32_b32 v224, -1, v224
	v_and_b32_e32 v222, 16, v224
	v_lshrrev_b32_e32 v224, 1, v222
	v_add_u32_e32 v222, v222, v224
	v_mov_b32_e32 v223, 0
	v_lshl_add_u64 v[220:221], v[108:109], 0, v[222:223]
	v_permlane16_swap_b32_e32 v212, v214
	v_permlane16_swap_b32_e32 v213, v215
	global_store_dwordx4 v[220:221], v[212:215], off
	v_and_b32_sdwa v104, v102, v232 dst_sel:DWORD dst_unused:UNUSED_PAD src0_sel:WORD_1 src1_sel:DWORD
	v_and_b32_sdwa v105, v100, v232 dst_sel:DWORD dst_unused:UNUSED_PAD src0_sel:WORD_1 src1_sel:DWORD
	v_add_f32_e32 v96, 1.0, v96
	v_add_f32_e32 v98, 1.0, v98
	v_add3_u32 v100, v100, v105, s43
	v_add3_u32 v102, v102, v104, s43
	v_and_b32_sdwa v104, v103, v232 dst_sel:DWORD dst_unused:UNUSED_PAD src0_sel:WORD_1 src1_sel:DWORD
	v_and_b32_sdwa v105, v101, v232 dst_sel:DWORD dst_unused:UNUSED_PAD src0_sel:WORD_1 src1_sel:DWORD
	v_rcp_f32_e32 v96, v96
	v_add_f32_e32 v97, 1.0, v97
	v_rcp_f32_e32 v98, v98
	v_add_f32_e32 v99, 1.0, v99
; #define ST4(ptr, a, b, c_, d) (*(uint2*)(ptr) = make_uint2((unsigned)f2bf(a) | ((unsigned)f2bf(b) << 16), (unsigned)f2bf(c_) | ((unsigned)f2bf(d) << 16)))
; template <int EPI>
; __device__ __forceinline__ void gemm_phase(const Ctx& p, int hf, const u16* __restrict__ A, int lda, const u16* __restrict__ Bt, int K, int nN, u16* __restrict__ dst, int ldc, bool fromx = false) {
;     ...
;     else if constexpr (EPI == EPI_SIGMOID) { ACC_LOOP( _Pragma("unroll") for (int e = 0; e < 4; ++e) v4[e] = __builtin_amdgcn_rcpf(1.f + __expf(-v4[e]));
;                                                         ST4(dst + (size_t)row * ldc + bcol + col, v4[0], v4[1], v4[2], v4[3]); ) }
	v_add3_u32 v103, v103, v104, s43
	v_add3_u32 v101, v101, v105, s43
	v_rcp_f32_e32 v97, v97
	v_rcp_f32_e32 v99, v99
	v_and_b32_e32 v103, 0xffff0000, v103
	v_and_b32_e32 v104, 0xffff0000, v101
	v_or_b32_sdwa v101, v103, v102 dst_sel:DWORD dst_unused:UNUSED_PAD src0_sel:DWORD src1_sel:WORD_1
	v_or_b32_sdwa v100, v104, v100 dst_sel:DWORD dst_unused:UNUSED_PAD src0_sel:DWORD src1_sel:WORD_1
	s_nop 0
	v_mov_b32_e32 v216, v100
	v_mov_b32_e32 v217, v101
	v_and_b32_sdwa v100, v98, v232 dst_sel:DWORD dst_unused:UNUSED_PAD src0_sel:WORD_1 src1_sel:DWORD
	v_and_b32_sdwa v101, v96, v232 dst_sel:DWORD dst_unused:UNUSED_PAD src0_sel:WORD_1 src1_sel:DWORD
	v_add3_u32 v96, v96, v101, s43
	v_add3_u32 v98, v98, v100, s43
	v_and_b32_sdwa v100, v99, v232 dst_sel:DWORD dst_unused:UNUSED_PAD src0_sel:WORD_1 src1_sel:DWORD
	v_and_b32_sdwa v101, v97, v232 dst_sel:DWORD dst_unused:UNUSED_PAD src0_sel:WORD_1 src1_sel:DWORD
	v_add3_u32 v99, v99, v100, s43
	v_add3_u32 v97, v97, v101, s43
	v_and_b32_e32 v99, 0xffff0000, v99
	v_and_b32_e32 v100, 0xffff0000, v97
	v_or_b32_sdwa v97, v99, v98 dst_sel:DWORD dst_unused:UNUSED_PAD src0_sel:DWORD src1_sel:WORD_1
	v_or_b32_sdwa v96, v100, v96 dst_sel:DWORD dst_unused:UNUSED_PAD src0_sel:DWORD src1_sel:WORD_1
	s_nop 0
	v_mov_b32_e32 v218, v96
	v_mov_b32_e32 v219, v97
	s_nop 1
	v_permlane16_swap_b32_e32 v216, v218
	v_permlane16_swap_b32_e32 v217, v219
	global_store_dwordx4 v[220:221], v[216:219], off offset:64
	v_mul_f32_e32 v92, 0xbfb8aa3b, v92
	v_mul_f32_e32 v94, 0xbfb8aa3b, v94
	v_exp_f32_e32 v97, v92
	v_mul_f32_e32 v92, 0xbfb8aa3b, v93
	v_exp_f32_e32 v94, v94
	v_mul_f32_e32 v95, 0xbfb8aa3b, v95
	v_exp_f32_e32 v98, v92
	v_exp_f32_e32 v95, v95
	v_add_u32_e32 v96, 48, v148
	v_mad_i64_i32 v[92:93], s[0:1], v96, s84, v[146:147]
	v_add_f32_e32 v96, 1.0, v97
	v_add_f32_e32 v94, 1.0, v94
	v_mul_f32_e32 v88, 0xbfb8aa3b, v88
	v_mul_f32_e32 v90, 0xbfb8aa3b, v90
	v_rcp_f32_e32 v96, v96
	v_add_f32_e32 v97, 1.0, v98
	v_rcp_f32_e32 v94, v94
	v_add_f32_e32 v95, 1.0, v95
	v_exp_f32_e32 v88, v88
	v_mul_f32_e32 v89, 0xbfb8aa3b, v89
	v_exp_f32_e32 v90, v90
	v_mul_f32_e32 v91, 0xbfb8aa3b, v91
	v_rcp_f32_e32 v97, v97
	v_rcp_f32_e32 v95, v95
	v_exp_f32_e32 v89, v89
	v_exp_f32_e32 v91, v91
	v_and_b32_sdwa v98, v94, v232 dst_sel:DWORD dst_unused:UNUSED_PAD src0_sel:WORD_1 src1_sel:DWORD
	v_and_b32_sdwa v99, v96, v232 dst_sel:DWORD dst_unused:UNUSED_PAD src0_sel:WORD_1 src1_sel:DWORD
	v_add_f32_e32 v88, 1.0, v88
	v_add_f32_e32 v90, 1.0, v90
	v_mul_f32_e32 v84, 0xbfb8aa3b, v84
	v_mul_f32_e32 v86, 0xbfb8aa3b, v86
	v_add3_u32 v96, v96, v99, s43
	v_add3_u32 v94, v94, v98, s43
	v_and_b32_sdwa v98, v95, v232 dst_sel:DWORD dst_unused:UNUSED_PAD src0_sel:WORD_1 src1_sel:DWORD
	v_and_b32_sdwa v99, v97, v232 dst_sel:DWORD dst_unused:UNUSED_PAD src0_sel:WORD_1 src1_sel:DWORD
	v_rcp_f32_e32 v88, v88
	v_add_f32_e32 v89, 1.0, v89
	v_rcp_f32_e32 v90, v90
	v_add_f32_e32 v91, 1.0, v91
	v_exp_f32_e32 v84, v84
	v_mul_f32_e32 v85, 0xbfb8aa3b, v85
	v_exp_f32_e32 v86, v86
	v_mul_f32_e32 v87, 0xbfb8aa3b, v87
	v_add3_u32 v95, v95, v98, s43
	v_add3_u32 v97, v97, v99, s43
	v_rcp_f32_e32 v89, v89
	v_rcp_f32_e32 v91, v91
	v_exp_f32_e32 v85, v85
	v_exp_f32_e32 v87, v87
	v_and_b32_e32 v95, 0xffff0000, v95
	v_and_b32_e32 v97, 0xffff0000, v97
	v_lshl_add_u64 v[92:93], v[92:93], 0, v[128:129]
	v_or_b32_sdwa v95, v95, v94 dst_sel:DWORD dst_unused:UNUSED_PAD src0_sel:DWORD src1_sel:WORD_1
	v_or_b32_sdwa v94, v97, v96 dst_sel:DWORD dst_unused:UNUSED_PAD src0_sel:DWORD src1_sel:WORD_1
	s_nop 0
	v_mov_b32_e32 v212, v94
	v_mov_b32_e32 v213, v95
	v_and_b32_sdwa v94, v90, v232 dst_sel:DWORD dst_unused:UNUSED_PAD src0_sel:WORD_1 src1_sel:DWORD
	v_and_b32_sdwa v95, v88, v232 dst_sel:DWORD dst_unused:UNUSED_PAD src0_sel:WORD_1 src1_sel:DWORD
	v_add_f32_e32 v84, 1.0, v84
	v_add_f32_e32 v86, 1.0, v86
	v_mul_f32_e32 v80, 0xbfb8aa3b, v80
	v_mul_f32_e32 v82, 0xbfb8aa3b, v82
	v_add3_u32 v88, v88, v95, s43
	v_add3_u32 v90, v90, v94, s43
	v_and_b32_sdwa v94, v91, v232 dst_sel:DWORD dst_unused:UNUSED_PAD src0_sel:WORD_1 src1_sel:DWORD
	v_and_b32_sdwa v95, v89, v232 dst_sel:DWORD dst_unused:UNUSED_PAD src0_sel:WORD_1 src1_sel:DWORD
	v_rcp_f32_e32 v84, v84
	v_add_f32_e32 v85, 1.0, v85
	v_rcp_f32_e32 v86, v86
	v_add_f32_e32 v87, 1.0, v87
	v_exp_f32_e32 v80, v80
	v_mul_f32_e32 v81, 0xbfb8aa3b, v81
	v_exp_f32_e32 v82, v82
	v_mul_f32_e32 v83, 0xbfb8aa3b, v83
	v_add3_u32 v91, v91, v94, s43
	v_add3_u32 v89, v89, v95, s43
	v_rcp_f32_e32 v85, v85
	v_rcp_f32_e32 v87, v87
	v_exp_f32_e32 v81, v81
	v_exp_f32_e32 v83, v83
	v_and_b32_e32 v91, 0xffff0000, v91
	v_and_b32_e32 v94, 0xffff0000, v89
	v_or_b32_sdwa v89, v91, v90 dst_sel:DWORD dst_unused:UNUSED_PAD src0_sel:DWORD src1_sel:WORD_1
	v_or_b32_sdwa v88, v94, v88 dst_sel:DWORD dst_unused:UNUSED_PAD src0_sel:DWORD src1_sel:WORD_1
	s_nop 0
	v_mov_b32_e32 v214, v88
	v_mov_b32_e32 v215, v89
	v_mbcnt_lo_u32_b32 v224, -1, 0
	v_mbcnt_hi_u32_b32 v224, -1, v224
	v_and_b32_e32 v222, 16, v224
	v_lshrrev_b32_e32 v224, 1, v222
	v_add_u32_e32 v222, v222, v224
	v_mov_b32_e32 v223, 0
	v_lshl_add_u64 v[220:221], v[92:93], 0, v[222:223]
	v_permlane16_swap_b32_e32 v212, v214
	v_permlane16_swap_b32_e32 v213, v215
	global_store_dwordx4 v[220:221], v[212:215], off
	v_and_b32_sdwa v88, v86, v232 dst_sel:DWORD dst_unused:UNUSED_PAD src0_sel:WORD_1 src1_sel:DWORD
	v_and_b32_sdwa v89, v84, v232 dst_sel:DWORD dst_unused:UNUSED_PAD src0_sel:WORD_1 src1_sel:DWORD
	v_add_f32_e32 v80, 1.0, v80
	v_add_f32_e32 v82, 1.0, v82
	v_add3_u32 v84, v84, v89, s43
	v_add3_u32 v86, v86, v88, s43
	v_and_b32_sdwa v88, v87, v232 dst_sel:DWORD dst_unused:UNUSED_PAD src0_sel:WORD_1 src1_sel:DWORD
; #define ST4(ptr, a, b, c_, d) (*(uint2*)(ptr) = make_uint2((unsigned)f2bf(a) | ((unsigned)f2bf(b) << 16), (unsigned)f2bf(c_) | ((unsigned)f2bf(d) << 16)))
; template <int EPI>
; __device__ __forceinline__ void gemm_phase(const Ctx& p, int hf, const u16* __restrict__ A, int lda, const u16* __restrict__ Bt, int K, int nN, u16* __restrict__ dst, int ldc, bool fromx = false) {
;     ...
;     else if constexpr (EPI == EPI_SIGMOID) { ACC_LOOP( _Pragma("unroll") for (int e = 0; e < 4; ++e) v4[e] = __builtin_amdgcn_rcpf(1.f + __expf(-v4[e]));
;                                                         ST4(dst + (size_t)row * ldc + bcol + col, v4[0], v4[1], v4[2], v4[3]); ) }
	v_and_b32_sdwa v89, v85, v232 dst_sel:DWORD dst_unused:UNUSED_PAD src0_sel:WORD_1 src1_sel:DWORD
	v_rcp_f32_e32 v80, v80
	v_add_f32_e32 v81, 1.0, v81
	v_rcp_f32_e32 v82, v82
	v_add_f32_e32 v83, 1.0, v83
	v_add3_u32 v87, v87, v88, s43
	v_add3_u32 v85, v85, v89, s43
	v_rcp_f32_e32 v81, v81
	v_rcp_f32_e32 v83, v83
	v_and_b32_e32 v87, 0xffff0000, v87
	v_and_b32_e32 v88, 0xffff0000, v85
	v_or_b32_sdwa v85, v87, v86 dst_sel:DWORD dst_unused:UNUSED_PAD src0_sel:DWORD src1_sel:WORD_1
	v_or_b32_sdwa v84, v88, v84 dst_sel:DWORD dst_unused:UNUSED_PAD src0_sel:DWORD src1_sel:WORD_1
	s_nop 0
	v_mov_b32_e32 v216, v84
	v_mov_b32_e32 v217, v85
	v_and_b32_sdwa v84, v82, v232 dst_sel:DWORD dst_unused:UNUSED_PAD src0_sel:WORD_1 src1_sel:DWORD
	v_and_b32_sdwa v85, v80, v232 dst_sel:DWORD dst_unused:UNUSED_PAD src0_sel:WORD_1 src1_sel:DWORD
	v_add3_u32 v80, v80, v85, s43
	v_add3_u32 v82, v82, v84, s43
	v_and_b32_sdwa v84, v83, v232 dst_sel:DWORD dst_unused:UNUSED_PAD src0_sel:WORD_1 src1_sel:DWORD
	v_and_b32_sdwa v85, v81, v232 dst_sel:DWORD dst_unused:UNUSED_PAD src0_sel:WORD_1 src1_sel:DWORD
	v_add3_u32 v83, v83, v84, s43
	v_add3_u32 v81, v81, v85, s43
	v_and_b32_e32 v83, 0xffff0000, v83
	v_and_b32_e32 v84, 0xffff0000, v81
	v_or_b32_sdwa v81, v83, v82 dst_sel:DWORD dst_unused:UNUSED_PAD src0_sel:DWORD src1_sel:WORD_1
	v_or_b32_sdwa v80, v84, v80 dst_sel:DWORD dst_unused:UNUSED_PAD src0_sel:DWORD src1_sel:WORD_1
	s_nop 0
	v_mov_b32_e32 v218, v80
	v_mov_b32_e32 v219, v81
	s_nop 1
	v_permlane16_swap_b32_e32 v216, v218
	v_permlane16_swap_b32_e32 v217, v219
	global_store_dwordx4 v[220:221], v[216:219], off offset:64
	v_mul_f32_e32 v76, 0xbfb8aa3b, v76
	v_mul_f32_e32 v78, 0xbfb8aa3b, v78
	v_exp_f32_e32 v81, v76
	v_mul_f32_e32 v76, 0xbfb8aa3b, v77
	v_exp_f32_e32 v78, v78
	v_mul_f32_e32 v79, 0xbfb8aa3b, v79
	v_exp_f32_e32 v82, v76
	v_exp_f32_e32 v79, v79
	v_add_u32_e32 v80, 64, v148
	v_mad_i64_i32 v[76:77], s[0:1], v80, s84, v[146:147]
	v_add_f32_e32 v80, 1.0, v81
	v_add_f32_e32 v78, 1.0, v78
	v_mul_f32_e32 v72, 0xbfb8aa3b, v72
	v_mul_f32_e32 v74, 0xbfb8aa3b, v74
	v_rcp_f32_e32 v80, v80
	v_add_f32_e32 v81, 1.0, v82
	v_rcp_f32_e32 v78, v78
	v_add_f32_e32 v79, 1.0, v79
	v_exp_f32_e32 v72, v72
	v_mul_f32_e32 v73, 0xbfb8aa3b, v73
	v_exp_f32_e32 v74, v74
	v_mul_f32_e32 v75, 0xbfb8aa3b, v75
	v_rcp_f32_e32 v81, v81
	v_rcp_f32_e32 v79, v79
	v_exp_f32_e32 v73, v73
	v_exp_f32_e32 v75, v75
	v_and_b32_sdwa v82, v78, v232 dst_sel:DWORD dst_unused:UNUSED_PAD src0_sel:WORD_1 src1_sel:DWORD
	v_and_b32_sdwa v83, v80, v232 dst_sel:DWORD dst_unused:UNUSED_PAD src0_sel:WORD_1 src1_sel:DWORD
	v_add_f32_e32 v72, 1.0, v72
	v_add_f32_e32 v74, 1.0, v74
	v_mul_f32_e32 v68, 0xbfb8aa3b, v68
	v_mul_f32_e32 v70, 0xbfb8aa3b, v70
	v_add3_u32 v80, v80, v83, s43
	v_add3_u32 v78, v78, v82, s43
	v_and_b32_sdwa v82, v79, v232 dst_sel:DWORD dst_unused:UNUSED_PAD src0_sel:WORD_1 src1_sel:DWORD
	v_and_b32_sdwa v83, v81, v232 dst_sel:DWORD dst_unused:UNUSED_PAD src0_sel:WORD_1 src1_sel:DWORD
	v_rcp_f32_e32 v72, v72
	v_add_f32_e32 v73, 1.0, v73
	v_rcp_f32_e32 v74, v74
	v_add_f32_e32 v75, 1.0, v75
	v_exp_f32_e32 v68, v68
	v_mul_f32_e32 v69, 0xbfb8aa3b, v69
	v_exp_f32_e32 v70, v70
	v_mul_f32_e32 v71, 0xbfb8aa3b, v71
	v_add3_u32 v79, v79, v82, s43
	v_add3_u32 v81, v81, v83, s43
	v_rcp_f32_e32 v73, v73
	v_rcp_f32_e32 v75, v75
	v_exp_f32_e32 v69, v69
	v_exp_f32_e32 v71, v71
	v_and_b32_e32 v79, 0xffff0000, v79
	v_and_b32_e32 v81, 0xffff0000, v81
	v_lshl_add_u64 v[76:77], v[76:77], 0, v[128:129]
	v_or_b32_sdwa v79, v79, v78 dst_sel:DWORD dst_unused:UNUSED_PAD src0_sel:DWORD src1_sel:WORD_1
	v_or_b32_sdwa v78, v81, v80 dst_sel:DWORD dst_unused:UNUSED_PAD src0_sel:DWORD src1_sel:WORD_1
	s_nop 0
	v_mov_b32_e32 v212, v78
	v_mov_b32_e32 v213, v79
	v_and_b32_sdwa v78, v74, v232 dst_sel:DWORD dst_unused:UNUSED_PAD src0_sel:WORD_1 src1_sel:DWORD
	v_and_b32_sdwa v79, v72, v232 dst_sel:DWORD dst_unused:UNUSED_PAD src0_sel:WORD_1 src1_sel:DWORD
	v_add_f32_e32 v68, 1.0, v68
	v_add_f32_e32 v70, 1.0, v70
	v_mul_f32_e32 v64, 0xbfb8aa3b, v64
	v_mul_f32_e32 v66, 0xbfb8aa3b, v66
	v_add3_u32 v72, v72, v79, s43
	v_add3_u32 v74, v74, v78, s43
	v_and_b32_sdwa v78, v75, v232 dst_sel:DWORD dst_unused:UNUSED_PAD src0_sel:WORD_1 src1_sel:DWORD
	v_and_b32_sdwa v79, v73, v232 dst_sel:DWORD dst_unused:UNUSED_PAD src0_sel:WORD_1 src1_sel:DWORD
	v_rcp_f32_e32 v68, v68
	v_add_f32_e32 v69, 1.0, v69
	v_rcp_f32_e32 v70, v70
	v_add_f32_e32 v71, 1.0, v71
	v_exp_f32_e32 v64, v64
	v_mul_f32_e32 v65, 0xbfb8aa3b, v65
	v_exp_f32_e32 v66, v66
	v_mul_f32_e32 v67, 0xbfb8aa3b, v67
	v_add3_u32 v75, v75, v78, s43
	v_add3_u32 v73, v73, v79, s43
	v_rcp_f32_e32 v69, v69
	v_rcp_f32_e32 v71, v71
	v_exp_f32_e32 v65, v65
	v_exp_f32_e32 v67, v67
	v_and_b32_e32 v75, 0xffff0000, v75
	v_and_b32_e32 v78, 0xffff0000, v73
	v_or_b32_sdwa v73, v75, v74 dst_sel:DWORD dst_unused:UNUSED_PAD src0_sel:DWORD src1_sel:WORD_1
	v_or_b32_sdwa v72, v78, v72 dst_sel:DWORD dst_unused:UNUSED_PAD src0_sel:DWORD src1_sel:WORD_1
	s_nop 0
	v_mov_b32_e32 v214, v72
	v_mov_b32_e32 v215, v73
	v_mbcnt_lo_u32_b32 v224, -1, 0
	v_mbcnt_hi_u32_b32 v224, -1, v224
	v_and_b32_e32 v222, 16, v224
	v_lshrrev_b32_e32 v224, 1, v222
	v_add_u32_e32 v222, v222, v224
	v_mov_b32_e32 v223, 0
	v_lshl_add_u64 v[220:221], v[76:77], 0, v[222:223]
	v_permlane16_swap_b32_e32 v212, v214
	v_permlane16_swap_b32_e32 v213, v215
	global_store_dwordx4 v[220:221], v[212:215], off
	v_and_b32_sdwa v72, v70, v232 dst_sel:DWORD dst_unused:UNUSED_PAD src0_sel:WORD_1 src1_sel:DWORD
	v_and_b32_sdwa v73, v68, v232 dst_sel:DWORD dst_unused:UNUSED_PAD src0_sel:WORD_1 src1_sel:DWORD
	v_add_f32_e32 v64, 1.0, v64
	v_add_f32_e32 v66, 1.0, v66
; #define ST4(ptr, a, b, c_, d) (*(uint2*)(ptr) = make_uint2((unsigned)f2bf(a) | ((unsigned)f2bf(b) << 16), (unsigned)f2bf(c_) | ((unsigned)f2bf(d) << 16)))
; template <int EPI>
; __device__ __forceinline__ void gemm_phase(const Ctx& p, int hf, const u16* __restrict__ A, int lda, const u16* __restrict__ Bt, int K, int nN, u16* __restrict__ dst, int ldc, bool fromx = false) {
;     ...
;     else if constexpr (EPI == EPI_SIGMOID) { ACC_LOOP( _Pragma("unroll") for (int e = 0; e < 4; ++e) v4[e] = __builtin_amdgcn_rcpf(1.f + __expf(-v4[e]));
;                                                         ST4(dst + (size_t)row * ldc + bcol + col, v4[0], v4[1], v4[2], v4[3]); ) }
	v_add3_u32 v68, v68, v73, s43
	v_add3_u32 v70, v70, v72, s43
	v_and_b32_sdwa v72, v71, v232 dst_sel:DWORD dst_unused:UNUSED_PAD src0_sel:WORD_1 src1_sel:DWORD
	v_and_b32_sdwa v73, v69, v232 dst_sel:DWORD dst_unused:UNUSED_PAD src0_sel:WORD_1 src1_sel:DWORD
	v_rcp_f32_e32 v64, v64
	v_add_f32_e32 v65, 1.0, v65
	v_rcp_f32_e32 v66, v66
	v_add_f32_e32 v67, 1.0, v67
	v_add3_u32 v71, v71, v72, s43
	v_add3_u32 v69, v69, v73, s43
	v_rcp_f32_e32 v65, v65
	v_rcp_f32_e32 v67, v67
	v_and_b32_e32 v71, 0xffff0000, v71
	v_and_b32_e32 v72, 0xffff0000, v69
	v_or_b32_sdwa v69, v71, v70 dst_sel:DWORD dst_unused:UNUSED_PAD src0_sel:DWORD src1_sel:WORD_1
	v_or_b32_sdwa v68, v72, v68 dst_sel:DWORD dst_unused:UNUSED_PAD src0_sel:DWORD src1_sel:WORD_1
	s_nop 0
	v_mov_b32_e32 v216, v68
	v_mov_b32_e32 v217, v69
	v_and_b32_sdwa v68, v66, v232 dst_sel:DWORD dst_unused:UNUSED_PAD src0_sel:WORD_1 src1_sel:DWORD
	v_and_b32_sdwa v69, v64, v232 dst_sel:DWORD dst_unused:UNUSED_PAD src0_sel:WORD_1 src1_sel:DWORD
	v_add3_u32 v64, v64, v69, s43
	v_add3_u32 v66, v66, v68, s43
	v_and_b32_sdwa v68, v67, v232 dst_sel:DWORD dst_unused:UNUSED_PAD src0_sel:WORD_1 src1_sel:DWORD
	v_and_b32_sdwa v69, v65, v232 dst_sel:DWORD dst_unused:UNUSED_PAD src0_sel:WORD_1 src1_sel:DWORD
	v_add3_u32 v67, v67, v68, s43
	v_add3_u32 v65, v65, v69, s43
	v_and_b32_e32 v67, 0xffff0000, v67
	v_and_b32_e32 v68, 0xffff0000, v65
	v_or_b32_sdwa v65, v67, v66 dst_sel:DWORD dst_unused:UNUSED_PAD src0_sel:DWORD src1_sel:WORD_1
	v_or_b32_sdwa v64, v68, v64 dst_sel:DWORD dst_unused:UNUSED_PAD src0_sel:DWORD src1_sel:WORD_1
	s_nop 0
	v_mov_b32_e32 v218, v64
	v_mov_b32_e32 v219, v65
	s_nop 1
	v_permlane16_swap_b32_e32 v216, v218
	v_permlane16_swap_b32_e32 v217, v219
	global_store_dwordx4 v[220:221], v[216:219], off offset:64
	v_mul_f32_e32 v60, 0xbfb8aa3b, v60
	v_mul_f32_e32 v62, 0xbfb8aa3b, v62
	v_exp_f32_e32 v65, v60
	v_mul_f32_e32 v60, 0xbfb8aa3b, v61
	v_exp_f32_e32 v62, v62
	v_mul_f32_e32 v63, 0xbfb8aa3b, v63
	v_exp_f32_e32 v66, v60
	v_exp_f32_e32 v63, v63
	v_add_u32_e32 v64, 0x50, v148
	v_mad_i64_i32 v[60:61], s[0:1], v64, s84, v[146:147]
	v_add_f32_e32 v64, 1.0, v65
	v_add_f32_e32 v62, 1.0, v62
	v_mul_f32_e32 v56, 0xbfb8aa3b, v56
	v_mul_f32_e32 v58, 0xbfb8aa3b, v58
	v_rcp_f32_e32 v64, v64
	v_add_f32_e32 v65, 1.0, v66
	v_rcp_f32_e32 v62, v62
	v_add_f32_e32 v63, 1.0, v63
	v_exp_f32_e32 v56, v56
	v_mul_f32_e32 v57, 0xbfb8aa3b, v57
	v_exp_f32_e32 v58, v58
	v_mul_f32_e32 v59, 0xbfb8aa3b, v59
	v_rcp_f32_e32 v65, v65
	v_rcp_f32_e32 v63, v63
	v_exp_f32_e32 v57, v57
	v_exp_f32_e32 v59, v59
	v_and_b32_sdwa v66, v62, v232 dst_sel:DWORD dst_unused:UNUSED_PAD src0_sel:WORD_1 src1_sel:DWORD
	v_and_b32_sdwa v67, v64, v232 dst_sel:DWORD dst_unused:UNUSED_PAD src0_sel:WORD_1 src1_sel:DWORD
	v_add_f32_e32 v56, 1.0, v56
	v_add_f32_e32 v58, 1.0, v58
	v_mul_f32_e32 v52, 0xbfb8aa3b, v52
	v_mul_f32_e32 v54, 0xbfb8aa3b, v54
	v_add3_u32 v64, v64, v67, s43
	v_add3_u32 v62, v62, v66, s43
	v_and_b32_sdwa v66, v63, v232 dst_sel:DWORD dst_unused:UNUSED_PAD src0_sel:WORD_1 src1_sel:DWORD
	v_and_b32_sdwa v67, v65, v232 dst_sel:DWORD dst_unused:UNUSED_PAD src0_sel:WORD_1 src1_sel:DWORD
	v_rcp_f32_e32 v56, v56
	v_add_f32_e32 v57, 1.0, v57
	v_rcp_f32_e32 v58, v58
	v_add_f32_e32 v59, 1.0, v59
	v_exp_f32_e32 v52, v52
	v_mul_f32_e32 v53, 0xbfb8aa3b, v53
	v_exp_f32_e32 v54, v54
	v_mul_f32_e32 v55, 0xbfb8aa3b, v55
	v_add3_u32 v63, v63, v66, s43
	v_add3_u32 v65, v65, v67, s43
	v_rcp_f32_e32 v57, v57
	v_rcp_f32_e32 v59, v59
	v_exp_f32_e32 v53, v53
	v_exp_f32_e32 v55, v55
	v_and_b32_e32 v63, 0xffff0000, v63
	v_and_b32_e32 v65, 0xffff0000, v65
	v_lshl_add_u64 v[60:61], v[60:61], 0, v[128:129]
	v_or_b32_sdwa v63, v63, v62 dst_sel:DWORD dst_unused:UNUSED_PAD src0_sel:DWORD src1_sel:WORD_1
	v_or_b32_sdwa v62, v65, v64 dst_sel:DWORD dst_unused:UNUSED_PAD src0_sel:DWORD src1_sel:WORD_1
	s_nop 0
	v_mov_b32_e32 v212, v62
	v_mov_b32_e32 v213, v63
	v_and_b32_sdwa v62, v58, v232 dst_sel:DWORD dst_unused:UNUSED_PAD src0_sel:WORD_1 src1_sel:DWORD
	v_and_b32_sdwa v63, v56, v232 dst_sel:DWORD dst_unused:UNUSED_PAD src0_sel:WORD_1 src1_sel:DWORD
	v_add_f32_e32 v52, 1.0, v52
	v_add_f32_e32 v54, 1.0, v54
	v_mul_f32_e32 v48, 0xbfb8aa3b, v48
	v_mul_f32_e32 v50, 0xbfb8aa3b, v50
	v_add3_u32 v56, v56, v63, s43
	v_add3_u32 v58, v58, v62, s43
	v_and_b32_sdwa v62, v59, v232 dst_sel:DWORD dst_unused:UNUSED_PAD src0_sel:WORD_1 src1_sel:DWORD
	v_and_b32_sdwa v63, v57, v232 dst_sel:DWORD dst_unused:UNUSED_PAD src0_sel:WORD_1 src1_sel:DWORD
	v_rcp_f32_e32 v52, v52
	v_add_f32_e32 v53, 1.0, v53
	v_rcp_f32_e32 v54, v54
	v_add_f32_e32 v55, 1.0, v55
	v_exp_f32_e32 v48, v48
	v_mul_f32_e32 v49, 0xbfb8aa3b, v49
	v_exp_f32_e32 v50, v50
	v_mul_f32_e32 v51, 0xbfb8aa3b, v51
	v_add3_u32 v59, v59, v62, s43
	v_add3_u32 v57, v57, v63, s43
	v_rcp_f32_e32 v53, v53
	v_rcp_f32_e32 v55, v55
	v_exp_f32_e32 v49, v49
	v_exp_f32_e32 v51, v51
	v_and_b32_e32 v59, 0xffff0000, v59
	v_and_b32_e32 v62, 0xffff0000, v57
	v_or_b32_sdwa v57, v59, v58 dst_sel:DWORD dst_unused:UNUSED_PAD src0_sel:DWORD src1_sel:WORD_1
	v_or_b32_sdwa v56, v62, v56 dst_sel:DWORD dst_unused:UNUSED_PAD src0_sel:DWORD src1_sel:WORD_1
	s_nop 0
	v_mov_b32_e32 v214, v56
	v_mov_b32_e32 v215, v57
	v_mbcnt_lo_u32_b32 v224, -1, 0
	v_mbcnt_hi_u32_b32 v224, -1, v224
	v_and_b32_e32 v222, 16, v224
	v_lshrrev_b32_e32 v224, 1, v222
	v_add_u32_e32 v222, v222, v224
	v_mov_b32_e32 v223, 0
	v_lshl_add_u64 v[220:221], v[60:61], 0, v[222:223]
	v_permlane16_swap_b32_e32 v212, v214
	v_permlane16_swap_b32_e32 v213, v215
	global_store_dwordx4 v[220:221], v[212:215], off
	v_and_b32_sdwa v56, v54, v232 dst_sel:DWORD dst_unused:UNUSED_PAD src0_sel:WORD_1 src1_sel:DWORD
; #define ST4(ptr, a, b, c_, d) (*(uint2*)(ptr) = make_uint2((unsigned)f2bf(a) | ((unsigned)f2bf(b) << 16), (unsigned)f2bf(c_) | ((unsigned)f2bf(d) << 16)))
; template <int EPI>
; __device__ __forceinline__ void gemm_phase(const Ctx& p, int hf, const u16* __restrict__ A, int lda, const u16* __restrict__ Bt, int K, int nN, u16* __restrict__ dst, int ldc, bool fromx = false) {
;     ...
;     else if constexpr (EPI == EPI_SIGMOID) { ACC_LOOP( _Pragma("unroll") for (int e = 0; e < 4; ++e) v4[e] = __builtin_amdgcn_rcpf(1.f + __expf(-v4[e]));
;                                                         ST4(dst + (size_t)row * ldc + bcol + col, v4[0], v4[1], v4[2], v4[3]); ) }
	v_and_b32_sdwa v57, v52, v232 dst_sel:DWORD dst_unused:UNUSED_PAD src0_sel:WORD_1 src1_sel:DWORD
	v_add_f32_e32 v48, 1.0, v48
	v_add_f32_e32 v50, 1.0, v50
	v_add3_u32 v52, v52, v57, s43
	v_add3_u32 v54, v54, v56, s43
	v_and_b32_sdwa v56, v55, v232 dst_sel:DWORD dst_unused:UNUSED_PAD src0_sel:WORD_1 src1_sel:DWORD
	v_and_b32_sdwa v57, v53, v232 dst_sel:DWORD dst_unused:UNUSED_PAD src0_sel:WORD_1 src1_sel:DWORD
	v_rcp_f32_e32 v48, v48
	v_add_f32_e32 v49, 1.0, v49
	v_rcp_f32_e32 v50, v50
	v_add_f32_e32 v51, 1.0, v51
	v_add3_u32 v55, v55, v56, s43
	v_add3_u32 v53, v53, v57, s43
	v_rcp_f32_e32 v49, v49
	v_rcp_f32_e32 v51, v51
	v_and_b32_e32 v55, 0xffff0000, v55
	v_and_b32_e32 v56, 0xffff0000, v53
	v_or_b32_sdwa v53, v55, v54 dst_sel:DWORD dst_unused:UNUSED_PAD src0_sel:DWORD src1_sel:WORD_1
	v_or_b32_sdwa v52, v56, v52 dst_sel:DWORD dst_unused:UNUSED_PAD src0_sel:DWORD src1_sel:WORD_1
	s_nop 0
	v_mov_b32_e32 v216, v52
	v_mov_b32_e32 v217, v53
	v_and_b32_sdwa v52, v50, v232 dst_sel:DWORD dst_unused:UNUSED_PAD src0_sel:WORD_1 src1_sel:DWORD
	v_and_b32_sdwa v53, v48, v232 dst_sel:DWORD dst_unused:UNUSED_PAD src0_sel:WORD_1 src1_sel:DWORD
	v_add3_u32 v48, v48, v53, s43
	v_add3_u32 v50, v50, v52, s43
	v_and_b32_sdwa v52, v51, v232 dst_sel:DWORD dst_unused:UNUSED_PAD src0_sel:WORD_1 src1_sel:DWORD
	v_and_b32_sdwa v53, v49, v232 dst_sel:DWORD dst_unused:UNUSED_PAD src0_sel:WORD_1 src1_sel:DWORD
	v_add3_u32 v51, v51, v52, s43
	v_add3_u32 v49, v49, v53, s43
	v_and_b32_e32 v51, 0xffff0000, v51
	v_and_b32_e32 v52, 0xffff0000, v49
	v_or_b32_sdwa v49, v51, v50 dst_sel:DWORD dst_unused:UNUSED_PAD src0_sel:DWORD src1_sel:WORD_1
	v_or_b32_sdwa v48, v52, v48 dst_sel:DWORD dst_unused:UNUSED_PAD src0_sel:DWORD src1_sel:WORD_1
	s_nop 0
	v_mov_b32_e32 v218, v48
	v_mov_b32_e32 v219, v49
	s_nop 1
	v_permlane16_swap_b32_e32 v216, v218
	v_permlane16_swap_b32_e32 v217, v219
	global_store_dwordx4 v[220:221], v[216:219], off offset:64
	v_mul_f32_e32 v44, 0xbfb8aa3b, v44
	v_mul_f32_e32 v46, 0xbfb8aa3b, v46
	v_exp_f32_e32 v49, v44
	v_mul_f32_e32 v44, 0xbfb8aa3b, v45
	v_exp_f32_e32 v46, v46
	v_mul_f32_e32 v47, 0xbfb8aa3b, v47
	v_exp_f32_e32 v50, v44
	v_exp_f32_e32 v47, v47
	v_add_u32_e32 v48, 0x60, v148
	v_mad_i64_i32 v[44:45], s[0:1], v48, s84, v[146:147]
	v_add_f32_e32 v48, 1.0, v49
	v_add_f32_e32 v46, 1.0, v46
	v_mul_f32_e32 v40, 0xbfb8aa3b, v40
	v_mul_f32_e32 v42, 0xbfb8aa3b, v42
	v_rcp_f32_e32 v48, v48
	v_add_f32_e32 v49, 1.0, v50
	v_rcp_f32_e32 v46, v46
	v_add_f32_e32 v47, 1.0, v47
	v_exp_f32_e32 v40, v40
	v_mul_f32_e32 v41, 0xbfb8aa3b, v41
	v_exp_f32_e32 v42, v42
	v_mul_f32_e32 v43, 0xbfb8aa3b, v43
	v_rcp_f32_e32 v49, v49
	v_rcp_f32_e32 v47, v47
	v_exp_f32_e32 v41, v41
	v_exp_f32_e32 v43, v43
	v_and_b32_sdwa v50, v46, v232 dst_sel:DWORD dst_unused:UNUSED_PAD src0_sel:WORD_1 src1_sel:DWORD
	v_and_b32_sdwa v51, v48, v232 dst_sel:DWORD dst_unused:UNUSED_PAD src0_sel:WORD_1 src1_sel:DWORD
	v_add_f32_e32 v40, 1.0, v40
	v_add_f32_e32 v42, 1.0, v42
	v_mul_f32_e32 v36, 0xbfb8aa3b, v36
	v_mul_f32_e32 v38, 0xbfb8aa3b, v38
	v_add3_u32 v48, v48, v51, s43
	v_add3_u32 v46, v46, v50, s43
	v_and_b32_sdwa v50, v47, v232 dst_sel:DWORD dst_unused:UNUSED_PAD src0_sel:WORD_1 src1_sel:DWORD
	v_and_b32_sdwa v51, v49, v232 dst_sel:DWORD dst_unused:UNUSED_PAD src0_sel:WORD_1 src1_sel:DWORD
	v_rcp_f32_e32 v40, v40
	v_add_f32_e32 v41, 1.0, v41
	v_rcp_f32_e32 v42, v42
	v_add_f32_e32 v43, 1.0, v43
	v_exp_f32_e32 v36, v36
	v_mul_f32_e32 v37, 0xbfb8aa3b, v37
	v_exp_f32_e32 v38, v38
	v_mul_f32_e32 v39, 0xbfb8aa3b, v39
	v_add3_u32 v47, v47, v50, s43
	v_add3_u32 v49, v49, v51, s43
	v_rcp_f32_e32 v41, v41
	v_rcp_f32_e32 v43, v43
	v_exp_f32_e32 v37, v37
	v_exp_f32_e32 v39, v39
	v_and_b32_e32 v47, 0xffff0000, v47
	v_and_b32_e32 v49, 0xffff0000, v49
	v_lshl_add_u64 v[44:45], v[44:45], 0, v[128:129]
	v_or_b32_sdwa v47, v47, v46 dst_sel:DWORD dst_unused:UNUSED_PAD src0_sel:DWORD src1_sel:WORD_1
	v_or_b32_sdwa v46, v49, v48 dst_sel:DWORD dst_unused:UNUSED_PAD src0_sel:DWORD src1_sel:WORD_1
	s_nop 0
	v_mov_b32_e32 v212, v46
	v_mov_b32_e32 v213, v47
	v_and_b32_sdwa v46, v42, v232 dst_sel:DWORD dst_unused:UNUSED_PAD src0_sel:WORD_1 src1_sel:DWORD
	v_and_b32_sdwa v47, v40, v232 dst_sel:DWORD dst_unused:UNUSED_PAD src0_sel:WORD_1 src1_sel:DWORD
	v_add_f32_e32 v36, 1.0, v36
	v_add_f32_e32 v38, 1.0, v38
	v_mul_f32_e32 v32, 0xbfb8aa3b, v32
	v_mul_f32_e32 v34, 0xbfb8aa3b, v34
	v_add3_u32 v40, v40, v47, s43
	v_add3_u32 v42, v42, v46, s43
	v_and_b32_sdwa v46, v43, v232 dst_sel:DWORD dst_unused:UNUSED_PAD src0_sel:WORD_1 src1_sel:DWORD
	v_and_b32_sdwa v47, v41, v232 dst_sel:DWORD dst_unused:UNUSED_PAD src0_sel:WORD_1 src1_sel:DWORD
	v_rcp_f32_e32 v36, v36
	v_add_f32_e32 v37, 1.0, v37
	v_rcp_f32_e32 v38, v38
	v_add_f32_e32 v39, 1.0, v39
	v_exp_f32_e32 v32, v32
	v_mul_f32_e32 v33, 0xbfb8aa3b, v33
	v_exp_f32_e32 v34, v34
	v_mul_f32_e32 v35, 0xbfb8aa3b, v35
	v_add3_u32 v43, v43, v46, s43
	v_add3_u32 v41, v41, v47, s43
	v_rcp_f32_e32 v37, v37
	v_rcp_f32_e32 v39, v39
	v_exp_f32_e32 v33, v33
	v_exp_f32_e32 v35, v35
	v_and_b32_e32 v43, 0xffff0000, v43
	v_and_b32_e32 v46, 0xffff0000, v41
	v_or_b32_sdwa v41, v43, v42 dst_sel:DWORD dst_unused:UNUSED_PAD src0_sel:DWORD src1_sel:WORD_1
	v_or_b32_sdwa v40, v46, v40 dst_sel:DWORD dst_unused:UNUSED_PAD src0_sel:DWORD src1_sel:WORD_1
	s_nop 0
	v_mov_b32_e32 v214, v40
	v_mov_b32_e32 v215, v41
	v_mbcnt_lo_u32_b32 v224, -1, 0
	v_mbcnt_hi_u32_b32 v224, -1, v224
	v_and_b32_e32 v222, 16, v224
	v_lshrrev_b32_e32 v224, 1, v222
	v_add_u32_e32 v222, v222, v224
	v_mov_b32_e32 v223, 0
	v_lshl_add_u64 v[220:221], v[44:45], 0, v[222:223]
	v_permlane16_swap_b32_e32 v212, v214
; #define ST4(ptr, a, b, c_, d) (*(uint2*)(ptr) = make_uint2((unsigned)f2bf(a) | ((unsigned)f2bf(b) << 16), (unsigned)f2bf(c_) | ((unsigned)f2bf(d) << 16)))
; template <int EPI>
; __device__ __forceinline__ void gemm_phase(const Ctx& p, int hf, const u16* __restrict__ A, int lda, const u16* __restrict__ Bt, int K, int nN, u16* __restrict__ dst, int ldc, bool fromx = false) {
;     ...
;     else if constexpr (EPI == EPI_SIGMOID) { ACC_LOOP( _Pragma("unroll") for (int e = 0; e < 4; ++e) v4[e] = __builtin_amdgcn_rcpf(1.f + __expf(-v4[e]));
;                                                         ST4(dst + (size_t)row * ldc + bcol + col, v4[0], v4[1], v4[2], v4[3]); ) }
	v_permlane16_swap_b32_e32 v213, v215
	global_store_dwordx4 v[220:221], v[212:215], off
	v_and_b32_sdwa v40, v38, v232 dst_sel:DWORD dst_unused:UNUSED_PAD src0_sel:WORD_1 src1_sel:DWORD
	v_and_b32_sdwa v41, v36, v232 dst_sel:DWORD dst_unused:UNUSED_PAD src0_sel:WORD_1 src1_sel:DWORD
	v_add_f32_e32 v32, 1.0, v32
	v_add_f32_e32 v34, 1.0, v34
	v_add3_u32 v36, v36, v41, s43
	v_add3_u32 v38, v38, v40, s43
	v_and_b32_sdwa v40, v39, v232 dst_sel:DWORD dst_unused:UNUSED_PAD src0_sel:WORD_1 src1_sel:DWORD
	v_and_b32_sdwa v41, v37, v232 dst_sel:DWORD dst_unused:UNUSED_PAD src0_sel:WORD_1 src1_sel:DWORD
	v_rcp_f32_e32 v32, v32
	v_add_f32_e32 v33, 1.0, v33
	v_rcp_f32_e32 v34, v34
	v_add_f32_e32 v35, 1.0, v35
	v_add3_u32 v39, v39, v40, s43
	v_add3_u32 v37, v37, v41, s43
	v_rcp_f32_e32 v33, v33
	v_rcp_f32_e32 v35, v35
	v_and_b32_e32 v39, 0xffff0000, v39
	v_and_b32_e32 v40, 0xffff0000, v37
	v_or_b32_sdwa v37, v39, v38 dst_sel:DWORD dst_unused:UNUSED_PAD src0_sel:DWORD src1_sel:WORD_1
	v_or_b32_sdwa v36, v40, v36 dst_sel:DWORD dst_unused:UNUSED_PAD src0_sel:DWORD src1_sel:WORD_1
	s_nop 0
	v_mov_b32_e32 v216, v36
	v_mov_b32_e32 v217, v37
	v_and_b32_sdwa v36, v34, v232 dst_sel:DWORD dst_unused:UNUSED_PAD src0_sel:WORD_1 src1_sel:DWORD
	v_and_b32_sdwa v37, v32, v232 dst_sel:DWORD dst_unused:UNUSED_PAD src0_sel:WORD_1 src1_sel:DWORD
	v_add3_u32 v32, v32, v37, s43
	v_add3_u32 v34, v34, v36, s43
	v_and_b32_sdwa v36, v35, v232 dst_sel:DWORD dst_unused:UNUSED_PAD src0_sel:WORD_1 src1_sel:DWORD
	v_and_b32_sdwa v37, v33, v232 dst_sel:DWORD dst_unused:UNUSED_PAD src0_sel:WORD_1 src1_sel:DWORD
	v_add3_u32 v35, v35, v36, s43
	v_add3_u32 v33, v33, v37, s43
	v_and_b32_e32 v35, 0xffff0000, v35
	v_and_b32_e32 v36, 0xffff0000, v33
	v_or_b32_sdwa v33, v35, v34 dst_sel:DWORD dst_unused:UNUSED_PAD src0_sel:DWORD src1_sel:WORD_1
	v_or_b32_sdwa v32, v36, v32 dst_sel:DWORD dst_unused:UNUSED_PAD src0_sel:DWORD src1_sel:WORD_1
	s_nop 0
	v_mov_b32_e32 v218, v32
	v_mov_b32_e32 v219, v33
	s_nop 1
	v_permlane16_swap_b32_e32 v216, v218
	v_permlane16_swap_b32_e32 v217, v219
	global_store_dwordx4 v[220:221], v[216:219], off offset:64
	v_mul_f32_e32 v28, 0xbfb8aa3b, v28
	v_mul_f32_e32 v30, 0xbfb8aa3b, v30
	v_exp_f32_e32 v33, v28
	v_mul_f32_e32 v28, 0xbfb8aa3b, v29
	v_exp_f32_e32 v30, v30
	v_mul_f32_e32 v31, 0xbfb8aa3b, v31
	v_exp_f32_e32 v34, v28
	v_exp_f32_e32 v31, v31
	v_add_u32_e32 v32, 0x70, v148
	v_mad_i64_i32 v[28:29], s[0:1], v32, s84, v[146:147]
	v_add_f32_e32 v32, 1.0, v33
	v_add_f32_e32 v30, 1.0, v30
	v_mul_f32_e32 v24, 0xbfb8aa3b, v24
	v_mul_f32_e32 v26, 0xbfb8aa3b, v26
	v_rcp_f32_e32 v32, v32
	v_add_f32_e32 v33, 1.0, v34
	v_rcp_f32_e32 v30, v30
	v_add_f32_e32 v31, 1.0, v31
	v_exp_f32_e32 v24, v24
	v_mul_f32_e32 v25, 0xbfb8aa3b, v25
	v_exp_f32_e32 v26, v26
	v_mul_f32_e32 v27, 0xbfb8aa3b, v27
	v_rcp_f32_e32 v33, v33
	v_rcp_f32_e32 v31, v31
	v_exp_f32_e32 v25, v25
	v_exp_f32_e32 v27, v27
	v_and_b32_sdwa v34, v30, v232 dst_sel:DWORD dst_unused:UNUSED_PAD src0_sel:WORD_1 src1_sel:DWORD
	v_and_b32_sdwa v35, v32, v232 dst_sel:DWORD dst_unused:UNUSED_PAD src0_sel:WORD_1 src1_sel:DWORD
	v_add_f32_e32 v24, 1.0, v24
	v_add_f32_e32 v26, 1.0, v26
	v_mul_f32_e32 v20, 0xbfb8aa3b, v20
	v_mul_f32_e32 v22, 0xbfb8aa3b, v22
	v_add3_u32 v32, v32, v35, s43
	v_add3_u32 v30, v30, v34, s43
	v_and_b32_sdwa v34, v31, v232 dst_sel:DWORD dst_unused:UNUSED_PAD src0_sel:WORD_1 src1_sel:DWORD
	v_and_b32_sdwa v35, v33, v232 dst_sel:DWORD dst_unused:UNUSED_PAD src0_sel:WORD_1 src1_sel:DWORD
	v_rcp_f32_e32 v24, v24
	v_add_f32_e32 v25, 1.0, v25
	v_rcp_f32_e32 v26, v26
	v_add_f32_e32 v27, 1.0, v27
	v_exp_f32_e32 v20, v20
	v_mul_f32_e32 v21, 0xbfb8aa3b, v21
	v_exp_f32_e32 v22, v22
	v_mul_f32_e32 v23, 0xbfb8aa3b, v23
	v_add3_u32 v31, v31, v34, s43
	v_add3_u32 v33, v33, v35, s43
	v_rcp_f32_e32 v25, v25
	v_rcp_f32_e32 v27, v27
	v_exp_f32_e32 v21, v21
	v_exp_f32_e32 v23, v23
	v_and_b32_e32 v31, 0xffff0000, v31
	v_and_b32_e32 v33, 0xffff0000, v33
	v_lshl_add_u64 v[28:29], v[28:29], 0, v[128:129]
	v_or_b32_sdwa v31, v31, v30 dst_sel:DWORD dst_unused:UNUSED_PAD src0_sel:DWORD src1_sel:WORD_1
	v_or_b32_sdwa v30, v33, v32 dst_sel:DWORD dst_unused:UNUSED_PAD src0_sel:DWORD src1_sel:WORD_1
	s_nop 0
	v_mov_b32_e32 v212, v30
	v_mov_b32_e32 v213, v31
	v_and_b32_sdwa v30, v26, v232 dst_sel:DWORD dst_unused:UNUSED_PAD src0_sel:WORD_1 src1_sel:DWORD
	v_and_b32_sdwa v31, v24, v232 dst_sel:DWORD dst_unused:UNUSED_PAD src0_sel:WORD_1 src1_sel:DWORD
	v_add_f32_e32 v20, 1.0, v20
	v_add_f32_e32 v22, 1.0, v22
	v_mul_f32_e32 v16, 0xbfb8aa3b, v16
	v_mul_f32_e32 v18, 0xbfb8aa3b, v18
	v_add3_u32 v24, v24, v31, s43
	v_add3_u32 v26, v26, v30, s43
	v_and_b32_sdwa v30, v27, v232 dst_sel:DWORD dst_unused:UNUSED_PAD src0_sel:WORD_1 src1_sel:DWORD
	v_and_b32_sdwa v31, v25, v232 dst_sel:DWORD dst_unused:UNUSED_PAD src0_sel:WORD_1 src1_sel:DWORD
	v_rcp_f32_e32 v20, v20
	v_add_f32_e32 v21, 1.0, v21
	v_rcp_f32_e32 v22, v22
	v_add_f32_e32 v23, 1.0, v23
	v_exp_f32_e32 v16, v16
	v_mul_f32_e32 v17, 0xbfb8aa3b, v17
	v_exp_f32_e32 v18, v18
	v_mul_f32_e32 v19, 0xbfb8aa3b, v19
	v_add3_u32 v27, v27, v30, s43
	v_add3_u32 v25, v25, v31, s43
	v_rcp_f32_e32 v21, v21
	v_rcp_f32_e32 v23, v23
	v_exp_f32_e32 v17, v17
	v_exp_f32_e32 v19, v19
	v_and_b32_e32 v27, 0xffff0000, v27
	v_and_b32_e32 v30, 0xffff0000, v25
	v_or_b32_sdwa v25, v27, v26 dst_sel:DWORD dst_unused:UNUSED_PAD src0_sel:DWORD src1_sel:WORD_1
	v_or_b32_sdwa v24, v30, v24 dst_sel:DWORD dst_unused:UNUSED_PAD src0_sel:DWORD src1_sel:WORD_1
	s_nop 0
	v_mov_b32_e32 v214, v24
	v_mov_b32_e32 v215, v25
	v_mbcnt_lo_u32_b32 v224, -1, 0
	v_mbcnt_hi_u32_b32 v224, -1, v224
	v_and_b32_e32 v222, 16, v224
; #define ST4(ptr, a, b, c_, d) (*(uint2*)(ptr) = make_uint2((unsigned)f2bf(a) | ((unsigned)f2bf(b) << 16), (unsigned)f2bf(c_) | ((unsigned)f2bf(d) << 16)))
; template <int EPI>
; __device__ __forceinline__ void gemm_phase(const Ctx& p, int hf, const u16* __restrict__ A, int lda, const u16* __restrict__ Bt, int K, int nN, u16* __restrict__ dst, int ldc, bool fromx = false) {
;     ...
;     else if constexpr (EPI == EPI_SIGMOID) { ACC_LOOP( _Pragma("unroll") for (int e = 0; e < 4; ++e) v4[e] = __builtin_amdgcn_rcpf(1.f + __expf(-v4[e]));
;                                                         ST4(dst + (size_t)row * ldc + bcol + col, v4[0], v4[1], v4[2], v4[3]); ) }
	v_lshrrev_b32_e32 v224, 1, v222
	v_add_u32_e32 v222, v222, v224
	v_mov_b32_e32 v223, 0
	v_lshl_add_u64 v[220:221], v[28:29], 0, v[222:223]
	v_permlane16_swap_b32_e32 v212, v214
	v_permlane16_swap_b32_e32 v213, v215
	global_store_dwordx4 v[220:221], v[212:215], off
	v_and_b32_sdwa v24, v22, v232 dst_sel:DWORD dst_unused:UNUSED_PAD src0_sel:WORD_1 src1_sel:DWORD
	v_and_b32_sdwa v25, v20, v232 dst_sel:DWORD dst_unused:UNUSED_PAD src0_sel:WORD_1 src1_sel:DWORD
	v_add_f32_e32 v16, 1.0, v16
	v_add_f32_e32 v18, 1.0, v18
	v_add3_u32 v20, v20, v25, s43
	v_add3_u32 v22, v22, v24, s43
	v_and_b32_sdwa v24, v23, v232 dst_sel:DWORD dst_unused:UNUSED_PAD src0_sel:WORD_1 src1_sel:DWORD
	v_and_b32_sdwa v25, v21, v232 dst_sel:DWORD dst_unused:UNUSED_PAD src0_sel:WORD_1 src1_sel:DWORD
	v_rcp_f32_e32 v16, v16
	v_add_f32_e32 v17, 1.0, v17
	v_rcp_f32_e32 v18, v18
	v_add_f32_e32 v19, 1.0, v19
	v_add3_u32 v23, v23, v24, s43
	v_add3_u32 v21, v21, v25, s43
	v_rcp_f32_e32 v17, v17
	v_rcp_f32_e32 v19, v19
	v_and_b32_e32 v23, 0xffff0000, v23
	v_and_b32_e32 v24, 0xffff0000, v21
	v_or_b32_sdwa v21, v23, v22 dst_sel:DWORD dst_unused:UNUSED_PAD src0_sel:DWORD src1_sel:WORD_1
	v_or_b32_sdwa v20, v24, v20 dst_sel:DWORD dst_unused:UNUSED_PAD src0_sel:DWORD src1_sel:WORD_1
	s_nop 0
	v_mov_b32_e32 v216, v20
	v_mov_b32_e32 v217, v21
	v_and_b32_sdwa v20, v18, v232 dst_sel:DWORD dst_unused:UNUSED_PAD src0_sel:WORD_1 src1_sel:DWORD
	v_and_b32_sdwa v21, v16, v232 dst_sel:DWORD dst_unused:UNUSED_PAD src0_sel:WORD_1 src1_sel:DWORD
	v_add3_u32 v16, v16, v21, s43
	v_add3_u32 v18, v18, v20, s43
	v_and_b32_sdwa v20, v19, v232 dst_sel:DWORD dst_unused:UNUSED_PAD src0_sel:WORD_1 src1_sel:DWORD
	v_and_b32_sdwa v21, v17, v232 dst_sel:DWORD dst_unused:UNUSED_PAD src0_sel:WORD_1 src1_sel:DWORD
	v_add3_u32 v19, v19, v20, s43
	v_add3_u32 v17, v17, v21, s43
	v_and_b32_e32 v19, 0xffff0000, v19
	v_and_b32_e32 v20, 0xffff0000, v17
	v_or_b32_sdwa v17, v19, v18 dst_sel:DWORD dst_unused:UNUSED_PAD src0_sel:DWORD src1_sel:WORD_1
	v_or_b32_sdwa v16, v20, v16 dst_sel:DWORD dst_unused:UNUSED_PAD src0_sel:DWORD src1_sel:WORD_1
	s_nop 0
	v_mov_b32_e32 v218, v16
	v_mov_b32_e32 v219, v17
	s_nop 1
	v_permlane16_swap_b32_e32 v216, v218
	v_permlane16_swap_b32_e32 v217, v219
	global_store_dwordx4 v[220:221], v[216:219], off offset:64
	s_and_b64 s[16:17], vcc, s[16:17]
	s_and_saveexec_b64 s[0:1], s[16:17]
	s_cbranch_execz .LBB0_1290
; #define ST4(ptr, a, b, c_, d) (*(uint2*)(ptr) = make_uint2((unsigned)f2bf(a) | ((unsigned)f2bf(b) << 16), (unsigned)f2bf(c_) | ((unsigned)f2bf(d) << 16)))
; template <int EPI>
; __device__ __forceinline__ void gemm_phase(const Ctx& p, int hf, const u16* __restrict__ A, int lda, const u16* __restrict__ Bt, int K, int nN, u16* __restrict__ dst, int ldc, bool fromx = false) {
;     ...
;     else if constexpr (EPI == EPI_SIGMOID) { ACC_LOOP( _Pragma("unroll") for (int e = 0; e < 4; ++e) v4[e] = __builtin_amdgcn_rcpf(1.f + __expf(-v4[e]));
;                                                         ST4(dst + (size_t)row * ldc + bcol + col, v4[0], v4[1], v4[2], v4[3]); ) }
	v_add_u32_e32 v18, s14, v180
	v_mov_b64_e32 v[16:17], s[4:5]
	v_mul_f32_e32 v12, 0xbfb8aa3b, v12
	v_mul_f32_e32 v14, 0xbfb8aa3b, v14
	v_mad_i64_i32 v[16:17], s[14:15], v18, s84, v[16:17]
	v_exp_f32_e32 v18, v12
	v_mul_f32_e32 v12, 0xbfb8aa3b, v13
	v_exp_f32_e32 v14, v14
	v_mul_f32_e32 v15, 0xbfb8aa3b, v15
	v_exp_f32_e32 v19, v12
	v_exp_f32_e32 v15, v15
	v_lshl_add_u64 v[12:13], s[12:13], 1, v[16:17]
	v_add_f32_e32 v16, 1.0, v18
	v_add_f32_e32 v14, 1.0, v14
	v_mul_f32_e32 v8, 0xbfb8aa3b, v8
	v_mul_f32_e32 v10, 0xbfb8aa3b, v10
	v_rcp_f32_e32 v16, v16
	v_add_f32_e32 v17, 1.0, v19
	v_rcp_f32_e32 v14, v14
	v_add_f32_e32 v15, 1.0, v15
	v_exp_f32_e32 v8, v8
	v_mul_f32_e32 v9, 0xbfb8aa3b, v9
	v_exp_f32_e32 v10, v10
	v_mul_f32_e32 v11, 0xbfb8aa3b, v11
	v_rcp_f32_e32 v17, v17
	v_rcp_f32_e32 v15, v15
	v_exp_f32_e32 v9, v9
	v_exp_f32_e32 v11, v11
	v_and_b32_sdwa v18, v14, v232 dst_sel:DWORD dst_unused:UNUSED_PAD src0_sel:WORD_1 src1_sel:DWORD
	v_and_b32_sdwa v19, v16, v232 dst_sel:DWORD dst_unused:UNUSED_PAD src0_sel:WORD_1 src1_sel:DWORD
	v_add_f32_e32 v8, 1.0, v8
	v_add_f32_e32 v10, 1.0, v10
	v_mul_f32_e32 v4, 0xbfb8aa3b, v4
	v_mul_f32_e32 v6, 0xbfb8aa3b, v6
	v_add3_u32 v16, v16, v19, s43
	v_add3_u32 v14, v14, v18, s43
	v_and_b32_sdwa v18, v15, v232 dst_sel:DWORD dst_unused:UNUSED_PAD src0_sel:WORD_1 src1_sel:DWORD
	v_and_b32_sdwa v19, v17, v232 dst_sel:DWORD dst_unused:UNUSED_PAD src0_sel:WORD_1 src1_sel:DWORD
	v_rcp_f32_e32 v8, v8
	v_add_f32_e32 v9, 1.0, v9
	v_rcp_f32_e32 v10, v10
	v_add_f32_e32 v11, 1.0, v11
	v_exp_f32_e32 v4, v4
	v_mul_f32_e32 v5, 0xbfb8aa3b, v5
	v_exp_f32_e32 v6, v6
	v_mul_f32_e32 v7, 0xbfb8aa3b, v7
	v_add3_u32 v15, v15, v18, s43
	v_add3_u32 v17, v17, v19, s43
	v_rcp_f32_e32 v9, v9
	v_rcp_f32_e32 v11, v11
	v_exp_f32_e32 v5, v5
	v_exp_f32_e32 v7, v7
	v_and_b32_e32 v15, 0xffff0000, v15
	v_and_b32_e32 v17, 0xffff0000, v17
	v_lshl_add_u64 v[12:13], v[12:13], 0, v[128:129]
	v_or_b32_sdwa v15, v15, v14 dst_sel:DWORD dst_unused:UNUSED_PAD src0_sel:DWORD src1_sel:WORD_1
	v_or_b32_sdwa v14, v17, v16 dst_sel:DWORD dst_unused:UNUSED_PAD src0_sel:DWORD src1_sel:WORD_1
	s_nop 0
	v_mov_b32_e32 v212, v14
	v_mov_b32_e32 v213, v15
	v_and_b32_sdwa v14, v10, v232 dst_sel:DWORD dst_unused:UNUSED_PAD src0_sel:WORD_1 src1_sel:DWORD
	v_and_b32_sdwa v15, v8, v232 dst_sel:DWORD dst_unused:UNUSED_PAD src0_sel:WORD_1 src1_sel:DWORD
	v_add_f32_e32 v4, 1.0, v4
	v_add_f32_e32 v6, 1.0, v6
	v_mul_f32_e32 v0, 0xbfb8aa3b, v0
	v_mul_f32_e32 v2, 0xbfb8aa3b, v2
	v_add3_u32 v8, v8, v15, s43
	v_add3_u32 v10, v10, v14, s43
	v_and_b32_sdwa v14, v11, v232 dst_sel:DWORD dst_unused:UNUSED_PAD src0_sel:WORD_1 src1_sel:DWORD
	v_and_b32_sdwa v15, v9, v232 dst_sel:DWORD dst_unused:UNUSED_PAD src0_sel:WORD_1 src1_sel:DWORD
	v_rcp_f32_e32 v4, v4
	v_add_f32_e32 v5, 1.0, v5
	v_rcp_f32_e32 v6, v6
	v_add_f32_e32 v7, 1.0, v7
	v_exp_f32_e32 v0, v0
	v_mul_f32_e32 v1, 0xbfb8aa3b, v1
	v_exp_f32_e32 v2, v2
	v_mul_f32_e32 v3, 0xbfb8aa3b, v3
	v_add3_u32 v11, v11, v14, s43
	v_add3_u32 v9, v9, v15, s43
	v_rcp_f32_e32 v5, v5
	v_rcp_f32_e32 v7, v7
	v_exp_f32_e32 v1, v1
	v_exp_f32_e32 v3, v3
	v_and_b32_e32 v11, 0xffff0000, v11
	v_and_b32_e32 v14, 0xffff0000, v9
	v_or_b32_sdwa v9, v11, v10 dst_sel:DWORD dst_unused:UNUSED_PAD src0_sel:DWORD src1_sel:WORD_1
	v_or_b32_sdwa v8, v14, v8 dst_sel:DWORD dst_unused:UNUSED_PAD src0_sel:DWORD src1_sel:WORD_1
	s_nop 0
	v_mov_b32_e32 v214, v8
	v_mov_b32_e32 v215, v9
	v_mbcnt_lo_u32_b32 v224, -1, 0
	v_mbcnt_hi_u32_b32 v224, -1, v224
	v_and_b32_e32 v222, 16, v224
	v_lshrrev_b32_e32 v224, 1, v222
	v_add_u32_e32 v222, v222, v224
	v_mov_b32_e32 v223, 0
	v_lshl_add_u64 v[220:221], v[12:13], 0, v[222:223]
	v_permlane16_swap_b32_e32 v212, v214
	v_permlane16_swap_b32_e32 v213, v215
	global_store_dwordx4 v[220:221], v[212:215], off
	v_and_b32_sdwa v8, v6, v232 dst_sel:DWORD dst_unused:UNUSED_PAD src0_sel:WORD_1 src1_sel:DWORD
	v_and_b32_sdwa v9, v4, v232 dst_sel:DWORD dst_unused:UNUSED_PAD src0_sel:WORD_1 src1_sel:DWORD
	v_add_f32_e32 v0, 1.0, v0
	v_add_f32_e32 v2, 1.0, v2
	v_add3_u32 v4, v4, v9, s43
	v_add3_u32 v6, v6, v8, s43
	v_and_b32_sdwa v8, v7, v232 dst_sel:DWORD dst_unused:UNUSED_PAD src0_sel:WORD_1 src1_sel:DWORD
	v_and_b32_sdwa v9, v5, v232 dst_sel:DWORD dst_unused:UNUSED_PAD src0_sel:WORD_1 src1_sel:DWORD
	v_rcp_f32_e32 v0, v0
	v_add_f32_e32 v1, 1.0, v1
	v_rcp_f32_e32 v2, v2
	v_add_f32_e32 v3, 1.0, v3
	v_add3_u32 v7, v7, v8, s43
	v_add3_u32 v5, v5, v9, s43
	v_rcp_f32_e32 v1, v1
	v_rcp_f32_e32 v3, v3
	v_and_b32_e32 v7, 0xffff0000, v7
	v_and_b32_e32 v8, 0xffff0000, v5
	v_or_b32_sdwa v5, v7, v6 dst_sel:DWORD dst_unused:UNUSED_PAD src0_sel:DWORD src1_sel:WORD_1
	v_or_b32_sdwa v4, v8, v4 dst_sel:DWORD dst_unused:UNUSED_PAD src0_sel:DWORD src1_sel:WORD_1
	s_nop 0
	v_mov_b32_e32 v216, v4
	v_mov_b32_e32 v217, v5
	v_and_b32_sdwa v4, v2, v232 dst_sel:DWORD dst_unused:UNUSED_PAD src0_sel:WORD_1 src1_sel:DWORD
	v_and_b32_sdwa v5, v0, v232 dst_sel:DWORD dst_unused:UNUSED_PAD src0_sel:WORD_1 src1_sel:DWORD
	v_add3_u32 v0, v0, v5, s43
	v_add3_u32 v2, v2, v4, s43
	v_and_b32_sdwa v4, v3, v232 dst_sel:DWORD dst_unused:UNUSED_PAD src0_sel:WORD_1 src1_sel:DWORD
	v_and_b32_sdwa v5, v1, v232 dst_sel:DWORD dst_unused:UNUSED_PAD src0_sel:WORD_1 src1_sel:DWORD
	v_add3_u32 v3, v3, v4, s43
	v_add3_u32 v1, v1, v5, s43
	v_and_b32_e32 v3, 0xffff0000, v3
	v_and_b32_e32 v4, 0xffff0000, v1
	v_or_b32_sdwa v1, v3, v2 dst_sel:DWORD dst_unused:UNUSED_PAD src0_sel:DWORD src1_sel:WORD_1
	v_or_b32_sdwa v0, v4, v0 dst_sel:DWORD dst_unused:UNUSED_PAD src0_sel:DWORD src1_sel:WORD_1
	s_nop 0
	v_mov_b32_e32 v218, v0
	v_mov_b32_e32 v219, v1
	s_nop 1
	v_permlane16_swap_b32_e32 v216, v218
	v_permlane16_swap_b32_e32 v217, v219
	global_store_dwordx4 v[220:221], v[216:219], off offset:64
	s_branch .LBB0_1290

; #define SBAR() __builtin_amdgcn_sched_barrier(0)
; #define ST4(ptr, a, b, c_, d) (*(uint2*)(ptr) = make_uint2((unsigned)f2bf(a) | ((unsigned)f2bf(b) << 16), (unsigned)f2bf(c_) | ((unsigned)f2bf(d) << 16)))
; __device__ __forceinline__ void merge_phase(const Ctx& p, int hf) {
;     ...
;     u16* mt = MG + (size_t)brow * DM + bcol + wc * 32 + fq * 4;
; #pragma unroll
;     for (int m = 0; m < 8; ++m) {
; #pragma unroll
;       for (int n = 0; n < 2; ++n) ST4(mt + (size_t)(wr * 128 + m * 16 + fr) * DM + n * 16, msum[m][n][0], msum[m][n][1], msum[m][n][2], msum[m][n][3]);
;       SBAR();
;     }
.LBB0_1334:
	s_lshl_b64 s[6:7], s[10:11], 11
	s_add_u32 s6, s59, s6
	s_addc_u32 s7, s66, s7
	s_add_u32 s6, s6, s12
	v_and_b32_sdwa v13, v196, v232 dst_sel:DWORD dst_unused:UNUSED_PAD src0_sel:WORD_1 src1_sel:DWORD
	s_addc_u32 s7, s7, s13
	v_mov_b32_e32 v121, v129
	v_add3_u32 v14, v196, v13, s43
	v_and_b32_sdwa v13, v195, v232 dst_sel:DWORD dst_unused:UNUSED_PAD src0_sel:WORD_1 src1_sel:DWORD
	v_and_b32_sdwa v15, v194, v232 dst_sel:DWORD dst_unused:UNUSED_PAD src0_sel:WORD_1 src1_sel:DWORD
	v_lshl_add_u64 v[8:9], s[6:7], 0, v[120:121]
	v_mov_b32_e32 v123, v129
	v_and_b32_sdwa v12, v197, v232 dst_sel:DWORD dst_unused:UNUSED_PAD src0_sel:WORD_1 src1_sel:DWORD
	v_add3_u32 v13, v195, v13, s43
	v_add3_u32 v15, v194, v15, s43
	v_lshl_add_u64 v[8:9], v[8:9], 0, v[122:123]
	v_add3_u32 v12, v197, v12, s43
	v_and_b32_e32 v13, 0xffff0000, v13
	v_and_b32_e32 v15, 0xffff0000, v15
	v_lshl_add_u64 v[10:11], v[8:9], 0, v[104:105]
	v_or_b32_sdwa v13, v13, v12 dst_sel:DWORD dst_unused:UNUSED_PAD src0_sel:DWORD src1_sel:WORD_1
	v_or_b32_sdwa v12, v15, v14 dst_sel:DWORD dst_unused:UNUSED_PAD src0_sel:DWORD src1_sel:WORD_1
	s_nop 0
	v_mov_b32_e32 v244, v12
	v_mov_b32_e32 v245, v13
	v_and_b32_sdwa v13, v192, v232 dst_sel:DWORD dst_unused:UNUSED_PAD src0_sel:WORD_1 src1_sel:DWORD
	v_add3_u32 v14, v192, v13, s43
	v_and_b32_sdwa v13, v191, v232 dst_sel:DWORD dst_unused:UNUSED_PAD src0_sel:WORD_1 src1_sel:DWORD
	v_and_b32_sdwa v15, v190, v232 dst_sel:DWORD dst_unused:UNUSED_PAD src0_sel:WORD_1 src1_sel:DWORD
	v_and_b32_sdwa v12, v193, v232 dst_sel:DWORD dst_unused:UNUSED_PAD src0_sel:WORD_1 src1_sel:DWORD
	v_add3_u32 v13, v191, v13, s43
	v_add3_u32 v15, v190, v15, s43
	v_add3_u32 v12, v193, v12, s43
	v_and_b32_e32 v13, 0xffff0000, v13
	v_and_b32_e32 v15, 0xffff0000, v15
	v_or_b32_sdwa v13, v13, v12 dst_sel:DWORD dst_unused:UNUSED_PAD src0_sel:DWORD src1_sel:WORD_1
	v_or_b32_sdwa v12, v15, v14 dst_sel:DWORD dst_unused:UNUSED_PAD src0_sel:DWORD src1_sel:WORD_1
	s_nop 0
	v_mov_b32_e32 v246, v12
	v_mov_b32_e32 v247, v13
	v_mbcnt_lo_u32_b32 v252, -1, 0
	v_mbcnt_hi_u32_b32 v252, -1, v252
	v_and_b32_e32 v250, 16, v252
	v_lshrrev_b32_e32 v252, 1, v250
	v_add_u32_e32 v250, v250, v252
	v_mov_b32_e32 v251, 0
	v_lshl_add_u64 v[248:249], v[10:11], 0, v[250:251]
	v_permlane16_swap_b32_e32 v244, v246
	v_permlane16_swap_b32_e32 v245, v247
	global_store_dwordx4 v[248:249], v[244:247], off
	v_and_b32_sdwa v13, v188, v232 dst_sel:DWORD dst_unused:UNUSED_PAD src0_sel:WORD_1 src1_sel:DWORD
	v_add3_u32 v14, v188, v13, s43
	v_and_b32_sdwa v13, v187, v232 dst_sel:DWORD dst_unused:UNUSED_PAD src0_sel:WORD_1 src1_sel:DWORD
	v_and_b32_sdwa v15, v186, v232 dst_sel:DWORD dst_unused:UNUSED_PAD src0_sel:WORD_1 src1_sel:DWORD
	v_and_b32_sdwa v12, v189, v232 dst_sel:DWORD dst_unused:UNUSED_PAD src0_sel:WORD_1 src1_sel:DWORD
	v_add3_u32 v13, v187, v13, s43
	v_add3_u32 v15, v186, v15, s43
	v_add3_u32 v12, v189, v12, s43
	v_and_b32_e32 v13, 0xffff0000, v13
	v_and_b32_e32 v15, 0xffff0000, v15
	v_lshl_add_u64 v[10:11], v[8:9], 0, v[106:107]
	v_or_b32_sdwa v13, v13, v12 dst_sel:DWORD dst_unused:UNUSED_PAD src0_sel:DWORD src1_sel:WORD_1
	v_or_b32_sdwa v12, v15, v14 dst_sel:DWORD dst_unused:UNUSED_PAD src0_sel:DWORD src1_sel:WORD_1
	s_nop 0
	v_mov_b32_e32 v244, v12
	v_mov_b32_e32 v245, v13
	v_and_b32_sdwa v13, v184, v232 dst_sel:DWORD dst_unused:UNUSED_PAD src0_sel:WORD_1 src1_sel:DWORD
	v_add3_u32 v14, v184, v13, s43
	v_and_b32_sdwa v13, v183, v232 dst_sel:DWORD dst_unused:UNUSED_PAD src0_sel:WORD_1 src1_sel:DWORD
	v_and_b32_sdwa v15, v182, v232 dst_sel:DWORD dst_unused:UNUSED_PAD src0_sel:WORD_1 src1_sel:DWORD
	v_and_b32_sdwa v12, v185, v232 dst_sel:DWORD dst_unused:UNUSED_PAD src0_sel:WORD_1 src1_sel:DWORD
	v_add3_u32 v13, v183, v13, s43
	v_add3_u32 v15, v182, v15, s43
	v_add3_u32 v12, v185, v12, s43
	v_and_b32_e32 v13, 0xffff0000, v13
	v_and_b32_e32 v15, 0xffff0000, v15
	v_or_b32_sdwa v13, v13, v12 dst_sel:DWORD dst_unused:UNUSED_PAD src0_sel:DWORD src1_sel:WORD_1
	v_or_b32_sdwa v12, v15, v14 dst_sel:DWORD dst_unused:UNUSED_PAD src0_sel:DWORD src1_sel:WORD_1
	s_nop 0
	v_mov_b32_e32 v246, v12
	v_mov_b32_e32 v247, v13
	v_mbcnt_lo_u32_b32 v252, -1, 0
	v_mbcnt_hi_u32_b32 v252, -1, v252
	v_and_b32_e32 v250, 16, v252
	v_lshrrev_b32_e32 v252, 1, v250
	v_add_u32_e32 v250, v250, v252
	v_mov_b32_e32 v251, 0
	v_lshl_add_u64 v[248:249], v[10:11], 0, v[250:251]
	v_permlane16_swap_b32_e32 v244, v246
	v_permlane16_swap_b32_e32 v245, v247
	global_store_dwordx4 v[248:249], v[244:247], off
	v_and_b32_sdwa v13, v178, v232 dst_sel:DWORD dst_unused:UNUSED_PAD src0_sel:WORD_1 src1_sel:DWORD
	v_add3_u32 v14, v178, v13, s43
	v_and_b32_sdwa v13, v177, v232 dst_sel:DWORD dst_unused:UNUSED_PAD src0_sel:WORD_1 src1_sel:DWORD
	v_and_b32_sdwa v15, v176, v232 dst_sel:DWORD dst_unused:UNUSED_PAD src0_sel:WORD_1 src1_sel:DWORD
	v_and_b32_sdwa v12, v179, v232 dst_sel:DWORD dst_unused:UNUSED_PAD src0_sel:WORD_1 src1_sel:DWORD
	v_add3_u32 v13, v177, v13, s43
	v_add3_u32 v15, v176, v15, s43
	v_add3_u32 v12, v179, v12, s43
	v_and_b32_e32 v13, 0xffff0000, v13
	v_and_b32_e32 v15, 0xffff0000, v15
	v_lshl_add_u64 v[10:11], v[8:9], 0, v[108:109]
	v_or_b32_sdwa v13, v13, v12 dst_sel:DWORD dst_unused:UNUSED_PAD src0_sel:DWORD src1_sel:WORD_1
	v_or_b32_sdwa v12, v15, v14 dst_sel:DWORD dst_unused:UNUSED_PAD src0_sel:DWORD src1_sel:WORD_1
	s_nop 0
	v_mov_b32_e32 v244, v12
	v_mov_b32_e32 v245, v13
	v_and_b32_sdwa v13, v174, v232 dst_sel:DWORD dst_unused:UNUSED_PAD src0_sel:WORD_1 src1_sel:DWORD
	v_add3_u32 v14, v174, v13, s43
	v_and_b32_sdwa v13, v173, v232 dst_sel:DWORD dst_unused:UNUSED_PAD src0_sel:WORD_1 src1_sel:DWORD
; #define SBAR() __builtin_amdgcn_sched_barrier(0)
; #define ST4(ptr, a, b, c_, d) (*(uint2*)(ptr) = make_uint2((unsigned)f2bf(a) | ((unsigned)f2bf(b) << 16), (unsigned)f2bf(c_) | ((unsigned)f2bf(d) << 16)))
; __device__ __forceinline__ void merge_phase(const Ctx& p, int hf) {
;     ...
;     u16* mt = MG + (size_t)brow * DM + bcol + wc * 32 + fq * 4;
; #pragma unroll
;     for (int m = 0; m < 8; ++m) {
; #pragma unroll
;       for (int n = 0; n < 2; ++n) ST4(mt + (size_t)(wr * 128 + m * 16 + fr) * DM + n * 16, msum[m][n][0], msum[m][n][1], msum[m][n][2], msum[m][n][3]);
;       SBAR();
;     }
	v_and_b32_sdwa v15, v172, v232 dst_sel:DWORD dst_unused:UNUSED_PAD src0_sel:WORD_1 src1_sel:DWORD
	v_and_b32_sdwa v12, v175, v232 dst_sel:DWORD dst_unused:UNUSED_PAD src0_sel:WORD_1 src1_sel:DWORD
	v_add3_u32 v13, v173, v13, s43
	v_add3_u32 v15, v172, v15, s43
	v_add3_u32 v12, v175, v12, s43
	v_and_b32_e32 v13, 0xffff0000, v13
	v_and_b32_e32 v15, 0xffff0000, v15
	v_or_b32_sdwa v13, v13, v12 dst_sel:DWORD dst_unused:UNUSED_PAD src0_sel:DWORD src1_sel:WORD_1
	v_or_b32_sdwa v12, v15, v14 dst_sel:DWORD dst_unused:UNUSED_PAD src0_sel:DWORD src1_sel:WORD_1
	s_nop 0
	v_mov_b32_e32 v246, v12
	v_mov_b32_e32 v247, v13
	v_mbcnt_lo_u32_b32 v252, -1, 0
	v_mbcnt_hi_u32_b32 v252, -1, v252
	v_and_b32_e32 v250, 16, v252
	v_lshrrev_b32_e32 v252, 1, v250
	v_add_u32_e32 v250, v250, v252
	v_mov_b32_e32 v251, 0
	v_lshl_add_u64 v[248:249], v[10:11], 0, v[250:251]
	v_permlane16_swap_b32_e32 v244, v246
	v_permlane16_swap_b32_e32 v245, v247
	global_store_dwordx4 v[248:249], v[244:247], off
	v_and_b32_sdwa v13, v170, v232 dst_sel:DWORD dst_unused:UNUSED_PAD src0_sel:WORD_1 src1_sel:DWORD
	v_add3_u32 v14, v170, v13, s43
	v_and_b32_sdwa v13, v169, v232 dst_sel:DWORD dst_unused:UNUSED_PAD src0_sel:WORD_1 src1_sel:DWORD
	v_and_b32_sdwa v15, v168, v232 dst_sel:DWORD dst_unused:UNUSED_PAD src0_sel:WORD_1 src1_sel:DWORD
	v_and_b32_sdwa v12, v171, v232 dst_sel:DWORD dst_unused:UNUSED_PAD src0_sel:WORD_1 src1_sel:DWORD
	v_add3_u32 v13, v169, v13, s43
	v_add3_u32 v15, v168, v15, s43
	v_add3_u32 v12, v171, v12, s43
	v_and_b32_e32 v13, 0xffff0000, v13
	v_and_b32_e32 v15, 0xffff0000, v15
	v_lshl_add_u64 v[10:11], v[8:9], 0, v[110:111]
	v_or_b32_sdwa v13, v13, v12 dst_sel:DWORD dst_unused:UNUSED_PAD src0_sel:DWORD src1_sel:WORD_1
	v_or_b32_sdwa v12, v15, v14 dst_sel:DWORD dst_unused:UNUSED_PAD src0_sel:DWORD src1_sel:WORD_1
	s_nop 0
	v_mov_b32_e32 v244, v12
	v_mov_b32_e32 v245, v13
	v_and_b32_sdwa v13, v166, v232 dst_sel:DWORD dst_unused:UNUSED_PAD src0_sel:WORD_1 src1_sel:DWORD
	v_add3_u32 v14, v166, v13, s43
	v_and_b32_sdwa v13, v165, v232 dst_sel:DWORD dst_unused:UNUSED_PAD src0_sel:WORD_1 src1_sel:DWORD
	v_and_b32_sdwa v15, v164, v232 dst_sel:DWORD dst_unused:UNUSED_PAD src0_sel:WORD_1 src1_sel:DWORD
	v_and_b32_sdwa v12, v167, v232 dst_sel:DWORD dst_unused:UNUSED_PAD src0_sel:WORD_1 src1_sel:DWORD
	v_add3_u32 v13, v165, v13, s43
	v_add3_u32 v15, v164, v15, s43
	v_add3_u32 v12, v167, v12, s43
	v_and_b32_e32 v13, 0xffff0000, v13
	v_and_b32_e32 v15, 0xffff0000, v15
	v_or_b32_sdwa v13, v13, v12 dst_sel:DWORD dst_unused:UNUSED_PAD src0_sel:DWORD src1_sel:WORD_1
	v_or_b32_sdwa v12, v15, v14 dst_sel:DWORD dst_unused:UNUSED_PAD src0_sel:DWORD src1_sel:WORD_1
	s_nop 0
	v_mov_b32_e32 v246, v12
	v_mov_b32_e32 v247, v13
	v_mbcnt_lo_u32_b32 v252, -1, 0
	v_mbcnt_hi_u32_b32 v252, -1, v252
	v_and_b32_e32 v250, 16, v252
	v_lshrrev_b32_e32 v252, 1, v250
	v_add_u32_e32 v250, v250, v252
	v_mov_b32_e32 v251, 0
	v_lshl_add_u64 v[248:249], v[10:11], 0, v[250:251]
	v_permlane16_swap_b32_e32 v244, v246
	v_permlane16_swap_b32_e32 v245, v247
	global_store_dwordx4 v[248:249], v[244:247], off
	v_and_b32_sdwa v13, v162, v232 dst_sel:DWORD dst_unused:UNUSED_PAD src0_sel:WORD_1 src1_sel:DWORD
	v_add3_u32 v14, v162, v13, s43
	v_and_b32_sdwa v13, v161, v232 dst_sel:DWORD dst_unused:UNUSED_PAD src0_sel:WORD_1 src1_sel:DWORD
	v_and_b32_sdwa v15, v160, v232 dst_sel:DWORD dst_unused:UNUSED_PAD src0_sel:WORD_1 src1_sel:DWORD
	v_and_b32_sdwa v12, v163, v232 dst_sel:DWORD dst_unused:UNUSED_PAD src0_sel:WORD_1 src1_sel:DWORD
	v_add3_u32 v13, v161, v13, s43
	v_add3_u32 v15, v160, v15, s43
	v_add3_u32 v12, v163, v12, s43
	v_and_b32_e32 v13, 0xffff0000, v13
	v_and_b32_e32 v15, 0xffff0000, v15
	v_lshl_add_u64 v[10:11], v[8:9], 0, v[112:113]
	v_or_b32_sdwa v13, v13, v12 dst_sel:DWORD dst_unused:UNUSED_PAD src0_sel:DWORD src1_sel:WORD_1
	v_or_b32_sdwa v12, v15, v14 dst_sel:DWORD dst_unused:UNUSED_PAD src0_sel:DWORD src1_sel:WORD_1
	s_nop 0
	v_mov_b32_e32 v244, v12
	v_mov_b32_e32 v245, v13
	v_and_b32_sdwa v13, v158, v232 dst_sel:DWORD dst_unused:UNUSED_PAD src0_sel:WORD_1 src1_sel:DWORD
	v_add3_u32 v14, v158, v13, s43
	v_and_b32_sdwa v13, v157, v232 dst_sel:DWORD dst_unused:UNUSED_PAD src0_sel:WORD_1 src1_sel:DWORD
	v_and_b32_sdwa v15, v156, v232 dst_sel:DWORD dst_unused:UNUSED_PAD src0_sel:WORD_1 src1_sel:DWORD
	v_and_b32_sdwa v12, v159, v232 dst_sel:DWORD dst_unused:UNUSED_PAD src0_sel:WORD_1 src1_sel:DWORD
	v_add3_u32 v13, v157, v13, s43
	v_add3_u32 v15, v156, v15, s43
	v_add3_u32 v12, v159, v12, s43
	v_and_b32_e32 v13, 0xffff0000, v13
	v_and_b32_e32 v15, 0xffff0000, v15
	v_or_b32_sdwa v13, v13, v12 dst_sel:DWORD dst_unused:UNUSED_PAD src0_sel:DWORD src1_sel:WORD_1
	v_or_b32_sdwa v12, v15, v14 dst_sel:DWORD dst_unused:UNUSED_PAD src0_sel:DWORD src1_sel:WORD_1
	s_nop 0
	v_mov_b32_e32 v246, v12
	v_mov_b32_e32 v247, v13
	v_mbcnt_lo_u32_b32 v252, -1, 0
	v_mbcnt_hi_u32_b32 v252, -1, v252
	v_and_b32_e32 v250, 16, v252
	v_lshrrev_b32_e32 v252, 1, v250
	v_add_u32_e32 v250, v250, v252
	v_mov_b32_e32 v251, 0
	v_lshl_add_u64 v[248:249], v[10:11], 0, v[250:251]
	v_permlane16_swap_b32_e32 v244, v246
	v_permlane16_swap_b32_e32 v245, v247
	global_store_dwordx4 v[248:249], v[244:247], off
	v_and_b32_sdwa v13, v154, v232 dst_sel:DWORD dst_unused:UNUSED_PAD src0_sel:WORD_1 src1_sel:DWORD
	v_add3_u32 v14, v154, v13, s43
	v_and_b32_sdwa v13, v153, v232 dst_sel:DWORD dst_unused:UNUSED_PAD src0_sel:WORD_1 src1_sel:DWORD
	v_and_b32_sdwa v15, v152, v232 dst_sel:DWORD dst_unused:UNUSED_PAD src0_sel:WORD_1 src1_sel:DWORD
	v_and_b32_sdwa v12, v155, v232 dst_sel:DWORD dst_unused:UNUSED_PAD src0_sel:WORD_1 src1_sel:DWORD
	v_add3_u32 v13, v153, v13, s43
; #define SBAR() __builtin_amdgcn_sched_barrier(0)
; #define ST4(ptr, a, b, c_, d) (*(uint2*)(ptr) = make_uint2((unsigned)f2bf(a) | ((unsigned)f2bf(b) << 16), (unsigned)f2bf(c_) | ((unsigned)f2bf(d) << 16)))
; __device__ __forceinline__ void merge_phase(const Ctx& p, int hf) {
;     ...
;     u16* mt = MG + (size_t)brow * DM + bcol + wc * 32 + fq * 4;
; #pragma unroll
;     for (int m = 0; m < 8; ++m) {
; #pragma unroll
;       for (int n = 0; n < 2; ++n) ST4(mt + (size_t)(wr * 128 + m * 16 + fr) * DM + n * 16, msum[m][n][0], msum[m][n][1], msum[m][n][2], msum[m][n][3]);
;       SBAR();
;     }
	v_add3_u32 v15, v152, v15, s43
	v_add3_u32 v12, v155, v12, s43
	v_and_b32_e32 v13, 0xffff0000, v13
	v_and_b32_e32 v15, 0xffff0000, v15
	v_lshl_add_u64 v[10:11], v[8:9], 0, v[114:115]
	v_or_b32_sdwa v13, v13, v12 dst_sel:DWORD dst_unused:UNUSED_PAD src0_sel:DWORD src1_sel:WORD_1
	v_or_b32_sdwa v12, v15, v14 dst_sel:DWORD dst_unused:UNUSED_PAD src0_sel:DWORD src1_sel:WORD_1
	s_nop 0
	v_mov_b32_e32 v244, v12
	v_mov_b32_e32 v245, v13
	v_and_b32_sdwa v13, v150, v232 dst_sel:DWORD dst_unused:UNUSED_PAD src0_sel:WORD_1 src1_sel:DWORD
	v_add3_u32 v14, v150, v13, s43
	v_and_b32_sdwa v13, v149, v232 dst_sel:DWORD dst_unused:UNUSED_PAD src0_sel:WORD_1 src1_sel:DWORD
	v_and_b32_sdwa v15, v148, v232 dst_sel:DWORD dst_unused:UNUSED_PAD src0_sel:WORD_1 src1_sel:DWORD
	v_and_b32_sdwa v12, v151, v232 dst_sel:DWORD dst_unused:UNUSED_PAD src0_sel:WORD_1 src1_sel:DWORD
	v_add3_u32 v13, v149, v13, s43
	v_add3_u32 v15, v148, v15, s43
	v_add3_u32 v12, v151, v12, s43
	v_and_b32_e32 v13, 0xffff0000, v13
	v_and_b32_e32 v15, 0xffff0000, v15
	v_or_b32_sdwa v13, v13, v12 dst_sel:DWORD dst_unused:UNUSED_PAD src0_sel:DWORD src1_sel:WORD_1
	v_or_b32_sdwa v12, v15, v14 dst_sel:DWORD dst_unused:UNUSED_PAD src0_sel:DWORD src1_sel:WORD_1
	s_nop 0
	v_mov_b32_e32 v246, v12
	v_mov_b32_e32 v247, v13
	v_mbcnt_lo_u32_b32 v252, -1, 0
	v_mbcnt_hi_u32_b32 v252, -1, v252
	v_and_b32_e32 v250, 16, v252
	v_lshrrev_b32_e32 v252, 1, v250
	v_add_u32_e32 v250, v250, v252
	v_mov_b32_e32 v251, 0
	v_lshl_add_u64 v[248:249], v[10:11], 0, v[250:251]
	v_permlane16_swap_b32_e32 v244, v246
	v_permlane16_swap_b32_e32 v245, v247
	global_store_dwordx4 v[248:249], v[244:247], off
	v_and_b32_sdwa v13, v146, v232 dst_sel:DWORD dst_unused:UNUSED_PAD src0_sel:WORD_1 src1_sel:DWORD
	v_add3_u32 v14, v146, v13, s43
	v_and_b32_sdwa v13, v145, v232 dst_sel:DWORD dst_unused:UNUSED_PAD src0_sel:WORD_1 src1_sel:DWORD
	v_and_b32_sdwa v15, v144, v232 dst_sel:DWORD dst_unused:UNUSED_PAD src0_sel:WORD_1 src1_sel:DWORD
	v_and_b32_sdwa v12, v147, v232 dst_sel:DWORD dst_unused:UNUSED_PAD src0_sel:WORD_1 src1_sel:DWORD
	v_add3_u32 v13, v145, v13, s43
	v_add3_u32 v15, v144, v15, s43
	v_add3_u32 v12, v147, v12, s43
	v_and_b32_e32 v13, 0xffff0000, v13
	v_and_b32_e32 v15, 0xffff0000, v15
	v_lshl_add_u64 v[10:11], v[8:9], 0, v[116:117]
	v_or_b32_sdwa v13, v13, v12 dst_sel:DWORD dst_unused:UNUSED_PAD src0_sel:DWORD src1_sel:WORD_1
	v_or_b32_sdwa v12, v15, v14 dst_sel:DWORD dst_unused:UNUSED_PAD src0_sel:DWORD src1_sel:WORD_1
	s_nop 0
	v_mov_b32_e32 v244, v12
	v_mov_b32_e32 v245, v13
	v_and_b32_sdwa v13, v142, v232 dst_sel:DWORD dst_unused:UNUSED_PAD src0_sel:WORD_1 src1_sel:DWORD
	v_add3_u32 v14, v142, v13, s43
	v_and_b32_sdwa v13, v141, v232 dst_sel:DWORD dst_unused:UNUSED_PAD src0_sel:WORD_1 src1_sel:DWORD
	v_and_b32_sdwa v15, v140, v232 dst_sel:DWORD dst_unused:UNUSED_PAD src0_sel:WORD_1 src1_sel:DWORD
	v_and_b32_sdwa v12, v143, v232 dst_sel:DWORD dst_unused:UNUSED_PAD src0_sel:WORD_1 src1_sel:DWORD
	v_add3_u32 v13, v141, v13, s43
	v_add3_u32 v15, v140, v15, s43
	v_add3_u32 v12, v143, v12, s43
	v_and_b32_e32 v13, 0xffff0000, v13
	v_and_b32_e32 v15, 0xffff0000, v15
	v_or_b32_sdwa v13, v13, v12 dst_sel:DWORD dst_unused:UNUSED_PAD src0_sel:DWORD src1_sel:WORD_1
	v_or_b32_sdwa v12, v15, v14 dst_sel:DWORD dst_unused:UNUSED_PAD src0_sel:DWORD src1_sel:WORD_1
	s_nop 0
	v_mov_b32_e32 v246, v12
	v_mov_b32_e32 v247, v13
	v_mbcnt_lo_u32_b32 v252, -1, 0
	v_mbcnt_hi_u32_b32 v252, -1, v252
	v_and_b32_e32 v250, 16, v252
	v_lshrrev_b32_e32 v252, 1, v250
	v_add_u32_e32 v250, v250, v252
	v_mov_b32_e32 v251, 0
	v_lshl_add_u64 v[248:249], v[10:11], 0, v[250:251]
	v_permlane16_swap_b32_e32 v244, v246
	v_permlane16_swap_b32_e32 v245, v247
	global_store_dwordx4 v[248:249], v[244:247], off
	v_and_b32_sdwa v13, v138, v232 dst_sel:DWORD dst_unused:UNUSED_PAD src0_sel:WORD_1 src1_sel:DWORD
	v_add3_u32 v14, v138, v13, s43
	v_and_b32_sdwa v13, v137, v232 dst_sel:DWORD dst_unused:UNUSED_PAD src0_sel:WORD_1 src1_sel:DWORD
	v_and_b32_sdwa v15, v136, v232 dst_sel:DWORD dst_unused:UNUSED_PAD src0_sel:WORD_1 src1_sel:DWORD
	v_and_b32_sdwa v12, v139, v232 dst_sel:DWORD dst_unused:UNUSED_PAD src0_sel:WORD_1 src1_sel:DWORD
	v_add3_u32 v13, v137, v13, s43
	v_add3_u32 v15, v136, v15, s43
	v_add3_u32 v12, v139, v12, s43
	v_and_b32_e32 v13, 0xffff0000, v13
	v_and_b32_e32 v15, 0xffff0000, v15
	v_lshl_add_u64 v[10:11], v[8:9], 0, v[118:119]
	v_or_b32_sdwa v13, v13, v12 dst_sel:DWORD dst_unused:UNUSED_PAD src0_sel:DWORD src1_sel:WORD_1
	v_or_b32_sdwa v12, v15, v14 dst_sel:DWORD dst_unused:UNUSED_PAD src0_sel:DWORD src1_sel:WORD_1
	s_nop 0
	v_mov_b32_e32 v244, v12
	v_mov_b32_e32 v245, v13
	v_and_b32_sdwa v13, v132, v232 dst_sel:DWORD dst_unused:UNUSED_PAD src0_sel:WORD_1 src1_sel:DWORD
	v_add3_u32 v14, v132, v13, s43
	v_and_b32_sdwa v13, v135, v232 dst_sel:DWORD dst_unused:UNUSED_PAD src0_sel:WORD_1 src1_sel:DWORD
	v_and_b32_sdwa v15, v134, v232 dst_sel:DWORD dst_unused:UNUSED_PAD src0_sel:WORD_1 src1_sel:DWORD
	v_and_b32_sdwa v12, v133, v232 dst_sel:DWORD dst_unused:UNUSED_PAD src0_sel:WORD_1 src1_sel:DWORD
	v_add3_u32 v13, v135, v13, s43
	v_add3_u32 v15, v134, v15, s43
	v_add3_u32 v12, v133, v12, s43
	v_and_b32_e32 v13, 0xffff0000, v13
	v_and_b32_e32 v15, 0xffff0000, v15
	v_or_b32_sdwa v13, v13, v12 dst_sel:DWORD dst_unused:UNUSED_PAD src0_sel:DWORD src1_sel:WORD_1
	v_or_b32_sdwa v12, v15, v14 dst_sel:DWORD dst_unused:UNUSED_PAD src0_sel:DWORD src1_sel:WORD_1
	s_nop 0
	v_mov_b32_e32 v246, v12
	v_mov_b32_e32 v247, v13
	v_mbcnt_lo_u32_b32 v252, -1, 0
	v_mbcnt_hi_u32_b32 v252, -1, v252
	v_and_b32_e32 v250, 16, v252
	v_lshrrev_b32_e32 v252, 1, v250
	v_add_u32_e32 v250, v250, v252
	v_mov_b32_e32 v251, 0
	v_lshl_add_u64 v[248:249], v[10:11], 0, v[250:251]
	v_permlane16_swap_b32_e32 v244, v246
	v_permlane16_swap_b32_e32 v245, v247
	global_store_dwordx4 v[248:249], v[244:247], off
	s_and_saveexec_b64 s[6:7], s[4:5]
	s_cbranch_execz .LBB0_1315
; #define ST4(ptr, a, b, c_, d) (*(uint2*)(ptr) = make_uint2((unsigned)f2bf(a) | ((unsigned)f2bf(b) << 16), (unsigned)f2bf(c_) | ((unsigned)f2bf(d) << 16)))
; __device__ __forceinline__ void merge_phase(const Ctx& p, int hf) {
;     ...
;     if (fat && wr == 1) {
; #pragma unroll
;       for (int n = 0; n < 2; ++n) ST4(mt + (size_t)(256 + fr) * DM + n * 16, msumx[n][0], msumx[n][1], msumx[n][2], msumx[n][3]);
;     }
	v_and_b32_sdwa v10, v6, v232 dst_sel:DWORD dst_unused:UNUSED_PAD src0_sel:WORD_1 src1_sel:DWORD
	v_and_b32_sdwa v11, v4, v232 dst_sel:DWORD dst_unused:UNUSED_PAD src0_sel:WORD_1 src1_sel:DWORD
	v_add3_u32 v6, v6, v10, s43
	v_and_b32_sdwa v10, v7, v232 dst_sel:DWORD dst_unused:UNUSED_PAD src0_sel:WORD_1 src1_sel:DWORD
	v_mov_b32_e32 v127, v129
	v_add3_u32 v4, v4, v11, s43
	v_and_b32_sdwa v11, v5, v232 dst_sel:DWORD dst_unused:UNUSED_PAD src0_sel:WORD_1 src1_sel:DWORD
	v_add3_u32 v7, v7, v10, s43
	v_lshl_add_u64 v[8:9], v[8:9], 0, v[126:127]
	v_add3_u32 v5, v5, v11, s43
	v_and_b32_e32 v7, 0xffff0000, v7
	s_mov_b32 s4, 0x80000
	v_and_b32_e32 v10, 0xffff0000, v5
	v_or_b32_sdwa v5, v7, v6 dst_sel:DWORD dst_unused:UNUSED_PAD src0_sel:DWORD src1_sel:WORD_1
	v_add_co_u32_e32 v6, vcc, s4, v8
	v_or_b32_sdwa v4, v10, v4 dst_sel:DWORD dst_unused:UNUSED_PAD src0_sel:DWORD src1_sel:WORD_1
	s_nop 0
	v_addc_co_u32_e32 v7, vcc, 0, v9, vcc
	s_nop 0
	v_mov_b32_e32 v244, v4
	v_mov_b32_e32 v245, v5
	v_and_b32_sdwa v4, v2, v232 dst_sel:DWORD dst_unused:UNUSED_PAD src0_sel:WORD_1 src1_sel:DWORD
	v_and_b32_sdwa v5, v0, v232 dst_sel:DWORD dst_unused:UNUSED_PAD src0_sel:WORD_1 src1_sel:DWORD
	v_add3_u32 v0, v0, v5, s43
	v_add3_u32 v2, v2, v4, s43
	v_and_b32_sdwa v4, v3, v232 dst_sel:DWORD dst_unused:UNUSED_PAD src0_sel:WORD_1 src1_sel:DWORD
	v_and_b32_sdwa v5, v1, v232 dst_sel:DWORD dst_unused:UNUSED_PAD src0_sel:WORD_1 src1_sel:DWORD
	v_add3_u32 v3, v3, v4, s43
	v_add3_u32 v1, v1, v5, s43
	v_and_b32_e32 v3, 0xffff0000, v3
	v_and_b32_e32 v4, 0xffff0000, v1
	v_or_b32_sdwa v1, v3, v2 dst_sel:DWORD dst_unused:UNUSED_PAD src0_sel:DWORD src1_sel:WORD_1
	v_or_b32_sdwa v0, v4, v0 dst_sel:DWORD dst_unused:UNUSED_PAD src0_sel:DWORD src1_sel:WORD_1
	s_nop 0
	v_mov_b32_e32 v246, v0
	v_mov_b32_e32 v247, v1
	v_mbcnt_lo_u32_b32 v252, -1, 0
	v_mbcnt_hi_u32_b32 v252, -1, v252
	v_and_b32_e32 v250, 16, v252
	v_lshrrev_b32_e32 v252, 1, v250
	v_add_u32_e32 v250, v250, v252
	v_mov_b32_e32 v251, 0
	v_lshl_add_u64 v[248:249], v[6:7], 0, v[250:251]
	v_permlane16_swap_b32_e32 v244, v246
	v_permlane16_swap_b32_e32 v245, v247
	global_store_dwordx4 v[248:249], v[244:247], off
	s_branch .LBB0_1315

; #define ST4(ptr, a, b, c_, d) (*(uint2*)(ptr) = make_uint2((unsigned)f2bf(a) | ((unsigned)f2bf(b) << 16), (unsigned)f2bf(c_) | ((unsigned)f2bf(d) << 16)))
; template <int EPI>
; __device__ __forceinline__ void gemm_phase(const Ctx& p, int hf, const u16* __restrict__ A, int lda, const u16* __restrict__ Bt, int K, int nN, u16* __restrict__ dst, int ldc, bool fromx = false) {
;     ...
;     else if constexpr (EPI == EPI_RELU2) { ACC_LOOP( _Pragma("unroll") for (int e = 0; e < 4; ++e) { float r = fmaxf(v4[e], 0.f); v4[e] = r * r; }
;                                                       ST4(dst + (size_t)row * ldc + bcol + col, v4[0], v4[1], v4[2], v4[3]); ) }
.LBB0_1728:
	s_or_b64 exec, exec, s[18:19]
	v_add_u32_e32 v146, s14, v181
	s_lshl_b64 s[0:1], s[12:13], 1
	v_max_f32_e32 v143, v143, v143
	s_add_u32 s0, s4, s0
	v_ashrrev_i32_e32 v147, 31, v146
	v_max_f32_e32 v142, v142, v142
	v_max_f32_e32 v150, 0, v143
	v_max_f32_e32 v143, v144, v144
	s_addc_u32 s1, s5, s1
	v_lshlrev_b64 v[148:149], 13, v[146:147]
	v_max_f32_e32 v142, 0, v142
	v_max_f32_e32 v143, 0, v143
	v_max_f32_e32 v144, v145, v145
	v_lshl_add_u64 v[148:149], s[0:1], 0, v[148:149]
	v_max_f32_e32 v151, 0, v144
	v_pk_mul_f32 v[142:143], v[142:143], v[142:143]
	v_lshl_add_u64 v[144:145], v[148:149], 0, v[128:129]
	v_pk_mul_f32 v[148:149], v[150:151], v[150:151]
	v_and_b32_sdwa v147, v143, v232 dst_sel:DWORD dst_unused:UNUSED_PAD src0_sel:WORD_1 src1_sel:DWORD
	v_and_b32_sdwa v150, v142, v232 dst_sel:DWORD dst_unused:UNUSED_PAD src0_sel:WORD_1 src1_sel:DWORD
	v_add3_u32 v142, v142, v150, s43
	v_add3_u32 v143, v143, v147, s43
	v_and_b32_sdwa v147, v149, v232 dst_sel:DWORD dst_unused:UNUSED_PAD src0_sel:WORD_1 src1_sel:DWORD
	v_and_b32_sdwa v150, v148, v232 dst_sel:DWORD dst_unused:UNUSED_PAD src0_sel:WORD_1 src1_sel:DWORD
	v_add3_u32 v147, v149, v147, s43
	v_add3_u32 v148, v148, v150, s43
	v_and_b32_e32 v147, 0xffff0000, v147
	v_and_b32_e32 v148, 0xffff0000, v148
	v_or_b32_sdwa v143, v147, v143 dst_sel:DWORD dst_unused:UNUSED_PAD src0_sel:DWORD src1_sel:WORD_1
	v_or_b32_sdwa v142, v148, v142 dst_sel:DWORD dst_unused:UNUSED_PAD src0_sel:DWORD src1_sel:WORD_1
	v_max_f32_e32 v139, v139, v139
	s_waitcnt vmcnt(0)
	s_barrier
	s_nop 0
	v_mov_b32_e32 v212, v142
	v_mov_b32_e32 v213, v143
	v_max_f32_e32 v138, v138, v138
	v_max_f32_e32 v142, 0, v139
	v_max_f32_e32 v139, v140, v140
	v_max_f32_e32 v138, 0, v138
	v_max_f32_e32 v139, 0, v139
	v_max_f32_e32 v140, v141, v141
	v_max_f32_e32 v143, 0, v140
	v_pk_mul_f32 v[138:139], v[138:139], v[138:139]
	v_pk_mul_f32 v[140:141], v[142:143], v[142:143]
	v_and_b32_sdwa v142, v139, v232 dst_sel:DWORD dst_unused:UNUSED_PAD src0_sel:WORD_1 src1_sel:DWORD
	v_and_b32_sdwa v143, v138, v232 dst_sel:DWORD dst_unused:UNUSED_PAD src0_sel:WORD_1 src1_sel:DWORD
	v_add3_u32 v138, v138, v143, s43
	v_add3_u32 v139, v139, v142, s43
	v_and_b32_sdwa v142, v141, v232 dst_sel:DWORD dst_unused:UNUSED_PAD src0_sel:WORD_1 src1_sel:DWORD
	v_and_b32_sdwa v143, v140, v232 dst_sel:DWORD dst_unused:UNUSED_PAD src0_sel:WORD_1 src1_sel:DWORD
	v_add3_u32 v141, v141, v142, s43
	v_add3_u32 v140, v140, v143, s43
	v_and_b32_e32 v141, 0xffff0000, v141
	v_and_b32_e32 v140, 0xffff0000, v140
	v_or_b32_sdwa v139, v141, v139 dst_sel:DWORD dst_unused:UNUSED_PAD src0_sel:DWORD src1_sel:WORD_1
	v_or_b32_sdwa v138, v140, v138 dst_sel:DWORD dst_unused:UNUSED_PAD src0_sel:DWORD src1_sel:WORD_1
	v_max_f32_e32 v135, v135, v135
	s_nop 0
	v_mov_b32_e32 v214, v138
	v_mov_b32_e32 v215, v139
	v_mbcnt_lo_u32_b32 v224, -1, 0
	v_mbcnt_hi_u32_b32 v224, -1, v224
	v_and_b32_e32 v222, 16, v224
	v_lshrrev_b32_e32 v224, 1, v222
	v_add_u32_e32 v222, v222, v224
	v_mov_b32_e32 v223, 0
	v_lshl_add_u64 v[220:221], v[144:145], 0, v[222:223]
	v_permlane16_swap_b32_e32 v212, v214
	v_permlane16_swap_b32_e32 v213, v215
	global_store_dwordx4 v[220:221], v[212:215], off
	v_max_f32_e32 v134, v134, v134
	v_max_f32_e32 v138, 0, v135
	v_max_f32_e32 v135, v136, v136
	v_max_f32_e32 v134, 0, v134
	v_max_f32_e32 v135, 0, v135
	v_max_f32_e32 v136, v137, v137
	v_max_f32_e32 v139, 0, v136
	v_pk_mul_f32 v[134:135], v[134:135], v[134:135]
	v_pk_mul_f32 v[136:137], v[138:139], v[138:139]
	v_and_b32_sdwa v138, v135, v232 dst_sel:DWORD dst_unused:UNUSED_PAD src0_sel:WORD_1 src1_sel:DWORD
	v_and_b32_sdwa v139, v134, v232 dst_sel:DWORD dst_unused:UNUSED_PAD src0_sel:WORD_1 src1_sel:DWORD
	v_add3_u32 v134, v134, v139, s43
	v_add3_u32 v135, v135, v138, s43
	v_and_b32_sdwa v138, v137, v232 dst_sel:DWORD dst_unused:UNUSED_PAD src0_sel:WORD_1 src1_sel:DWORD
	v_and_b32_sdwa v139, v136, v232 dst_sel:DWORD dst_unused:UNUSED_PAD src0_sel:WORD_1 src1_sel:DWORD
	v_add3_u32 v137, v137, v138, s43
	v_add3_u32 v136, v136, v139, s43
	v_and_b32_e32 v137, 0xffff0000, v137
	v_and_b32_e32 v136, 0xffff0000, v136
	v_or_b32_sdwa v135, v137, v135 dst_sel:DWORD dst_unused:UNUSED_PAD src0_sel:DWORD src1_sel:WORD_1
	v_or_b32_sdwa v134, v136, v134 dst_sel:DWORD dst_unused:UNUSED_PAD src0_sel:DWORD src1_sel:WORD_1
	v_max_f32_e32 v131, v131, v131
	s_nop 0
	v_mov_b32_e32 v216, v134
	v_mov_b32_e32 v217, v135
	v_max_f32_e32 v130, v130, v130
	v_max_f32_e32 v134, 0, v131
	v_max_f32_e32 v131, v132, v132
	v_max_f32_e32 v130, 0, v130
	v_max_f32_e32 v131, 0, v131
	v_max_f32_e32 v132, v133, v133
	v_max_f32_e32 v135, 0, v132
	v_pk_mul_f32 v[130:131], v[130:131], v[130:131]
	v_pk_mul_f32 v[132:133], v[134:135], v[134:135]
	v_and_b32_sdwa v134, v131, v232 dst_sel:DWORD dst_unused:UNUSED_PAD src0_sel:WORD_1 src1_sel:DWORD
	v_and_b32_sdwa v135, v130, v232 dst_sel:DWORD dst_unused:UNUSED_PAD src0_sel:WORD_1 src1_sel:DWORD
	v_add3_u32 v130, v130, v135, s43
	v_add3_u32 v131, v131, v134, s43
	v_and_b32_sdwa v134, v133, v232 dst_sel:DWORD dst_unused:UNUSED_PAD src0_sel:WORD_1 src1_sel:DWORD
	v_and_b32_sdwa v135, v132, v232 dst_sel:DWORD dst_unused:UNUSED_PAD src0_sel:WORD_1 src1_sel:DWORD
	v_add3_u32 v133, v133, v134, s43
	v_add3_u32 v132, v132, v135, s43
	v_and_b32_e32 v133, 0xffff0000, v133
	v_and_b32_e32 v132, 0xffff0000, v132
	v_or_b32_sdwa v131, v133, v131 dst_sel:DWORD dst_unused:UNUSED_PAD src0_sel:DWORD src1_sel:WORD_1
	v_or_b32_sdwa v130, v132, v130 dst_sel:DWORD dst_unused:UNUSED_PAD src0_sel:DWORD src1_sel:WORD_1
	s_nop 0
	v_mov_b32_e32 v218, v130
	v_mov_b32_e32 v219, v131
	s_nop 1
	v_permlane16_swap_b32_e32 v216, v218
; #define ST4(ptr, a, b, c_, d) (*(uint2*)(ptr) = make_uint2((unsigned)f2bf(a) | ((unsigned)f2bf(b) << 16), (unsigned)f2bf(c_) | ((unsigned)f2bf(d) << 16)))
; template <int EPI>
; __device__ __forceinline__ void gemm_phase(const Ctx& p, int hf, const u16* __restrict__ A, int lda, const u16* __restrict__ Bt, int K, int nN, u16* __restrict__ dst, int ldc, bool fromx = false) {
;     ...
;     else if constexpr (EPI == EPI_RELU2) { ACC_LOOP( _Pragma("unroll") for (int e = 0; e < 4; ++e) { float r = fmaxf(v4[e], 0.f); v4[e] = r * r; }
;                                                       ST4(dst + (size_t)row * ldc + bcol + col, v4[0], v4[1], v4[2], v4[3]); ) }
	v_permlane16_swap_b32_e32 v217, v219
	global_store_dwordx4 v[220:221], v[216:219], off offset:64
	v_add_u32_e32 v130, 16, v146
	v_max_f32_e32 v125, v125, v125
	v_ashrrev_i32_e32 v131, 31, v130
	v_max_f32_e32 v124, v124, v124
	v_max_f32_e32 v132, 0, v125
	v_max_f32_e32 v125, v126, v126
	v_lshlrev_b64 v[130:131], 13, v[130:131]
	v_max_f32_e32 v124, 0, v124
	v_max_f32_e32 v125, 0, v125
	v_max_f32_e32 v126, v127, v127
	v_lshl_add_u64 v[130:131], s[0:1], 0, v[130:131]
	v_max_f32_e32 v133, 0, v126
	v_pk_mul_f32 v[124:125], v[124:125], v[124:125]
	v_lshl_add_u64 v[126:127], v[130:131], 0, v[128:129]
	v_pk_mul_f32 v[130:131], v[132:133], v[132:133]
	v_and_b32_sdwa v132, v125, v232 dst_sel:DWORD dst_unused:UNUSED_PAD src0_sel:WORD_1 src1_sel:DWORD
	v_and_b32_sdwa v133, v124, v232 dst_sel:DWORD dst_unused:UNUSED_PAD src0_sel:WORD_1 src1_sel:DWORD
	v_add3_u32 v124, v124, v133, s43
	v_add3_u32 v125, v125, v132, s43
	v_and_b32_sdwa v132, v131, v232 dst_sel:DWORD dst_unused:UNUSED_PAD src0_sel:WORD_1 src1_sel:DWORD
	v_and_b32_sdwa v133, v130, v232 dst_sel:DWORD dst_unused:UNUSED_PAD src0_sel:WORD_1 src1_sel:DWORD
	v_add3_u32 v131, v131, v132, s43
	v_add3_u32 v130, v130, v133, s43
	v_and_b32_e32 v131, 0xffff0000, v131
	v_and_b32_e32 v130, 0xffff0000, v130
	v_or_b32_sdwa v125, v131, v125 dst_sel:DWORD dst_unused:UNUSED_PAD src0_sel:DWORD src1_sel:WORD_1
	v_or_b32_sdwa v124, v130, v124 dst_sel:DWORD dst_unused:UNUSED_PAD src0_sel:DWORD src1_sel:WORD_1
	v_max_f32_e32 v121, v121, v121
	s_nop 0
	v_mov_b32_e32 v212, v124
	v_mov_b32_e32 v213, v125
	v_max_f32_e32 v120, v120, v120
	v_max_f32_e32 v124, 0, v121
	v_max_f32_e32 v121, v122, v122
	v_max_f32_e32 v120, 0, v120
	v_max_f32_e32 v121, 0, v121
	v_max_f32_e32 v122, v123, v123
	v_max_f32_e32 v125, 0, v122
	v_pk_mul_f32 v[120:121], v[120:121], v[120:121]
	v_pk_mul_f32 v[122:123], v[124:125], v[124:125]
	v_and_b32_sdwa v124, v121, v232 dst_sel:DWORD dst_unused:UNUSED_PAD src0_sel:WORD_1 src1_sel:DWORD
	v_and_b32_sdwa v125, v120, v232 dst_sel:DWORD dst_unused:UNUSED_PAD src0_sel:WORD_1 src1_sel:DWORD
	v_add3_u32 v120, v120, v125, s43
	v_add3_u32 v121, v121, v124, s43
	v_and_b32_sdwa v124, v123, v232 dst_sel:DWORD dst_unused:UNUSED_PAD src0_sel:WORD_1 src1_sel:DWORD
	v_and_b32_sdwa v125, v122, v232 dst_sel:DWORD dst_unused:UNUSED_PAD src0_sel:WORD_1 src1_sel:DWORD
	v_add3_u32 v123, v123, v124, s43
	v_add3_u32 v122, v122, v125, s43
	v_and_b32_e32 v123, 0xffff0000, v123
	v_and_b32_e32 v122, 0xffff0000, v122
	v_or_b32_sdwa v121, v123, v121 dst_sel:DWORD dst_unused:UNUSED_PAD src0_sel:DWORD src1_sel:WORD_1
	v_or_b32_sdwa v120, v122, v120 dst_sel:DWORD dst_unused:UNUSED_PAD src0_sel:DWORD src1_sel:WORD_1
	v_max_f32_e32 v117, v117, v117
	s_nop 0
	v_mov_b32_e32 v214, v120
	v_mov_b32_e32 v215, v121
	v_mbcnt_lo_u32_b32 v224, -1, 0
	v_mbcnt_hi_u32_b32 v224, -1, v224
	v_and_b32_e32 v222, 16, v224
	v_lshrrev_b32_e32 v224, 1, v222
	v_add_u32_e32 v222, v222, v224
	v_mov_b32_e32 v223, 0
	v_lshl_add_u64 v[220:221], v[126:127], 0, v[222:223]
	v_permlane16_swap_b32_e32 v212, v214
	v_permlane16_swap_b32_e32 v213, v215
	global_store_dwordx4 v[220:221], v[212:215], off
	v_max_f32_e32 v116, v116, v116
	v_max_f32_e32 v120, 0, v117
	v_max_f32_e32 v117, v118, v118
	v_max_f32_e32 v116, 0, v116
	v_max_f32_e32 v117, 0, v117
	v_max_f32_e32 v118, v119, v119
	v_max_f32_e32 v121, 0, v118
	v_pk_mul_f32 v[116:117], v[116:117], v[116:117]
	v_pk_mul_f32 v[118:119], v[120:121], v[120:121]
	v_and_b32_sdwa v120, v117, v232 dst_sel:DWORD dst_unused:UNUSED_PAD src0_sel:WORD_1 src1_sel:DWORD
	v_and_b32_sdwa v121, v116, v232 dst_sel:DWORD dst_unused:UNUSED_PAD src0_sel:WORD_1 src1_sel:DWORD
	v_add3_u32 v116, v116, v121, s43
	v_add3_u32 v117, v117, v120, s43
	v_and_b32_sdwa v120, v119, v232 dst_sel:DWORD dst_unused:UNUSED_PAD src0_sel:WORD_1 src1_sel:DWORD
	v_and_b32_sdwa v121, v118, v232 dst_sel:DWORD dst_unused:UNUSED_PAD src0_sel:WORD_1 src1_sel:DWORD
	v_add3_u32 v119, v119, v120, s43
	v_add3_u32 v118, v118, v121, s43
	v_and_b32_e32 v119, 0xffff0000, v119
	v_and_b32_e32 v118, 0xffff0000, v118
	v_or_b32_sdwa v117, v119, v117 dst_sel:DWORD dst_unused:UNUSED_PAD src0_sel:DWORD src1_sel:WORD_1
	v_or_b32_sdwa v116, v118, v116 dst_sel:DWORD dst_unused:UNUSED_PAD src0_sel:DWORD src1_sel:WORD_1
	v_max_f32_e32 v113, v113, v113
	s_nop 0
	v_mov_b32_e32 v216, v116
	v_mov_b32_e32 v217, v117
	v_max_f32_e32 v112, v112, v112
	v_max_f32_e32 v116, 0, v113
	v_max_f32_e32 v113, v114, v114
	v_max_f32_e32 v112, 0, v112
	v_max_f32_e32 v113, 0, v113
	v_max_f32_e32 v114, v115, v115
	v_max_f32_e32 v117, 0, v114
	v_pk_mul_f32 v[112:113], v[112:113], v[112:113]
	v_pk_mul_f32 v[114:115], v[116:117], v[116:117]
	v_and_b32_sdwa v116, v113, v232 dst_sel:DWORD dst_unused:UNUSED_PAD src0_sel:WORD_1 src1_sel:DWORD
	v_and_b32_sdwa v117, v112, v232 dst_sel:DWORD dst_unused:UNUSED_PAD src0_sel:WORD_1 src1_sel:DWORD
	v_add3_u32 v112, v112, v117, s43
	v_add3_u32 v113, v113, v116, s43
	v_and_b32_sdwa v116, v115, v232 dst_sel:DWORD dst_unused:UNUSED_PAD src0_sel:WORD_1 src1_sel:DWORD
	v_and_b32_sdwa v117, v114, v232 dst_sel:DWORD dst_unused:UNUSED_PAD src0_sel:WORD_1 src1_sel:DWORD
	v_add3_u32 v115, v115, v116, s43
	v_add3_u32 v114, v114, v117, s43
	v_and_b32_e32 v115, 0xffff0000, v115
	v_and_b32_e32 v114, 0xffff0000, v114
	v_or_b32_sdwa v113, v115, v113 dst_sel:DWORD dst_unused:UNUSED_PAD src0_sel:DWORD src1_sel:WORD_1
	v_or_b32_sdwa v112, v114, v112 dst_sel:DWORD dst_unused:UNUSED_PAD src0_sel:DWORD src1_sel:WORD_1
	s_nop 0
	v_mov_b32_e32 v218, v112
	v_mov_b32_e32 v219, v113
	s_nop 1
	v_permlane16_swap_b32_e32 v216, v218
	v_permlane16_swap_b32_e32 v217, v219
; #define ST4(ptr, a, b, c_, d) (*(uint2*)(ptr) = make_uint2((unsigned)f2bf(a) | ((unsigned)f2bf(b) << 16), (unsigned)f2bf(c_) | ((unsigned)f2bf(d) << 16)))
; template <int EPI>
; __device__ __forceinline__ void gemm_phase(const Ctx& p, int hf, const u16* __restrict__ A, int lda, const u16* __restrict__ Bt, int K, int nN, u16* __restrict__ dst, int ldc, bool fromx = false) {
;     ...
;     else if constexpr (EPI == EPI_RELU2) { ACC_LOOP( _Pragma("unroll") for (int e = 0; e < 4; ++e) { float r = fmaxf(v4[e], 0.f); v4[e] = r * r; }
;                                                       ST4(dst + (size_t)row * ldc + bcol + col, v4[0], v4[1], v4[2], v4[3]); ) }
	global_store_dwordx4 v[220:221], v[216:219], off offset:64
	v_add_u32_e32 v112, 32, v146
	v_max_f32_e32 v109, v109, v109
	v_ashrrev_i32_e32 v113, 31, v112
	v_max_f32_e32 v108, v108, v108
	v_max_f32_e32 v114, 0, v109
	v_max_f32_e32 v109, v110, v110
	v_lshlrev_b64 v[112:113], 13, v[112:113]
	v_max_f32_e32 v108, 0, v108
	v_max_f32_e32 v109, 0, v109
	v_max_f32_e32 v110, v111, v111
	v_lshl_add_u64 v[112:113], s[0:1], 0, v[112:113]
	v_max_f32_e32 v115, 0, v110
	v_pk_mul_f32 v[108:109], v[108:109], v[108:109]
	v_lshl_add_u64 v[110:111], v[112:113], 0, v[128:129]
	v_pk_mul_f32 v[112:113], v[114:115], v[114:115]
	v_and_b32_sdwa v114, v109, v232 dst_sel:DWORD dst_unused:UNUSED_PAD src0_sel:WORD_1 src1_sel:DWORD
	v_and_b32_sdwa v115, v108, v232 dst_sel:DWORD dst_unused:UNUSED_PAD src0_sel:WORD_1 src1_sel:DWORD
	v_add3_u32 v108, v108, v115, s43
	v_add3_u32 v109, v109, v114, s43
	v_and_b32_sdwa v114, v113, v232 dst_sel:DWORD dst_unused:UNUSED_PAD src0_sel:WORD_1 src1_sel:DWORD
	v_and_b32_sdwa v115, v112, v232 dst_sel:DWORD dst_unused:UNUSED_PAD src0_sel:WORD_1 src1_sel:DWORD
	v_add3_u32 v113, v113, v114, s43
	v_add3_u32 v112, v112, v115, s43
	v_and_b32_e32 v113, 0xffff0000, v113
	v_and_b32_e32 v112, 0xffff0000, v112
	v_or_b32_sdwa v109, v113, v109 dst_sel:DWORD dst_unused:UNUSED_PAD src0_sel:DWORD src1_sel:WORD_1
	v_or_b32_sdwa v108, v112, v108 dst_sel:DWORD dst_unused:UNUSED_PAD src0_sel:DWORD src1_sel:WORD_1
	v_max_f32_e32 v105, v105, v105
	s_nop 0
	v_mov_b32_e32 v212, v108
	v_mov_b32_e32 v213, v109
	v_max_f32_e32 v104, v104, v104
	v_max_f32_e32 v108, 0, v105
	v_max_f32_e32 v105, v106, v106
	v_max_f32_e32 v104, 0, v104
	v_max_f32_e32 v105, 0, v105
	v_max_f32_e32 v106, v107, v107
	v_max_f32_e32 v109, 0, v106
	v_pk_mul_f32 v[104:105], v[104:105], v[104:105]
	v_pk_mul_f32 v[106:107], v[108:109], v[108:109]
	v_and_b32_sdwa v108, v105, v232 dst_sel:DWORD dst_unused:UNUSED_PAD src0_sel:WORD_1 src1_sel:DWORD
	v_and_b32_sdwa v109, v104, v232 dst_sel:DWORD dst_unused:UNUSED_PAD src0_sel:WORD_1 src1_sel:DWORD
	v_add3_u32 v104, v104, v109, s43
	v_add3_u32 v105, v105, v108, s43
	v_and_b32_sdwa v108, v107, v232 dst_sel:DWORD dst_unused:UNUSED_PAD src0_sel:WORD_1 src1_sel:DWORD
	v_and_b32_sdwa v109, v106, v232 dst_sel:DWORD dst_unused:UNUSED_PAD src0_sel:WORD_1 src1_sel:DWORD
	v_add3_u32 v107, v107, v108, s43
	v_add3_u32 v106, v106, v109, s43
	v_and_b32_e32 v107, 0xffff0000, v107
	v_and_b32_e32 v106, 0xffff0000, v106
	v_or_b32_sdwa v105, v107, v105 dst_sel:DWORD dst_unused:UNUSED_PAD src0_sel:DWORD src1_sel:WORD_1
	v_or_b32_sdwa v104, v106, v104 dst_sel:DWORD dst_unused:UNUSED_PAD src0_sel:DWORD src1_sel:WORD_1
	v_max_f32_e32 v101, v101, v101
	s_nop 0
	v_mov_b32_e32 v214, v104
	v_mov_b32_e32 v215, v105
	v_mbcnt_lo_u32_b32 v224, -1, 0
	v_mbcnt_hi_u32_b32 v224, -1, v224
	v_and_b32_e32 v222, 16, v224
	v_lshrrev_b32_e32 v224, 1, v222
	v_add_u32_e32 v222, v222, v224
	v_mov_b32_e32 v223, 0
	v_lshl_add_u64 v[220:221], v[110:111], 0, v[222:223]
	v_permlane16_swap_b32_e32 v212, v214
	v_permlane16_swap_b32_e32 v213, v215
	global_store_dwordx4 v[220:221], v[212:215], off
	v_max_f32_e32 v100, v100, v100
	v_max_f32_e32 v104, 0, v101
	v_max_f32_e32 v101, v102, v102
	v_max_f32_e32 v100, 0, v100
	v_max_f32_e32 v101, 0, v101
	v_max_f32_e32 v102, v103, v103
	v_max_f32_e32 v105, 0, v102
	v_pk_mul_f32 v[100:101], v[100:101], v[100:101]
	v_pk_mul_f32 v[102:103], v[104:105], v[104:105]
	v_and_b32_sdwa v104, v101, v232 dst_sel:DWORD dst_unused:UNUSED_PAD src0_sel:WORD_1 src1_sel:DWORD
	v_and_b32_sdwa v105, v100, v232 dst_sel:DWORD dst_unused:UNUSED_PAD src0_sel:WORD_1 src1_sel:DWORD
	v_add3_u32 v100, v100, v105, s43
	v_add3_u32 v101, v101, v104, s43
	v_and_b32_sdwa v104, v103, v232 dst_sel:DWORD dst_unused:UNUSED_PAD src0_sel:WORD_1 src1_sel:DWORD
	v_and_b32_sdwa v105, v102, v232 dst_sel:DWORD dst_unused:UNUSED_PAD src0_sel:WORD_1 src1_sel:DWORD
	v_add3_u32 v103, v103, v104, s43
	v_add3_u32 v102, v102, v105, s43
	v_and_b32_e32 v103, 0xffff0000, v103
	v_and_b32_e32 v102, 0xffff0000, v102
	v_or_b32_sdwa v101, v103, v101 dst_sel:DWORD dst_unused:UNUSED_PAD src0_sel:DWORD src1_sel:WORD_1
	v_or_b32_sdwa v100, v102, v100 dst_sel:DWORD dst_unused:UNUSED_PAD src0_sel:DWORD src1_sel:WORD_1
	v_max_f32_e32 v97, v97, v97
	s_nop 0
	v_mov_b32_e32 v216, v100
	v_mov_b32_e32 v217, v101
	v_max_f32_e32 v96, v96, v96
	v_max_f32_e32 v100, 0, v97
	v_max_f32_e32 v97, v98, v98
	v_max_f32_e32 v96, 0, v96
	v_max_f32_e32 v97, 0, v97
	v_max_f32_e32 v98, v99, v99
	v_max_f32_e32 v101, 0, v98
	v_pk_mul_f32 v[96:97], v[96:97], v[96:97]
	v_pk_mul_f32 v[98:99], v[100:101], v[100:101]
	v_and_b32_sdwa v100, v97, v232 dst_sel:DWORD dst_unused:UNUSED_PAD src0_sel:WORD_1 src1_sel:DWORD
	v_and_b32_sdwa v101, v96, v232 dst_sel:DWORD dst_unused:UNUSED_PAD src0_sel:WORD_1 src1_sel:DWORD
	v_add3_u32 v96, v96, v101, s43
	v_add3_u32 v97, v97, v100, s43
	v_and_b32_sdwa v100, v99, v232 dst_sel:DWORD dst_unused:UNUSED_PAD src0_sel:WORD_1 src1_sel:DWORD
	v_and_b32_sdwa v101, v98, v232 dst_sel:DWORD dst_unused:UNUSED_PAD src0_sel:WORD_1 src1_sel:DWORD
	v_add3_u32 v99, v99, v100, s43
	v_add3_u32 v98, v98, v101, s43
	v_and_b32_e32 v99, 0xffff0000, v99
	v_and_b32_e32 v98, 0xffff0000, v98
	v_or_b32_sdwa v97, v99, v97 dst_sel:DWORD dst_unused:UNUSED_PAD src0_sel:DWORD src1_sel:WORD_1
	v_or_b32_sdwa v96, v98, v96 dst_sel:DWORD dst_unused:UNUSED_PAD src0_sel:DWORD src1_sel:WORD_1
	s_nop 0
	v_mov_b32_e32 v218, v96
	v_mov_b32_e32 v219, v97
	s_nop 1
	v_permlane16_swap_b32_e32 v216, v218
	v_permlane16_swap_b32_e32 v217, v219
	global_store_dwordx4 v[220:221], v[216:219], off offset:64
	v_add_u32_e32 v96, 48, v146
	v_max_f32_e32 v93, v93, v93
; #define ST4(ptr, a, b, c_, d) (*(uint2*)(ptr) = make_uint2((unsigned)f2bf(a) | ((unsigned)f2bf(b) << 16), (unsigned)f2bf(c_) | ((unsigned)f2bf(d) << 16)))
; template <int EPI>
; __device__ __forceinline__ void gemm_phase(const Ctx& p, int hf, const u16* __restrict__ A, int lda, const u16* __restrict__ Bt, int K, int nN, u16* __restrict__ dst, int ldc, bool fromx = false) {
;     ...
;     else if constexpr (EPI == EPI_RELU2) { ACC_LOOP( _Pragma("unroll") for (int e = 0; e < 4; ++e) { float r = fmaxf(v4[e], 0.f); v4[e] = r * r; }
;                                                       ST4(dst + (size_t)row * ldc + bcol + col, v4[0], v4[1], v4[2], v4[3]); ) }
	v_ashrrev_i32_e32 v97, 31, v96
	v_max_f32_e32 v92, v92, v92
	v_max_f32_e32 v98, 0, v93
	v_max_f32_e32 v93, v94, v94
	v_lshlrev_b64 v[96:97], 13, v[96:97]
	v_max_f32_e32 v92, 0, v92
	v_max_f32_e32 v93, 0, v93
	v_max_f32_e32 v94, v95, v95
	v_lshl_add_u64 v[96:97], s[0:1], 0, v[96:97]
	v_max_f32_e32 v99, 0, v94
	v_pk_mul_f32 v[92:93], v[92:93], v[92:93]
	v_lshl_add_u64 v[94:95], v[96:97], 0, v[128:129]
	v_pk_mul_f32 v[96:97], v[98:99], v[98:99]
	v_and_b32_sdwa v98, v93, v232 dst_sel:DWORD dst_unused:UNUSED_PAD src0_sel:WORD_1 src1_sel:DWORD
	v_and_b32_sdwa v99, v92, v232 dst_sel:DWORD dst_unused:UNUSED_PAD src0_sel:WORD_1 src1_sel:DWORD
	v_add3_u32 v92, v92, v99, s43
	v_add3_u32 v93, v93, v98, s43
	v_and_b32_sdwa v98, v97, v232 dst_sel:DWORD dst_unused:UNUSED_PAD src0_sel:WORD_1 src1_sel:DWORD
	v_and_b32_sdwa v99, v96, v232 dst_sel:DWORD dst_unused:UNUSED_PAD src0_sel:WORD_1 src1_sel:DWORD
	v_add3_u32 v97, v97, v98, s43
	v_add3_u32 v96, v96, v99, s43
	v_and_b32_e32 v97, 0xffff0000, v97
	v_and_b32_e32 v96, 0xffff0000, v96
	v_or_b32_sdwa v93, v97, v93 dst_sel:DWORD dst_unused:UNUSED_PAD src0_sel:DWORD src1_sel:WORD_1
	v_or_b32_sdwa v92, v96, v92 dst_sel:DWORD dst_unused:UNUSED_PAD src0_sel:DWORD src1_sel:WORD_1
	v_max_f32_e32 v89, v89, v89
	s_nop 0
	v_mov_b32_e32 v212, v92
	v_mov_b32_e32 v213, v93
	v_max_f32_e32 v88, v88, v88
	v_max_f32_e32 v92, 0, v89
	v_max_f32_e32 v89, v90, v90
	v_max_f32_e32 v88, 0, v88
	v_max_f32_e32 v89, 0, v89
	v_max_f32_e32 v90, v91, v91
	v_max_f32_e32 v93, 0, v90
	v_pk_mul_f32 v[88:89], v[88:89], v[88:89]
	v_pk_mul_f32 v[90:91], v[92:93], v[92:93]
	v_and_b32_sdwa v92, v89, v232 dst_sel:DWORD dst_unused:UNUSED_PAD src0_sel:WORD_1 src1_sel:DWORD
	v_and_b32_sdwa v93, v88, v232 dst_sel:DWORD dst_unused:UNUSED_PAD src0_sel:WORD_1 src1_sel:DWORD
	v_add3_u32 v88, v88, v93, s43
	v_add3_u32 v89, v89, v92, s43
	v_and_b32_sdwa v92, v91, v232 dst_sel:DWORD dst_unused:UNUSED_PAD src0_sel:WORD_1 src1_sel:DWORD
	v_and_b32_sdwa v93, v90, v232 dst_sel:DWORD dst_unused:UNUSED_PAD src0_sel:WORD_1 src1_sel:DWORD
	v_add3_u32 v91, v91, v92, s43
	v_add3_u32 v90, v90, v93, s43
	v_and_b32_e32 v91, 0xffff0000, v91
	v_and_b32_e32 v90, 0xffff0000, v90
	v_or_b32_sdwa v89, v91, v89 dst_sel:DWORD dst_unused:UNUSED_PAD src0_sel:DWORD src1_sel:WORD_1
	v_or_b32_sdwa v88, v90, v88 dst_sel:DWORD dst_unused:UNUSED_PAD src0_sel:DWORD src1_sel:WORD_1
	v_max_f32_e32 v85, v85, v85
	s_nop 0
	v_mov_b32_e32 v214, v88
	v_mov_b32_e32 v215, v89
	v_mbcnt_lo_u32_b32 v224, -1, 0
	v_mbcnt_hi_u32_b32 v224, -1, v224
	v_and_b32_e32 v222, 16, v224
	v_lshrrev_b32_e32 v224, 1, v222
	v_add_u32_e32 v222, v222, v224
	v_mov_b32_e32 v223, 0
	v_lshl_add_u64 v[220:221], v[94:95], 0, v[222:223]
	v_permlane16_swap_b32_e32 v212, v214
	v_permlane16_swap_b32_e32 v213, v215
	global_store_dwordx4 v[220:221], v[212:215], off
	v_max_f32_e32 v84, v84, v84
	v_max_f32_e32 v88, 0, v85
	v_max_f32_e32 v85, v86, v86
	v_max_f32_e32 v84, 0, v84
	v_max_f32_e32 v85, 0, v85
	v_max_f32_e32 v86, v87, v87
	v_max_f32_e32 v89, 0, v86
	v_pk_mul_f32 v[84:85], v[84:85], v[84:85]
	v_pk_mul_f32 v[86:87], v[88:89], v[88:89]
	v_and_b32_sdwa v88, v85, v232 dst_sel:DWORD dst_unused:UNUSED_PAD src0_sel:WORD_1 src1_sel:DWORD
	v_and_b32_sdwa v89, v84, v232 dst_sel:DWORD dst_unused:UNUSED_PAD src0_sel:WORD_1 src1_sel:DWORD
	v_add3_u32 v84, v84, v89, s43
	v_add3_u32 v85, v85, v88, s43
	v_and_b32_sdwa v88, v87, v232 dst_sel:DWORD dst_unused:UNUSED_PAD src0_sel:WORD_1 src1_sel:DWORD
	v_and_b32_sdwa v89, v86, v232 dst_sel:DWORD dst_unused:UNUSED_PAD src0_sel:WORD_1 src1_sel:DWORD
	v_add3_u32 v87, v87, v88, s43
	v_add3_u32 v86, v86, v89, s43
	v_and_b32_e32 v87, 0xffff0000, v87
	v_and_b32_e32 v86, 0xffff0000, v86
	v_or_b32_sdwa v85, v87, v85 dst_sel:DWORD dst_unused:UNUSED_PAD src0_sel:DWORD src1_sel:WORD_1
	v_or_b32_sdwa v84, v86, v84 dst_sel:DWORD dst_unused:UNUSED_PAD src0_sel:DWORD src1_sel:WORD_1
	v_max_f32_e32 v81, v81, v81
	s_nop 0
	v_mov_b32_e32 v216, v84
	v_mov_b32_e32 v217, v85
	v_max_f32_e32 v80, v80, v80
	v_max_f32_e32 v84, 0, v81
	v_max_f32_e32 v81, v82, v82
	v_max_f32_e32 v80, 0, v80
	v_max_f32_e32 v81, 0, v81
	v_max_f32_e32 v82, v83, v83
	v_max_f32_e32 v85, 0, v82
	v_pk_mul_f32 v[80:81], v[80:81], v[80:81]
	v_pk_mul_f32 v[82:83], v[84:85], v[84:85]
	v_and_b32_sdwa v84, v81, v232 dst_sel:DWORD dst_unused:UNUSED_PAD src0_sel:WORD_1 src1_sel:DWORD
	v_and_b32_sdwa v85, v80, v232 dst_sel:DWORD dst_unused:UNUSED_PAD src0_sel:WORD_1 src1_sel:DWORD
	v_add3_u32 v80, v80, v85, s43
	v_add3_u32 v81, v81, v84, s43
	v_and_b32_sdwa v84, v83, v232 dst_sel:DWORD dst_unused:UNUSED_PAD src0_sel:WORD_1 src1_sel:DWORD
	v_and_b32_sdwa v85, v82, v232 dst_sel:DWORD dst_unused:UNUSED_PAD src0_sel:WORD_1 src1_sel:DWORD
	v_add3_u32 v83, v83, v84, s43
	v_add3_u32 v82, v82, v85, s43
	v_and_b32_e32 v83, 0xffff0000, v83
	v_and_b32_e32 v82, 0xffff0000, v82
	v_or_b32_sdwa v81, v83, v81 dst_sel:DWORD dst_unused:UNUSED_PAD src0_sel:DWORD src1_sel:WORD_1
	v_or_b32_sdwa v80, v82, v80 dst_sel:DWORD dst_unused:UNUSED_PAD src0_sel:DWORD src1_sel:WORD_1
	s_nop 0
	v_mov_b32_e32 v218, v80
	v_mov_b32_e32 v219, v81
	s_nop 1
	v_permlane16_swap_b32_e32 v216, v218
	v_permlane16_swap_b32_e32 v217, v219
	global_store_dwordx4 v[220:221], v[216:219], off offset:64
	v_add_u32_e32 v80, 64, v146
	v_max_f32_e32 v77, v77, v77
	v_ashrrev_i32_e32 v81, 31, v80
	v_max_f32_e32 v76, v76, v76
	v_max_f32_e32 v82, 0, v77
	v_max_f32_e32 v77, v78, v78
	v_lshlrev_b64 v[80:81], 13, v[80:81]
	v_max_f32_e32 v76, 0, v76
	v_max_f32_e32 v77, 0, v77
	v_max_f32_e32 v78, v79, v79
	v_lshl_add_u64 v[80:81], s[0:1], 0, v[80:81]
	v_max_f32_e32 v83, 0, v78
	v_pk_mul_f32 v[76:77], v[76:77], v[76:77]
; #define ST4(ptr, a, b, c_, d) (*(uint2*)(ptr) = make_uint2((unsigned)f2bf(a) | ((unsigned)f2bf(b) << 16), (unsigned)f2bf(c_) | ((unsigned)f2bf(d) << 16)))
; template <int EPI>
; __device__ __forceinline__ void gemm_phase(const Ctx& p, int hf, const u16* __restrict__ A, int lda, const u16* __restrict__ Bt, int K, int nN, u16* __restrict__ dst, int ldc, bool fromx = false) {
;     ...
;     else if constexpr (EPI == EPI_RELU2) { ACC_LOOP( _Pragma("unroll") for (int e = 0; e < 4; ++e) { float r = fmaxf(v4[e], 0.f); v4[e] = r * r; }
;                                                       ST4(dst + (size_t)row * ldc + bcol + col, v4[0], v4[1], v4[2], v4[3]); ) }
	v_lshl_add_u64 v[78:79], v[80:81], 0, v[128:129]
	v_pk_mul_f32 v[80:81], v[82:83], v[82:83]
	v_and_b32_sdwa v82, v77, v232 dst_sel:DWORD dst_unused:UNUSED_PAD src0_sel:WORD_1 src1_sel:DWORD
	v_and_b32_sdwa v83, v76, v232 dst_sel:DWORD dst_unused:UNUSED_PAD src0_sel:WORD_1 src1_sel:DWORD
	v_add3_u32 v76, v76, v83, s43
	v_add3_u32 v77, v77, v82, s43
	v_and_b32_sdwa v82, v81, v232 dst_sel:DWORD dst_unused:UNUSED_PAD src0_sel:WORD_1 src1_sel:DWORD
	v_and_b32_sdwa v83, v80, v232 dst_sel:DWORD dst_unused:UNUSED_PAD src0_sel:WORD_1 src1_sel:DWORD
	v_add3_u32 v81, v81, v82, s43
	v_add3_u32 v80, v80, v83, s43
	v_and_b32_e32 v81, 0xffff0000, v81
	v_and_b32_e32 v80, 0xffff0000, v80
	v_or_b32_sdwa v77, v81, v77 dst_sel:DWORD dst_unused:UNUSED_PAD src0_sel:DWORD src1_sel:WORD_1
	v_or_b32_sdwa v76, v80, v76 dst_sel:DWORD dst_unused:UNUSED_PAD src0_sel:DWORD src1_sel:WORD_1
	v_max_f32_e32 v73, v73, v73
	s_nop 0
	v_mov_b32_e32 v212, v76
	v_mov_b32_e32 v213, v77
	v_max_f32_e32 v72, v72, v72
	v_max_f32_e32 v76, 0, v73
	v_max_f32_e32 v73, v74, v74
	v_max_f32_e32 v72, 0, v72
	v_max_f32_e32 v73, 0, v73
	v_max_f32_e32 v74, v75, v75
	v_max_f32_e32 v77, 0, v74
	v_pk_mul_f32 v[72:73], v[72:73], v[72:73]
	v_pk_mul_f32 v[74:75], v[76:77], v[76:77]
	v_and_b32_sdwa v76, v73, v232 dst_sel:DWORD dst_unused:UNUSED_PAD src0_sel:WORD_1 src1_sel:DWORD
	v_and_b32_sdwa v77, v72, v232 dst_sel:DWORD dst_unused:UNUSED_PAD src0_sel:WORD_1 src1_sel:DWORD
	v_add3_u32 v72, v72, v77, s43
	v_add3_u32 v73, v73, v76, s43
	v_and_b32_sdwa v76, v75, v232 dst_sel:DWORD dst_unused:UNUSED_PAD src0_sel:WORD_1 src1_sel:DWORD
	v_and_b32_sdwa v77, v74, v232 dst_sel:DWORD dst_unused:UNUSED_PAD src0_sel:WORD_1 src1_sel:DWORD
	v_add3_u32 v75, v75, v76, s43
	v_add3_u32 v74, v74, v77, s43
	v_and_b32_e32 v75, 0xffff0000, v75
	v_and_b32_e32 v74, 0xffff0000, v74
	v_or_b32_sdwa v73, v75, v73 dst_sel:DWORD dst_unused:UNUSED_PAD src0_sel:DWORD src1_sel:WORD_1
	v_or_b32_sdwa v72, v74, v72 dst_sel:DWORD dst_unused:UNUSED_PAD src0_sel:DWORD src1_sel:WORD_1
	v_max_f32_e32 v69, v69, v69
	s_nop 0
	v_mov_b32_e32 v214, v72
	v_mov_b32_e32 v215, v73
	v_mbcnt_lo_u32_b32 v224, -1, 0
	v_mbcnt_hi_u32_b32 v224, -1, v224
	v_and_b32_e32 v222, 16, v224
	v_lshrrev_b32_e32 v224, 1, v222
	v_add_u32_e32 v222, v222, v224
	v_mov_b32_e32 v223, 0
	v_lshl_add_u64 v[220:221], v[78:79], 0, v[222:223]
	v_permlane16_swap_b32_e32 v212, v214
	v_permlane16_swap_b32_e32 v213, v215
	global_store_dwordx4 v[220:221], v[212:215], off
	v_max_f32_e32 v68, v68, v68
	v_max_f32_e32 v72, 0, v69
	v_max_f32_e32 v69, v70, v70
	v_max_f32_e32 v68, 0, v68
	v_max_f32_e32 v69, 0, v69
	v_max_f32_e32 v70, v71, v71
	v_max_f32_e32 v73, 0, v70
	v_pk_mul_f32 v[68:69], v[68:69], v[68:69]
	v_pk_mul_f32 v[70:71], v[72:73], v[72:73]
	v_and_b32_sdwa v72, v69, v232 dst_sel:DWORD dst_unused:UNUSED_PAD src0_sel:WORD_1 src1_sel:DWORD
	v_and_b32_sdwa v73, v68, v232 dst_sel:DWORD dst_unused:UNUSED_PAD src0_sel:WORD_1 src1_sel:DWORD
	v_add3_u32 v68, v68, v73, s43
	v_add3_u32 v69, v69, v72, s43
	v_and_b32_sdwa v72, v71, v232 dst_sel:DWORD dst_unused:UNUSED_PAD src0_sel:WORD_1 src1_sel:DWORD
	v_and_b32_sdwa v73, v70, v232 dst_sel:DWORD dst_unused:UNUSED_PAD src0_sel:WORD_1 src1_sel:DWORD
	v_add3_u32 v71, v71, v72, s43
	v_add3_u32 v70, v70, v73, s43
	v_and_b32_e32 v71, 0xffff0000, v71
	v_and_b32_e32 v70, 0xffff0000, v70
	v_or_b32_sdwa v69, v71, v69 dst_sel:DWORD dst_unused:UNUSED_PAD src0_sel:DWORD src1_sel:WORD_1
	v_or_b32_sdwa v68, v70, v68 dst_sel:DWORD dst_unused:UNUSED_PAD src0_sel:DWORD src1_sel:WORD_1
	v_max_f32_e32 v65, v65, v65
	s_nop 0
	v_mov_b32_e32 v216, v68
	v_mov_b32_e32 v217, v69
	v_max_f32_e32 v64, v64, v64
	v_max_f32_e32 v68, 0, v65
	v_max_f32_e32 v65, v66, v66
	v_max_f32_e32 v64, 0, v64
	v_max_f32_e32 v65, 0, v65
	v_max_f32_e32 v66, v67, v67
	v_max_f32_e32 v69, 0, v66
	v_pk_mul_f32 v[64:65], v[64:65], v[64:65]
	v_pk_mul_f32 v[66:67], v[68:69], v[68:69]
	v_and_b32_sdwa v68, v65, v232 dst_sel:DWORD dst_unused:UNUSED_PAD src0_sel:WORD_1 src1_sel:DWORD
	v_and_b32_sdwa v69, v64, v232 dst_sel:DWORD dst_unused:UNUSED_PAD src0_sel:WORD_1 src1_sel:DWORD
	v_add3_u32 v64, v64, v69, s43
	v_add3_u32 v65, v65, v68, s43
	v_and_b32_sdwa v68, v67, v232 dst_sel:DWORD dst_unused:UNUSED_PAD src0_sel:WORD_1 src1_sel:DWORD
	v_and_b32_sdwa v69, v66, v232 dst_sel:DWORD dst_unused:UNUSED_PAD src0_sel:WORD_1 src1_sel:DWORD
	v_add3_u32 v67, v67, v68, s43
	v_add3_u32 v66, v66, v69, s43
	v_and_b32_e32 v67, 0xffff0000, v67
	v_and_b32_e32 v66, 0xffff0000, v66
	v_or_b32_sdwa v65, v67, v65 dst_sel:DWORD dst_unused:UNUSED_PAD src0_sel:DWORD src1_sel:WORD_1
	v_or_b32_sdwa v64, v66, v64 dst_sel:DWORD dst_unused:UNUSED_PAD src0_sel:DWORD src1_sel:WORD_1
	s_nop 0
	v_mov_b32_e32 v218, v64
	v_mov_b32_e32 v219, v65
	s_nop 1
	v_permlane16_swap_b32_e32 v216, v218
	v_permlane16_swap_b32_e32 v217, v219
	global_store_dwordx4 v[220:221], v[216:219], off offset:64
	v_add_u32_e32 v64, 0x50, v146
	v_max_f32_e32 v61, v61, v61
	v_ashrrev_i32_e32 v65, 31, v64
	v_max_f32_e32 v60, v60, v60
	v_max_f32_e32 v66, 0, v61
	v_max_f32_e32 v61, v62, v62
	v_lshlrev_b64 v[64:65], 13, v[64:65]
	v_max_f32_e32 v60, 0, v60
	v_max_f32_e32 v61, 0, v61
	v_max_f32_e32 v62, v63, v63
	v_lshl_add_u64 v[64:65], s[0:1], 0, v[64:65]
	v_max_f32_e32 v67, 0, v62
	v_pk_mul_f32 v[60:61], v[60:61], v[60:61]
	v_lshl_add_u64 v[62:63], v[64:65], 0, v[128:129]
	v_pk_mul_f32 v[64:65], v[66:67], v[66:67]
	v_and_b32_sdwa v66, v61, v232 dst_sel:DWORD dst_unused:UNUSED_PAD src0_sel:WORD_1 src1_sel:DWORD
	v_and_b32_sdwa v67, v60, v232 dst_sel:DWORD dst_unused:UNUSED_PAD src0_sel:WORD_1 src1_sel:DWORD
	v_add3_u32 v60, v60, v67, s43
	v_add3_u32 v61, v61, v66, s43
; #define ST4(ptr, a, b, c_, d) (*(uint2*)(ptr) = make_uint2((unsigned)f2bf(a) | ((unsigned)f2bf(b) << 16), (unsigned)f2bf(c_) | ((unsigned)f2bf(d) << 16)))
; template <int EPI>
; __device__ __forceinline__ void gemm_phase(const Ctx& p, int hf, const u16* __restrict__ A, int lda, const u16* __restrict__ Bt, int K, int nN, u16* __restrict__ dst, int ldc, bool fromx = false) {
;     ...
;     else if constexpr (EPI == EPI_RELU2) { ACC_LOOP( _Pragma("unroll") for (int e = 0; e < 4; ++e) { float r = fmaxf(v4[e], 0.f); v4[e] = r * r; }
;                                                       ST4(dst + (size_t)row * ldc + bcol + col, v4[0], v4[1], v4[2], v4[3]); ) }
	v_and_b32_sdwa v66, v65, v232 dst_sel:DWORD dst_unused:UNUSED_PAD src0_sel:WORD_1 src1_sel:DWORD
	v_and_b32_sdwa v67, v64, v232 dst_sel:DWORD dst_unused:UNUSED_PAD src0_sel:WORD_1 src1_sel:DWORD
	v_add3_u32 v65, v65, v66, s43
	v_add3_u32 v64, v64, v67, s43
	v_and_b32_e32 v65, 0xffff0000, v65
	v_and_b32_e32 v64, 0xffff0000, v64
	v_or_b32_sdwa v61, v65, v61 dst_sel:DWORD dst_unused:UNUSED_PAD src0_sel:DWORD src1_sel:WORD_1
	v_or_b32_sdwa v60, v64, v60 dst_sel:DWORD dst_unused:UNUSED_PAD src0_sel:DWORD src1_sel:WORD_1
	v_max_f32_e32 v57, v57, v57
	s_nop 0
	v_mov_b32_e32 v212, v60
	v_mov_b32_e32 v213, v61
	v_max_f32_e32 v56, v56, v56
	v_max_f32_e32 v60, 0, v57
	v_max_f32_e32 v57, v58, v58
	v_max_f32_e32 v56, 0, v56
	v_max_f32_e32 v57, 0, v57
	v_max_f32_e32 v58, v59, v59
	v_max_f32_e32 v61, 0, v58
	v_pk_mul_f32 v[56:57], v[56:57], v[56:57]
	v_pk_mul_f32 v[58:59], v[60:61], v[60:61]
	v_and_b32_sdwa v60, v57, v232 dst_sel:DWORD dst_unused:UNUSED_PAD src0_sel:WORD_1 src1_sel:DWORD
	v_and_b32_sdwa v61, v56, v232 dst_sel:DWORD dst_unused:UNUSED_PAD src0_sel:WORD_1 src1_sel:DWORD
	v_add3_u32 v56, v56, v61, s43
	v_add3_u32 v57, v57, v60, s43
	v_and_b32_sdwa v60, v59, v232 dst_sel:DWORD dst_unused:UNUSED_PAD src0_sel:WORD_1 src1_sel:DWORD
	v_and_b32_sdwa v61, v58, v232 dst_sel:DWORD dst_unused:UNUSED_PAD src0_sel:WORD_1 src1_sel:DWORD
	v_add3_u32 v59, v59, v60, s43
	v_add3_u32 v58, v58, v61, s43
	v_and_b32_e32 v59, 0xffff0000, v59
	v_and_b32_e32 v58, 0xffff0000, v58
	v_or_b32_sdwa v57, v59, v57 dst_sel:DWORD dst_unused:UNUSED_PAD src0_sel:DWORD src1_sel:WORD_1
	v_or_b32_sdwa v56, v58, v56 dst_sel:DWORD dst_unused:UNUSED_PAD src0_sel:DWORD src1_sel:WORD_1
	v_max_f32_e32 v53, v53, v53
	s_nop 0
	v_mov_b32_e32 v214, v56
	v_mov_b32_e32 v215, v57
	v_mbcnt_lo_u32_b32 v224, -1, 0
	v_mbcnt_hi_u32_b32 v224, -1, v224
	v_and_b32_e32 v222, 16, v224
	v_lshrrev_b32_e32 v224, 1, v222
	v_add_u32_e32 v222, v222, v224
	v_mov_b32_e32 v223, 0
	v_lshl_add_u64 v[220:221], v[62:63], 0, v[222:223]
	v_permlane16_swap_b32_e32 v212, v214
	v_permlane16_swap_b32_e32 v213, v215
	global_store_dwordx4 v[220:221], v[212:215], off
	v_max_f32_e32 v52, v52, v52
	v_max_f32_e32 v56, 0, v53
	v_max_f32_e32 v53, v54, v54
	v_max_f32_e32 v52, 0, v52
	v_max_f32_e32 v53, 0, v53
	v_max_f32_e32 v54, v55, v55
	v_max_f32_e32 v57, 0, v54
	v_pk_mul_f32 v[52:53], v[52:53], v[52:53]
	v_pk_mul_f32 v[54:55], v[56:57], v[56:57]
	v_and_b32_sdwa v56, v53, v232 dst_sel:DWORD dst_unused:UNUSED_PAD src0_sel:WORD_1 src1_sel:DWORD
	v_and_b32_sdwa v57, v52, v232 dst_sel:DWORD dst_unused:UNUSED_PAD src0_sel:WORD_1 src1_sel:DWORD
	v_add3_u32 v52, v52, v57, s43
	v_add3_u32 v53, v53, v56, s43
	v_and_b32_sdwa v56, v55, v232 dst_sel:DWORD dst_unused:UNUSED_PAD src0_sel:WORD_1 src1_sel:DWORD
	v_and_b32_sdwa v57, v54, v232 dst_sel:DWORD dst_unused:UNUSED_PAD src0_sel:WORD_1 src1_sel:DWORD
	v_add3_u32 v55, v55, v56, s43
	v_add3_u32 v54, v54, v57, s43
	v_and_b32_e32 v55, 0xffff0000, v55
	v_and_b32_e32 v54, 0xffff0000, v54
	v_or_b32_sdwa v53, v55, v53 dst_sel:DWORD dst_unused:UNUSED_PAD src0_sel:DWORD src1_sel:WORD_1
	v_or_b32_sdwa v52, v54, v52 dst_sel:DWORD dst_unused:UNUSED_PAD src0_sel:DWORD src1_sel:WORD_1
	v_max_f32_e32 v49, v49, v49
	s_nop 0
	v_mov_b32_e32 v216, v52
	v_mov_b32_e32 v217, v53
	v_max_f32_e32 v48, v48, v48
	v_max_f32_e32 v52, 0, v49
	v_max_f32_e32 v49, v50, v50
	v_max_f32_e32 v48, 0, v48
	v_max_f32_e32 v49, 0, v49
	v_max_f32_e32 v50, v51, v51
	v_max_f32_e32 v53, 0, v50
	v_pk_mul_f32 v[48:49], v[48:49], v[48:49]
	v_pk_mul_f32 v[50:51], v[52:53], v[52:53]
	v_and_b32_sdwa v52, v49, v232 dst_sel:DWORD dst_unused:UNUSED_PAD src0_sel:WORD_1 src1_sel:DWORD
	v_and_b32_sdwa v53, v48, v232 dst_sel:DWORD dst_unused:UNUSED_PAD src0_sel:WORD_1 src1_sel:DWORD
	v_add3_u32 v48, v48, v53, s43
	v_add3_u32 v49, v49, v52, s43
	v_and_b32_sdwa v52, v51, v232 dst_sel:DWORD dst_unused:UNUSED_PAD src0_sel:WORD_1 src1_sel:DWORD
	v_and_b32_sdwa v53, v50, v232 dst_sel:DWORD dst_unused:UNUSED_PAD src0_sel:WORD_1 src1_sel:DWORD
	v_add3_u32 v51, v51, v52, s43
	v_add3_u32 v50, v50, v53, s43
	v_and_b32_e32 v51, 0xffff0000, v51
	v_and_b32_e32 v50, 0xffff0000, v50
	v_or_b32_sdwa v49, v51, v49 dst_sel:DWORD dst_unused:UNUSED_PAD src0_sel:DWORD src1_sel:WORD_1
	v_or_b32_sdwa v48, v50, v48 dst_sel:DWORD dst_unused:UNUSED_PAD src0_sel:DWORD src1_sel:WORD_1
	s_nop 0
	v_mov_b32_e32 v218, v48
	v_mov_b32_e32 v219, v49
	s_nop 1
	v_permlane16_swap_b32_e32 v216, v218
	v_permlane16_swap_b32_e32 v217, v219
	global_store_dwordx4 v[220:221], v[216:219], off offset:64
	v_add_u32_e32 v48, 0x60, v146
	v_max_f32_e32 v45, v45, v45
	v_ashrrev_i32_e32 v49, 31, v48
	v_max_f32_e32 v44, v44, v44
	v_max_f32_e32 v50, 0, v45
	v_max_f32_e32 v45, v46, v46
	v_lshlrev_b64 v[48:49], 13, v[48:49]
	v_max_f32_e32 v44, 0, v44
	v_max_f32_e32 v45, 0, v45
	v_max_f32_e32 v46, v47, v47
	v_lshl_add_u64 v[48:49], s[0:1], 0, v[48:49]
	v_max_f32_e32 v51, 0, v46
	v_pk_mul_f32 v[44:45], v[44:45], v[44:45]
	v_lshl_add_u64 v[46:47], v[48:49], 0, v[128:129]
	v_pk_mul_f32 v[48:49], v[50:51], v[50:51]
	v_and_b32_sdwa v50, v45, v232 dst_sel:DWORD dst_unused:UNUSED_PAD src0_sel:WORD_1 src1_sel:DWORD
	v_and_b32_sdwa v51, v44, v232 dst_sel:DWORD dst_unused:UNUSED_PAD src0_sel:WORD_1 src1_sel:DWORD
	v_add3_u32 v44, v44, v51, s43
	v_add3_u32 v45, v45, v50, s43
	v_and_b32_sdwa v50, v49, v232 dst_sel:DWORD dst_unused:UNUSED_PAD src0_sel:WORD_1 src1_sel:DWORD
	v_and_b32_sdwa v51, v48, v232 dst_sel:DWORD dst_unused:UNUSED_PAD src0_sel:WORD_1 src1_sel:DWORD
	v_add3_u32 v49, v49, v50, s43
	v_add3_u32 v48, v48, v51, s43
	v_and_b32_e32 v49, 0xffff0000, v49
	v_and_b32_e32 v48, 0xffff0000, v48
; #define ST4(ptr, a, b, c_, d) (*(uint2*)(ptr) = make_uint2((unsigned)f2bf(a) | ((unsigned)f2bf(b) << 16), (unsigned)f2bf(c_) | ((unsigned)f2bf(d) << 16)))
; template <int EPI>
; __device__ __forceinline__ void gemm_phase(const Ctx& p, int hf, const u16* __restrict__ A, int lda, const u16* __restrict__ Bt, int K, int nN, u16* __restrict__ dst, int ldc, bool fromx = false) {
;     ...
;     else if constexpr (EPI == EPI_RELU2) { ACC_LOOP( _Pragma("unroll") for (int e = 0; e < 4; ++e) { float r = fmaxf(v4[e], 0.f); v4[e] = r * r; }
;                                                       ST4(dst + (size_t)row * ldc + bcol + col, v4[0], v4[1], v4[2], v4[3]); ) }
	v_or_b32_sdwa v45, v49, v45 dst_sel:DWORD dst_unused:UNUSED_PAD src0_sel:DWORD src1_sel:WORD_1
	v_or_b32_sdwa v44, v48, v44 dst_sel:DWORD dst_unused:UNUSED_PAD src0_sel:DWORD src1_sel:WORD_1
	v_max_f32_e32 v41, v41, v41
	s_nop 0
	v_mov_b32_e32 v212, v44
	v_mov_b32_e32 v213, v45
	v_max_f32_e32 v40, v40, v40
	v_max_f32_e32 v44, 0, v41
	v_max_f32_e32 v41, v42, v42
	v_max_f32_e32 v40, 0, v40
	v_max_f32_e32 v41, 0, v41
	v_max_f32_e32 v42, v43, v43
	v_max_f32_e32 v45, 0, v42
	v_pk_mul_f32 v[40:41], v[40:41], v[40:41]
	v_pk_mul_f32 v[42:43], v[44:45], v[44:45]
	v_and_b32_sdwa v44, v41, v232 dst_sel:DWORD dst_unused:UNUSED_PAD src0_sel:WORD_1 src1_sel:DWORD
	v_and_b32_sdwa v45, v40, v232 dst_sel:DWORD dst_unused:UNUSED_PAD src0_sel:WORD_1 src1_sel:DWORD
	v_add3_u32 v40, v40, v45, s43
	v_add3_u32 v41, v41, v44, s43
	v_and_b32_sdwa v44, v43, v232 dst_sel:DWORD dst_unused:UNUSED_PAD src0_sel:WORD_1 src1_sel:DWORD
	v_and_b32_sdwa v45, v42, v232 dst_sel:DWORD dst_unused:UNUSED_PAD src0_sel:WORD_1 src1_sel:DWORD
	v_add3_u32 v43, v43, v44, s43
	v_add3_u32 v42, v42, v45, s43
	v_and_b32_e32 v43, 0xffff0000, v43
	v_and_b32_e32 v42, 0xffff0000, v42
	v_or_b32_sdwa v41, v43, v41 dst_sel:DWORD dst_unused:UNUSED_PAD src0_sel:DWORD src1_sel:WORD_1
	v_or_b32_sdwa v40, v42, v40 dst_sel:DWORD dst_unused:UNUSED_PAD src0_sel:DWORD src1_sel:WORD_1
	v_max_f32_e32 v37, v37, v37
	s_nop 0
	v_mov_b32_e32 v214, v40
	v_mov_b32_e32 v215, v41
	v_mbcnt_lo_u32_b32 v224, -1, 0
	v_mbcnt_hi_u32_b32 v224, -1, v224
	v_and_b32_e32 v222, 16, v224
	v_lshrrev_b32_e32 v224, 1, v222
	v_add_u32_e32 v222, v222, v224
	v_mov_b32_e32 v223, 0
	v_lshl_add_u64 v[220:221], v[46:47], 0, v[222:223]
	v_permlane16_swap_b32_e32 v212, v214
	v_permlane16_swap_b32_e32 v213, v215
	global_store_dwordx4 v[220:221], v[212:215], off
	v_max_f32_e32 v36, v36, v36
	v_max_f32_e32 v40, 0, v37
	v_max_f32_e32 v37, v38, v38
	v_max_f32_e32 v36, 0, v36
	v_max_f32_e32 v37, 0, v37
	v_max_f32_e32 v38, v39, v39
	v_max_f32_e32 v41, 0, v38
	v_pk_mul_f32 v[36:37], v[36:37], v[36:37]
	v_pk_mul_f32 v[38:39], v[40:41], v[40:41]
	v_and_b32_sdwa v40, v37, v232 dst_sel:DWORD dst_unused:UNUSED_PAD src0_sel:WORD_1 src1_sel:DWORD
	v_and_b32_sdwa v41, v36, v232 dst_sel:DWORD dst_unused:UNUSED_PAD src0_sel:WORD_1 src1_sel:DWORD
	v_add3_u32 v36, v36, v41, s43
	v_add3_u32 v37, v37, v40, s43
	v_and_b32_sdwa v40, v39, v232 dst_sel:DWORD dst_unused:UNUSED_PAD src0_sel:WORD_1 src1_sel:DWORD
	v_and_b32_sdwa v41, v38, v232 dst_sel:DWORD dst_unused:UNUSED_PAD src0_sel:WORD_1 src1_sel:DWORD
	v_add3_u32 v39, v39, v40, s43
	v_add3_u32 v38, v38, v41, s43
	v_and_b32_e32 v39, 0xffff0000, v39
	v_and_b32_e32 v38, 0xffff0000, v38
	v_or_b32_sdwa v37, v39, v37 dst_sel:DWORD dst_unused:UNUSED_PAD src0_sel:DWORD src1_sel:WORD_1
	v_or_b32_sdwa v36, v38, v36 dst_sel:DWORD dst_unused:UNUSED_PAD src0_sel:DWORD src1_sel:WORD_1
	v_max_f32_e32 v33, v33, v33
	s_nop 0
	v_mov_b32_e32 v216, v36
	v_mov_b32_e32 v217, v37
	v_max_f32_e32 v32, v32, v32
	v_max_f32_e32 v36, 0, v33
	v_max_f32_e32 v33, v34, v34
	v_max_f32_e32 v32, 0, v32
	v_max_f32_e32 v33, 0, v33
	v_max_f32_e32 v34, v35, v35
	v_max_f32_e32 v37, 0, v34
	v_pk_mul_f32 v[32:33], v[32:33], v[32:33]
	v_pk_mul_f32 v[34:35], v[36:37], v[36:37]
	v_and_b32_sdwa v36, v33, v232 dst_sel:DWORD dst_unused:UNUSED_PAD src0_sel:WORD_1 src1_sel:DWORD
	v_and_b32_sdwa v37, v32, v232 dst_sel:DWORD dst_unused:UNUSED_PAD src0_sel:WORD_1 src1_sel:DWORD
	v_add3_u32 v32, v32, v37, s43
	v_add3_u32 v33, v33, v36, s43
	v_and_b32_sdwa v36, v35, v232 dst_sel:DWORD dst_unused:UNUSED_PAD src0_sel:WORD_1 src1_sel:DWORD
	v_and_b32_sdwa v37, v34, v232 dst_sel:DWORD dst_unused:UNUSED_PAD src0_sel:WORD_1 src1_sel:DWORD
	v_add3_u32 v35, v35, v36, s43
	v_add3_u32 v34, v34, v37, s43
	v_and_b32_e32 v35, 0xffff0000, v35
	v_and_b32_e32 v34, 0xffff0000, v34
	v_or_b32_sdwa v33, v35, v33 dst_sel:DWORD dst_unused:UNUSED_PAD src0_sel:DWORD src1_sel:WORD_1
	v_or_b32_sdwa v32, v34, v32 dst_sel:DWORD dst_unused:UNUSED_PAD src0_sel:DWORD src1_sel:WORD_1
	s_nop 0
	v_mov_b32_e32 v218, v32
	v_mov_b32_e32 v219, v33
	s_nop 1
	v_permlane16_swap_b32_e32 v216, v218
	v_permlane16_swap_b32_e32 v217, v219
	global_store_dwordx4 v[220:221], v[216:219], off offset:64
	v_add_u32_e32 v32, 0x70, v146
	v_max_f32_e32 v29, v29, v29
	v_ashrrev_i32_e32 v33, 31, v32
	v_max_f32_e32 v28, v28, v28
	v_max_f32_e32 v34, 0, v29
	v_max_f32_e32 v29, v30, v30
	v_lshlrev_b64 v[32:33], 13, v[32:33]
	v_max_f32_e32 v28, 0, v28
	v_max_f32_e32 v29, 0, v29
	v_max_f32_e32 v30, v31, v31
	v_lshl_add_u64 v[32:33], s[0:1], 0, v[32:33]
	v_max_f32_e32 v35, 0, v30
	v_pk_mul_f32 v[28:29], v[28:29], v[28:29]
	v_lshl_add_u64 v[30:31], v[32:33], 0, v[128:129]
	v_pk_mul_f32 v[32:33], v[34:35], v[34:35]
	v_and_b32_sdwa v34, v29, v232 dst_sel:DWORD dst_unused:UNUSED_PAD src0_sel:WORD_1 src1_sel:DWORD
	v_and_b32_sdwa v35, v28, v232 dst_sel:DWORD dst_unused:UNUSED_PAD src0_sel:WORD_1 src1_sel:DWORD
	v_add3_u32 v28, v28, v35, s43
	v_add3_u32 v29, v29, v34, s43
	v_and_b32_sdwa v34, v33, v232 dst_sel:DWORD dst_unused:UNUSED_PAD src0_sel:WORD_1 src1_sel:DWORD
	v_and_b32_sdwa v35, v32, v232 dst_sel:DWORD dst_unused:UNUSED_PAD src0_sel:WORD_1 src1_sel:DWORD
	v_add3_u32 v33, v33, v34, s43
	v_add3_u32 v32, v32, v35, s43
	v_and_b32_e32 v33, 0xffff0000, v33
	v_and_b32_e32 v32, 0xffff0000, v32
	v_or_b32_sdwa v29, v33, v29 dst_sel:DWORD dst_unused:UNUSED_PAD src0_sel:DWORD src1_sel:WORD_1
	v_or_b32_sdwa v28, v32, v28 dst_sel:DWORD dst_unused:UNUSED_PAD src0_sel:DWORD src1_sel:WORD_1
	v_max_f32_e32 v25, v25, v25
	s_nop 0
	v_mov_b32_e32 v212, v28
	v_mov_b32_e32 v213, v29
	v_max_f32_e32 v24, v24, v24
	v_max_f32_e32 v28, 0, v25
; #define ST4(ptr, a, b, c_, d) (*(uint2*)(ptr) = make_uint2((unsigned)f2bf(a) | ((unsigned)f2bf(b) << 16), (unsigned)f2bf(c_) | ((unsigned)f2bf(d) << 16)))
; template <int EPI>
; __device__ __forceinline__ void gemm_phase(const Ctx& p, int hf, const u16* __restrict__ A, int lda, const u16* __restrict__ Bt, int K, int nN, u16* __restrict__ dst, int ldc, bool fromx = false) {
;     ...
;     else if constexpr (EPI == EPI_RELU2) { ACC_LOOP( _Pragma("unroll") for (int e = 0; e < 4; ++e) { float r = fmaxf(v4[e], 0.f); v4[e] = r * r; }
;                                                       ST4(dst + (size_t)row * ldc + bcol + col, v4[0], v4[1], v4[2], v4[3]); ) }
	v_max_f32_e32 v25, v26, v26
	v_max_f32_e32 v24, 0, v24
	v_max_f32_e32 v25, 0, v25
	v_max_f32_e32 v26, v27, v27
	v_max_f32_e32 v29, 0, v26
	v_pk_mul_f32 v[24:25], v[24:25], v[24:25]
	v_pk_mul_f32 v[26:27], v[28:29], v[28:29]
	v_and_b32_sdwa v28, v25, v232 dst_sel:DWORD dst_unused:UNUSED_PAD src0_sel:WORD_1 src1_sel:DWORD
	v_and_b32_sdwa v29, v24, v232 dst_sel:DWORD dst_unused:UNUSED_PAD src0_sel:WORD_1 src1_sel:DWORD
	v_add3_u32 v24, v24, v29, s43
	v_add3_u32 v25, v25, v28, s43
	v_and_b32_sdwa v28, v27, v232 dst_sel:DWORD dst_unused:UNUSED_PAD src0_sel:WORD_1 src1_sel:DWORD
	v_and_b32_sdwa v29, v26, v232 dst_sel:DWORD dst_unused:UNUSED_PAD src0_sel:WORD_1 src1_sel:DWORD
	v_add3_u32 v27, v27, v28, s43
	v_add3_u32 v26, v26, v29, s43
	v_and_b32_e32 v27, 0xffff0000, v27
	v_and_b32_e32 v26, 0xffff0000, v26
	v_or_b32_sdwa v25, v27, v25 dst_sel:DWORD dst_unused:UNUSED_PAD src0_sel:DWORD src1_sel:WORD_1
	v_or_b32_sdwa v24, v26, v24 dst_sel:DWORD dst_unused:UNUSED_PAD src0_sel:DWORD src1_sel:WORD_1
	v_max_f32_e32 v21, v21, v21
	s_nop 0
	v_mov_b32_e32 v214, v24
	v_mov_b32_e32 v215, v25
	v_mbcnt_lo_u32_b32 v224, -1, 0
	v_mbcnt_hi_u32_b32 v224, -1, v224
	v_and_b32_e32 v222, 16, v224
	v_lshrrev_b32_e32 v224, 1, v222
	v_add_u32_e32 v222, v222, v224
	v_mov_b32_e32 v223, 0
	v_lshl_add_u64 v[220:221], v[30:31], 0, v[222:223]
	v_permlane16_swap_b32_e32 v212, v214
	v_permlane16_swap_b32_e32 v213, v215
	global_store_dwordx4 v[220:221], v[212:215], off
	v_max_f32_e32 v20, v20, v20
	v_max_f32_e32 v24, 0, v21
	v_max_f32_e32 v21, v22, v22
	v_max_f32_e32 v20, 0, v20
	v_max_f32_e32 v21, 0, v21
	v_max_f32_e32 v22, v23, v23
	v_max_f32_e32 v25, 0, v22
	v_pk_mul_f32 v[20:21], v[20:21], v[20:21]
	v_pk_mul_f32 v[22:23], v[24:25], v[24:25]
	v_and_b32_sdwa v24, v21, v232 dst_sel:DWORD dst_unused:UNUSED_PAD src0_sel:WORD_1 src1_sel:DWORD
	v_and_b32_sdwa v25, v20, v232 dst_sel:DWORD dst_unused:UNUSED_PAD src0_sel:WORD_1 src1_sel:DWORD
	v_add3_u32 v20, v20, v25, s43
	v_add3_u32 v21, v21, v24, s43
	v_and_b32_sdwa v24, v23, v232 dst_sel:DWORD dst_unused:UNUSED_PAD src0_sel:WORD_1 src1_sel:DWORD
	v_and_b32_sdwa v25, v22, v232 dst_sel:DWORD dst_unused:UNUSED_PAD src0_sel:WORD_1 src1_sel:DWORD
	v_add3_u32 v23, v23, v24, s43
	v_add3_u32 v22, v22, v25, s43
	v_and_b32_e32 v23, 0xffff0000, v23
	v_and_b32_e32 v22, 0xffff0000, v22
	v_or_b32_sdwa v21, v23, v21 dst_sel:DWORD dst_unused:UNUSED_PAD src0_sel:DWORD src1_sel:WORD_1
	v_or_b32_sdwa v20, v22, v20 dst_sel:DWORD dst_unused:UNUSED_PAD src0_sel:DWORD src1_sel:WORD_1
	v_max_f32_e32 v17, v17, v17
	s_nop 0
	v_mov_b32_e32 v216, v20
	v_mov_b32_e32 v217, v21
	v_max_f32_e32 v16, v16, v16
	v_max_f32_e32 v20, 0, v17
	v_max_f32_e32 v17, v18, v18
	v_max_f32_e32 v16, 0, v16
	v_max_f32_e32 v17, 0, v17
	v_max_f32_e32 v18, v19, v19
	v_max_f32_e32 v21, 0, v18
	v_pk_mul_f32 v[16:17], v[16:17], v[16:17]
	v_pk_mul_f32 v[18:19], v[20:21], v[20:21]
	v_and_b32_sdwa v20, v17, v232 dst_sel:DWORD dst_unused:UNUSED_PAD src0_sel:WORD_1 src1_sel:DWORD
	v_and_b32_sdwa v21, v16, v232 dst_sel:DWORD dst_unused:UNUSED_PAD src0_sel:WORD_1 src1_sel:DWORD
	v_add3_u32 v16, v16, v21, s43
	v_add3_u32 v17, v17, v20, s43
	v_and_b32_sdwa v20, v19, v232 dst_sel:DWORD dst_unused:UNUSED_PAD src0_sel:WORD_1 src1_sel:DWORD
	v_and_b32_sdwa v21, v18, v232 dst_sel:DWORD dst_unused:UNUSED_PAD src0_sel:WORD_1 src1_sel:DWORD
	v_add3_u32 v19, v19, v20, s43
	v_add3_u32 v18, v18, v21, s43
	v_and_b32_e32 v19, 0xffff0000, v19
	v_and_b32_e32 v18, 0xffff0000, v18
	v_or_b32_sdwa v17, v19, v17 dst_sel:DWORD dst_unused:UNUSED_PAD src0_sel:DWORD src1_sel:WORD_1
	v_or_b32_sdwa v16, v18, v16 dst_sel:DWORD dst_unused:UNUSED_PAD src0_sel:DWORD src1_sel:WORD_1
	s_nop 0
	v_mov_b32_e32 v218, v16
	v_mov_b32_e32 v219, v17
	s_nop 1
	v_permlane16_swap_b32_e32 v216, v218
	v_permlane16_swap_b32_e32 v217, v219
	global_store_dwordx4 v[220:221], v[216:219], off offset:64
	s_and_b64 s[16:17], vcc, s[16:17]
	s_and_saveexec_b64 s[0:1], s[16:17]
	s_cbranch_execz .LBB0_1713
; #define ST4(ptr, a, b, c_, d) (*(uint2*)(ptr) = make_uint2((unsigned)f2bf(a) | ((unsigned)f2bf(b) << 16), (unsigned)f2bf(c_) | ((unsigned)f2bf(d) << 16)))
; template <int EPI>
; __device__ __forceinline__ void gemm_phase(const Ctx& p, int hf, const u16* __restrict__ A, int lda, const u16* __restrict__ Bt, int K, int nN, u16* __restrict__ dst, int ldc, bool fromx = false) {
;     ...
;     else if constexpr (EPI == EPI_RELU2) { ACC_LOOP( _Pragma("unroll") for (int e = 0; e < 4; ++e) { float r = fmaxf(v4[e], 0.f); v4[e] = r * r; }
;                                                       ST4(dst + (size_t)row * ldc + bcol + col, v4[0], v4[1], v4[2], v4[3]); ) }
	v_add_u32_e32 v16, s14, v180
	v_ashrrev_i32_e32 v17, 31, v16
	v_max_f32_e32 v13, v13, v13
	v_lshlrev_b64 v[16:17], 13, v[16:17]
	v_max_f32_e32 v12, v12, v12
	v_max_f32_e32 v18, 0, v13
	v_max_f32_e32 v13, v14, v14
	v_lshl_add_u64 v[16:17], s[4:5], 0, v[16:17]
	v_max_f32_e32 v12, 0, v12
	v_max_f32_e32 v13, 0, v13
	v_max_f32_e32 v14, v15, v15
	v_lshl_add_u64 v[16:17], s[12:13], 1, v[16:17]
	v_max_f32_e32 v19, 0, v14
	v_pk_mul_f32 v[12:13], v[12:13], v[12:13]
	v_lshl_add_u64 v[14:15], v[16:17], 0, v[128:129]
	v_pk_mul_f32 v[16:17], v[18:19], v[18:19]
	v_and_b32_sdwa v18, v13, v232 dst_sel:DWORD dst_unused:UNUSED_PAD src0_sel:WORD_1 src1_sel:DWORD
	v_and_b32_sdwa v19, v12, v232 dst_sel:DWORD dst_unused:UNUSED_PAD src0_sel:WORD_1 src1_sel:DWORD
	v_add3_u32 v12, v12, v19, s43
	v_add3_u32 v13, v13, v18, s43
	v_and_b32_sdwa v18, v17, v232 dst_sel:DWORD dst_unused:UNUSED_PAD src0_sel:WORD_1 src1_sel:DWORD
	v_and_b32_sdwa v19, v16, v232 dst_sel:DWORD dst_unused:UNUSED_PAD src0_sel:WORD_1 src1_sel:DWORD
	v_add3_u32 v17, v17, v18, s43
	v_add3_u32 v16, v16, v19, s43
	v_and_b32_e32 v17, 0xffff0000, v17
	v_and_b32_e32 v16, 0xffff0000, v16
	v_or_b32_sdwa v13, v17, v13 dst_sel:DWORD dst_unused:UNUSED_PAD src0_sel:DWORD src1_sel:WORD_1
	v_or_b32_sdwa v12, v16, v12 dst_sel:DWORD dst_unused:UNUSED_PAD src0_sel:DWORD src1_sel:WORD_1
	v_max_f32_e32 v9, v9, v9
	s_nop 0
	v_mov_b32_e32 v212, v12
	v_mov_b32_e32 v213, v13
	v_max_f32_e32 v8, v8, v8
	v_max_f32_e32 v12, 0, v9
	v_max_f32_e32 v9, v10, v10
	v_max_f32_e32 v8, 0, v8
	v_max_f32_e32 v9, 0, v9
	v_max_f32_e32 v10, v11, v11
	v_max_f32_e32 v13, 0, v10
	v_pk_mul_f32 v[8:9], v[8:9], v[8:9]
	v_pk_mul_f32 v[10:11], v[12:13], v[12:13]
	v_and_b32_sdwa v12, v9, v232 dst_sel:DWORD dst_unused:UNUSED_PAD src0_sel:WORD_1 src1_sel:DWORD
	v_and_b32_sdwa v13, v8, v232 dst_sel:DWORD dst_unused:UNUSED_PAD src0_sel:WORD_1 src1_sel:DWORD
	v_add3_u32 v8, v8, v13, s43
	v_add3_u32 v9, v9, v12, s43
	v_and_b32_sdwa v12, v11, v232 dst_sel:DWORD dst_unused:UNUSED_PAD src0_sel:WORD_1 src1_sel:DWORD
	v_and_b32_sdwa v13, v10, v232 dst_sel:DWORD dst_unused:UNUSED_PAD src0_sel:WORD_1 src1_sel:DWORD
	v_add3_u32 v11, v11, v12, s43
	v_add3_u32 v10, v10, v13, s43
	v_and_b32_e32 v11, 0xffff0000, v11
	v_and_b32_e32 v10, 0xffff0000, v10
	v_or_b32_sdwa v9, v11, v9 dst_sel:DWORD dst_unused:UNUSED_PAD src0_sel:DWORD src1_sel:WORD_1
	v_or_b32_sdwa v8, v10, v8 dst_sel:DWORD dst_unused:UNUSED_PAD src0_sel:DWORD src1_sel:WORD_1
	v_max_f32_e32 v5, v5, v5
	s_nop 0
	v_mov_b32_e32 v214, v8
	v_mov_b32_e32 v215, v9
	v_mbcnt_lo_u32_b32 v224, -1, 0
	v_mbcnt_hi_u32_b32 v224, -1, v224
	v_and_b32_e32 v222, 16, v224
	v_lshrrev_b32_e32 v224, 1, v222
	v_add_u32_e32 v222, v222, v224
	v_mov_b32_e32 v223, 0
	v_lshl_add_u64 v[220:221], v[14:15], 0, v[222:223]
	v_permlane16_swap_b32_e32 v212, v214
	v_permlane16_swap_b32_e32 v213, v215
	global_store_dwordx4 v[220:221], v[212:215], off
	v_max_f32_e32 v4, v4, v4
	v_max_f32_e32 v8, 0, v5
	v_max_f32_e32 v5, v6, v6
	v_max_f32_e32 v4, 0, v4
	v_max_f32_e32 v5, 0, v5
	v_max_f32_e32 v6, v7, v7
	v_max_f32_e32 v9, 0, v6
	v_pk_mul_f32 v[4:5], v[4:5], v[4:5]
	v_pk_mul_f32 v[6:7], v[8:9], v[8:9]
	v_and_b32_sdwa v8, v5, v232 dst_sel:DWORD dst_unused:UNUSED_PAD src0_sel:WORD_1 src1_sel:DWORD
	v_and_b32_sdwa v9, v4, v232 dst_sel:DWORD dst_unused:UNUSED_PAD src0_sel:WORD_1 src1_sel:DWORD
	v_add3_u32 v4, v4, v9, s43
	v_add3_u32 v5, v5, v8, s43
	v_and_b32_sdwa v8, v7, v232 dst_sel:DWORD dst_unused:UNUSED_PAD src0_sel:WORD_1 src1_sel:DWORD
	v_and_b32_sdwa v9, v6, v232 dst_sel:DWORD dst_unused:UNUSED_PAD src0_sel:WORD_1 src1_sel:DWORD
	v_add3_u32 v7, v7, v8, s43
	v_add3_u32 v6, v6, v9, s43
	v_and_b32_e32 v7, 0xffff0000, v7
	v_and_b32_e32 v6, 0xffff0000, v6
	v_or_b32_sdwa v5, v7, v5 dst_sel:DWORD dst_unused:UNUSED_PAD src0_sel:DWORD src1_sel:WORD_1
	v_or_b32_sdwa v4, v6, v4 dst_sel:DWORD dst_unused:UNUSED_PAD src0_sel:DWORD src1_sel:WORD_1
	v_max_f32_e32 v1, v1, v1
	s_nop 0
	v_mov_b32_e32 v216, v4
	v_mov_b32_e32 v217, v5
	v_max_f32_e32 v0, v0, v0
	v_max_f32_e32 v4, 0, v1
	v_max_f32_e32 v1, v2, v2
	v_max_f32_e32 v0, 0, v0
	v_max_f32_e32 v1, 0, v1
	v_max_f32_e32 v2, v3, v3
	v_max_f32_e32 v5, 0, v2
	v_pk_mul_f32 v[0:1], v[0:1], v[0:1]
	v_pk_mul_f32 v[2:3], v[4:5], v[4:5]
	v_and_b32_sdwa v4, v1, v232 dst_sel:DWORD dst_unused:UNUSED_PAD src0_sel:WORD_1 src1_sel:DWORD
	v_and_b32_sdwa v5, v0, v232 dst_sel:DWORD dst_unused:UNUSED_PAD src0_sel:WORD_1 src1_sel:DWORD
	v_add3_u32 v0, v0, v5, s43
	v_add3_u32 v1, v1, v4, s43
	v_and_b32_sdwa v4, v3, v232 dst_sel:DWORD dst_unused:UNUSED_PAD src0_sel:WORD_1 src1_sel:DWORD
	v_and_b32_sdwa v5, v2, v232 dst_sel:DWORD dst_unused:UNUSED_PAD src0_sel:WORD_1 src1_sel:DWORD
	v_add3_u32 v3, v3, v4, s43
	v_add3_u32 v2, v2, v5, s43
	v_and_b32_e32 v3, 0xffff0000, v3
	v_and_b32_e32 v2, 0xffff0000, v2
	v_or_b32_sdwa v1, v3, v1 dst_sel:DWORD dst_unused:UNUSED_PAD src0_sel:DWORD src1_sel:WORD_1
	v_or_b32_sdwa v0, v2, v0 dst_sel:DWORD dst_unused:UNUSED_PAD src0_sel:DWORD src1_sel:WORD_1
	s_nop 0
	v_mov_b32_e32 v218, v0
	v_mov_b32_e32 v219, v1
	s_nop 1
	v_permlane16_swap_b32_e32 v216, v218
	v_permlane16_swap_b32_e32 v217, v219
	global_store_dwordx4 v[220:221], v[216:219], off offset:64
	s_branch .LBB0_1713
